# K-loops: the barrier in front of each 32-MFMA segment sunk behind the segment's first 8 MFMAs (MFMAs touch no LDS; all LDS/DMA/waitcnt ops keep their barrier epoch) so barrier turnaround overlaps MFMA
# speedup vs baseline: 1.0027x; 1.0027x over previous
; #define PG8_STAGE(bufoff, gbase, voff) do { _Pragma("unroll") for (int _i = 0; _i < 2; ++_i) \
;         __builtin_amdgcn_global_load_lds((const unsigned*)((const char*)(gbase) + (voff)[_i]), (PG8_LAS unsigned*)(lds + (bufoff) + ldsw + _i * 8192), 16, 0, 0); } while (0)
; #define PG8_LDA(dst, b, h) do { _Pragma("unroll") for (int m = 0; m < 4; ++m) _Pragma("unroll") for (int k = 0; k < 2; ++k) dst[m][k] = *(const PG8_LAS bf16x8*)(lds + PG8_SA(b, h) + aoff + m * 2048 + k * 1024); } while (0)
; #define PG8_LDB(dst, b, h) do { _Pragma("unroll") for (int n = 0; n < 2; ++n) _Pragma("unroll") for (int k = 0; k < 2; ++k) dst[n][k] = *(const PG8_LAS bf16x8*)(lds + PG8_SB(b, h) + boff + n * 2048 + k * 1024); } while (0)
; #define PG8_MMA(ai, bj, At, Bt) do { __builtin_amdgcn_s_setprio(1); _Pragma("unroll") for (int m = 0; m < 4; ++m) _Pragma("unroll") for (int n = 0; n < 2; ++n) _Pragma("unroll") for (int k = 0; k < 2; ++k) \
;         acc[ai][bj][m][n] = __builtin_amdgcn_mfma_f32_16x16x32_bf16(Bt[n][k], At[m][k], acc[ai][bj][m][n], 0, 0, 0); __builtin_amdgcn_s_setprio(0); } while (0)
; template <class Epi, class Sched, bool ALIGN_EPI = false, bool SP2 = false>
; __device__ __forceinline__ void gemm_phase(PG8_LAS unsigned char* lds, const Gemm g, const Sched& S, const Epi& E, int wave0) {
;     ...
;             PG8_LDB(B0, 0, 0); PG8_LDB(B1, 0, 1); PG8_SCHED; PG8_LDA(At, 0, 0); PG8_STAGE(PG8_SA(1, 1), a1 + hstep, voffA);
;             PG8_WAIT_V(8); PG8_WAIT_L(0); PG8_BAR; PG8_MMA(0, 0, At, B0); PG8_MMA(0, 1, At, B1); PG8_BAR; PG8_SCHED;
;             PG8_LDA(At, 0, 1); PG8_STAGE(PG8_SB(0, 0), b2, voffB); PG8_STAGE(PG8_SB(0, 1), b2 + hstep, voffB); PG8_STAGE(PG8_SA(0, 0), a2, voffA);
;             PG8_WAIT_V(8); PG8_WAIT_L(0); PG8_BAR; if (!cur.half) { PG8_MMA(1, 0, At, B0); PG8_MMA(1, 1, At, B1); } PG8_BAR; PG8_SCHED;
;             PG8_LDB(B0, 1, 0); PG8_LDB(B1, 1, 1); PG8_SCHED; PG8_LDA(At, 1, 0); PG8_STAGE(PG8_SA(0, 1), a2 + hstep, voffA);
;             PG8_WAIT_V(8); PG8_WAIT_L(0); PG8_BAR; PG8_MMA(0, 0, At, B0); PG8_MMA(0, 1, At, B1); PG8_BAR; PG8_SCHED;
;             PG8_LDA(At, 1, 1); PG8_STAGE(PG8_SB(1, 0), b3, voffB); PG8_STAGE(PG8_SB(1, 1), b3 + hstep, voffB); PG8_STAGE(PG8_SA(1, 0), a3, voffA);
;             PG8_WAIT_V(8); PG8_WAIT_L(0); PG8_BAR; if (!cur.half) { PG8_MMA(1, 0, At, B0); PG8_MMA(1, 1, At, B1); } PG8_BAR; PG8_SCHED;
.LBB0_94:
	ds_read_b128 v[144:147], v169
	ds_read_b128 v[148:151], v169 offset:1024
	ds_read_b128 v[152:155], v169 offset:2048
	ds_read_b128 v[156:159], v169 offset:3072
	ds_read_b128 v[160:163], v170
	ds_read_b128 v[174:177], v170 offset:1024
	ds_read_b128 v[178:181], v170 offset:2048
	ds_read_b128 v[182:185], v170 offset:3072
	s_add_u32 s14, s52, 0xfffc0080
	s_addc_u32 s15, s53, -1
	s_cmp_eq_u32 s68, 12
	s_cselect_b32 s63, s3, s15
	s_cselect_b32 s62, s7, s14
	s_cselect_b32 s57, s43, vcc_hi
	s_cselect_b32 s56, s45, vcc_lo
	v_lshl_add_u64 v[164:165], s[52:53], 0, v[136:137]
	s_add_i32 m0, s19, 0xc000
	ds_read_b128 v[186:189], v171
	ds_read_b128 v[190:193], v171 offset:1024
	ds_read_b128 v[194:197], v171 offset:2048
	ds_read_b128 v[198:201], v171 offset:3072
	ds_read_b128 v[202:205], v171 offset:4096
	ds_read_b128 v[206:209], v171 offset:5120
	ds_read_b128 v[210:213], v171 offset:6144
	ds_read_b128 v[218:221], v171 offset:7168
	global_load_lds_dwordx4 v[164:165], off
	v_lshl_add_u64 v[164:165], s[52:53], 0, v[138:139]
	s_add_i32 m0, s19, 0xe000
	s_nop 0
	global_load_lds_dwordx4 v[164:165], off
	s_waitcnt lgkmcnt(0)
	s_setprio 1
	s_waitcnt lgkmcnt(0)
	v_mfma_f32_16x16x32_bf16 v[124:127], v[144:147], v[186:189], v[124:127]
	v_mfma_f32_16x16x32_bf16 v[120:123], v[152:155], v[186:189], v[120:123]
	v_mfma_f32_16x16x32_bf16 v[108:111], v[144:147], v[194:197], v[108:111]
	v_mfma_f32_16x16x32_bf16 v[104:107], v[152:155], v[194:197], v[104:107]
	v_mfma_f32_16x16x32_bf16 v[92:95], v[144:147], v[202:205], v[92:95]
	v_mfma_f32_16x16x32_bf16 v[88:91], v[152:155], v[202:205], v[88:91]
	v_mfma_f32_16x16x32_bf16 v[76:79], v[144:147], v[210:213], v[76:79]
	v_mfma_f32_16x16x32_bf16 v[72:75], v[152:155], v[210:213], v[72:75]
	s_waitcnt vmcnt(8)
	s_barrier
	v_mfma_f32_16x16x32_bf16 v[124:127], v[148:151], v[190:193], v[124:127]
	v_mfma_f32_16x16x32_bf16 v[120:123], v[156:159], v[190:193], v[120:123]
	v_mfma_f32_16x16x32_bf16 v[108:111], v[148:151], v[198:201], v[108:111]
	v_mfma_f32_16x16x32_bf16 v[104:107], v[156:159], v[198:201], v[104:107]
	v_mfma_f32_16x16x32_bf16 v[92:95], v[148:151], v[206:209], v[92:95]
	v_mfma_f32_16x16x32_bf16 v[88:91], v[156:159], v[206:209], v[88:91]
	v_mfma_f32_16x16x32_bf16 v[76:79], v[148:151], v[218:221], v[76:79]
	v_mfma_f32_16x16x32_bf16 v[72:75], v[156:159], v[218:221], v[72:75]
	s_setprio 0
	s_setprio 1
	v_mfma_f32_16x16x32_bf16 v[116:119], v[160:163], v[186:189], v[116:119]
	v_mfma_f32_16x16x32_bf16 v[112:115], v[178:181], v[186:189], v[112:115]
	v_mfma_f32_16x16x32_bf16 v[100:103], v[160:163], v[194:197], v[100:103]
	v_mfma_f32_16x16x32_bf16 v[96:99], v[178:181], v[194:197], v[96:99]
	v_mfma_f32_16x16x32_bf16 v[84:87], v[160:163], v[202:205], v[84:87]
	v_mfma_f32_16x16x32_bf16 v[80:83], v[178:181], v[202:205], v[80:83]
	v_mfma_f32_16x16x32_bf16 v[68:71], v[160:163], v[210:213], v[68:71]
	v_mfma_f32_16x16x32_bf16 v[64:67], v[178:181], v[210:213], v[64:67]
	v_mfma_f32_16x16x32_bf16 v[116:119], v[174:177], v[190:193], v[116:119]
	v_mfma_f32_16x16x32_bf16 v[112:115], v[182:185], v[190:193], v[112:115]
	v_mfma_f32_16x16x32_bf16 v[100:103], v[174:177], v[198:201], v[100:103]
	v_mfma_f32_16x16x32_bf16 v[96:99], v[182:185], v[198:201], v[96:99]
	v_mfma_f32_16x16x32_bf16 v[84:87], v[174:177], v[206:209], v[84:87]
	v_mfma_f32_16x16x32_bf16 v[80:83], v[182:185], v[206:209], v[80:83]
	v_mfma_f32_16x16x32_bf16 v[68:71], v[174:177], v[218:221], v[68:71]
	v_mfma_f32_16x16x32_bf16 v[64:67], v[182:185], v[218:221], v[64:67]
	s_setprio 0
	s_barrier
	s_add_i32 s14, s85, s17
	v_lshl_add_u64 v[164:165], s[56:57], 0, v[130:131]
	s_mov_b32 m0, s14
	ds_read_b128 v[186:189], v171 offset:16384
	ds_read_b128 v[190:193], v171 offset:17408
	ds_read_b128 v[194:197], v171 offset:18432
	ds_read_b128 v[198:201], v171 offset:19456
	ds_read_b128 v[202:205], v171 offset:20480
	ds_read_b128 v[206:209], v171 offset:21504
	ds_read_b128 v[210:213], v171 offset:22528
	ds_read_b128 v[218:221], v171 offset:23552
	global_load_lds_dwordx4 v[164:165], off
	s_add_i32 m0, s14, 0x2000
	s_add_u32 s14, s56, 0x40000
	v_lshl_add_u64 v[214:215], s[56:57], 0, v[134:135]
	s_addc_u32 s15, s57, 0
	s_add_i32 s69, s86, s17
	global_load_lds_dwordx4 v[214:215], off
	v_lshl_add_u64 v[222:223], s[14:15], 0, v[130:131]
	s_mov_b32 m0, s69
	v_lshl_add_u64 v[224:225], s[62:63], 0, v[132:133]
	global_load_lds_dwordx4 v[222:223], off
	v_lshl_add_u64 v[222:223], s[14:15], 0, v[134:135]
	s_add_i32 m0, s69, 0x2000
	s_nop 0
	global_load_lds_dwordx4 v[222:223], off
	v_lshl_add_u64 v[222:223], s[62:63], 0, v[128:129]
	s_mov_b32 m0, s19
	s_nop 0
	global_load_lds_dwordx4 v[222:223], off
	s_mov_b32 m0, s21
	s_nop 0
	global_load_lds_dwordx4 v[224:225], off
	s_waitcnt lgkmcnt(0)
	s_setprio 1
	s_waitcnt lgkmcnt(0)
	v_mfma_f32_16x16x32_bf16 v[60:63], v[144:147], v[186:189], v[60:63]
	v_mfma_f32_16x16x32_bf16 v[56:59], v[152:155], v[186:189], v[56:59]
	v_mfma_f32_16x16x32_bf16 v[44:47], v[144:147], v[194:197], v[44:47]
	v_mfma_f32_16x16x32_bf16 v[40:43], v[152:155], v[194:197], v[40:43]
	v_mfma_f32_16x16x32_bf16 v[28:31], v[144:147], v[202:205], v[28:31]
	v_mfma_f32_16x16x32_bf16 v[24:27], v[152:155], v[202:205], v[24:27]
	v_mfma_f32_16x16x32_bf16 v[12:15], v[144:147], v[210:213], v[12:15]
	v_mfma_f32_16x16x32_bf16 v[8:11], v[152:155], v[210:213], v[8:11]
	s_waitcnt vmcnt(8)
	s_barrier
; #define PG8_STAGE(bufoff, gbase, voff) do { _Pragma("unroll") for (int _i = 0; _i < 2; ++_i) \
;         __builtin_amdgcn_global_load_lds((const unsigned*)((const char*)(gbase) + (voff)[_i]), (PG8_LAS unsigned*)(lds + (bufoff) + ldsw + _i * 8192), 16, 0, 0); } while (0)
; #define PG8_LDA(dst, b, h) do { _Pragma("unroll") for (int m = 0; m < 4; ++m) _Pragma("unroll") for (int k = 0; k < 2; ++k) dst[m][k] = *(const PG8_LAS bf16x8*)(lds + PG8_SA(b, h) + aoff + m * 2048 + k * 1024); } while (0)
; #define PG8_LDB(dst, b, h) do { _Pragma("unroll") for (int n = 0; n < 2; ++n) _Pragma("unroll") for (int k = 0; k < 2; ++k) dst[n][k] = *(const PG8_LAS bf16x8*)(lds + PG8_SB(b, h) + boff + n * 2048 + k * 1024); } while (0)
; #define PG8_MMA(ai, bj, At, Bt) do { __builtin_amdgcn_s_setprio(1); _Pragma("unroll") for (int m = 0; m < 4; ++m) _Pragma("unroll") for (int n = 0; n < 2; ++n) _Pragma("unroll") for (int k = 0; k < 2; ++k) \
;         acc[ai][bj][m][n] = __builtin_amdgcn_mfma_f32_16x16x32_bf16(Bt[n][k], At[m][k], acc[ai][bj][m][n], 0, 0, 0); __builtin_amdgcn_s_setprio(0); } while (0)
; template <class Epi, class Sched, bool ALIGN_EPI = false, bool SP2 = false>
; __device__ __forceinline__ void gemm_phase(PG8_LAS unsigned char* lds, const Gemm g, const Sched& S, const Epi& E, int wave0) {
;     ...
;             PG8_LDB(B0, 0, 0); PG8_LDB(B1, 0, 1); PG8_SCHED; PG8_LDA(At, 0, 0); PG8_STAGE(PG8_SA(1, 1), a1 + hstep, voffA);
;             PG8_WAIT_V(8); PG8_WAIT_L(0); PG8_BAR; PG8_MMA(0, 0, At, B0); PG8_MMA(0, 1, At, B1); PG8_BAR; PG8_SCHED;
;             PG8_LDA(At, 0, 1); PG8_STAGE(PG8_SB(0, 0), b2, voffB); PG8_STAGE(PG8_SB(0, 1), b2 + hstep, voffB); PG8_STAGE(PG8_SA(0, 0), a2, voffA);
;             PG8_WAIT_V(8); PG8_WAIT_L(0); PG8_BAR; if (!cur.half) { PG8_MMA(1, 0, At, B0); PG8_MMA(1, 1, At, B1); } PG8_BAR; PG8_SCHED;
;             PG8_LDB(B0, 1, 0); PG8_LDB(B1, 1, 1); PG8_SCHED; PG8_LDA(At, 1, 0); PG8_STAGE(PG8_SA(0, 1), a2 + hstep, voffA);
;             PG8_WAIT_V(8); PG8_WAIT_L(0); PG8_BAR; PG8_MMA(0, 0, At, B0); PG8_MMA(0, 1, At, B1); PG8_BAR; PG8_SCHED;
;             PG8_LDA(At, 1, 1); PG8_STAGE(PG8_SB(1, 0), b3, voffB); PG8_STAGE(PG8_SB(1, 1), b3 + hstep, voffB); PG8_STAGE(PG8_SA(1, 0), a3, voffA);
;             PG8_WAIT_V(8); PG8_WAIT_L(0); PG8_BAR; if (!cur.half) { PG8_MMA(1, 0, At, B0); PG8_MMA(1, 1, At, B1); } PG8_BAR; PG8_SCHED;
	v_mfma_f32_16x16x32_bf16 v[60:63], v[148:151], v[190:193], v[60:63]
	v_mfma_f32_16x16x32_bf16 v[56:59], v[156:159], v[190:193], v[56:59]
	v_mfma_f32_16x16x32_bf16 v[44:47], v[148:151], v[198:201], v[44:47]
	v_mfma_f32_16x16x32_bf16 v[40:43], v[156:159], v[198:201], v[40:43]
	v_mfma_f32_16x16x32_bf16 v[28:31], v[148:151], v[206:209], v[28:31]
	v_mfma_f32_16x16x32_bf16 v[24:27], v[156:159], v[206:209], v[24:27]
	v_mfma_f32_16x16x32_bf16 v[12:15], v[148:151], v[218:221], v[12:15]
	v_mfma_f32_16x16x32_bf16 v[8:11], v[156:159], v[218:221], v[8:11]
	s_setprio 0
	s_setprio 1
	v_mfma_f32_16x16x32_bf16 v[52:55], v[160:163], v[186:189], v[52:55]
	v_mfma_f32_16x16x32_bf16 v[48:51], v[178:181], v[186:189], v[48:51]
	v_mfma_f32_16x16x32_bf16 v[36:39], v[160:163], v[194:197], v[36:39]
	v_mfma_f32_16x16x32_bf16 v[32:35], v[178:181], v[194:197], v[32:35]
	v_mfma_f32_16x16x32_bf16 v[20:23], v[160:163], v[202:205], v[20:23]
	v_mfma_f32_16x16x32_bf16 v[16:19], v[178:181], v[202:205], v[16:19]
	v_mfma_f32_16x16x32_bf16 v[4:7], v[160:163], v[210:213], v[4:7]
	v_mfma_f32_16x16x32_bf16 v[0:3], v[178:181], v[210:213], v[0:3]
	v_mfma_f32_16x16x32_bf16 v[52:55], v[174:177], v[190:193], v[52:55]
	v_mfma_f32_16x16x32_bf16 v[48:51], v[182:185], v[190:193], v[48:51]
	v_mfma_f32_16x16x32_bf16 v[36:39], v[174:177], v[198:201], v[36:39]
	v_mfma_f32_16x16x32_bf16 v[32:35], v[182:185], v[198:201], v[32:35]
	v_mfma_f32_16x16x32_bf16 v[20:23], v[174:177], v[206:209], v[20:23]
	v_mfma_f32_16x16x32_bf16 v[16:19], v[182:185], v[206:209], v[16:19]
	v_mfma_f32_16x16x32_bf16 v[4:7], v[174:177], v[218:221], v[4:7]
	v_mfma_f32_16x16x32_bf16 v[0:3], v[182:185], v[218:221], v[0:3]
	s_setprio 0
	s_barrier
	s_add_i32 s69, 0, 0x18000
	s_add_i32 s35, 0, 0x1c000
	v_add_u32_e32 v156, s69, v168
	v_add_u32_e32 v182, s35, v168
	ds_read_b128 v[144:147], v156
	ds_read_b128 v[148:151], v156 offset:1024
	ds_read_b128 v[152:155], v156 offset:2048
	ds_read_b128 v[156:159], v156 offset:3072
	ds_read_b128 v[160:163], v182
	ds_read_b128 v[174:177], v182 offset:1024
	ds_read_b128 v[178:181], v182 offset:2048
	ds_read_b128 v[182:185], v182 offset:3072
	s_add_u32 s14, s62, 0x40000
	s_addc_u32 s15, s63, 0
	s_mov_b32 m0, s29
	v_lshl_add_u64 v[226:227], s[14:15], 0, v[128:129]
	ds_read_b128 v[186:189], v171 offset:32768
	ds_read_b128 v[190:193], v171 offset:33792
	ds_read_b128 v[194:197], v171 offset:34816
	ds_read_b128 v[198:201], v171 offset:35840
	ds_read_b128 v[202:205], v171 offset:36864
	ds_read_b128 v[206:209], v171 offset:37888
	ds_read_b128 v[210:213], v171 offset:38912
	ds_read_b128 v[218:221], v171 offset:39936
	global_load_lds_dwordx4 v[226:227], off
	v_lshl_add_u64 v[226:227], s[14:15], 0, v[132:133]
	s_mov_b32 m0, s31
	s_nop 0
	global_load_lds_dwordx4 v[226:227], off
	s_waitcnt lgkmcnt(0)
	s_setprio 1
	s_waitcnt lgkmcnt(0)
	v_mfma_f32_16x16x32_bf16 v[124:127], v[144:147], v[186:189], v[124:127]
	v_mfma_f32_16x16x32_bf16 v[120:123], v[152:155], v[186:189], v[120:123]
	v_mfma_f32_16x16x32_bf16 v[108:111], v[144:147], v[194:197], v[108:111]
	v_mfma_f32_16x16x32_bf16 v[104:107], v[152:155], v[194:197], v[104:107]
	v_mfma_f32_16x16x32_bf16 v[92:95], v[144:147], v[202:205], v[92:95]
	v_mfma_f32_16x16x32_bf16 v[88:91], v[152:155], v[202:205], v[88:91]
	v_mfma_f32_16x16x32_bf16 v[76:79], v[144:147], v[210:213], v[76:79]
	v_mfma_f32_16x16x32_bf16 v[72:75], v[152:155], v[210:213], v[72:75]
	s_waitcnt vmcnt(8)
	s_barrier
	v_mfma_f32_16x16x32_bf16 v[124:127], v[148:151], v[190:193], v[124:127]
	v_mfma_f32_16x16x32_bf16 v[120:123], v[156:159], v[190:193], v[120:123]
	v_mfma_f32_16x16x32_bf16 v[108:111], v[148:151], v[198:201], v[108:111]
	v_mfma_f32_16x16x32_bf16 v[104:107], v[156:159], v[198:201], v[104:107]
	v_mfma_f32_16x16x32_bf16 v[92:95], v[148:151], v[206:209], v[92:95]
	v_mfma_f32_16x16x32_bf16 v[88:91], v[156:159], v[206:209], v[88:91]
	v_mfma_f32_16x16x32_bf16 v[76:79], v[148:151], v[218:221], v[76:79]
	v_mfma_f32_16x16x32_bf16 v[72:75], v[156:159], v[218:221], v[72:75]
	s_setprio 0
	s_setprio 1
	v_mfma_f32_16x16x32_bf16 v[116:119], v[160:163], v[186:189], v[116:119]
	v_mfma_f32_16x16x32_bf16 v[112:115], v[178:181], v[186:189], v[112:115]
	v_mfma_f32_16x16x32_bf16 v[100:103], v[160:163], v[194:197], v[100:103]
	v_mfma_f32_16x16x32_bf16 v[96:99], v[178:181], v[194:197], v[96:99]
	v_mfma_f32_16x16x32_bf16 v[84:87], v[160:163], v[202:205], v[84:87]
	v_mfma_f32_16x16x32_bf16 v[80:83], v[178:181], v[202:205], v[80:83]
	v_mfma_f32_16x16x32_bf16 v[68:71], v[160:163], v[210:213], v[68:71]
	v_mfma_f32_16x16x32_bf16 v[64:67], v[178:181], v[210:213], v[64:67]
	v_mfma_f32_16x16x32_bf16 v[116:119], v[174:177], v[190:193], v[116:119]
	v_mfma_f32_16x16x32_bf16 v[112:115], v[182:185], v[190:193], v[112:115]
	v_mfma_f32_16x16x32_bf16 v[100:103], v[174:177], v[198:201], v[100:103]
	v_mfma_f32_16x16x32_bf16 v[96:99], v[182:185], v[198:201], v[96:99]
	v_mfma_f32_16x16x32_bf16 v[84:87], v[174:177], v[206:209], v[84:87]
	v_mfma_f32_16x16x32_bf16 v[80:83], v[182:185], v[206:209], v[80:83]
	v_mfma_f32_16x16x32_bf16 v[68:71], v[174:177], v[218:221], v[68:71]
	v_mfma_f32_16x16x32_bf16 v[64:67], v[182:185], v[218:221], v[64:67]
	s_setprio 0
	s_barrier
; #define PG8_STAGE(bufoff, gbase, voff) do { _Pragma("unroll") for (int _i = 0; _i < 2; ++_i) \
;         __builtin_amdgcn_global_load_lds((const unsigned*)((const char*)(gbase) + (voff)[_i]), (PG8_LAS unsigned*)(lds + (bufoff) + ldsw + _i * 8192), 16, 0, 0); } while (0)
; #define PG8_LDA(dst, b, h) do { _Pragma("unroll") for (int m = 0; m < 4; ++m) _Pragma("unroll") for (int k = 0; k < 2; ++k) dst[m][k] = *(const PG8_LAS bf16x8*)(lds + PG8_SA(b, h) + aoff + m * 2048 + k * 1024); } while (0)
; #define PG8_LDB(dst, b, h) do { _Pragma("unroll") for (int n = 0; n < 2; ++n) _Pragma("unroll") for (int k = 0; k < 2; ++k) dst[n][k] = *(const PG8_LAS bf16x8*)(lds + PG8_SB(b, h) + boff + n * 2048 + k * 1024); } while (0)
; #define PG8_WAIT_V(n) asm volatile("s_waitcnt vmcnt(" #n ")" ::: "memory")
; template <class Epi, class Sched, bool ALIGN_EPI = false, bool SP2 = false>
; __device__ __forceinline__ void gemm_phase(PG8_LAS unsigned char* lds, const Gemm g, const Sched& S, const Epi& E, int wave0) {
;     ...
;         for (int t = 0; t < nt; t += 2) {
;             const bool last = (t == nt - 2);
;             const char* a1 = cA + (size_t)(t + 1) * kstep;
;             const char* a2 = last ? nA : cA + (size_t)(t + 2) * kstep; const char* b2 = last ? nB : cB + (size_t)(t + 2) * kstep;
;     ...
;             PG8_LDB(B0, 0, 0); PG8_LDB(B1, 0, 1); PG8_SCHED; PG8_LDA(At, 0, 0); PG8_STAGE(PG8_SA(1, 1), a1 + hstep, voffA);
;             PG8_WAIT_V(8); PG8_WAIT_L(0); PG8_BAR; PG8_MMA(0, 0, At, B0); PG8_MMA(0, 1, At, B1); PG8_BAR; PG8_SCHED;
;             PG8_LDA(At, 0, 1); PG8_STAGE(PG8_SB(0, 0), b2, voffB); PG8_STAGE(PG8_SB(0, 1), b2 + hstep, voffB); PG8_STAGE(PG8_SA(0, 0), a2, voffA);
;             PG8_WAIT_V(8); PG8_WAIT_L(0); PG8_BAR; if (!cur.half) { PG8_MMA(1, 0, At, B0); PG8_MMA(1, 1, At, B1); } PG8_BAR; PG8_SCHED;
;             PG8_LDB(B0, 1, 0); PG8_LDB(B1, 1, 1); PG8_SCHED; PG8_LDA(At, 1, 0); PG8_STAGE(PG8_SA(0, 1), a2 + hstep, voffA);
;             PG8_WAIT_V(8); PG8_WAIT_L(0); PG8_BAR; PG8_MMA(0, 0, At, B0); PG8_MMA(0, 1, At, B1); PG8_BAR; PG8_SCHED;
;             PG8_LDA(At, 1, 1); PG8_STAGE(PG8_SB(1, 0), b3, voffB); PG8_STAGE(PG8_SB(1, 1), b3 + hstep, voffB); PG8_STAGE(PG8_SA(1, 0), a3, voffA);
;             PG8_WAIT_V(8); PG8_WAIT_L(0); PG8_BAR; if (!cur.half) { PG8_MMA(1, 0, At, B0); PG8_MMA(1, 1, At, B1); } PG8_BAR; PG8_SCHED;
	s_add_i32 s14, s69, s17
	v_lshl_add_u64 v[164:165], v[164:165], 0, s[10:11]
	s_mov_b32 m0, s14
	ds_read_b128 v[186:189], v171 offset:49152
	ds_read_b128 v[190:193], v171 offset:50176
	ds_read_b128 v[194:197], v171 offset:51200
	ds_read_b128 v[198:201], v171 offset:52224
	ds_read_b128 v[202:205], v171 offset:53248
	ds_read_b128 v[206:209], v171 offset:54272
	ds_read_b128 v[210:213], v171 offset:55296
	ds_read_b128 v[218:221], v171 offset:56320
	global_load_lds_dwordx4 v[164:165], off
	s_add_i32 m0, s14, 0x2000
	s_add_u32 s14, s56, 0x40080
	v_lshl_add_u64 v[164:165], v[214:215], 0, s[10:11]
	s_addc_u32 s15, s57, 0
	s_add_i32 s35, s35, s17
	global_load_lds_dwordx4 v[164:165], off
	v_lshl_add_u64 v[164:165], s[14:15], 0, v[130:131]
	s_mov_b32 m0, s35
	s_nop 0
	global_load_lds_dwordx4 v[164:165], off
	v_lshl_add_u64 v[164:165], s[14:15], 0, v[134:135]
	s_add_i32 m0, s35, 0x2000
	s_nop 0
	global_load_lds_dwordx4 v[164:165], off
	v_lshl_add_u64 v[164:165], v[222:223], 0, s[10:11]
	s_mov_b32 m0, s39
	s_nop 0
	global_load_lds_dwordx4 v[164:165], off
	v_lshl_add_u64 v[164:165], v[224:225], 0, s[10:11]
	s_mov_b32 m0, s41
	s_nop 0
	global_load_lds_dwordx4 v[164:165], off
	s_waitcnt lgkmcnt(0)
	s_setprio 1
	s_waitcnt lgkmcnt(0)
	v_mfma_f32_16x16x32_bf16 v[60:63], v[144:147], v[186:189], v[60:63]
	v_mfma_f32_16x16x32_bf16 v[56:59], v[152:155], v[186:189], v[56:59]
	v_mfma_f32_16x16x32_bf16 v[44:47], v[144:147], v[194:197], v[44:47]
	v_mfma_f32_16x16x32_bf16 v[40:43], v[152:155], v[194:197], v[40:43]
	v_mfma_f32_16x16x32_bf16 v[28:31], v[144:147], v[202:205], v[28:31]
	v_mfma_f32_16x16x32_bf16 v[24:27], v[152:155], v[202:205], v[24:27]
	v_mfma_f32_16x16x32_bf16 v[12:15], v[144:147], v[210:213], v[12:15]
	v_mfma_f32_16x16x32_bf16 v[8:11], v[152:155], v[210:213], v[8:11]
	s_waitcnt vmcnt(8)
	s_barrier
	v_mfma_f32_16x16x32_bf16 v[60:63], v[148:151], v[190:193], v[60:63]
	v_mfma_f32_16x16x32_bf16 v[56:59], v[156:159], v[190:193], v[56:59]
	v_mfma_f32_16x16x32_bf16 v[44:47], v[148:151], v[198:201], v[44:47]
	v_mfma_f32_16x16x32_bf16 v[40:43], v[156:159], v[198:201], v[40:43]
	v_mfma_f32_16x16x32_bf16 v[28:31], v[148:151], v[206:209], v[28:31]
	v_mfma_f32_16x16x32_bf16 v[24:27], v[156:159], v[206:209], v[24:27]
	v_mfma_f32_16x16x32_bf16 v[12:15], v[148:151], v[218:221], v[12:15]
	v_mfma_f32_16x16x32_bf16 v[8:11], v[156:159], v[218:221], v[8:11]
	s_setprio 0
	s_setprio 1
	v_mfma_f32_16x16x32_bf16 v[52:55], v[160:163], v[186:189], v[52:55]
	v_mfma_f32_16x16x32_bf16 v[48:51], v[178:181], v[186:189], v[48:51]
	v_mfma_f32_16x16x32_bf16 v[36:39], v[160:163], v[194:197], v[36:39]
	v_mfma_f32_16x16x32_bf16 v[32:35], v[178:181], v[194:197], v[32:35]
	v_mfma_f32_16x16x32_bf16 v[20:23], v[160:163], v[202:205], v[20:23]
	v_mfma_f32_16x16x32_bf16 v[16:19], v[178:181], v[202:205], v[16:19]
	v_mfma_f32_16x16x32_bf16 v[4:7], v[160:163], v[210:213], v[4:7]
	v_mfma_f32_16x16x32_bf16 v[0:3], v[178:181], v[210:213], v[0:3]
	v_mfma_f32_16x16x32_bf16 v[52:55], v[174:177], v[190:193], v[52:55]
	v_mfma_f32_16x16x32_bf16 v[48:51], v[182:185], v[190:193], v[48:51]
	v_mfma_f32_16x16x32_bf16 v[36:39], v[174:177], v[198:201], v[36:39]
	v_mfma_f32_16x16x32_bf16 v[32:35], v[182:185], v[198:201], v[32:35]
	v_mfma_f32_16x16x32_bf16 v[20:23], v[174:177], v[206:209], v[20:23]
	v_mfma_f32_16x16x32_bf16 v[16:19], v[182:185], v[206:209], v[16:19]
	v_mfma_f32_16x16x32_bf16 v[4:7], v[174:177], v[218:221], v[4:7]
	v_mfma_f32_16x16x32_bf16 v[0:3], v[182:185], v[218:221], v[0:3]
	s_setprio 0
	s_barrier
	s_add_i32 s68, s68, 2
	s_add_u32 s52, s52, 0x100
	s_addc_u32 s53, s53, 0
	s_add_u32 vcc_lo, vcc_lo, 0x100
	s_addc_u32 vcc_hi, vcc_hi, 0
	s_cmp_gt_u32 s68, 13
	s_cbranch_scc0 .LBB0_94
	s_and_b64 vcc, exec, s[64:65]
	s_cbranch_vccz .LBB0_97
	s_barrier

; #define PG8_STAGE(bufoff, gbase, voff) do { _Pragma("unroll") for (int _i = 0; _i < 2; ++_i) \
;         __builtin_amdgcn_global_load_lds((const unsigned*)((const char*)(gbase) + (voff)[_i]), (PG8_LAS unsigned*)(lds + (bufoff) + ldsw + _i * 8192), 16, 0, 0); } while (0)
; #define PG8_LDA(dst, b, h) do { _Pragma("unroll") for (int m = 0; m < 4; ++m) _Pragma("unroll") for (int k = 0; k < 2; ++k) dst[m][k] = *(const PG8_LAS bf16x8*)(lds + PG8_SA(b, h) + aoff + m * 2048 + k * 1024); } while (0)
; #define PG8_LDB(dst, b, h) do { _Pragma("unroll") for (int n = 0; n < 2; ++n) _Pragma("unroll") for (int k = 0; k < 2; ++k) dst[n][k] = *(const PG8_LAS bf16x8*)(lds + PG8_SB(b, h) + boff + n * 2048 + k * 1024); } while (0)
; #define PG8_MMA(ai, bj, At, Bt) do { __builtin_amdgcn_s_setprio(1); _Pragma("unroll") for (int m = 0; m < 4; ++m) _Pragma("unroll") for (int n = 0; n < 2; ++n) _Pragma("unroll") for (int k = 0; k < 2; ++k) \
;         acc[ai][bj][m][n] = __builtin_amdgcn_mfma_f32_16x16x32_bf16(Bt[n][k], At[m][k], acc[ai][bj][m][n], 0, 0, 0); __builtin_amdgcn_s_setprio(0); } while (0)
; template <class Epi, class Sched, bool ALIGN_EPI = false, bool SP2 = false>
; __device__ __forceinline__ void gemm_phase(PG8_LAS unsigned char* lds, const Gemm g, const Sched& S, const Epi& E, int wave0) {
;     ...
;             PG8_LDB(B0, 0, 0); PG8_LDB(B1, 0, 1); PG8_SCHED; PG8_LDA(At, 0, 0); PG8_STAGE(PG8_SA(1, 1), a1 + hstep, voffA);
;             PG8_WAIT_V(8); PG8_WAIT_L(0); PG8_BAR; PG8_MMA(0, 0, At, B0); PG8_MMA(0, 1, At, B1); PG8_BAR; PG8_SCHED;
;             PG8_LDA(At, 0, 1); PG8_STAGE(PG8_SB(0, 0), b2, voffB); PG8_STAGE(PG8_SB(0, 1), b2 + hstep, voffB); PG8_STAGE(PG8_SA(0, 0), a2, voffA);
;             PG8_WAIT_V(8); PG8_WAIT_L(0); PG8_BAR; if (!cur.half) { PG8_MMA(1, 0, At, B0); PG8_MMA(1, 1, At, B1); } PG8_BAR; PG8_SCHED;
;             PG8_LDB(B0, 1, 0); PG8_LDB(B1, 1, 1); PG8_SCHED; PG8_LDA(At, 1, 0); PG8_STAGE(PG8_SA(0, 1), a2 + hstep, voffA);
;             PG8_WAIT_V(8); PG8_WAIT_L(0); PG8_BAR; PG8_MMA(0, 0, At, B0); PG8_MMA(0, 1, At, B1); PG8_BAR; PG8_SCHED;
;             PG8_LDA(At, 1, 1); PG8_STAGE(PG8_SB(1, 0), b3, voffB); PG8_STAGE(PG8_SB(1, 1), b3 + hstep, voffB); PG8_STAGE(PG8_SA(1, 0), a3, voffA);
;             PG8_WAIT_V(8); PG8_WAIT_L(0); PG8_BAR; if (!cur.half) { PG8_MMA(1, 0, At, B0); PG8_MMA(1, 1, At, B1); } PG8_BAR; PG8_SCHED;
.LBB0_363:
	ds_read_b128 v[128:131], v165
	ds_read_b128 v[132:135], v165 offset:1024
	ds_read_b128 v[152:155], v165 offset:2048
	ds_read_b128 v[156:159], v165 offset:3072
	ds_read_b128 v[170:173], v166
	ds_read_b128 v[174:177], v166 offset:1024
	ds_read_b128 v[178:181], v166 offset:2048
	ds_read_b128 v[182:185], v166 offset:3072
	s_add_u32 s30, s28, 0xfffc0080
	s_addc_u32 s31, s29, -1
	s_cmp_eq_u32 s53, 12
	s_cselect_b32 s35, s1, s31
	s_cselect_b32 s34, s17, s30
	s_cselect_b32 s31, s15, s52
	s_cselect_b32 s30, s50, s51
	v_lshl_add_u64 v[160:161], s[28:29], 0, v[144:145]
	s_add_i32 m0, s7, 0xc000
	ds_read_b128 v[186:189], v167
	ds_read_b128 v[190:193], v167 offset:1024
	ds_read_b128 v[194:197], v167 offset:2048
	ds_read_b128 v[198:201], v167 offset:3072
	ds_read_b128 v[202:205], v167 offset:4096
	ds_read_b128 v[206:209], v167 offset:5120
	ds_read_b128 v[210:213], v167 offset:6144
	ds_read_b128 v[218:221], v167 offset:7168
	global_load_lds_dwordx4 v[160:161], off
	v_lshl_add_u64 v[160:161], s[28:29], 0, v[146:147]
	s_add_i32 m0, s7, 0xe000
	s_nop 0
	global_load_lds_dwordx4 v[160:161], off
	s_waitcnt lgkmcnt(0)
	s_setprio 1
	s_waitcnt lgkmcnt(0)
	v_mfma_f32_16x16x32_bf16 v[124:127], v[128:131], v[186:189], v[124:127]
	v_mfma_f32_16x16x32_bf16 v[120:123], v[152:155], v[186:189], v[120:123]
	v_mfma_f32_16x16x32_bf16 v[108:111], v[128:131], v[194:197], v[108:111]
	v_mfma_f32_16x16x32_bf16 v[104:107], v[152:155], v[194:197], v[104:107]
	v_mfma_f32_16x16x32_bf16 v[92:95], v[128:131], v[202:205], v[92:95]
	v_mfma_f32_16x16x32_bf16 v[88:91], v[152:155], v[202:205], v[88:91]
	v_mfma_f32_16x16x32_bf16 v[76:79], v[128:131], v[210:213], v[76:79]
	v_mfma_f32_16x16x32_bf16 v[72:75], v[152:155], v[210:213], v[72:75]
	s_waitcnt vmcnt(8)
	s_barrier
	v_mfma_f32_16x16x32_bf16 v[124:127], v[132:135], v[190:193], v[124:127]
	v_mfma_f32_16x16x32_bf16 v[120:123], v[156:159], v[190:193], v[120:123]
	v_mfma_f32_16x16x32_bf16 v[108:111], v[132:135], v[198:201], v[108:111]
	v_mfma_f32_16x16x32_bf16 v[104:107], v[156:159], v[198:201], v[104:107]
	v_mfma_f32_16x16x32_bf16 v[92:95], v[132:135], v[206:209], v[92:95]
	v_mfma_f32_16x16x32_bf16 v[88:91], v[156:159], v[206:209], v[88:91]
	v_mfma_f32_16x16x32_bf16 v[76:79], v[132:135], v[218:221], v[76:79]
	v_mfma_f32_16x16x32_bf16 v[72:75], v[156:159], v[218:221], v[72:75]
	s_setprio 0
	s_setprio 1
	v_mfma_f32_16x16x32_bf16 v[116:119], v[170:173], v[186:189], v[116:119]
	v_mfma_f32_16x16x32_bf16 v[112:115], v[178:181], v[186:189], v[112:115]
	v_mfma_f32_16x16x32_bf16 v[100:103], v[170:173], v[194:197], v[100:103]
	v_mfma_f32_16x16x32_bf16 v[96:99], v[178:181], v[194:197], v[96:99]
	v_mfma_f32_16x16x32_bf16 v[84:87], v[170:173], v[202:205], v[84:87]
	v_mfma_f32_16x16x32_bf16 v[80:83], v[178:181], v[202:205], v[80:83]
	v_mfma_f32_16x16x32_bf16 v[68:71], v[170:173], v[210:213], v[68:71]
	v_mfma_f32_16x16x32_bf16 v[64:67], v[178:181], v[210:213], v[64:67]
	v_mfma_f32_16x16x32_bf16 v[116:119], v[174:177], v[190:193], v[116:119]
	v_mfma_f32_16x16x32_bf16 v[112:115], v[182:185], v[190:193], v[112:115]
	v_mfma_f32_16x16x32_bf16 v[100:103], v[174:177], v[198:201], v[100:103]
	v_mfma_f32_16x16x32_bf16 v[96:99], v[182:185], v[198:201], v[96:99]
	v_mfma_f32_16x16x32_bf16 v[84:87], v[174:177], v[206:209], v[84:87]
	v_mfma_f32_16x16x32_bf16 v[80:83], v[182:185], v[206:209], v[80:83]
	v_mfma_f32_16x16x32_bf16 v[68:71], v[174:177], v[218:221], v[68:71]
	v_mfma_f32_16x16x32_bf16 v[64:67], v[182:185], v[218:221], v[64:67]
	s_setprio 0
	s_barrier
	s_add_i32 s54, s46, s6
	v_lshl_add_u64 v[160:161], s[30:31], 0, v[138:139]
	s_mov_b32 m0, s54
	ds_read_b128 v[186:189], v167 offset:16384
	ds_read_b128 v[190:193], v167 offset:17408
	ds_read_b128 v[194:197], v167 offset:18432
	ds_read_b128 v[198:201], v167 offset:19456
	ds_read_b128 v[202:205], v167 offset:20480
	ds_read_b128 v[206:209], v167 offset:21504
	ds_read_b128 v[210:213], v167 offset:22528
	ds_read_b128 v[218:221], v167 offset:23552
	global_load_lds_dwordx4 v[160:161], off
	s_add_i32 m0, s54, 0x2000
	s_add_u32 s54, s30, 0x40000
	v_lshl_add_u64 v[214:215], s[30:31], 0, v[142:143]
	s_addc_u32 s55, s31, 0
	s_add_i32 s56, s47, s6
	global_load_lds_dwordx4 v[214:215], off
	v_lshl_add_u64 v[222:223], s[54:55], 0, v[138:139]
	s_mov_b32 m0, s56
	v_lshl_add_u64 v[224:225], s[34:35], 0, v[140:141]
	global_load_lds_dwordx4 v[222:223], off
	v_lshl_add_u64 v[222:223], s[54:55], 0, v[142:143]
	s_add_i32 m0, s56, 0x2000
	s_nop 0
	global_load_lds_dwordx4 v[222:223], off
	v_lshl_add_u64 v[222:223], s[34:35], 0, v[136:137]
	s_mov_b32 m0, s7
	s_nop 0
	global_load_lds_dwordx4 v[222:223], off
	s_mov_b32 m0, s33
	s_nop 0
	global_load_lds_dwordx4 v[224:225], off
	s_waitcnt lgkmcnt(0)
	s_setprio 1
	s_waitcnt lgkmcnt(0)
	v_mfma_f32_16x16x32_bf16 v[60:63], v[128:131], v[186:189], v[60:63]
	v_mfma_f32_16x16x32_bf16 v[56:59], v[152:155], v[186:189], v[56:59]
	v_mfma_f32_16x16x32_bf16 v[44:47], v[128:131], v[194:197], v[44:47]
	v_mfma_f32_16x16x32_bf16 v[40:43], v[152:155], v[194:197], v[40:43]
	v_mfma_f32_16x16x32_bf16 v[28:31], v[128:131], v[202:205], v[28:31]
	v_mfma_f32_16x16x32_bf16 v[24:27], v[152:155], v[202:205], v[24:27]
	v_mfma_f32_16x16x32_bf16 v[12:15], v[128:131], v[210:213], v[12:15]
	v_mfma_f32_16x16x32_bf16 v[8:11], v[152:155], v[210:213], v[8:11]
	s_waitcnt vmcnt(8)
	s_barrier
; #define PG8_STAGE(bufoff, gbase, voff) do { _Pragma("unroll") for (int _i = 0; _i < 2; ++_i) \
;         __builtin_amdgcn_global_load_lds((const unsigned*)((const char*)(gbase) + (voff)[_i]), (PG8_LAS unsigned*)(lds + (bufoff) + ldsw + _i * 8192), 16, 0, 0); } while (0)
; #define PG8_LDA(dst, b, h) do { _Pragma("unroll") for (int m = 0; m < 4; ++m) _Pragma("unroll") for (int k = 0; k < 2; ++k) dst[m][k] = *(const PG8_LAS bf16x8*)(lds + PG8_SA(b, h) + aoff + m * 2048 + k * 1024); } while (0)
; #define PG8_LDB(dst, b, h) do { _Pragma("unroll") for (int n = 0; n < 2; ++n) _Pragma("unroll") for (int k = 0; k < 2; ++k) dst[n][k] = *(const PG8_LAS bf16x8*)(lds + PG8_SB(b, h) + boff + n * 2048 + k * 1024); } while (0)
; #define PG8_MMA(ai, bj, At, Bt) do { __builtin_amdgcn_s_setprio(1); _Pragma("unroll") for (int m = 0; m < 4; ++m) _Pragma("unroll") for (int n = 0; n < 2; ++n) _Pragma("unroll") for (int k = 0; k < 2; ++k) \
;         acc[ai][bj][m][n] = __builtin_amdgcn_mfma_f32_16x16x32_bf16(Bt[n][k], At[m][k], acc[ai][bj][m][n], 0, 0, 0); __builtin_amdgcn_s_setprio(0); } while (0)
; template <class Epi, class Sched, bool ALIGN_EPI = false, bool SP2 = false>
; __device__ __forceinline__ void gemm_phase(PG8_LAS unsigned char* lds, const Gemm g, const Sched& S, const Epi& E, int wave0) {
;     ...
;             PG8_LDB(B0, 0, 0); PG8_LDB(B1, 0, 1); PG8_SCHED; PG8_LDA(At, 0, 0); PG8_STAGE(PG8_SA(1, 1), a1 + hstep, voffA);
;             PG8_WAIT_V(8); PG8_WAIT_L(0); PG8_BAR; PG8_MMA(0, 0, At, B0); PG8_MMA(0, 1, At, B1); PG8_BAR; PG8_SCHED;
;             PG8_LDA(At, 0, 1); PG8_STAGE(PG8_SB(0, 0), b2, voffB); PG8_STAGE(PG8_SB(0, 1), b2 + hstep, voffB); PG8_STAGE(PG8_SA(0, 0), a2, voffA);
;             PG8_WAIT_V(8); PG8_WAIT_L(0); PG8_BAR; if (!cur.half) { PG8_MMA(1, 0, At, B0); PG8_MMA(1, 1, At, B1); } PG8_BAR; PG8_SCHED;
;             PG8_LDB(B0, 1, 0); PG8_LDB(B1, 1, 1); PG8_SCHED; PG8_LDA(At, 1, 0); PG8_STAGE(PG8_SA(0, 1), a2 + hstep, voffA);
;             PG8_WAIT_V(8); PG8_WAIT_L(0); PG8_BAR; PG8_MMA(0, 0, At, B0); PG8_MMA(0, 1, At, B1); PG8_BAR; PG8_SCHED;
;             PG8_LDA(At, 1, 1); PG8_STAGE(PG8_SB(1, 0), b3, voffB); PG8_STAGE(PG8_SB(1, 1), b3 + hstep, voffB); PG8_STAGE(PG8_SA(1, 0), a3, voffA);
;             PG8_WAIT_V(8); PG8_WAIT_L(0); PG8_BAR; if (!cur.half) { PG8_MMA(1, 0, At, B0); PG8_MMA(1, 1, At, B1); } PG8_BAR; PG8_SCHED;
	v_mfma_f32_16x16x32_bf16 v[60:63], v[132:135], v[190:193], v[60:63]
	v_mfma_f32_16x16x32_bf16 v[56:59], v[156:159], v[190:193], v[56:59]
	v_mfma_f32_16x16x32_bf16 v[44:47], v[132:135], v[198:201], v[44:47]
	v_mfma_f32_16x16x32_bf16 v[40:43], v[156:159], v[198:201], v[40:43]
	v_mfma_f32_16x16x32_bf16 v[28:31], v[132:135], v[206:209], v[28:31]
	v_mfma_f32_16x16x32_bf16 v[24:27], v[156:159], v[206:209], v[24:27]
	v_mfma_f32_16x16x32_bf16 v[12:15], v[132:135], v[218:221], v[12:15]
	v_mfma_f32_16x16x32_bf16 v[8:11], v[156:159], v[218:221], v[8:11]
	s_setprio 0
	s_setprio 1
	v_mfma_f32_16x16x32_bf16 v[52:55], v[170:173], v[186:189], v[52:55]
	v_mfma_f32_16x16x32_bf16 v[48:51], v[178:181], v[186:189], v[48:51]
	v_mfma_f32_16x16x32_bf16 v[36:39], v[170:173], v[194:197], v[36:39]
	v_mfma_f32_16x16x32_bf16 v[32:35], v[178:181], v[194:197], v[32:35]
	v_mfma_f32_16x16x32_bf16 v[20:23], v[170:173], v[202:205], v[20:23]
	v_mfma_f32_16x16x32_bf16 v[16:19], v[178:181], v[202:205], v[16:19]
	v_mfma_f32_16x16x32_bf16 v[4:7], v[170:173], v[210:213], v[4:7]
	v_mfma_f32_16x16x32_bf16 v[0:3], v[178:181], v[210:213], v[0:3]
	v_mfma_f32_16x16x32_bf16 v[52:55], v[174:177], v[190:193], v[52:55]
	v_mfma_f32_16x16x32_bf16 v[48:51], v[182:185], v[190:193], v[48:51]
	v_mfma_f32_16x16x32_bf16 v[36:39], v[174:177], v[198:201], v[36:39]
	v_mfma_f32_16x16x32_bf16 v[32:35], v[182:185], v[198:201], v[32:35]
	v_mfma_f32_16x16x32_bf16 v[20:23], v[174:177], v[206:209], v[20:23]
	v_mfma_f32_16x16x32_bf16 v[16:19], v[182:185], v[206:209], v[16:19]
	v_mfma_f32_16x16x32_bf16 v[4:7], v[174:177], v[218:221], v[4:7]
	v_mfma_f32_16x16x32_bf16 v[0:3], v[182:185], v[218:221], v[0:3]
	s_setprio 0
	s_barrier
	s_add_i32 s54, 0, 0x18000
	s_add_i32 s55, 0, 0x1c000
	v_add_u32_e32 v156, s54, v164
	v_add_u32_e32 v169, s55, v164
	ds_read_b128 v[128:131], v156
	ds_read_b128 v[132:135], v156 offset:1024
	ds_read_b128 v[152:155], v156 offset:2048
	ds_read_b128 v[156:159], v156 offset:3072
	ds_read_b128 v[170:173], v169
	ds_read_b128 v[174:177], v169 offset:1024
	ds_read_b128 v[178:181], v169 offset:2048
	ds_read_b128 v[182:185], v169 offset:3072
	s_add_u32 s34, s34, 0x40000
	s_addc_u32 s35, s35, 0
	s_mov_b32 m0, s36
	v_lshl_add_u64 v[226:227], s[34:35], 0, v[136:137]
	ds_read_b128 v[186:189], v167 offset:32768
	ds_read_b128 v[190:193], v167 offset:33792
	ds_read_b128 v[194:197], v167 offset:34816
	ds_read_b128 v[198:201], v167 offset:35840
	ds_read_b128 v[202:205], v167 offset:36864
	ds_read_b128 v[206:209], v167 offset:37888
	ds_read_b128 v[210:213], v167 offset:38912
	ds_read_b128 v[218:221], v167 offset:39936
	global_load_lds_dwordx4 v[226:227], off
	v_lshl_add_u64 v[226:227], s[34:35], 0, v[140:141]
	s_mov_b32 m0, s37
	s_nop 0
	global_load_lds_dwordx4 v[226:227], off
	s_waitcnt lgkmcnt(0)
	s_setprio 1
	s_waitcnt lgkmcnt(0)
	v_mfma_f32_16x16x32_bf16 v[124:127], v[128:131], v[186:189], v[124:127]
	v_mfma_f32_16x16x32_bf16 v[120:123], v[152:155], v[186:189], v[120:123]
	v_mfma_f32_16x16x32_bf16 v[108:111], v[128:131], v[194:197], v[108:111]
	v_mfma_f32_16x16x32_bf16 v[104:107], v[152:155], v[194:197], v[104:107]
	v_mfma_f32_16x16x32_bf16 v[92:95], v[128:131], v[202:205], v[92:95]
	v_mfma_f32_16x16x32_bf16 v[88:91], v[152:155], v[202:205], v[88:91]
	v_mfma_f32_16x16x32_bf16 v[76:79], v[128:131], v[210:213], v[76:79]
	v_mfma_f32_16x16x32_bf16 v[72:75], v[152:155], v[210:213], v[72:75]
	s_waitcnt vmcnt(8)
	s_barrier
	v_mfma_f32_16x16x32_bf16 v[124:127], v[132:135], v[190:193], v[124:127]
	v_mfma_f32_16x16x32_bf16 v[120:123], v[156:159], v[190:193], v[120:123]
	v_mfma_f32_16x16x32_bf16 v[108:111], v[132:135], v[198:201], v[108:111]
	v_mfma_f32_16x16x32_bf16 v[104:107], v[156:159], v[198:201], v[104:107]
	v_mfma_f32_16x16x32_bf16 v[92:95], v[132:135], v[206:209], v[92:95]
	v_mfma_f32_16x16x32_bf16 v[88:91], v[156:159], v[206:209], v[88:91]
	v_mfma_f32_16x16x32_bf16 v[76:79], v[132:135], v[218:221], v[76:79]
	v_mfma_f32_16x16x32_bf16 v[72:75], v[156:159], v[218:221], v[72:75]
	s_setprio 0
	s_setprio 1
	v_mfma_f32_16x16x32_bf16 v[116:119], v[170:173], v[186:189], v[116:119]
	v_mfma_f32_16x16x32_bf16 v[112:115], v[178:181], v[186:189], v[112:115]
	v_mfma_f32_16x16x32_bf16 v[100:103], v[170:173], v[194:197], v[100:103]
	v_mfma_f32_16x16x32_bf16 v[96:99], v[178:181], v[194:197], v[96:99]
	v_mfma_f32_16x16x32_bf16 v[84:87], v[170:173], v[202:205], v[84:87]
	v_mfma_f32_16x16x32_bf16 v[80:83], v[178:181], v[202:205], v[80:83]
	v_mfma_f32_16x16x32_bf16 v[68:71], v[170:173], v[210:213], v[68:71]
	v_mfma_f32_16x16x32_bf16 v[64:67], v[178:181], v[210:213], v[64:67]
	v_mfma_f32_16x16x32_bf16 v[116:119], v[174:177], v[190:193], v[116:119]
	v_mfma_f32_16x16x32_bf16 v[112:115], v[182:185], v[190:193], v[112:115]
	v_mfma_f32_16x16x32_bf16 v[100:103], v[174:177], v[198:201], v[100:103]
	v_mfma_f32_16x16x32_bf16 v[96:99], v[182:185], v[198:201], v[96:99]
	v_mfma_f32_16x16x32_bf16 v[84:87], v[174:177], v[206:209], v[84:87]
	v_mfma_f32_16x16x32_bf16 v[80:83], v[182:185], v[206:209], v[80:83]
	v_mfma_f32_16x16x32_bf16 v[68:71], v[174:177], v[218:221], v[68:71]
	v_mfma_f32_16x16x32_bf16 v[64:67], v[182:185], v[218:221], v[64:67]
	s_setprio 0
	s_barrier
; #define PG8_STAGE(bufoff, gbase, voff) do { _Pragma("unroll") for (int _i = 0; _i < 2; ++_i) \
;         __builtin_amdgcn_global_load_lds((const unsigned*)((const char*)(gbase) + (voff)[_i]), (PG8_LAS unsigned*)(lds + (bufoff) + ldsw + _i * 8192), 16, 0, 0); } while (0)
; #define PG8_LDA(dst, b, h) do { _Pragma("unroll") for (int m = 0; m < 4; ++m) _Pragma("unroll") for (int k = 0; k < 2; ++k) dst[m][k] = *(const PG8_LAS bf16x8*)(lds + PG8_SA(b, h) + aoff + m * 2048 + k * 1024); } while (0)
; #define PG8_LDB(dst, b, h) do { _Pragma("unroll") for (int n = 0; n < 2; ++n) _Pragma("unroll") for (int k = 0; k < 2; ++k) dst[n][k] = *(const PG8_LAS bf16x8*)(lds + PG8_SB(b, h) + boff + n * 2048 + k * 1024); } while (0)
; #define PG8_WAIT_V(n) asm volatile("s_waitcnt vmcnt(" #n ")" ::: "memory")
; template <class Epi, class Sched, bool ALIGN_EPI = false, bool SP2 = false>
; __device__ __forceinline__ void gemm_phase(PG8_LAS unsigned char* lds, const Gemm g, const Sched& S, const Epi& E, int wave0) {
;     ...
;         for (int t = 0; t < nt; t += 2) {
;             const bool last = (t == nt - 2);
;             const char* a1 = cA + (size_t)(t + 1) * kstep;
;             const char* a2 = last ? nA : cA + (size_t)(t + 2) * kstep; const char* b2 = last ? nB : cB + (size_t)(t + 2) * kstep;
;     ...
;             PG8_LDB(B0, 0, 0); PG8_LDB(B1, 0, 1); PG8_SCHED; PG8_LDA(At, 0, 0); PG8_STAGE(PG8_SA(1, 1), a1 + hstep, voffA);
;             PG8_WAIT_V(8); PG8_WAIT_L(0); PG8_BAR; PG8_MMA(0, 0, At, B0); PG8_MMA(0, 1, At, B1); PG8_BAR; PG8_SCHED;
;             PG8_LDA(At, 0, 1); PG8_STAGE(PG8_SB(0, 0), b2, voffB); PG8_STAGE(PG8_SB(0, 1), b2 + hstep, voffB); PG8_STAGE(PG8_SA(0, 0), a2, voffA);
;             PG8_WAIT_V(8); PG8_WAIT_L(0); PG8_BAR; if (!cur.half) { PG8_MMA(1, 0, At, B0); PG8_MMA(1, 1, At, B1); } PG8_BAR; PG8_SCHED;
;             PG8_LDB(B0, 1, 0); PG8_LDB(B1, 1, 1); PG8_SCHED; PG8_LDA(At, 1, 0); PG8_STAGE(PG8_SA(0, 1), a2 + hstep, voffA);
;             PG8_WAIT_V(8); PG8_WAIT_L(0); PG8_BAR; PG8_MMA(0, 0, At, B0); PG8_MMA(0, 1, At, B1); PG8_BAR; PG8_SCHED;
;             PG8_LDA(At, 1, 1); PG8_STAGE(PG8_SB(1, 0), b3, voffB); PG8_STAGE(PG8_SB(1, 1), b3 + hstep, voffB); PG8_STAGE(PG8_SA(1, 0), a3, voffA);
;             PG8_WAIT_V(8); PG8_WAIT_L(0); PG8_BAR; if (!cur.half) { PG8_MMA(1, 0, At, B0); PG8_MMA(1, 1, At, B1); } PG8_BAR; PG8_SCHED;
	s_add_i32 s34, s54, s6
	v_lshl_add_u64 v[160:161], v[160:161], 0, s[8:9]
	s_mov_b32 m0, s34
	ds_read_b128 v[186:189], v167 offset:49152
	ds_read_b128 v[190:193], v167 offset:50176
	ds_read_b128 v[194:197], v167 offset:51200
	ds_read_b128 v[198:201], v167 offset:52224
	ds_read_b128 v[202:205], v167 offset:53248
	ds_read_b128 v[206:209], v167 offset:54272
	ds_read_b128 v[210:213], v167 offset:55296
	ds_read_b128 v[218:221], v167 offset:56320
	global_load_lds_dwordx4 v[160:161], off
	s_add_i32 m0, s34, 0x2000
	s_add_u32 s30, s30, 0x40080
	v_lshl_add_u64 v[160:161], v[214:215], 0, s[8:9]
	s_addc_u32 s31, s31, 0
	s_add_i32 s34, s55, s6
	global_load_lds_dwordx4 v[160:161], off
	v_lshl_add_u64 v[160:161], s[30:31], 0, v[138:139]
	s_mov_b32 m0, s34
	s_nop 0
	global_load_lds_dwordx4 v[160:161], off
	v_lshl_add_u64 v[160:161], s[30:31], 0, v[142:143]
	s_add_i32 m0, s34, 0x2000
	s_nop 0
	global_load_lds_dwordx4 v[160:161], off
	v_lshl_add_u64 v[160:161], v[222:223], 0, s[8:9]
	s_mov_b32 m0, s41
	s_nop 0
	global_load_lds_dwordx4 v[160:161], off
	v_lshl_add_u64 v[160:161], v[224:225], 0, s[8:9]
	s_mov_b32 m0, s42
	s_nop 0
	global_load_lds_dwordx4 v[160:161], off
	s_waitcnt lgkmcnt(0)
	s_setprio 1
	s_waitcnt lgkmcnt(0)
	v_mfma_f32_16x16x32_bf16 v[60:63], v[128:131], v[186:189], v[60:63]
	v_mfma_f32_16x16x32_bf16 v[56:59], v[152:155], v[186:189], v[56:59]
	v_mfma_f32_16x16x32_bf16 v[44:47], v[128:131], v[194:197], v[44:47]
	v_mfma_f32_16x16x32_bf16 v[40:43], v[152:155], v[194:197], v[40:43]
	v_mfma_f32_16x16x32_bf16 v[28:31], v[128:131], v[202:205], v[28:31]
	v_mfma_f32_16x16x32_bf16 v[24:27], v[152:155], v[202:205], v[24:27]
	v_mfma_f32_16x16x32_bf16 v[12:15], v[128:131], v[210:213], v[12:15]
	v_mfma_f32_16x16x32_bf16 v[8:11], v[152:155], v[210:213], v[8:11]
	s_waitcnt vmcnt(8)
	s_barrier
	v_mfma_f32_16x16x32_bf16 v[60:63], v[132:135], v[190:193], v[60:63]
	v_mfma_f32_16x16x32_bf16 v[56:59], v[156:159], v[190:193], v[56:59]
	v_mfma_f32_16x16x32_bf16 v[44:47], v[132:135], v[198:201], v[44:47]
	v_mfma_f32_16x16x32_bf16 v[40:43], v[156:159], v[198:201], v[40:43]
	v_mfma_f32_16x16x32_bf16 v[28:31], v[132:135], v[206:209], v[28:31]
	v_mfma_f32_16x16x32_bf16 v[24:27], v[156:159], v[206:209], v[24:27]
	v_mfma_f32_16x16x32_bf16 v[12:15], v[132:135], v[218:221], v[12:15]
	v_mfma_f32_16x16x32_bf16 v[8:11], v[156:159], v[218:221], v[8:11]
	s_setprio 0
	s_setprio 1
	v_mfma_f32_16x16x32_bf16 v[52:55], v[170:173], v[186:189], v[52:55]
	v_mfma_f32_16x16x32_bf16 v[48:51], v[178:181], v[186:189], v[48:51]
	v_mfma_f32_16x16x32_bf16 v[36:39], v[170:173], v[194:197], v[36:39]
	v_mfma_f32_16x16x32_bf16 v[32:35], v[178:181], v[194:197], v[32:35]
	v_mfma_f32_16x16x32_bf16 v[20:23], v[170:173], v[202:205], v[20:23]
	v_mfma_f32_16x16x32_bf16 v[16:19], v[178:181], v[202:205], v[16:19]
	v_mfma_f32_16x16x32_bf16 v[4:7], v[170:173], v[210:213], v[4:7]
	v_mfma_f32_16x16x32_bf16 v[0:3], v[178:181], v[210:213], v[0:3]
	v_mfma_f32_16x16x32_bf16 v[52:55], v[174:177], v[190:193], v[52:55]
	v_mfma_f32_16x16x32_bf16 v[48:51], v[182:185], v[190:193], v[48:51]
	v_mfma_f32_16x16x32_bf16 v[36:39], v[174:177], v[198:201], v[36:39]
	v_mfma_f32_16x16x32_bf16 v[32:35], v[182:185], v[198:201], v[32:35]
	v_mfma_f32_16x16x32_bf16 v[20:23], v[174:177], v[206:209], v[20:23]
	v_mfma_f32_16x16x32_bf16 v[16:19], v[182:185], v[206:209], v[16:19]
	v_mfma_f32_16x16x32_bf16 v[4:7], v[174:177], v[218:221], v[4:7]
	v_mfma_f32_16x16x32_bf16 v[0:3], v[182:185], v[218:221], v[0:3]
	s_setprio 0
	s_barrier
	s_add_i32 s53, s53, 2
	s_add_u32 s28, s28, 0x100
	s_addc_u32 s29, s29, 0
	s_add_u32 s51, s51, 0x100
	s_addc_u32 s52, s52, 0
	s_cmp_gt_u32 s53, 13
	s_cbranch_scc0 .LBB0_363
	s_and_b64 vcc, exec, s[10:11]
	s_cbranch_vccz .LBB0_366
	s_barrier

; #define PG8_STAGE(bufoff, gbase, voff) do { _Pragma("unroll") for (int _i = 0; _i < 2; ++_i) \
;         __builtin_amdgcn_global_load_lds((const unsigned*)((const char*)(gbase) + (voff)[_i]), (PG8_LAS unsigned*)(lds + (bufoff) + ldsw + _i * 8192), 16, 0, 0); } while (0)
; #define PG8_LDA(dst, b, h) do { _Pragma("unroll") for (int m = 0; m < 4; ++m) _Pragma("unroll") for (int k = 0; k < 2; ++k) dst[m][k] = *(const PG8_LAS bf16x8*)(lds + PG8_SA(b, h) + aoff + m * 2048 + k * 1024); } while (0)
; #define PG8_LDB(dst, b, h) do { _Pragma("unroll") for (int n = 0; n < 2; ++n) _Pragma("unroll") for (int k = 0; k < 2; ++k) dst[n][k] = *(const PG8_LAS bf16x8*)(lds + PG8_SB(b, h) + boff + n * 2048 + k * 1024); } while (0)
; #define PG8_MMA(ai, bj, At, Bt) do { __builtin_amdgcn_s_setprio(1); _Pragma("unroll") for (int m = 0; m < 4; ++m) _Pragma("unroll") for (int n = 0; n < 2; ++n) _Pragma("unroll") for (int k = 0; k < 2; ++k) \
;         acc[ai][bj][m][n] = __builtin_amdgcn_mfma_f32_16x16x32_bf16(Bt[n][k], At[m][k], acc[ai][bj][m][n], 0, 0, 0); __builtin_amdgcn_s_setprio(0); } while (0)
; template <class Epi, class Sched, bool ALIGN_EPI = false, bool SP2 = false>
; __device__ __forceinline__ void gemm_phase(PG8_LAS unsigned char* lds, const Gemm g, const Sched& S, const Epi& E, int wave0) {
;     ...
;             PG8_LDB(B0, 0, 0); PG8_LDB(B1, 0, 1); PG8_SCHED; PG8_LDA(At, 0, 0); PG8_STAGE(PG8_SA(1, 1), a1 + hstep, voffA);
;             PG8_WAIT_V(8); PG8_WAIT_L(0); PG8_BAR; PG8_MMA(0, 0, At, B0); PG8_MMA(0, 1, At, B1); PG8_BAR; PG8_SCHED;
;             PG8_LDA(At, 0, 1); PG8_STAGE(PG8_SB(0, 0), b2, voffB); PG8_STAGE(PG8_SB(0, 1), b2 + hstep, voffB); PG8_STAGE(PG8_SA(0, 0), a2, voffA);
;             PG8_WAIT_V(8); PG8_WAIT_L(0); PG8_BAR; if (!cur.half) { PG8_MMA(1, 0, At, B0); PG8_MMA(1, 1, At, B1); } PG8_BAR; PG8_SCHED;
;             PG8_LDB(B0, 1, 0); PG8_LDB(B1, 1, 1); PG8_SCHED; PG8_LDA(At, 1, 0); PG8_STAGE(PG8_SA(0, 1), a2 + hstep, voffA);
;             PG8_WAIT_V(8); PG8_WAIT_L(0); PG8_BAR; PG8_MMA(0, 0, At, B0); PG8_MMA(0, 1, At, B1); PG8_BAR; PG8_SCHED;
;             PG8_LDA(At, 1, 1); PG8_STAGE(PG8_SB(1, 0), b3, voffB); PG8_STAGE(PG8_SB(1, 1), b3 + hstep, voffB); PG8_STAGE(PG8_SA(1, 0), a3, voffA);
;             PG8_WAIT_V(8); PG8_WAIT_L(0); PG8_BAR; if (!cur.half) { PG8_MMA(1, 0, At, B0); PG8_MMA(1, 1, At, B1); } PG8_BAR; PG8_SCHED;
.LBB0_480:
	ds_read_b128 v[144:147], v169
	ds_read_b128 v[148:151], v169 offset:1024
	ds_read_b128 v[152:155], v169 offset:2048
	ds_read_b128 v[156:159], v169 offset:3072
	ds_read_b128 v[160:163], v170
	ds_read_b128 v[174:177], v170 offset:1024
	ds_read_b128 v[178:181], v170 offset:2048
	ds_read_b128 v[182:185], v170 offset:3072
	s_add_u32 s52, s50, 0xfffc0080
	s_addc_u32 s53, s51, -1
	s_cmp_eq_u32 s68, 12
	s_cselect_b32 s55, s3, s53
	s_cselect_b32 s54, s11, s52
	s_cselect_b32 s53, s43, s86
	s_cselect_b32 s52, s45, s85
	v_lshl_add_u64 v[164:165], s[50:51], 0, v[136:137]
	s_add_i32 m0, s7, 0xc000
	ds_read_b128 v[186:189], v171
	ds_read_b128 v[190:193], v171 offset:1024
	ds_read_b128 v[194:197], v171 offset:2048
	ds_read_b128 v[198:201], v171 offset:3072
	ds_read_b128 v[202:205], v171 offset:4096
	ds_read_b128 v[206:209], v171 offset:5120
	ds_read_b128 v[210:213], v171 offset:6144
	ds_read_b128 v[218:221], v171 offset:7168
	global_load_lds_dwordx4 v[164:165], off
	v_lshl_add_u64 v[164:165], s[50:51], 0, v[138:139]
	s_add_i32 m0, s7, 0xe000
	s_nop 0
	global_load_lds_dwordx4 v[164:165], off
	s_waitcnt lgkmcnt(0)
	s_setprio 1
	s_waitcnt lgkmcnt(0)
	v_mfma_f32_16x16x32_bf16 v[124:127], v[144:147], v[186:189], v[124:127]
	v_mfma_f32_16x16x32_bf16 v[120:123], v[152:155], v[186:189], v[120:123]
	v_mfma_f32_16x16x32_bf16 v[108:111], v[144:147], v[194:197], v[108:111]
	v_mfma_f32_16x16x32_bf16 v[104:107], v[152:155], v[194:197], v[104:107]
	v_mfma_f32_16x16x32_bf16 v[92:95], v[144:147], v[202:205], v[92:95]
	v_mfma_f32_16x16x32_bf16 v[88:91], v[152:155], v[202:205], v[88:91]
	v_mfma_f32_16x16x32_bf16 v[76:79], v[144:147], v[210:213], v[76:79]
	v_mfma_f32_16x16x32_bf16 v[72:75], v[152:155], v[210:213], v[72:75]
	s_waitcnt vmcnt(8)
	s_barrier
	v_mfma_f32_16x16x32_bf16 v[124:127], v[148:151], v[190:193], v[124:127]
	v_mfma_f32_16x16x32_bf16 v[120:123], v[156:159], v[190:193], v[120:123]
	v_mfma_f32_16x16x32_bf16 v[108:111], v[148:151], v[198:201], v[108:111]
	v_mfma_f32_16x16x32_bf16 v[104:107], v[156:159], v[198:201], v[104:107]
	v_mfma_f32_16x16x32_bf16 v[92:95], v[148:151], v[206:209], v[92:95]
	v_mfma_f32_16x16x32_bf16 v[88:91], v[156:159], v[206:209], v[88:91]
	v_mfma_f32_16x16x32_bf16 v[76:79], v[148:151], v[218:221], v[76:79]
	v_mfma_f32_16x16x32_bf16 v[72:75], v[156:159], v[218:221], v[72:75]
	s_setprio 0
	s_setprio 1
	v_mfma_f32_16x16x32_bf16 v[116:119], v[160:163], v[186:189], v[116:119]
	v_mfma_f32_16x16x32_bf16 v[112:115], v[178:181], v[186:189], v[112:115]
	v_mfma_f32_16x16x32_bf16 v[100:103], v[160:163], v[194:197], v[100:103]
	v_mfma_f32_16x16x32_bf16 v[96:99], v[178:181], v[194:197], v[96:99]
	v_mfma_f32_16x16x32_bf16 v[84:87], v[160:163], v[202:205], v[84:87]
	v_mfma_f32_16x16x32_bf16 v[80:83], v[178:181], v[202:205], v[80:83]
	v_mfma_f32_16x16x32_bf16 v[68:71], v[160:163], v[210:213], v[68:71]
	v_mfma_f32_16x16x32_bf16 v[64:67], v[178:181], v[210:213], v[64:67]
	v_mfma_f32_16x16x32_bf16 v[116:119], v[174:177], v[190:193], v[116:119]
	v_mfma_f32_16x16x32_bf16 v[112:115], v[182:185], v[190:193], v[112:115]
	v_mfma_f32_16x16x32_bf16 v[100:103], v[174:177], v[198:201], v[100:103]
	v_mfma_f32_16x16x32_bf16 v[96:99], v[182:185], v[198:201], v[96:99]
	v_mfma_f32_16x16x32_bf16 v[84:87], v[174:177], v[206:209], v[84:87]
	v_mfma_f32_16x16x32_bf16 v[80:83], v[182:185], v[206:209], v[80:83]
	v_mfma_f32_16x16x32_bf16 v[68:71], v[174:177], v[218:221], v[68:71]
	v_mfma_f32_16x16x32_bf16 v[64:67], v[182:185], v[218:221], v[64:67]
	s_setprio 0
	s_barrier
	s_add_i32 s69, s57, s6
	v_lshl_add_u64 v[164:165], s[52:53], 0, v[130:131]
	s_mov_b32 m0, s69
	ds_read_b128 v[186:189], v171 offset:16384
	ds_read_b128 v[190:193], v171 offset:17408
	ds_read_b128 v[194:197], v171 offset:18432
	ds_read_b128 v[198:201], v171 offset:19456
	ds_read_b128 v[202:205], v171 offset:20480
	ds_read_b128 v[206:209], v171 offset:21504
	ds_read_b128 v[210:213], v171 offset:22528
	ds_read_b128 v[218:221], v171 offset:23552
	global_load_lds_dwordx4 v[164:165], off
	s_add_i32 m0, s69, 0x2000
	s_add_u32 vcc_lo, s52, 0x40000
	v_lshl_add_u64 v[214:215], s[52:53], 0, v[134:135]
	s_addc_u32 vcc_hi, s53, 0
	s_add_i32 s69, s62, s6
	global_load_lds_dwordx4 v[214:215], off
	v_lshl_add_u64 v[222:223], vcc, 0, v[130:131]
	s_mov_b32 m0, s69
	v_lshl_add_u64 v[224:225], s[54:55], 0, v[132:133]
	global_load_lds_dwordx4 v[222:223], off
	v_lshl_add_u64 v[222:223], vcc, 0, v[134:135]
	s_add_i32 m0, s69, 0x2000
	s_nop 0
	global_load_lds_dwordx4 v[222:223], off
	v_lshl_add_u64 v[222:223], s[54:55], 0, v[128:129]
	s_mov_b32 m0, s7
	s_nop 0
	global_load_lds_dwordx4 v[222:223], off
	s_mov_b32 m0, s17
	s_nop 0
	global_load_lds_dwordx4 v[224:225], off
	s_waitcnt lgkmcnt(0)
	s_setprio 1
	s_waitcnt lgkmcnt(0)
	v_mfma_f32_16x16x32_bf16 v[60:63], v[144:147], v[186:189], v[60:63]
	v_mfma_f32_16x16x32_bf16 v[56:59], v[152:155], v[186:189], v[56:59]
	v_mfma_f32_16x16x32_bf16 v[44:47], v[144:147], v[194:197], v[44:47]
	v_mfma_f32_16x16x32_bf16 v[40:43], v[152:155], v[194:197], v[40:43]
	v_mfma_f32_16x16x32_bf16 v[28:31], v[144:147], v[202:205], v[28:31]
	v_mfma_f32_16x16x32_bf16 v[24:27], v[152:155], v[202:205], v[24:27]
	v_mfma_f32_16x16x32_bf16 v[12:15], v[144:147], v[210:213], v[12:15]
	v_mfma_f32_16x16x32_bf16 v[8:11], v[152:155], v[210:213], v[8:11]
	s_waitcnt vmcnt(8)
	s_barrier
; #define PG8_STAGE(bufoff, gbase, voff) do { _Pragma("unroll") for (int _i = 0; _i < 2; ++_i) \
;         __builtin_amdgcn_global_load_lds((const unsigned*)((const char*)(gbase) + (voff)[_i]), (PG8_LAS unsigned*)(lds + (bufoff) + ldsw + _i * 8192), 16, 0, 0); } while (0)
; #define PG8_LDA(dst, b, h) do { _Pragma("unroll") for (int m = 0; m < 4; ++m) _Pragma("unroll") for (int k = 0; k < 2; ++k) dst[m][k] = *(const PG8_LAS bf16x8*)(lds + PG8_SA(b, h) + aoff + m * 2048 + k * 1024); } while (0)
; #define PG8_LDB(dst, b, h) do { _Pragma("unroll") for (int n = 0; n < 2; ++n) _Pragma("unroll") for (int k = 0; k < 2; ++k) dst[n][k] = *(const PG8_LAS bf16x8*)(lds + PG8_SB(b, h) + boff + n * 2048 + k * 1024); } while (0)
; #define PG8_MMA(ai, bj, At, Bt) do { __builtin_amdgcn_s_setprio(1); _Pragma("unroll") for (int m = 0; m < 4; ++m) _Pragma("unroll") for (int n = 0; n < 2; ++n) _Pragma("unroll") for (int k = 0; k < 2; ++k) \
;         acc[ai][bj][m][n] = __builtin_amdgcn_mfma_f32_16x16x32_bf16(Bt[n][k], At[m][k], acc[ai][bj][m][n], 0, 0, 0); __builtin_amdgcn_s_setprio(0); } while (0)
; template <class Epi, class Sched, bool ALIGN_EPI = false, bool SP2 = false>
; __device__ __forceinline__ void gemm_phase(PG8_LAS unsigned char* lds, const Gemm g, const Sched& S, const Epi& E, int wave0) {
;     ...
;             PG8_LDB(B0, 0, 0); PG8_LDB(B1, 0, 1); PG8_SCHED; PG8_LDA(At, 0, 0); PG8_STAGE(PG8_SA(1, 1), a1 + hstep, voffA);
;             PG8_WAIT_V(8); PG8_WAIT_L(0); PG8_BAR; PG8_MMA(0, 0, At, B0); PG8_MMA(0, 1, At, B1); PG8_BAR; PG8_SCHED;
;             PG8_LDA(At, 0, 1); PG8_STAGE(PG8_SB(0, 0), b2, voffB); PG8_STAGE(PG8_SB(0, 1), b2 + hstep, voffB); PG8_STAGE(PG8_SA(0, 0), a2, voffA);
;             PG8_WAIT_V(8); PG8_WAIT_L(0); PG8_BAR; if (!cur.half) { PG8_MMA(1, 0, At, B0); PG8_MMA(1, 1, At, B1); } PG8_BAR; PG8_SCHED;
;             PG8_LDB(B0, 1, 0); PG8_LDB(B1, 1, 1); PG8_SCHED; PG8_LDA(At, 1, 0); PG8_STAGE(PG8_SA(0, 1), a2 + hstep, voffA);
;             PG8_WAIT_V(8); PG8_WAIT_L(0); PG8_BAR; PG8_MMA(0, 0, At, B0); PG8_MMA(0, 1, At, B1); PG8_BAR; PG8_SCHED;
;             PG8_LDA(At, 1, 1); PG8_STAGE(PG8_SB(1, 0), b3, voffB); PG8_STAGE(PG8_SB(1, 1), b3 + hstep, voffB); PG8_STAGE(PG8_SA(1, 0), a3, voffA);
;             PG8_WAIT_V(8); PG8_WAIT_L(0); PG8_BAR; if (!cur.half) { PG8_MMA(1, 0, At, B0); PG8_MMA(1, 1, At, B1); } PG8_BAR; PG8_SCHED;
	v_mfma_f32_16x16x32_bf16 v[60:63], v[148:151], v[190:193], v[60:63]
	v_mfma_f32_16x16x32_bf16 v[56:59], v[156:159], v[190:193], v[56:59]
	v_mfma_f32_16x16x32_bf16 v[44:47], v[148:151], v[198:201], v[44:47]
	v_mfma_f32_16x16x32_bf16 v[40:43], v[156:159], v[198:201], v[40:43]
	v_mfma_f32_16x16x32_bf16 v[28:31], v[148:151], v[206:209], v[28:31]
	v_mfma_f32_16x16x32_bf16 v[24:27], v[156:159], v[206:209], v[24:27]
	v_mfma_f32_16x16x32_bf16 v[12:15], v[148:151], v[218:221], v[12:15]
	v_mfma_f32_16x16x32_bf16 v[8:11], v[156:159], v[218:221], v[8:11]
	s_setprio 0
	s_setprio 1
	v_mfma_f32_16x16x32_bf16 v[52:55], v[160:163], v[186:189], v[52:55]
	v_mfma_f32_16x16x32_bf16 v[48:51], v[178:181], v[186:189], v[48:51]
	v_mfma_f32_16x16x32_bf16 v[36:39], v[160:163], v[194:197], v[36:39]
	v_mfma_f32_16x16x32_bf16 v[32:35], v[178:181], v[194:197], v[32:35]
	v_mfma_f32_16x16x32_bf16 v[20:23], v[160:163], v[202:205], v[20:23]
	v_mfma_f32_16x16x32_bf16 v[16:19], v[178:181], v[202:205], v[16:19]
	v_mfma_f32_16x16x32_bf16 v[4:7], v[160:163], v[210:213], v[4:7]
	v_mfma_f32_16x16x32_bf16 v[0:3], v[178:181], v[210:213], v[0:3]
	v_mfma_f32_16x16x32_bf16 v[52:55], v[174:177], v[190:193], v[52:55]
	v_mfma_f32_16x16x32_bf16 v[48:51], v[182:185], v[190:193], v[48:51]
	v_mfma_f32_16x16x32_bf16 v[36:39], v[174:177], v[198:201], v[36:39]
	v_mfma_f32_16x16x32_bf16 v[32:35], v[182:185], v[198:201], v[32:35]
	v_mfma_f32_16x16x32_bf16 v[20:23], v[174:177], v[206:209], v[20:23]
	v_mfma_f32_16x16x32_bf16 v[16:19], v[182:185], v[206:209], v[16:19]
	v_mfma_f32_16x16x32_bf16 v[4:7], v[174:177], v[218:221], v[4:7]
	v_mfma_f32_16x16x32_bf16 v[0:3], v[182:185], v[218:221], v[0:3]
	s_setprio 0
	s_barrier
	s_add_i32 s69, 0, 0x18000
	s_add_i32 s87, 0, 0x1c000
	v_add_u32_e32 v156, s69, v168
	v_add_u32_e32 v182, s87, v168
	ds_read_b128 v[144:147], v156
	ds_read_b128 v[148:151], v156 offset:1024
	ds_read_b128 v[152:155], v156 offset:2048
	ds_read_b128 v[156:159], v156 offset:3072
	ds_read_b128 v[160:163], v182
	ds_read_b128 v[174:177], v182 offset:1024
	ds_read_b128 v[178:181], v182 offset:2048
	ds_read_b128 v[182:185], v182 offset:3072
	s_add_u32 s54, s54, 0x40000
	s_addc_u32 s55, s55, 0
	s_mov_b32 m0, s19
	v_lshl_add_u64 v[226:227], s[54:55], 0, v[128:129]
	ds_read_b128 v[186:189], v171 offset:32768
	ds_read_b128 v[190:193], v171 offset:33792
	ds_read_b128 v[194:197], v171 offset:34816
	ds_read_b128 v[198:201], v171 offset:35840
	ds_read_b128 v[202:205], v171 offset:36864
	ds_read_b128 v[206:209], v171 offset:37888
	ds_read_b128 v[210:213], v171 offset:38912
	ds_read_b128 v[218:221], v171 offset:39936
	global_load_lds_dwordx4 v[226:227], off
	v_lshl_add_u64 v[226:227], s[54:55], 0, v[132:133]
	s_mov_b32 m0, s21
	s_nop 0
	global_load_lds_dwordx4 v[226:227], off
	s_waitcnt lgkmcnt(0)
	s_setprio 1
	s_waitcnt lgkmcnt(0)
	v_mfma_f32_16x16x32_bf16 v[124:127], v[144:147], v[186:189], v[124:127]
	v_mfma_f32_16x16x32_bf16 v[120:123], v[152:155], v[186:189], v[120:123]
	v_mfma_f32_16x16x32_bf16 v[108:111], v[144:147], v[194:197], v[108:111]
	v_mfma_f32_16x16x32_bf16 v[104:107], v[152:155], v[194:197], v[104:107]
	v_mfma_f32_16x16x32_bf16 v[92:95], v[144:147], v[202:205], v[92:95]
	v_mfma_f32_16x16x32_bf16 v[88:91], v[152:155], v[202:205], v[88:91]
	v_mfma_f32_16x16x32_bf16 v[76:79], v[144:147], v[210:213], v[76:79]
	v_mfma_f32_16x16x32_bf16 v[72:75], v[152:155], v[210:213], v[72:75]
	s_waitcnt vmcnt(8)
	s_barrier
	v_mfma_f32_16x16x32_bf16 v[124:127], v[148:151], v[190:193], v[124:127]
	v_mfma_f32_16x16x32_bf16 v[120:123], v[156:159], v[190:193], v[120:123]
	v_mfma_f32_16x16x32_bf16 v[108:111], v[148:151], v[198:201], v[108:111]
	v_mfma_f32_16x16x32_bf16 v[104:107], v[156:159], v[198:201], v[104:107]
	v_mfma_f32_16x16x32_bf16 v[92:95], v[148:151], v[206:209], v[92:95]
	v_mfma_f32_16x16x32_bf16 v[88:91], v[156:159], v[206:209], v[88:91]
	v_mfma_f32_16x16x32_bf16 v[76:79], v[148:151], v[218:221], v[76:79]
	v_mfma_f32_16x16x32_bf16 v[72:75], v[156:159], v[218:221], v[72:75]
	s_setprio 0
	s_setprio 1
	v_mfma_f32_16x16x32_bf16 v[116:119], v[160:163], v[186:189], v[116:119]
	v_mfma_f32_16x16x32_bf16 v[112:115], v[178:181], v[186:189], v[112:115]
	v_mfma_f32_16x16x32_bf16 v[100:103], v[160:163], v[194:197], v[100:103]
	v_mfma_f32_16x16x32_bf16 v[96:99], v[178:181], v[194:197], v[96:99]
	v_mfma_f32_16x16x32_bf16 v[84:87], v[160:163], v[202:205], v[84:87]
	v_mfma_f32_16x16x32_bf16 v[80:83], v[178:181], v[202:205], v[80:83]
	v_mfma_f32_16x16x32_bf16 v[68:71], v[160:163], v[210:213], v[68:71]
	v_mfma_f32_16x16x32_bf16 v[64:67], v[178:181], v[210:213], v[64:67]
	v_mfma_f32_16x16x32_bf16 v[116:119], v[174:177], v[190:193], v[116:119]
	v_mfma_f32_16x16x32_bf16 v[112:115], v[182:185], v[190:193], v[112:115]
	v_mfma_f32_16x16x32_bf16 v[100:103], v[174:177], v[198:201], v[100:103]
	v_mfma_f32_16x16x32_bf16 v[96:99], v[182:185], v[198:201], v[96:99]
	v_mfma_f32_16x16x32_bf16 v[84:87], v[174:177], v[206:209], v[84:87]
	v_mfma_f32_16x16x32_bf16 v[80:83], v[182:185], v[206:209], v[80:83]
	v_mfma_f32_16x16x32_bf16 v[68:71], v[174:177], v[218:221], v[68:71]
	v_mfma_f32_16x16x32_bf16 v[64:67], v[182:185], v[218:221], v[64:67]
	s_setprio 0
	s_barrier
; #define PG8_STAGE(bufoff, gbase, voff) do { _Pragma("unroll") for (int _i = 0; _i < 2; ++_i) \
;         __builtin_amdgcn_global_load_lds((const unsigned*)((const char*)(gbase) + (voff)[_i]), (PG8_LAS unsigned*)(lds + (bufoff) + ldsw + _i * 8192), 16, 0, 0); } while (0)
; #define PG8_LDA(dst, b, h) do { _Pragma("unroll") for (int m = 0; m < 4; ++m) _Pragma("unroll") for (int k = 0; k < 2; ++k) dst[m][k] = *(const PG8_LAS bf16x8*)(lds + PG8_SA(b, h) + aoff + m * 2048 + k * 1024); } while (0)
; #define PG8_LDB(dst, b, h) do { _Pragma("unroll") for (int n = 0; n < 2; ++n) _Pragma("unroll") for (int k = 0; k < 2; ++k) dst[n][k] = *(const PG8_LAS bf16x8*)(lds + PG8_SB(b, h) + boff + n * 2048 + k * 1024); } while (0)
; #define PG8_WAIT_V(n) asm volatile("s_waitcnt vmcnt(" #n ")" ::: "memory")
; template <class Epi, class Sched, bool ALIGN_EPI = false, bool SP2 = false>
; __device__ __forceinline__ void gemm_phase(PG8_LAS unsigned char* lds, const Gemm g, const Sched& S, const Epi& E, int wave0) {
;     ...
;         for (int t = 0; t < nt; t += 2) {
;             const bool last = (t == nt - 2);
;             const char* a1 = cA + (size_t)(t + 1) * kstep;
;             const char* a2 = last ? nA : cA + (size_t)(t + 2) * kstep; const char* b2 = last ? nB : cB + (size_t)(t + 2) * kstep;
;     ...
;             PG8_LDB(B0, 0, 0); PG8_LDB(B1, 0, 1); PG8_SCHED; PG8_LDA(At, 0, 0); PG8_STAGE(PG8_SA(1, 1), a1 + hstep, voffA);
;             PG8_WAIT_V(8); PG8_WAIT_L(0); PG8_BAR; PG8_MMA(0, 0, At, B0); PG8_MMA(0, 1, At, B1); PG8_BAR; PG8_SCHED;
;             PG8_LDA(At, 0, 1); PG8_STAGE(PG8_SB(0, 0), b2, voffB); PG8_STAGE(PG8_SB(0, 1), b2 + hstep, voffB); PG8_STAGE(PG8_SA(0, 0), a2, voffA);
;             PG8_WAIT_V(8); PG8_WAIT_L(0); PG8_BAR; if (!cur.half) { PG8_MMA(1, 0, At, B0); PG8_MMA(1, 1, At, B1); } PG8_BAR; PG8_SCHED;
;             PG8_LDB(B0, 1, 0); PG8_LDB(B1, 1, 1); PG8_SCHED; PG8_LDA(At, 1, 0); PG8_STAGE(PG8_SA(0, 1), a2 + hstep, voffA);
;             PG8_WAIT_V(8); PG8_WAIT_L(0); PG8_BAR; PG8_MMA(0, 0, At, B0); PG8_MMA(0, 1, At, B1); PG8_BAR; PG8_SCHED;
;             PG8_LDA(At, 1, 1); PG8_STAGE(PG8_SB(1, 0), b3, voffB); PG8_STAGE(PG8_SB(1, 1), b3 + hstep, voffB); PG8_STAGE(PG8_SA(1, 0), a3, voffA);
;             PG8_WAIT_V(8); PG8_WAIT_L(0); PG8_BAR; if (!cur.half) { PG8_MMA(1, 0, At, B0); PG8_MMA(1, 1, At, B1); } PG8_BAR; PG8_SCHED;
	s_add_i32 s54, s69, s6
	v_lshl_add_u64 v[164:165], v[164:165], 0, s[4:5]
	s_mov_b32 m0, s54
	ds_read_b128 v[186:189], v171 offset:49152
	ds_read_b128 v[190:193], v171 offset:50176
	ds_read_b128 v[194:197], v171 offset:51200
	ds_read_b128 v[198:201], v171 offset:52224
	ds_read_b128 v[202:205], v171 offset:53248
	ds_read_b128 v[206:209], v171 offset:54272
	ds_read_b128 v[210:213], v171 offset:55296
	ds_read_b128 v[218:221], v171 offset:56320
	global_load_lds_dwordx4 v[164:165], off
	s_add_i32 m0, s54, 0x2000
	s_add_u32 s52, s52, 0x40080
	v_lshl_add_u64 v[164:165], v[214:215], 0, s[4:5]
	s_addc_u32 s53, s53, 0
	s_add_i32 s54, s87, s6
	global_load_lds_dwordx4 v[164:165], off
	v_lshl_add_u64 v[164:165], s[52:53], 0, v[130:131]
	s_mov_b32 m0, s54
	s_nop 0
	global_load_lds_dwordx4 v[164:165], off
	v_lshl_add_u64 v[164:165], s[52:53], 0, v[134:135]
	s_add_i32 m0, s54, 0x2000
	s_nop 0
	global_load_lds_dwordx4 v[164:165], off
	v_lshl_add_u64 v[164:165], v[222:223], 0, s[4:5]
	s_mov_b32 m0, s35
	s_nop 0
	global_load_lds_dwordx4 v[164:165], off
	v_lshl_add_u64 v[164:165], v[224:225], 0, s[4:5]
	s_mov_b32 m0, s37
	s_nop 0
	global_load_lds_dwordx4 v[164:165], off
	s_waitcnt lgkmcnt(0)
	s_setprio 1
	s_waitcnt lgkmcnt(0)
	v_mfma_f32_16x16x32_bf16 v[60:63], v[144:147], v[186:189], v[60:63]
	v_mfma_f32_16x16x32_bf16 v[56:59], v[152:155], v[186:189], v[56:59]
	v_mfma_f32_16x16x32_bf16 v[44:47], v[144:147], v[194:197], v[44:47]
	v_mfma_f32_16x16x32_bf16 v[40:43], v[152:155], v[194:197], v[40:43]
	v_mfma_f32_16x16x32_bf16 v[28:31], v[144:147], v[202:205], v[28:31]
	v_mfma_f32_16x16x32_bf16 v[24:27], v[152:155], v[202:205], v[24:27]
	v_mfma_f32_16x16x32_bf16 v[12:15], v[144:147], v[210:213], v[12:15]
	v_mfma_f32_16x16x32_bf16 v[8:11], v[152:155], v[210:213], v[8:11]
	s_waitcnt vmcnt(8)
	s_barrier
	v_mfma_f32_16x16x32_bf16 v[60:63], v[148:151], v[190:193], v[60:63]
	v_mfma_f32_16x16x32_bf16 v[56:59], v[156:159], v[190:193], v[56:59]
	v_mfma_f32_16x16x32_bf16 v[44:47], v[148:151], v[198:201], v[44:47]
	v_mfma_f32_16x16x32_bf16 v[40:43], v[156:159], v[198:201], v[40:43]
	v_mfma_f32_16x16x32_bf16 v[28:31], v[148:151], v[206:209], v[28:31]
	v_mfma_f32_16x16x32_bf16 v[24:27], v[156:159], v[206:209], v[24:27]
	v_mfma_f32_16x16x32_bf16 v[12:15], v[148:151], v[218:221], v[12:15]
	v_mfma_f32_16x16x32_bf16 v[8:11], v[156:159], v[218:221], v[8:11]
	s_setprio 0
	s_setprio 1
	v_mfma_f32_16x16x32_bf16 v[52:55], v[160:163], v[186:189], v[52:55]
	v_mfma_f32_16x16x32_bf16 v[48:51], v[178:181], v[186:189], v[48:51]
	v_mfma_f32_16x16x32_bf16 v[36:39], v[160:163], v[194:197], v[36:39]
	v_mfma_f32_16x16x32_bf16 v[32:35], v[178:181], v[194:197], v[32:35]
	v_mfma_f32_16x16x32_bf16 v[20:23], v[160:163], v[202:205], v[20:23]
	v_mfma_f32_16x16x32_bf16 v[16:19], v[178:181], v[202:205], v[16:19]
	v_mfma_f32_16x16x32_bf16 v[4:7], v[160:163], v[210:213], v[4:7]
	v_mfma_f32_16x16x32_bf16 v[0:3], v[178:181], v[210:213], v[0:3]
	v_mfma_f32_16x16x32_bf16 v[52:55], v[174:177], v[190:193], v[52:55]
	v_mfma_f32_16x16x32_bf16 v[48:51], v[182:185], v[190:193], v[48:51]
	v_mfma_f32_16x16x32_bf16 v[36:39], v[174:177], v[198:201], v[36:39]
	v_mfma_f32_16x16x32_bf16 v[32:35], v[182:185], v[198:201], v[32:35]
	v_mfma_f32_16x16x32_bf16 v[20:23], v[174:177], v[206:209], v[20:23]
	v_mfma_f32_16x16x32_bf16 v[16:19], v[182:185], v[206:209], v[16:19]
	v_mfma_f32_16x16x32_bf16 v[4:7], v[174:177], v[218:221], v[4:7]
	v_mfma_f32_16x16x32_bf16 v[0:3], v[182:185], v[218:221], v[0:3]
	s_setprio 0
	s_barrier
	s_add_i32 s68, s68, 2
	s_add_u32 s50, s50, 0x100
	s_addc_u32 s51, s51, 0
	s_add_u32 s85, s85, 0x100
	s_addc_u32 s86, s86, 0
	s_cmp_gt_u32 s68, 13
	s_cbranch_scc0 .LBB0_480
	s_and_b64 vcc, exec, s[14:15]
	s_cbranch_vccz .LBB0_483
	s_barrier

; #define PG8_STAGE(bufoff, gbase, voff) do { _Pragma("unroll") for (int _i = 0; _i < 2; ++_i) \
;         __builtin_amdgcn_global_load_lds((const unsigned*)((const char*)(gbase) + (voff)[_i]), (PG8_LAS unsigned*)(lds + (bufoff) + ldsw + _i * 8192), 16, 0, 0); } while (0)
; #define PG8_LDA(dst, b, h) do { _Pragma("unroll") for (int m = 0; m < 4; ++m) _Pragma("unroll") for (int k = 0; k < 2; ++k) dst[m][k] = *(const PG8_LAS bf16x8*)(lds + PG8_SA(b, h) + aoff + m * 2048 + k * 1024); } while (0)
; #define PG8_LDB(dst, b, h) do { _Pragma("unroll") for (int n = 0; n < 2; ++n) _Pragma("unroll") for (int k = 0; k < 2; ++k) dst[n][k] = *(const PG8_LAS bf16x8*)(lds + PG8_SB(b, h) + boff + n * 2048 + k * 1024); } while (0)
; #define PG8_MMA(ai, bj, At, Bt) do { __builtin_amdgcn_s_setprio(1); _Pragma("unroll") for (int m = 0; m < 4; ++m) _Pragma("unroll") for (int n = 0; n < 2; ++n) _Pragma("unroll") for (int k = 0; k < 2; ++k) \
;         acc[ai][bj][m][n] = __builtin_amdgcn_mfma_f32_16x16x32_bf16(Bt[n][k], At[m][k], acc[ai][bj][m][n], 0, 0, 0); __builtin_amdgcn_s_setprio(0); } while (0)
; template <class Epi, class Sched, bool ALIGN_EPI = false, bool SP2 = false>
; __device__ __forceinline__ void gemm_phase(PG8_LAS unsigned char* lds, const Gemm g, const Sched& S, const Epi& E, int wave0) {
;     ...
;             PG8_LDB(B0, 0, 0); PG8_LDB(B1, 0, 1); PG8_SCHED; PG8_LDA(At, 0, 0); PG8_STAGE(PG8_SA(1, 1), a1 + hstep, voffA);
;             PG8_WAIT_V(8); PG8_WAIT_L(0); PG8_BAR; PG8_MMA(0, 0, At, B0); PG8_MMA(0, 1, At, B1); PG8_BAR; PG8_SCHED;
;             PG8_LDA(At, 0, 1); PG8_STAGE(PG8_SB(0, 0), b2, voffB); PG8_STAGE(PG8_SB(0, 1), b2 + hstep, voffB); PG8_STAGE(PG8_SA(0, 0), a2, voffA);
;             PG8_WAIT_V(8); PG8_WAIT_L(0); PG8_BAR; if (!cur.half) { PG8_MMA(1, 0, At, B0); PG8_MMA(1, 1, At, B1); } PG8_BAR; PG8_SCHED;
;             PG8_LDB(B0, 1, 0); PG8_LDB(B1, 1, 1); PG8_SCHED; PG8_LDA(At, 1, 0); PG8_STAGE(PG8_SA(0, 1), a2 + hstep, voffA);
;             PG8_WAIT_V(8); PG8_WAIT_L(0); PG8_BAR; PG8_MMA(0, 0, At, B0); PG8_MMA(0, 1, At, B1); PG8_BAR; PG8_SCHED;
;             PG8_LDA(At, 1, 1); PG8_STAGE(PG8_SB(1, 0), b3, voffB); PG8_STAGE(PG8_SB(1, 1), b3 + hstep, voffB); PG8_STAGE(PG8_SA(1, 0), a3, voffA);
;             PG8_WAIT_V(8); PG8_WAIT_L(0); PG8_BAR; if (!cur.half) { PG8_MMA(1, 0, At, B0); PG8_MMA(1, 1, At, B1); } PG8_BAR; PG8_SCHED;
.LBB0_705:
	ds_read_b128 v[128:131], v165
	ds_read_b128 v[132:135], v165 offset:1024
	ds_read_b128 v[152:155], v165 offset:2048
	ds_read_b128 v[156:159], v165 offset:3072
	ds_read_b128 v[170:173], v166
	ds_read_b128 v[174:177], v166 offset:1024
	ds_read_b128 v[178:181], v166 offset:2048
	ds_read_b128 v[182:185], v166 offset:3072
	s_add_u32 s36, s2, 0xfffe0080
	s_addc_u32 s37, s3, -1
	s_cmp_eq_u32 s55, 4
	s_cselect_b32 s39, s1, s37
	s_cselect_b32 s38, s29, s36
	s_cselect_b32 s37, s21, s54
	s_cselect_b32 s36, s52, s53
	v_lshl_add_u64 v[160:161], s[2:3], 0, v[144:145]
	s_add_i32 m0, s5, 0xc000
	ds_read_b128 v[186:189], v167
	ds_read_b128 v[190:193], v167 offset:1024
	ds_read_b128 v[194:197], v167 offset:2048
	ds_read_b128 v[198:201], v167 offset:3072
	ds_read_b128 v[202:205], v167 offset:4096
	ds_read_b128 v[206:209], v167 offset:5120
	ds_read_b128 v[210:213], v167 offset:6144
	ds_read_b128 v[218:221], v167 offset:7168
	global_load_lds_dwordx4 v[160:161], off
	v_lshl_add_u64 v[160:161], s[2:3], 0, v[146:147]
	s_add_i32 m0, s5, 0xe000
	s_nop 0
	global_load_lds_dwordx4 v[160:161], off
	s_waitcnt lgkmcnt(0)
	s_setprio 1
	s_waitcnt lgkmcnt(0)
	v_mfma_f32_16x16x32_bf16 v[124:127], v[128:131], v[186:189], v[124:127]
	v_mfma_f32_16x16x32_bf16 v[120:123], v[152:155], v[186:189], v[120:123]
	v_mfma_f32_16x16x32_bf16 v[108:111], v[128:131], v[194:197], v[108:111]
	v_mfma_f32_16x16x32_bf16 v[104:107], v[152:155], v[194:197], v[104:107]
	v_mfma_f32_16x16x32_bf16 v[92:95], v[128:131], v[202:205], v[92:95]
	v_mfma_f32_16x16x32_bf16 v[88:91], v[152:155], v[202:205], v[88:91]
	v_mfma_f32_16x16x32_bf16 v[76:79], v[128:131], v[210:213], v[76:79]
	v_mfma_f32_16x16x32_bf16 v[72:75], v[152:155], v[210:213], v[72:75]
	s_waitcnt vmcnt(8)
	s_barrier
	v_mfma_f32_16x16x32_bf16 v[124:127], v[132:135], v[190:193], v[124:127]
	v_mfma_f32_16x16x32_bf16 v[120:123], v[156:159], v[190:193], v[120:123]
	v_mfma_f32_16x16x32_bf16 v[108:111], v[132:135], v[198:201], v[108:111]
	v_mfma_f32_16x16x32_bf16 v[104:107], v[156:159], v[198:201], v[104:107]
	v_mfma_f32_16x16x32_bf16 v[92:95], v[132:135], v[206:209], v[92:95]
	v_mfma_f32_16x16x32_bf16 v[88:91], v[156:159], v[206:209], v[88:91]
	v_mfma_f32_16x16x32_bf16 v[76:79], v[132:135], v[218:221], v[76:79]
	v_mfma_f32_16x16x32_bf16 v[72:75], v[156:159], v[218:221], v[72:75]
	s_setprio 0
	s_setprio 1
	v_mfma_f32_16x16x32_bf16 v[116:119], v[170:173], v[186:189], v[116:119]
	v_mfma_f32_16x16x32_bf16 v[112:115], v[178:181], v[186:189], v[112:115]
	v_mfma_f32_16x16x32_bf16 v[100:103], v[170:173], v[194:197], v[100:103]
	v_mfma_f32_16x16x32_bf16 v[96:99], v[178:181], v[194:197], v[96:99]
	v_mfma_f32_16x16x32_bf16 v[84:87], v[170:173], v[202:205], v[84:87]
	v_mfma_f32_16x16x32_bf16 v[80:83], v[178:181], v[202:205], v[80:83]
	v_mfma_f32_16x16x32_bf16 v[68:71], v[170:173], v[210:213], v[68:71]
	v_mfma_f32_16x16x32_bf16 v[64:67], v[178:181], v[210:213], v[64:67]
	v_mfma_f32_16x16x32_bf16 v[116:119], v[174:177], v[190:193], v[116:119]
	v_mfma_f32_16x16x32_bf16 v[112:115], v[182:185], v[190:193], v[112:115]
	v_mfma_f32_16x16x32_bf16 v[100:103], v[174:177], v[198:201], v[100:103]
	v_mfma_f32_16x16x32_bf16 v[96:99], v[182:185], v[198:201], v[96:99]
	v_mfma_f32_16x16x32_bf16 v[84:87], v[174:177], v[206:209], v[84:87]
	v_mfma_f32_16x16x32_bf16 v[80:83], v[182:185], v[206:209], v[80:83]
	v_mfma_f32_16x16x32_bf16 v[68:71], v[174:177], v[218:221], v[68:71]
	v_mfma_f32_16x16x32_bf16 v[64:67], v[182:185], v[218:221], v[64:67]
	s_setprio 0
	s_barrier
	s_add_i32 s56, s48, s4
	v_lshl_add_u64 v[160:161], s[36:37], 0, v[138:139]
	s_mov_b32 m0, s56
	ds_read_b128 v[186:189], v167 offset:16384
	ds_read_b128 v[190:193], v167 offset:17408
	ds_read_b128 v[194:197], v167 offset:18432
	ds_read_b128 v[198:201], v167 offset:19456
	ds_read_b128 v[202:205], v167 offset:20480
	ds_read_b128 v[206:209], v167 offset:21504
	ds_read_b128 v[210:213], v167 offset:22528
	ds_read_b128 v[218:221], v167 offset:23552
	global_load_lds_dwordx4 v[160:161], off
	s_add_i32 m0, s56, 0x2000
	s_add_u32 s56, s36, 0x20000
	v_lshl_add_u64 v[214:215], s[36:37], 0, v[142:143]
	s_addc_u32 s57, s37, 0
	s_add_i32 s62, s49, s4
	global_load_lds_dwordx4 v[214:215], off
	v_lshl_add_u64 v[222:223], s[56:57], 0, v[138:139]
	s_mov_b32 m0, s62
	v_lshl_add_u64 v[224:225], s[38:39], 0, v[140:141]
	global_load_lds_dwordx4 v[222:223], off
	v_lshl_add_u64 v[222:223], s[56:57], 0, v[142:143]
	s_add_i32 m0, s62, 0x2000
	s_nop 0
	global_load_lds_dwordx4 v[222:223], off
	v_lshl_add_u64 v[222:223], s[38:39], 0, v[136:137]
	s_mov_b32 m0, s5
	s_nop 0
	global_load_lds_dwordx4 v[222:223], off
	s_mov_b32 m0, s6
	s_nop 0
	global_load_lds_dwordx4 v[224:225], off
	s_waitcnt lgkmcnt(0)
	s_setprio 1
	s_waitcnt lgkmcnt(0)
	v_mfma_f32_16x16x32_bf16 v[60:63], v[128:131], v[186:189], v[60:63]
	v_mfma_f32_16x16x32_bf16 v[56:59], v[152:155], v[186:189], v[56:59]
	v_mfma_f32_16x16x32_bf16 v[44:47], v[128:131], v[194:197], v[44:47]
	v_mfma_f32_16x16x32_bf16 v[40:43], v[152:155], v[194:197], v[40:43]
	v_mfma_f32_16x16x32_bf16 v[28:31], v[128:131], v[202:205], v[28:31]
	v_mfma_f32_16x16x32_bf16 v[24:27], v[152:155], v[202:205], v[24:27]
	v_mfma_f32_16x16x32_bf16 v[12:15], v[128:131], v[210:213], v[12:15]
	v_mfma_f32_16x16x32_bf16 v[8:11], v[152:155], v[210:213], v[8:11]
	s_waitcnt vmcnt(8)
	s_barrier
; #define PG8_STAGE(bufoff, gbase, voff) do { _Pragma("unroll") for (int _i = 0; _i < 2; ++_i) \
;         __builtin_amdgcn_global_load_lds((const unsigned*)((const char*)(gbase) + (voff)[_i]), (PG8_LAS unsigned*)(lds + (bufoff) + ldsw + _i * 8192), 16, 0, 0); } while (0)
; #define PG8_LDA(dst, b, h) do { _Pragma("unroll") for (int m = 0; m < 4; ++m) _Pragma("unroll") for (int k = 0; k < 2; ++k) dst[m][k] = *(const PG8_LAS bf16x8*)(lds + PG8_SA(b, h) + aoff + m * 2048 + k * 1024); } while (0)
; #define PG8_LDB(dst, b, h) do { _Pragma("unroll") for (int n = 0; n < 2; ++n) _Pragma("unroll") for (int k = 0; k < 2; ++k) dst[n][k] = *(const PG8_LAS bf16x8*)(lds + PG8_SB(b, h) + boff + n * 2048 + k * 1024); } while (0)
; #define PG8_MMA(ai, bj, At, Bt) do { __builtin_amdgcn_s_setprio(1); _Pragma("unroll") for (int m = 0; m < 4; ++m) _Pragma("unroll") for (int n = 0; n < 2; ++n) _Pragma("unroll") for (int k = 0; k < 2; ++k) \
;         acc[ai][bj][m][n] = __builtin_amdgcn_mfma_f32_16x16x32_bf16(Bt[n][k], At[m][k], acc[ai][bj][m][n], 0, 0, 0); __builtin_amdgcn_s_setprio(0); } while (0)
; template <class Epi, class Sched, bool ALIGN_EPI = false, bool SP2 = false>
; __device__ __forceinline__ void gemm_phase(PG8_LAS unsigned char* lds, const Gemm g, const Sched& S, const Epi& E, int wave0) {
;     ...
;             PG8_LDB(B0, 0, 0); PG8_LDB(B1, 0, 1); PG8_SCHED; PG8_LDA(At, 0, 0); PG8_STAGE(PG8_SA(1, 1), a1 + hstep, voffA);
;             PG8_WAIT_V(8); PG8_WAIT_L(0); PG8_BAR; PG8_MMA(0, 0, At, B0); PG8_MMA(0, 1, At, B1); PG8_BAR; PG8_SCHED;
;             PG8_LDA(At, 0, 1); PG8_STAGE(PG8_SB(0, 0), b2, voffB); PG8_STAGE(PG8_SB(0, 1), b2 + hstep, voffB); PG8_STAGE(PG8_SA(0, 0), a2, voffA);
;             PG8_WAIT_V(8); PG8_WAIT_L(0); PG8_BAR; if (!cur.half) { PG8_MMA(1, 0, At, B0); PG8_MMA(1, 1, At, B1); } PG8_BAR; PG8_SCHED;
;             PG8_LDB(B0, 1, 0); PG8_LDB(B1, 1, 1); PG8_SCHED; PG8_LDA(At, 1, 0); PG8_STAGE(PG8_SA(0, 1), a2 + hstep, voffA);
;             PG8_WAIT_V(8); PG8_WAIT_L(0); PG8_BAR; PG8_MMA(0, 0, At, B0); PG8_MMA(0, 1, At, B1); PG8_BAR; PG8_SCHED;
;             PG8_LDA(At, 1, 1); PG8_STAGE(PG8_SB(1, 0), b3, voffB); PG8_STAGE(PG8_SB(1, 1), b3 + hstep, voffB); PG8_STAGE(PG8_SA(1, 0), a3, voffA);
;             PG8_WAIT_V(8); PG8_WAIT_L(0); PG8_BAR; if (!cur.half) { PG8_MMA(1, 0, At, B0); PG8_MMA(1, 1, At, B1); } PG8_BAR; PG8_SCHED;
	v_mfma_f32_16x16x32_bf16 v[60:63], v[132:135], v[190:193], v[60:63]
	v_mfma_f32_16x16x32_bf16 v[56:59], v[156:159], v[190:193], v[56:59]
	v_mfma_f32_16x16x32_bf16 v[44:47], v[132:135], v[198:201], v[44:47]
	v_mfma_f32_16x16x32_bf16 v[40:43], v[156:159], v[198:201], v[40:43]
	v_mfma_f32_16x16x32_bf16 v[28:31], v[132:135], v[206:209], v[28:31]
	v_mfma_f32_16x16x32_bf16 v[24:27], v[156:159], v[206:209], v[24:27]
	v_mfma_f32_16x16x32_bf16 v[12:15], v[132:135], v[218:221], v[12:15]
	v_mfma_f32_16x16x32_bf16 v[8:11], v[156:159], v[218:221], v[8:11]
	s_setprio 0
	s_setprio 1
	v_mfma_f32_16x16x32_bf16 v[52:55], v[170:173], v[186:189], v[52:55]
	v_mfma_f32_16x16x32_bf16 v[48:51], v[178:181], v[186:189], v[48:51]
	v_mfma_f32_16x16x32_bf16 v[36:39], v[170:173], v[194:197], v[36:39]
	v_mfma_f32_16x16x32_bf16 v[32:35], v[178:181], v[194:197], v[32:35]
	v_mfma_f32_16x16x32_bf16 v[20:23], v[170:173], v[202:205], v[20:23]
	v_mfma_f32_16x16x32_bf16 v[16:19], v[178:181], v[202:205], v[16:19]
	v_mfma_f32_16x16x32_bf16 v[4:7], v[170:173], v[210:213], v[4:7]
	v_mfma_f32_16x16x32_bf16 v[0:3], v[178:181], v[210:213], v[0:3]
	v_mfma_f32_16x16x32_bf16 v[52:55], v[174:177], v[190:193], v[52:55]
	v_mfma_f32_16x16x32_bf16 v[48:51], v[182:185], v[190:193], v[48:51]
	v_mfma_f32_16x16x32_bf16 v[36:39], v[174:177], v[198:201], v[36:39]
	v_mfma_f32_16x16x32_bf16 v[32:35], v[182:185], v[198:201], v[32:35]
	v_mfma_f32_16x16x32_bf16 v[20:23], v[174:177], v[206:209], v[20:23]
	v_mfma_f32_16x16x32_bf16 v[16:19], v[182:185], v[206:209], v[16:19]
	v_mfma_f32_16x16x32_bf16 v[4:7], v[174:177], v[218:221], v[4:7]
	v_mfma_f32_16x16x32_bf16 v[0:3], v[182:185], v[218:221], v[0:3]
	s_setprio 0
	s_barrier
	s_add_i32 s56, 0, 0x18000
	s_add_i32 s57, 0, 0x1c000
	v_add_u32_e32 v156, s56, v164
	v_add_u32_e32 v169, s57, v164
	ds_read_b128 v[128:131], v156
	ds_read_b128 v[132:135], v156 offset:1024
	ds_read_b128 v[152:155], v156 offset:2048
	ds_read_b128 v[156:159], v156 offset:3072
	ds_read_b128 v[170:173], v169
	ds_read_b128 v[174:177], v169 offset:1024
	ds_read_b128 v[178:181], v169 offset:2048
	ds_read_b128 v[182:185], v169 offset:3072
	s_add_u32 s38, s38, 0x20000
	s_addc_u32 s39, s39, 0
	s_mov_b32 m0, s7
	v_lshl_add_u64 v[226:227], s[38:39], 0, v[136:137]
	ds_read_b128 v[186:189], v167 offset:32768
	ds_read_b128 v[190:193], v167 offset:33792
	ds_read_b128 v[194:197], v167 offset:34816
	ds_read_b128 v[198:201], v167 offset:35840
	ds_read_b128 v[202:205], v167 offset:36864
	ds_read_b128 v[206:209], v167 offset:37888
	ds_read_b128 v[210:213], v167 offset:38912
	ds_read_b128 v[218:221], v167 offset:39936
	global_load_lds_dwordx4 v[226:227], off
	v_lshl_add_u64 v[226:227], s[38:39], 0, v[140:141]
	s_mov_b32 m0, s33
	s_nop 0
	global_load_lds_dwordx4 v[226:227], off
	s_waitcnt lgkmcnt(0)
	s_setprio 1
	s_waitcnt lgkmcnt(0)
	v_mfma_f32_16x16x32_bf16 v[124:127], v[128:131], v[186:189], v[124:127]
	v_mfma_f32_16x16x32_bf16 v[120:123], v[152:155], v[186:189], v[120:123]
	v_mfma_f32_16x16x32_bf16 v[108:111], v[128:131], v[194:197], v[108:111]
	v_mfma_f32_16x16x32_bf16 v[104:107], v[152:155], v[194:197], v[104:107]
	v_mfma_f32_16x16x32_bf16 v[92:95], v[128:131], v[202:205], v[92:95]
	v_mfma_f32_16x16x32_bf16 v[88:91], v[152:155], v[202:205], v[88:91]
	v_mfma_f32_16x16x32_bf16 v[76:79], v[128:131], v[210:213], v[76:79]
	v_mfma_f32_16x16x32_bf16 v[72:75], v[152:155], v[210:213], v[72:75]
	s_waitcnt vmcnt(8)
	s_barrier
	v_mfma_f32_16x16x32_bf16 v[124:127], v[132:135], v[190:193], v[124:127]
	v_mfma_f32_16x16x32_bf16 v[120:123], v[156:159], v[190:193], v[120:123]
	v_mfma_f32_16x16x32_bf16 v[108:111], v[132:135], v[198:201], v[108:111]
	v_mfma_f32_16x16x32_bf16 v[104:107], v[156:159], v[198:201], v[104:107]
	v_mfma_f32_16x16x32_bf16 v[92:95], v[132:135], v[206:209], v[92:95]
	v_mfma_f32_16x16x32_bf16 v[88:91], v[156:159], v[206:209], v[88:91]
	v_mfma_f32_16x16x32_bf16 v[76:79], v[132:135], v[218:221], v[76:79]
	v_mfma_f32_16x16x32_bf16 v[72:75], v[156:159], v[218:221], v[72:75]
	s_setprio 0
	s_setprio 1
	v_mfma_f32_16x16x32_bf16 v[116:119], v[170:173], v[186:189], v[116:119]
	v_mfma_f32_16x16x32_bf16 v[112:115], v[178:181], v[186:189], v[112:115]
	v_mfma_f32_16x16x32_bf16 v[100:103], v[170:173], v[194:197], v[100:103]
	v_mfma_f32_16x16x32_bf16 v[96:99], v[178:181], v[194:197], v[96:99]
	v_mfma_f32_16x16x32_bf16 v[84:87], v[170:173], v[202:205], v[84:87]
	v_mfma_f32_16x16x32_bf16 v[80:83], v[178:181], v[202:205], v[80:83]
	v_mfma_f32_16x16x32_bf16 v[68:71], v[170:173], v[210:213], v[68:71]
	v_mfma_f32_16x16x32_bf16 v[64:67], v[178:181], v[210:213], v[64:67]
	v_mfma_f32_16x16x32_bf16 v[116:119], v[174:177], v[190:193], v[116:119]
	v_mfma_f32_16x16x32_bf16 v[112:115], v[182:185], v[190:193], v[112:115]
	v_mfma_f32_16x16x32_bf16 v[100:103], v[174:177], v[198:201], v[100:103]
	v_mfma_f32_16x16x32_bf16 v[96:99], v[182:185], v[198:201], v[96:99]
	v_mfma_f32_16x16x32_bf16 v[84:87], v[174:177], v[206:209], v[84:87]
	v_mfma_f32_16x16x32_bf16 v[80:83], v[182:185], v[206:209], v[80:83]
	v_mfma_f32_16x16x32_bf16 v[68:71], v[174:177], v[218:221], v[68:71]
	v_mfma_f32_16x16x32_bf16 v[64:67], v[182:185], v[218:221], v[64:67]
	s_setprio 0
	s_barrier
; #define PG8_STAGE(bufoff, gbase, voff) do { _Pragma("unroll") for (int _i = 0; _i < 2; ++_i) \
;         __builtin_amdgcn_global_load_lds((const unsigned*)((const char*)(gbase) + (voff)[_i]), (PG8_LAS unsigned*)(lds + (bufoff) + ldsw + _i * 8192), 16, 0, 0); } while (0)
; #define PG8_LDA(dst, b, h) do { _Pragma("unroll") for (int m = 0; m < 4; ++m) _Pragma("unroll") for (int k = 0; k < 2; ++k) dst[m][k] = *(const PG8_LAS bf16x8*)(lds + PG8_SA(b, h) + aoff + m * 2048 + k * 1024); } while (0)
; #define PG8_LDB(dst, b, h) do { _Pragma("unroll") for (int n = 0; n < 2; ++n) _Pragma("unroll") for (int k = 0; k < 2; ++k) dst[n][k] = *(const PG8_LAS bf16x8*)(lds + PG8_SB(b, h) + boff + n * 2048 + k * 1024); } while (0)
; #define PG8_WAIT_V(n) asm volatile("s_waitcnt vmcnt(" #n ")" ::: "memory")
; template <class Epi, class Sched, bool ALIGN_EPI = false, bool SP2 = false>
; __device__ __forceinline__ void gemm_phase(PG8_LAS unsigned char* lds, const Gemm g, const Sched& S, const Epi& E, int wave0) {
;     ...
;         for (int t = 0; t < nt; t += 2) {
;             const bool last = (t == nt - 2);
;             const char* a1 = cA + (size_t)(t + 1) * kstep;
;             const char* a2 = last ? nA : cA + (size_t)(t + 2) * kstep; const char* b2 = last ? nB : cB + (size_t)(t + 2) * kstep;
;     ...
;             PG8_LDB(B0, 0, 0); PG8_LDB(B1, 0, 1); PG8_SCHED; PG8_LDA(At, 0, 0); PG8_STAGE(PG8_SA(1, 1), a1 + hstep, voffA);
;             PG8_WAIT_V(8); PG8_WAIT_L(0); PG8_BAR; PG8_MMA(0, 0, At, B0); PG8_MMA(0, 1, At, B1); PG8_BAR; PG8_SCHED;
;             PG8_LDA(At, 0, 1); PG8_STAGE(PG8_SB(0, 0), b2, voffB); PG8_STAGE(PG8_SB(0, 1), b2 + hstep, voffB); PG8_STAGE(PG8_SA(0, 0), a2, voffA);
;             PG8_WAIT_V(8); PG8_WAIT_L(0); PG8_BAR; if (!cur.half) { PG8_MMA(1, 0, At, B0); PG8_MMA(1, 1, At, B1); } PG8_BAR; PG8_SCHED;
;             PG8_LDB(B0, 1, 0); PG8_LDB(B1, 1, 1); PG8_SCHED; PG8_LDA(At, 1, 0); PG8_STAGE(PG8_SA(0, 1), a2 + hstep, voffA);
;             PG8_WAIT_V(8); PG8_WAIT_L(0); PG8_BAR; PG8_MMA(0, 0, At, B0); PG8_MMA(0, 1, At, B1); PG8_BAR; PG8_SCHED;
;             PG8_LDA(At, 1, 1); PG8_STAGE(PG8_SB(1, 0), b3, voffB); PG8_STAGE(PG8_SB(1, 1), b3 + hstep, voffB); PG8_STAGE(PG8_SA(1, 0), a3, voffA);
;             PG8_WAIT_V(8); PG8_WAIT_L(0); PG8_BAR; if (!cur.half) { PG8_MMA(1, 0, At, B0); PG8_MMA(1, 1, At, B1); } PG8_BAR; PG8_SCHED;
	s_add_i32 s38, s56, s4
	v_lshl_add_u64 v[160:161], v[160:161], 0, s[16:17]
	s_mov_b32 m0, s38
	ds_read_b128 v[186:189], v167 offset:49152
	ds_read_b128 v[190:193], v167 offset:50176
	ds_read_b128 v[194:197], v167 offset:51200
	ds_read_b128 v[198:201], v167 offset:52224
	ds_read_b128 v[202:205], v167 offset:53248
	ds_read_b128 v[206:209], v167 offset:54272
	ds_read_b128 v[210:213], v167 offset:55296
	ds_read_b128 v[218:221], v167 offset:56320
	global_load_lds_dwordx4 v[160:161], off
	s_add_i32 m0, s38, 0x2000
	s_add_u32 s36, s36, 0x20080
	v_lshl_add_u64 v[160:161], v[214:215], 0, s[16:17]
	s_addc_u32 s37, s37, 0
	s_add_i32 s38, s57, s4
	global_load_lds_dwordx4 v[160:161], off
	v_lshl_add_u64 v[160:161], s[36:37], 0, v[138:139]
	s_mov_b32 m0, s38
	s_nop 0
	global_load_lds_dwordx4 v[160:161], off
	v_lshl_add_u64 v[160:161], s[36:37], 0, v[142:143]
	s_add_i32 m0, s38, 0x2000
	s_nop 0
	global_load_lds_dwordx4 v[160:161], off
	v_lshl_add_u64 v[160:161], v[222:223], 0, s[16:17]
	s_mov_b32 m0, s43
	s_nop 0
	global_load_lds_dwordx4 v[160:161], off
	v_lshl_add_u64 v[160:161], v[224:225], 0, s[16:17]
	s_mov_b32 m0, s44
	s_nop 0
	global_load_lds_dwordx4 v[160:161], off
	s_waitcnt lgkmcnt(0)
	s_setprio 1
	s_waitcnt lgkmcnt(0)
	v_mfma_f32_16x16x32_bf16 v[60:63], v[128:131], v[186:189], v[60:63]
	v_mfma_f32_16x16x32_bf16 v[56:59], v[152:155], v[186:189], v[56:59]
	v_mfma_f32_16x16x32_bf16 v[44:47], v[128:131], v[194:197], v[44:47]
	v_mfma_f32_16x16x32_bf16 v[40:43], v[152:155], v[194:197], v[40:43]
	v_mfma_f32_16x16x32_bf16 v[28:31], v[128:131], v[202:205], v[28:31]
	v_mfma_f32_16x16x32_bf16 v[24:27], v[152:155], v[202:205], v[24:27]
	v_mfma_f32_16x16x32_bf16 v[12:15], v[128:131], v[210:213], v[12:15]
	v_mfma_f32_16x16x32_bf16 v[8:11], v[152:155], v[210:213], v[8:11]
	s_waitcnt vmcnt(8)
	s_barrier
	v_mfma_f32_16x16x32_bf16 v[60:63], v[132:135], v[190:193], v[60:63]
	v_mfma_f32_16x16x32_bf16 v[56:59], v[156:159], v[190:193], v[56:59]
	v_mfma_f32_16x16x32_bf16 v[44:47], v[132:135], v[198:201], v[44:47]
	v_mfma_f32_16x16x32_bf16 v[40:43], v[156:159], v[198:201], v[40:43]
	v_mfma_f32_16x16x32_bf16 v[28:31], v[132:135], v[206:209], v[28:31]
	v_mfma_f32_16x16x32_bf16 v[24:27], v[156:159], v[206:209], v[24:27]
	v_mfma_f32_16x16x32_bf16 v[12:15], v[132:135], v[218:221], v[12:15]
	v_mfma_f32_16x16x32_bf16 v[8:11], v[156:159], v[218:221], v[8:11]
	s_setprio 0
	s_setprio 1
	v_mfma_f32_16x16x32_bf16 v[52:55], v[170:173], v[186:189], v[52:55]
	v_mfma_f32_16x16x32_bf16 v[48:51], v[178:181], v[186:189], v[48:51]
	v_mfma_f32_16x16x32_bf16 v[36:39], v[170:173], v[194:197], v[36:39]
	v_mfma_f32_16x16x32_bf16 v[32:35], v[178:181], v[194:197], v[32:35]
	v_mfma_f32_16x16x32_bf16 v[20:23], v[170:173], v[202:205], v[20:23]
	v_mfma_f32_16x16x32_bf16 v[16:19], v[178:181], v[202:205], v[16:19]
	v_mfma_f32_16x16x32_bf16 v[4:7], v[170:173], v[210:213], v[4:7]
	v_mfma_f32_16x16x32_bf16 v[0:3], v[178:181], v[210:213], v[0:3]
	v_mfma_f32_16x16x32_bf16 v[52:55], v[174:177], v[190:193], v[52:55]
	v_mfma_f32_16x16x32_bf16 v[48:51], v[182:185], v[190:193], v[48:51]
	v_mfma_f32_16x16x32_bf16 v[36:39], v[174:177], v[198:201], v[36:39]
	v_mfma_f32_16x16x32_bf16 v[32:35], v[182:185], v[198:201], v[32:35]
	v_mfma_f32_16x16x32_bf16 v[20:23], v[174:177], v[206:209], v[20:23]
	v_mfma_f32_16x16x32_bf16 v[16:19], v[182:185], v[206:209], v[16:19]
	v_mfma_f32_16x16x32_bf16 v[4:7], v[174:177], v[218:221], v[4:7]
	v_mfma_f32_16x16x32_bf16 v[0:3], v[182:185], v[218:221], v[0:3]
	s_setprio 0
	s_barrier
	s_add_i32 s55, s55, 2
	s_add_u32 s2, s2, 0x100
	s_addc_u32 s3, s3, 0
	s_add_u32 s53, s53, 0x100
	s_addc_u32 s54, s54, 0
	s_cmp_gt_u32 s55, 5
	s_cbranch_scc0 .LBB0_705
	s_and_b64 vcc, exec, s[18:19]
	s_cbranch_vccz .LBB0_708
	s_barrier

; #define PG8_STAGE(bufoff, gbase, voff) do { _Pragma("unroll") for (int _i = 0; _i < 2; ++_i) \
;         __builtin_amdgcn_global_load_lds((const unsigned*)((const char*)(gbase) + (voff)[_i]), (PG8_LAS unsigned*)(lds + (bufoff) + ldsw + _i * 8192), 16, 0, 0); } while (0)
; #define PG8_LDA(dst, b, h) do { _Pragma("unroll") for (int m = 0; m < 4; ++m) _Pragma("unroll") for (int k = 0; k < 2; ++k) dst[m][k] = *(const PG8_LAS bf16x8*)(lds + PG8_SA(b, h) + aoff + m * 2048 + k * 1024); } while (0)
; #define PG8_LDB(dst, b, h) do { _Pragma("unroll") for (int n = 0; n < 2; ++n) _Pragma("unroll") for (int k = 0; k < 2; ++k) dst[n][k] = *(const PG8_LAS bf16x8*)(lds + PG8_SB(b, h) + boff + n * 2048 + k * 1024); } while (0)
; #define PG8_MMA(ai, bj, At, Bt) do { __builtin_amdgcn_s_setprio(1); _Pragma("unroll") for (int m = 0; m < 4; ++m) _Pragma("unroll") for (int n = 0; n < 2; ++n) _Pragma("unroll") for (int k = 0; k < 2; ++k) \
;         acc[ai][bj][m][n] = __builtin_amdgcn_mfma_f32_16x16x32_bf16(Bt[n][k], At[m][k], acc[ai][bj][m][n], 0, 0, 0); __builtin_amdgcn_s_setprio(0); } while (0)
; template <class Epi, class Sched, bool ALIGN_EPI = false, bool SP2 = false>
; __device__ __forceinline__ void gemm_phase(PG8_LAS unsigned char* lds, const Gemm g, const Sched& S, const Epi& E, int wave0) {
;     ...
;             PG8_LDB(B0, 0, 0); PG8_LDB(B1, 0, 1); PG8_SCHED; PG8_LDA(At, 0, 0); PG8_STAGE(PG8_SA(1, 1), a1 + hstep, voffA);
;             PG8_WAIT_V(8); PG8_WAIT_L(0); PG8_BAR; PG8_MMA(0, 0, At, B0); PG8_MMA(0, 1, At, B1); PG8_BAR; PG8_SCHED;
;             PG8_LDA(At, 0, 1); PG8_STAGE(PG8_SB(0, 0), b2, voffB); PG8_STAGE(PG8_SB(0, 1), b2 + hstep, voffB); PG8_STAGE(PG8_SA(0, 0), a2, voffA);
;             PG8_WAIT_V(8); PG8_WAIT_L(0); PG8_BAR; if (!cur.half) { PG8_MMA(1, 0, At, B0); PG8_MMA(1, 1, At, B1); } PG8_BAR; PG8_SCHED;
;             PG8_LDB(B0, 1, 0); PG8_LDB(B1, 1, 1); PG8_SCHED; PG8_LDA(At, 1, 0); PG8_STAGE(PG8_SA(0, 1), a2 + hstep, voffA);
;             PG8_WAIT_V(8); PG8_WAIT_L(0); PG8_BAR; PG8_MMA(0, 0, At, B0); PG8_MMA(0, 1, At, B1); PG8_BAR; PG8_SCHED;
;             PG8_LDA(At, 1, 1); PG8_STAGE(PG8_SB(1, 0), b3, voffB); PG8_STAGE(PG8_SB(1, 1), b3 + hstep, voffB); PG8_STAGE(PG8_SA(1, 0), a3, voffA);
;             PG8_WAIT_V(8); PG8_WAIT_L(0); PG8_BAR; if (!cur.half) { PG8_MMA(1, 0, At, B0); PG8_MMA(1, 1, At, B1); } PG8_BAR; PG8_SCHED;
.LBB0_822:
	ds_read_b128 v[148:151], v221
	ds_read_b128 v[152:155], v221 offset:1024
	ds_read_b128 v[156:159], v221 offset:2048
	ds_read_b128 v[160:163], v221 offset:3072
	ds_read_b128 v[132:135], v222
	ds_read_b128 v[136:139], v222 offset:1024
	ds_read_b128 v[140:143], v222 offset:2048
	ds_read_b128 v[144:147], v222 offset:3072
	s_add_u32 s8, s42, 0xfffc0080
	s_addc_u32 s9, s43, -1
	s_cmp_eq_u32 s85, 12
	s_cselect_b32 s47, s1, s9
	s_cselect_b32 s46, s29, s8
	s_cselect_b32 s45, s21, s69
	s_cselect_b32 s44, s39, s68
	v_lshl_add_u64 v[2:3], s[42:43], 0, v[204:205]
	s_add_i32 m0, s7, 0xc000
	s_waitcnt lgkmcnt(0)
	ds_read_b128 v[164:167], v223
	ds_read_b128 v[168:171], v223 offset:1024
	ds_read_b128 v[172:175], v223 offset:2048
	ds_read_b128 v[176:179], v223 offset:3072
	ds_read_b128 v[180:183], v223 offset:4096
	ds_read_b128 v[184:187], v223 offset:5120
	ds_read_b128 v[188:191], v223 offset:6144
	ds_read_b128 v[192:195], v223 offset:7168
	global_load_lds_dwordx4 v[2:3], off
	v_lshl_add_u64 v[2:3], s[42:43], 0, v[206:207]
	s_add_i32 m0, s7, 0xe000
	s_nop 0
	global_load_lds_dwordx4 v[2:3], off
	s_waitcnt lgkmcnt(0)
	s_setprio 1
	s_waitcnt lgkmcnt(0)
	v_mfma_f32_16x16x32_bf16 v[128:131], v[148:151], v[164:167], v[128:131]
	v_mfma_f32_16x16x32_bf16 v[124:127], v[156:159], v[164:167], v[124:127]
	v_mfma_f32_16x16x32_bf16 v[112:115], v[148:151], v[172:175], v[112:115]
	v_mfma_f32_16x16x32_bf16 v[108:111], v[156:159], v[172:175], v[108:111]
	v_mfma_f32_16x16x32_bf16 v[96:99], v[148:151], v[180:183], v[96:99]
	v_mfma_f32_16x16x32_bf16 v[92:95], v[156:159], v[180:183], v[92:95]
	v_mfma_f32_16x16x32_bf16 v[80:83], v[148:151], v[188:191], v[80:83]
	v_mfma_f32_16x16x32_bf16 v[76:79], v[156:159], v[188:191], v[76:79]
	s_waitcnt vmcnt(8)
	s_barrier
	v_mfma_f32_16x16x32_bf16 v[128:131], v[152:155], v[168:171], v[128:131]
	v_mfma_f32_16x16x32_bf16 v[124:127], v[160:163], v[168:171], v[124:127]
	v_mfma_f32_16x16x32_bf16 v[112:115], v[152:155], v[176:179], v[112:115]
	v_mfma_f32_16x16x32_bf16 v[108:111], v[160:163], v[176:179], v[108:111]
	v_mfma_f32_16x16x32_bf16 v[96:99], v[152:155], v[184:187], v[96:99]
	v_mfma_f32_16x16x32_bf16 v[92:95], v[160:163], v[184:187], v[92:95]
	v_mfma_f32_16x16x32_bf16 v[80:83], v[152:155], v[192:195], v[80:83]
	v_mfma_f32_16x16x32_bf16 v[76:79], v[160:163], v[192:195], v[76:79]
	s_setprio 0
	s_setprio 1
	v_mfma_f32_16x16x32_bf16 v[120:123], v[132:135], v[164:167], v[120:123]
	v_mfma_f32_16x16x32_bf16 v[116:119], v[140:143], v[164:167], v[116:119]
	v_mfma_f32_16x16x32_bf16 v[104:107], v[132:135], v[172:175], v[104:107]
	v_mfma_f32_16x16x32_bf16 v[100:103], v[140:143], v[172:175], v[100:103]
	v_mfma_f32_16x16x32_bf16 v[88:91], v[132:135], v[180:183], v[88:91]
	v_mfma_f32_16x16x32_bf16 v[84:87], v[140:143], v[180:183], v[84:87]
	v_mfma_f32_16x16x32_bf16 v[72:75], v[132:135], v[188:191], v[72:75]
	v_mfma_f32_16x16x32_bf16 v[68:71], v[140:143], v[188:191], v[68:71]
	v_mfma_f32_16x16x32_bf16 v[120:123], v[136:139], v[168:171], v[120:123]
	v_mfma_f32_16x16x32_bf16 v[116:119], v[144:147], v[168:171], v[116:119]
	v_mfma_f32_16x16x32_bf16 v[104:107], v[136:139], v[176:179], v[104:107]
	v_mfma_f32_16x16x32_bf16 v[100:103], v[144:147], v[176:179], v[100:103]
	v_mfma_f32_16x16x32_bf16 v[88:91], v[136:139], v[184:187], v[88:91]
	v_mfma_f32_16x16x32_bf16 v[84:87], v[144:147], v[184:187], v[84:87]
	v_mfma_f32_16x16x32_bf16 v[72:75], v[136:139], v[192:195], v[72:75]
	v_mfma_f32_16x16x32_bf16 v[68:71], v[144:147], v[192:195], v[68:71]
	s_setprio 0
	s_barrier
	s_add_i32 s8, s55, s6
	v_lshl_add_u64 v[2:3], s[44:45], 0, v[198:199]
	s_mov_b32 m0, s8
	ds_read_b128 v[188:191], v223 offset:16384
	ds_read_b128 v[192:195], v223 offset:17408
	ds_read_b128 v[180:183], v223 offset:18432
	ds_read_b128 v[184:187], v223 offset:19456
	ds_read_b128 v[172:175], v223 offset:20480
	ds_read_b128 v[176:179], v223 offset:21504
	ds_read_b128 v[164:167], v223 offset:22528
	ds_read_b128 v[168:171], v223 offset:23552
	global_load_lds_dwordx4 v[2:3], off
	s_add_i32 m0, s8, 0x2000
	s_add_u32 s8, s44, 0x40000
	v_lshl_add_u64 v[210:211], s[44:45], 0, v[202:203]
	s_addc_u32 s9, s45, 0
	s_add_i32 s86, s56, s6
	global_load_lds_dwordx4 v[210:211], off
	v_lshl_add_u64 v[212:213], s[8:9], 0, v[198:199]
	s_mov_b32 m0, s86
	v_lshl_add_u64 v[214:215], s[46:47], 0, v[200:201]
	global_load_lds_dwordx4 v[212:213], off
	v_lshl_add_u64 v[212:213], s[8:9], 0, v[202:203]
	s_add_i32 m0, s86, 0x2000
	v_cmp_ne_u32_e64 s[8:9], 1, v225
	global_load_lds_dwordx4 v[212:213], off
	v_lshl_add_u64 v[212:213], s[46:47], 0, v[196:197]
	s_mov_b32 m0, s7
	s_andn2_b64 vcc, exec, s[40:41]
	global_load_lds_dwordx4 v[212:213], off
	s_mov_b32 m0, s33
	s_nop 0
	global_load_lds_dwordx4 v[214:215], off
	s_waitcnt vmcnt(8)
	s_waitcnt lgkmcnt(0)
	s_barrier
	s_cbranch_vccnz .LBB0_824
; #define PG8_MMA(ai, bj, At, Bt) do { __builtin_amdgcn_s_setprio(1); _Pragma("unroll") for (int m = 0; m < 4; ++m) _Pragma("unroll") for (int n = 0; n < 2; ++n) _Pragma("unroll") for (int k = 0; k < 2; ++k) \
;         acc[ai][bj][m][n] = __builtin_amdgcn_mfma_f32_16x16x32_bf16(Bt[n][k], At[m][k], acc[ai][bj][m][n], 0, 0, 0); __builtin_amdgcn_s_setprio(0); } while (0)
; #define PG8_WAIT_V(n) asm volatile("s_waitcnt vmcnt(" #n ")" ::: "memory")
; #define PG8_WAIT_L(n) asm volatile("s_waitcnt lgkmcnt(" #n ")" ::: "memory")
; #define PG8_BAR __builtin_amdgcn_s_barrier()
; #define PG8_SCHED __builtin_amdgcn_sched_barrier(0)
; template <class Epi, class Sched, bool ALIGN_EPI = false, bool SP2 = false>
; __device__ __forceinline__ void gemm_phase(PG8_LAS unsigned char* lds, const Gemm g, const Sched& S, const Epi& E, int wave0) {
;     ...
;             PG8_WAIT_V(8); PG8_WAIT_L(0); PG8_BAR; if (!cur.half) { PG8_MMA(1, 0, At, B0); PG8_MMA(1, 1, At, B1); } PG8_BAR; PG8_SCHED;
	s_setprio 1
	s_waitcnt lgkmcnt(0)
	v_mfma_f32_16x16x32_bf16 v[64:67], v[148:151], v[188:191], v[64:67]
	v_mfma_f32_16x16x32_bf16 v[60:63], v[156:159], v[188:191], v[60:63]
	v_mfma_f32_16x16x32_bf16 v[48:51], v[148:151], v[180:183], v[48:51]
	v_mfma_f32_16x16x32_bf16 v[44:47], v[156:159], v[180:183], v[44:47]
	v_mfma_f32_16x16x32_bf16 v[32:35], v[148:151], v[172:175], v[32:35]
	v_mfma_f32_16x16x32_bf16 v[28:31], v[156:159], v[172:175], v[28:31]
	v_mfma_f32_16x16x32_bf16 v[16:19], v[148:151], v[164:167], v[16:19]
	v_mfma_f32_16x16x32_bf16 v[12:15], v[156:159], v[164:167], v[12:15]
	v_mfma_f32_16x16x32_bf16 v[64:67], v[152:155], v[192:195], v[64:67]
	v_mfma_f32_16x16x32_bf16 v[60:63], v[160:163], v[192:195], v[60:63]
	v_mfma_f32_16x16x32_bf16 v[48:51], v[152:155], v[184:187], v[48:51]
	v_mfma_f32_16x16x32_bf16 v[44:47], v[160:163], v[184:187], v[44:47]
	v_mfma_f32_16x16x32_bf16 v[32:35], v[152:155], v[176:179], v[32:35]
	v_mfma_f32_16x16x32_bf16 v[28:31], v[160:163], v[176:179], v[28:31]
	v_mfma_f32_16x16x32_bf16 v[16:19], v[152:155], v[168:171], v[16:19]
	v_mfma_f32_16x16x32_bf16 v[12:15], v[160:163], v[168:171], v[12:15]
	s_setprio 0
	s_setprio 1
	v_mfma_f32_16x16x32_bf16 v[56:59], v[132:135], v[188:191], v[56:59]
	v_mfma_f32_16x16x32_bf16 v[52:55], v[140:143], v[188:191], v[52:55]
	v_mfma_f32_16x16x32_bf16 v[40:43], v[132:135], v[180:183], v[40:43]
	v_mfma_f32_16x16x32_bf16 v[36:39], v[140:143], v[180:183], v[36:39]
	v_mfma_f32_16x16x32_bf16 v[24:27], v[132:135], v[172:175], v[24:27]
	v_mfma_f32_16x16x32_bf16 v[20:23], v[140:143], v[172:175], v[20:23]
	v_mfma_f32_16x16x32_bf16 v[8:11], v[132:135], v[164:167], v[8:11]
	v_mfma_f32_16x16x32_bf16 v[4:7], v[140:143], v[164:167], v[4:7]
	v_mfma_f32_16x16x32_bf16 v[56:59], v[136:139], v[192:195], v[56:59]
	v_mfma_f32_16x16x32_bf16 v[52:55], v[144:147], v[192:195], v[52:55]
	v_mfma_f32_16x16x32_bf16 v[40:43], v[136:139], v[184:187], v[40:43]
	v_mfma_f32_16x16x32_bf16 v[36:39], v[144:147], v[184:187], v[36:39]
	v_mfma_f32_16x16x32_bf16 v[24:27], v[136:139], v[176:179], v[24:27]
	v_mfma_f32_16x16x32_bf16 v[20:23], v[144:147], v[176:179], v[20:23]
	v_mfma_f32_16x16x32_bf16 v[8:11], v[136:139], v[168:171], v[8:11]
	v_mfma_f32_16x16x32_bf16 v[4:7], v[144:147], v[168:171], v[4:7]
	s_setprio 0
; #define PG8_STAGE(bufoff, gbase, voff) do { _Pragma("unroll") for (int _i = 0; _i < 2; ++_i) \
;         __builtin_amdgcn_global_load_lds((const unsigned*)((const char*)(gbase) + (voff)[_i]), (PG8_LAS unsigned*)(lds + (bufoff) + ldsw + _i * 8192), 16, 0, 0); } while (0)
; #define PG8_LDA(dst, b, h) do { _Pragma("unroll") for (int m = 0; m < 4; ++m) _Pragma("unroll") for (int k = 0; k < 2; ++k) dst[m][k] = *(const PG8_LAS bf16x8*)(lds + PG8_SA(b, h) + aoff + m * 2048 + k * 1024); } while (0)
; #define PG8_LDB(dst, b, h) do { _Pragma("unroll") for (int n = 0; n < 2; ++n) _Pragma("unroll") for (int k = 0; k < 2; ++k) dst[n][k] = *(const PG8_LAS bf16x8*)(lds + PG8_SB(b, h) + boff + n * 2048 + k * 1024); } while (0)
; #define PG8_MMA(ai, bj, At, Bt) do { __builtin_amdgcn_s_setprio(1); _Pragma("unroll") for (int m = 0; m < 4; ++m) _Pragma("unroll") for (int n = 0; n < 2; ++n) _Pragma("unroll") for (int k = 0; k < 2; ++k) \
;         acc[ai][bj][m][n] = __builtin_amdgcn_mfma_f32_16x16x32_bf16(Bt[n][k], At[m][k], acc[ai][bj][m][n], 0, 0, 0); __builtin_amdgcn_s_setprio(0); } while (0)
; #define PG8_WAIT_V(n) asm volatile("s_waitcnt vmcnt(" #n ")" ::: "memory")
; #define PG8_WAIT_L(n) asm volatile("s_waitcnt lgkmcnt(" #n ")" ::: "memory")
; #define PG8_BAR __builtin_amdgcn_s_barrier()
; #define PG8_SCHED __builtin_amdgcn_sched_barrier(0)
; template <class Epi, class Sched, bool ALIGN_EPI = false, bool SP2 = false>
; __device__ __forceinline__ void gemm_phase(PG8_LAS unsigned char* lds, const Gemm g, const Sched& S, const Epi& E, int wave0) {
;     ...
;             PG8_LDB(B0, 1, 0); PG8_LDB(B1, 1, 1); PG8_SCHED; PG8_LDA(At, 1, 0); PG8_STAGE(PG8_SA(0, 1), a2 + hstep, voffA);
;             PG8_WAIT_V(8); PG8_WAIT_L(0); PG8_BAR; PG8_MMA(0, 0, At, B0); PG8_MMA(0, 1, At, B1); PG8_BAR; PG8_SCHED;
;             PG8_LDA(At, 1, 1); PG8_STAGE(PG8_SB(1, 0), b3, voffB); PG8_STAGE(PG8_SB(1, 1), b3 + hstep, voffB); PG8_STAGE(PG8_SA(1, 0), a3, voffA);
;             PG8_WAIT_V(8); PG8_WAIT_L(0); PG8_BAR; if (!cur.half) { PG8_MMA(1, 0, At, B0); PG8_MMA(1, 1, At, B1); } PG8_BAR; PG8_SCHED;
.LBB0_824:
	s_barrier
	s_add_i32 s86, 0, 0x18000
	v_add_u32_e32 v1, s86, v220
	s_add_i32 s87, 0, 0x1c000
	ds_read_b128 v[148:151], v1
	ds_read_b128 v[152:155], v1 offset:1024
	ds_read_b128 v[156:159], v1 offset:2048
	ds_read_b128 v[160:163], v1 offset:3072
	v_add_u32_e32 v1, s87, v220
	ds_read_b128 v[132:135], v1
	ds_read_b128 v[136:139], v1 offset:1024
	ds_read_b128 v[140:143], v1 offset:2048
	ds_read_b128 v[144:147], v1 offset:3072
	s_add_u32 s46, s46, 0x40000
	s_addc_u32 s47, s47, 0
	s_mov_b32 m0, s48
	v_lshl_add_u64 v[226:227], s[46:47], 0, v[196:197]
	s_waitcnt lgkmcnt(0)
	ds_read_b128 v[164:167], v223 offset:32768
	ds_read_b128 v[168:171], v223 offset:33792
	ds_read_b128 v[172:175], v223 offset:34816
	ds_read_b128 v[176:179], v223 offset:35840
	ds_read_b128 v[180:183], v223 offset:36864
	ds_read_b128 v[184:187], v223 offset:37888
	ds_read_b128 v[188:191], v223 offset:38912
	ds_read_b128 v[192:195], v223 offset:39936
	global_load_lds_dwordx4 v[226:227], off
	v_lshl_add_u64 v[226:227], s[46:47], 0, v[200:201]
	s_mov_b32 m0, s49
	s_nop 0
	global_load_lds_dwordx4 v[226:227], off
	s_waitcnt lgkmcnt(0)
	s_setprio 1
	s_waitcnt lgkmcnt(0)
	v_mfma_f32_16x16x32_bf16 v[128:131], v[148:151], v[164:167], v[128:131]
	v_mfma_f32_16x16x32_bf16 v[124:127], v[156:159], v[164:167], v[124:127]
	v_mfma_f32_16x16x32_bf16 v[112:115], v[148:151], v[172:175], v[112:115]
	v_mfma_f32_16x16x32_bf16 v[108:111], v[156:159], v[172:175], v[108:111]
	v_mfma_f32_16x16x32_bf16 v[96:99], v[148:151], v[180:183], v[96:99]
	v_mfma_f32_16x16x32_bf16 v[92:95], v[156:159], v[180:183], v[92:95]
	v_mfma_f32_16x16x32_bf16 v[80:83], v[148:151], v[188:191], v[80:83]
	v_mfma_f32_16x16x32_bf16 v[76:79], v[156:159], v[188:191], v[76:79]
	s_waitcnt vmcnt(8)
	s_barrier
	v_mfma_f32_16x16x32_bf16 v[128:131], v[152:155], v[168:171], v[128:131]
	v_mfma_f32_16x16x32_bf16 v[124:127], v[160:163], v[168:171], v[124:127]
	v_mfma_f32_16x16x32_bf16 v[112:115], v[152:155], v[176:179], v[112:115]
	v_mfma_f32_16x16x32_bf16 v[108:111], v[160:163], v[176:179], v[108:111]
	v_mfma_f32_16x16x32_bf16 v[96:99], v[152:155], v[184:187], v[96:99]
	v_mfma_f32_16x16x32_bf16 v[92:95], v[160:163], v[184:187], v[92:95]
	v_mfma_f32_16x16x32_bf16 v[80:83], v[152:155], v[192:195], v[80:83]
	v_mfma_f32_16x16x32_bf16 v[76:79], v[160:163], v[192:195], v[76:79]
	s_setprio 0
	s_setprio 1
	v_mfma_f32_16x16x32_bf16 v[120:123], v[132:135], v[164:167], v[120:123]
	v_mfma_f32_16x16x32_bf16 v[116:119], v[140:143], v[164:167], v[116:119]
	v_mfma_f32_16x16x32_bf16 v[104:107], v[132:135], v[172:175], v[104:107]
	v_mfma_f32_16x16x32_bf16 v[100:103], v[140:143], v[172:175], v[100:103]
	v_mfma_f32_16x16x32_bf16 v[88:91], v[132:135], v[180:183], v[88:91]
	v_mfma_f32_16x16x32_bf16 v[84:87], v[140:143], v[180:183], v[84:87]
	v_mfma_f32_16x16x32_bf16 v[72:75], v[132:135], v[188:191], v[72:75]
	v_mfma_f32_16x16x32_bf16 v[68:71], v[140:143], v[188:191], v[68:71]
	v_mfma_f32_16x16x32_bf16 v[120:123], v[136:139], v[168:171], v[120:123]
	v_mfma_f32_16x16x32_bf16 v[116:119], v[144:147], v[168:171], v[116:119]
	v_mfma_f32_16x16x32_bf16 v[104:107], v[136:139], v[176:179], v[104:107]
	v_mfma_f32_16x16x32_bf16 v[100:103], v[144:147], v[176:179], v[100:103]
	v_mfma_f32_16x16x32_bf16 v[88:91], v[136:139], v[184:187], v[88:91]
	v_mfma_f32_16x16x32_bf16 v[84:87], v[144:147], v[184:187], v[84:87]
	v_mfma_f32_16x16x32_bf16 v[72:75], v[136:139], v[192:195], v[72:75]
	v_mfma_f32_16x16x32_bf16 v[68:71], v[144:147], v[192:195], v[68:71]
	s_setprio 0
	s_barrier
	s_add_i32 s46, s86, s6
	v_lshl_add_u64 v[2:3], v[2:3], 0, s[16:17]
	s_mov_b32 m0, s46
	ds_read_b128 v[188:191], v223 offset:49152
	ds_read_b128 v[192:195], v223 offset:50176
	ds_read_b128 v[180:183], v223 offset:51200
	ds_read_b128 v[184:187], v223 offset:52224
	ds_read_b128 v[172:175], v223 offset:53248
	ds_read_b128 v[176:179], v223 offset:54272
	ds_read_b128 v[164:167], v223 offset:55296
	ds_read_b128 v[168:171], v223 offset:56320
	global_load_lds_dwordx4 v[2:3], off
	s_add_i32 m0, s46, 0x2000
	s_add_u32 s44, s44, 0x40080
	v_lshl_add_u64 v[2:3], v[210:211], 0, s[16:17]
	s_addc_u32 s45, s45, 0
	s_add_i32 s46, s87, s6
	global_load_lds_dwordx4 v[2:3], off
	v_lshl_add_u64 v[2:3], s[44:45], 0, v[198:199]
	s_mov_b32 m0, s46
	s_and_b64 vcc, exec, s[8:9]
	global_load_lds_dwordx4 v[2:3], off
	v_lshl_add_u64 v[2:3], s[44:45], 0, v[202:203]
	s_add_i32 m0, s46, 0x2000
	s_nop 0
	global_load_lds_dwordx4 v[2:3], off
	v_lshl_add_u64 v[2:3], v[212:213], 0, s[16:17]
	s_mov_b32 m0, s53
	s_nop 0
	global_load_lds_dwordx4 v[2:3], off
	v_lshl_add_u64 v[2:3], v[214:215], 0, s[16:17]
	s_mov_b32 m0, s54
	s_nop 0
	global_load_lds_dwordx4 v[2:3], off
	s_waitcnt vmcnt(8)
	s_waitcnt lgkmcnt(0)
	s_barrier
	s_cbranch_vccnz .LBB0_821
	s_setprio 1
	s_waitcnt lgkmcnt(0)
	v_mfma_f32_16x16x32_bf16 v[64:67], v[148:151], v[188:191], v[64:67]
	v_mfma_f32_16x16x32_bf16 v[60:63], v[156:159], v[188:191], v[60:63]
	v_mfma_f32_16x16x32_bf16 v[48:51], v[148:151], v[180:183], v[48:51]
	v_mfma_f32_16x16x32_bf16 v[44:47], v[156:159], v[180:183], v[44:47]
	v_mfma_f32_16x16x32_bf16 v[32:35], v[148:151], v[172:175], v[32:35]
	v_mfma_f32_16x16x32_bf16 v[28:31], v[156:159], v[172:175], v[28:31]
	v_mfma_f32_16x16x32_bf16 v[16:19], v[148:151], v[164:167], v[16:19]
	v_mfma_f32_16x16x32_bf16 v[12:15], v[156:159], v[164:167], v[12:15]
	v_mfma_f32_16x16x32_bf16 v[64:67], v[152:155], v[192:195], v[64:67]
	v_mfma_f32_16x16x32_bf16 v[60:63], v[160:163], v[192:195], v[60:63]
	v_mfma_f32_16x16x32_bf16 v[48:51], v[152:155], v[184:187], v[48:51]
	v_mfma_f32_16x16x32_bf16 v[44:47], v[160:163], v[184:187], v[44:47]
	v_mfma_f32_16x16x32_bf16 v[32:35], v[152:155], v[176:179], v[32:35]
	v_mfma_f32_16x16x32_bf16 v[28:31], v[160:163], v[176:179], v[28:31]
	v_mfma_f32_16x16x32_bf16 v[16:19], v[152:155], v[168:171], v[16:19]
	v_mfma_f32_16x16x32_bf16 v[12:15], v[160:163], v[168:171], v[12:15]
	s_setprio 0
	s_setprio 1
	v_mfma_f32_16x16x32_bf16 v[56:59], v[132:135], v[188:191], v[56:59]
	v_mfma_f32_16x16x32_bf16 v[52:55], v[140:143], v[188:191], v[52:55]
	v_mfma_f32_16x16x32_bf16 v[40:43], v[132:135], v[180:183], v[40:43]
	v_mfma_f32_16x16x32_bf16 v[36:39], v[140:143], v[180:183], v[36:39]
	v_mfma_f32_16x16x32_bf16 v[24:27], v[132:135], v[172:175], v[24:27]
	v_mfma_f32_16x16x32_bf16 v[20:23], v[140:143], v[172:175], v[20:23]
	v_mfma_f32_16x16x32_bf16 v[8:11], v[132:135], v[164:167], v[8:11]
	v_mfma_f32_16x16x32_bf16 v[2:5], v[140:143], v[164:167], v[4:7]
	v_mfma_f32_16x16x32_bf16 v[56:59], v[136:139], v[192:195], v[56:59]
	v_mfma_f32_16x16x32_bf16 v[52:55], v[144:147], v[192:195], v[52:55]
	v_mfma_f32_16x16x32_bf16 v[40:43], v[136:139], v[184:187], v[40:43]
	v_mfma_f32_16x16x32_bf16 v[36:39], v[144:147], v[184:187], v[36:39]
	v_mfma_f32_16x16x32_bf16 v[24:27], v[136:139], v[176:179], v[24:27]
	v_mfma_f32_16x16x32_bf16 v[20:23], v[144:147], v[176:179], v[20:23]
	v_mfma_f32_16x16x32_bf16 v[8:11], v[136:139], v[168:171], v[8:11]
	v_mfma_f32_16x16x32_bf16 v[4:7], v[144:147], v[168:171], v[2:5]
	s_setprio 0
	s_branch .LBB0_821

; #define PG8_STAGE(bufoff, gbase, voff) do { _Pragma("unroll") for (int _i = 0; _i < 2; ++_i) \
;         __builtin_amdgcn_global_load_lds((const unsigned*)((const char*)(gbase) + (voff)[_i]), (PG8_LAS unsigned*)(lds + (bufoff) + ldsw + _i * 8192), 16, 0, 0); } while (0)
; #define PG8_LDA(dst, b, h) do { _Pragma("unroll") for (int m = 0; m < 4; ++m) _Pragma("unroll") for (int k = 0; k < 2; ++k) dst[m][k] = *(const PG8_LAS bf16x8*)(lds + PG8_SA(b, h) + aoff + m * 2048 + k * 1024); } while (0)
; #define PG8_LDB(dst, b, h) do { _Pragma("unroll") for (int n = 0; n < 2; ++n) _Pragma("unroll") for (int k = 0; k < 2; ++k) dst[n][k] = *(const PG8_LAS bf16x8*)(lds + PG8_SB(b, h) + boff + n * 2048 + k * 1024); } while (0)
; #define PG8_MMA(ai, bj, At, Bt) do { __builtin_amdgcn_s_setprio(1); _Pragma("unroll") for (int m = 0; m < 4; ++m) _Pragma("unroll") for (int n = 0; n < 2; ++n) _Pragma("unroll") for (int k = 0; k < 2; ++k) \
;         acc[ai][bj][m][n] = __builtin_amdgcn_mfma_f32_16x16x32_bf16(Bt[n][k], At[m][k], acc[ai][bj][m][n], 0, 0, 0); __builtin_amdgcn_s_setprio(0); } while (0)
; #define PG8_WAIT_V(n) asm volatile("s_waitcnt vmcnt(" #n ")" ::: "memory")
; template <class Epi, class Sched, bool ALIGN_EPI = false, bool SP2 = false>
; __device__ __forceinline__ void gemm_phase(PG8_LAS unsigned char* lds, const Gemm g, const Sched& S, const Epi& E, int wave0) {
;     ...
;         for (int t = 0; t < nt; t += 2) {
;             const bool last = (t == nt - 2);
;             const char* a1 = cA + (size_t)(t + 1) * kstep;
;             const char* a2 = last ? nA : cA + (size_t)(t + 2) * kstep; const char* b2 = last ? nB : cB + (size_t)(t + 2) * kstep;
;             const char* a3 = a2 + kstep; const char* b3 = b2 + kstep;
;             if (last && has_next) S.a_ready(nxt);
;             if constexpr (SP2) {
;             PG8_LDB(B0, 0, 0); PG8_LDB(B1, 0, 1); PG8_SCHED; PG8_LDA(At, 0, 0); PG8_STAGE(PG8_SA(1, 1), a1 + hstep, voffA);
;             PG8_WAIT_V(8); PG8_WAIT_L(0); PG8_BAR; PG8_MMA(0, 0, At, B0); PG8_MMA(0, 1, At, B1); PG8_BAR; PG8_SCHED;
;             PG8_LDA(At, 0, 1); PG8_STAGE(PG8_SB(0, 0), b2, voffB); PG8_STAGE(PG8_SB(0, 1), b2 + hstep, voffB); PG8_STAGE(PG8_SA(0, 0), a2, voffA);
;             PG8_WAIT_V(8); PG8_WAIT_L(0); PG8_BAR; if (!cur.half) { PG8_MMA(1, 0, At, B0); PG8_MMA(1, 1, At, B1); } PG8_BAR; PG8_SCHED;
.LBB0_1001:
	ds_read_b128 v[148:151], v221
	ds_read_b128 v[152:155], v221 offset:1024
	ds_read_b128 v[156:159], v221 offset:2048
	ds_read_b128 v[160:163], v221 offset:3072
	ds_read_b128 v[132:135], v222
	ds_read_b128 v[136:139], v222 offset:1024
	ds_read_b128 v[140:143], v222 offset:2048
	ds_read_b128 v[144:147], v222 offset:3072
	s_add_u32 s0, s8, 0xfffc0080
	s_addc_u32 s1, s9, -1
	s_cmp_eq_u32 s49, 12
	s_cselect_b32 s87, s3, s1
	s_cselect_b32 s86, s29, s0
	s_cselect_b32 s11, s51, s69
	s_cselect_b32 s10, s53, s68
	v_lshl_add_u64 v[2:3], s[8:9], 0, v[204:205]
	s_add_i32 m0, s33, 0xc000
	s_waitcnt lgkmcnt(0)
	ds_read_b128 v[164:167], v223
	ds_read_b128 v[168:171], v223 offset:1024
	ds_read_b128 v[172:175], v223 offset:2048
	ds_read_b128 v[176:179], v223 offset:3072
	ds_read_b128 v[180:183], v223 offset:4096
	ds_read_b128 v[184:187], v223 offset:5120
	ds_read_b128 v[188:191], v223 offset:6144
	ds_read_b128 v[192:195], v223 offset:7168
	global_load_lds_dwordx4 v[2:3], off
	v_lshl_add_u64 v[2:3], s[8:9], 0, v[206:207]
	s_add_i32 m0, s33, 0xe000
	s_nop 0
	global_load_lds_dwordx4 v[2:3], off
	s_waitcnt lgkmcnt(0)
	s_setprio 1
	s_waitcnt lgkmcnt(0)
	v_mfma_f32_16x16x32_bf16 v[128:131], v[148:151], v[164:167], v[128:131]
	v_mfma_f32_16x16x32_bf16 v[124:127], v[156:159], v[164:167], v[124:127]
	v_mfma_f32_16x16x32_bf16 v[120:123], v[148:151], v[172:175], v[120:123]
	v_mfma_f32_16x16x32_bf16 v[116:119], v[156:159], v[172:175], v[116:119]
	v_mfma_f32_16x16x32_bf16 v[112:115], v[148:151], v[180:183], v[112:115]
	v_mfma_f32_16x16x32_bf16 v[108:111], v[156:159], v[180:183], v[108:111]
	v_mfma_f32_16x16x32_bf16 v[104:107], v[148:151], v[188:191], v[104:107]
	v_mfma_f32_16x16x32_bf16 v[100:103], v[156:159], v[188:191], v[100:103]
	s_waitcnt vmcnt(8)
	s_barrier
	v_mfma_f32_16x16x32_bf16 v[128:131], v[152:155], v[168:171], v[128:131]
	v_mfma_f32_16x16x32_bf16 v[124:127], v[160:163], v[168:171], v[124:127]
	v_mfma_f32_16x16x32_bf16 v[120:123], v[152:155], v[176:179], v[120:123]
	v_mfma_f32_16x16x32_bf16 v[116:119], v[160:163], v[176:179], v[116:119]
	v_mfma_f32_16x16x32_bf16 v[112:115], v[152:155], v[184:187], v[112:115]
	v_mfma_f32_16x16x32_bf16 v[108:111], v[160:163], v[184:187], v[108:111]
	v_mfma_f32_16x16x32_bf16 v[104:107], v[152:155], v[192:195], v[104:107]
	v_mfma_f32_16x16x32_bf16 v[100:103], v[160:163], v[192:195], v[100:103]
	s_setprio 0
	s_setprio 1
	v_mfma_f32_16x16x32_bf16 v[68:71], v[132:135], v[164:167], v[68:71]
	v_mfma_f32_16x16x32_bf16 v[60:63], v[140:143], v[164:167], v[60:63]
	v_mfma_f32_16x16x32_bf16 v[56:59], v[132:135], v[172:175], v[56:59]
	v_mfma_f32_16x16x32_bf16 v[52:55], v[140:143], v[172:175], v[52:55]
	v_mfma_f32_16x16x32_bf16 v[48:51], v[132:135], v[180:183], v[48:51]
	v_mfma_f32_16x16x32_bf16 v[44:47], v[140:143], v[180:183], v[44:47]
	v_mfma_f32_16x16x32_bf16 v[40:43], v[132:135], v[188:191], v[40:43]
	v_mfma_f32_16x16x32_bf16 v[36:39], v[140:143], v[188:191], v[36:39]
	v_mfma_f32_16x16x32_bf16 v[68:71], v[136:139], v[168:171], v[68:71]
	v_mfma_f32_16x16x32_bf16 v[60:63], v[144:147], v[168:171], v[60:63]
	v_mfma_f32_16x16x32_bf16 v[56:59], v[136:139], v[176:179], v[56:59]
	v_mfma_f32_16x16x32_bf16 v[52:55], v[144:147], v[176:179], v[52:55]
	v_mfma_f32_16x16x32_bf16 v[48:51], v[136:139], v[184:187], v[48:51]
	v_mfma_f32_16x16x32_bf16 v[44:47], v[144:147], v[184:187], v[44:47]
	v_mfma_f32_16x16x32_bf16 v[40:43], v[136:139], v[192:195], v[40:43]
	v_mfma_f32_16x16x32_bf16 v[36:39], v[144:147], v[192:195], v[36:39]
	s_setprio 0
	s_barrier
	s_add_i32 s0, s15, s31
	v_lshl_add_u64 v[2:3], s[10:11], 0, v[198:199]
	s_mov_b32 m0, s0
	ds_read_b128 v[188:191], v223 offset:16384
	ds_read_b128 v[192:195], v223 offset:17408
	ds_read_b128 v[180:183], v223 offset:18432
	ds_read_b128 v[184:187], v223 offset:19456
	ds_read_b128 v[172:175], v223 offset:20480
	ds_read_b128 v[176:179], v223 offset:21504
	ds_read_b128 v[164:167], v223 offset:22528
	ds_read_b128 v[168:171], v223 offset:23552
	global_load_lds_dwordx4 v[2:3], off
	s_add_i32 m0, s0, 0x2000
	s_add_u32 s0, s10, 0x40000
	v_lshl_add_u64 v[210:211], s[10:11], 0, v[202:203]
	s_addc_u32 s1, s11, 0
	s_add_i32 vcc_lo, s4, s31
	global_load_lds_dwordx4 v[210:211], off
	v_lshl_add_u64 v[212:213], s[0:1], 0, v[198:199]
	s_mov_b32 m0, vcc_lo
	v_lshl_add_u64 v[214:215], s[86:87], 0, v[200:201]
	global_load_lds_dwordx4 v[212:213], off
	v_lshl_add_u64 v[212:213], s[0:1], 0, v[202:203]
	s_add_i32 m0, vcc_lo, 0x2000
	v_cmp_ne_u32_e64 s[0:1], 1, v226
	global_load_lds_dwordx4 v[212:213], off
	v_lshl_add_u64 v[212:213], s[86:87], 0, v[196:197]
	s_mov_b32 m0, s33
	s_andn2_b64 vcc, exec, s[84:85]
	global_load_lds_dwordx4 v[212:213], off
	s_mov_b32 m0, s35
	s_nop 0
	global_load_lds_dwordx4 v[214:215], off
	s_waitcnt vmcnt(8)
	s_waitcnt lgkmcnt(0)
	s_barrier
	s_cbranch_vccnz .LBB0_1003
; #define PG8_MMA(ai, bj, At, Bt) do { __builtin_amdgcn_s_setprio(1); _Pragma("unroll") for (int m = 0; m < 4; ++m) _Pragma("unroll") for (int n = 0; n < 2; ++n) _Pragma("unroll") for (int k = 0; k < 2; ++k) \
;         acc[ai][bj][m][n] = __builtin_amdgcn_mfma_f32_16x16x32_bf16(Bt[n][k], At[m][k], acc[ai][bj][m][n], 0, 0, 0); __builtin_amdgcn_s_setprio(0); } while (0)
; #define PG8_WAIT_V(n) asm volatile("s_waitcnt vmcnt(" #n ")" ::: "memory")
; #define PG8_WAIT_L(n) asm volatile("s_waitcnt lgkmcnt(" #n ")" ::: "memory")
; #define PG8_BAR __builtin_amdgcn_s_barrier()
; #define PG8_SCHED __builtin_amdgcn_sched_barrier(0)
; template <class Epi, class Sched, bool ALIGN_EPI = false, bool SP2 = false>
; __device__ __forceinline__ void gemm_phase(PG8_LAS unsigned char* lds, const Gemm g, const Sched& S, const Epi& E, int wave0) {
;     ...
;             PG8_WAIT_V(8); PG8_WAIT_L(0); PG8_BAR; if (!cur.half) { PG8_MMA(1, 0, At, B0); PG8_MMA(1, 1, At, B1); } PG8_BAR; PG8_SCHED;
	s_setprio 1
	s_waitcnt lgkmcnt(0)
	v_mfma_f32_16x16x32_bf16 v[96:99], v[148:151], v[188:191], v[96:99]
	v_mfma_f32_16x16x32_bf16 v[92:95], v[156:159], v[188:191], v[92:95]
	v_mfma_f32_16x16x32_bf16 v[88:91], v[148:151], v[180:183], v[88:91]
	v_mfma_f32_16x16x32_bf16 v[84:87], v[156:159], v[180:183], v[84:87]
	v_mfma_f32_16x16x32_bf16 v[80:83], v[148:151], v[172:175], v[80:83]
	v_mfma_f32_16x16x32_bf16 v[76:79], v[156:159], v[172:175], v[76:79]
	v_mfma_f32_16x16x32_bf16 v[72:75], v[148:151], v[164:167], v[72:75]
	v_mfma_f32_16x16x32_bf16 v[64:67], v[156:159], v[164:167], v[64:67]
	v_mfma_f32_16x16x32_bf16 v[96:99], v[152:155], v[192:195], v[96:99]
	v_mfma_f32_16x16x32_bf16 v[92:95], v[160:163], v[192:195], v[92:95]
	v_mfma_f32_16x16x32_bf16 v[88:91], v[152:155], v[184:187], v[88:91]
	v_mfma_f32_16x16x32_bf16 v[84:87], v[160:163], v[184:187], v[84:87]
	v_mfma_f32_16x16x32_bf16 v[80:83], v[152:155], v[176:179], v[80:83]
	v_mfma_f32_16x16x32_bf16 v[76:79], v[160:163], v[176:179], v[76:79]
	v_mfma_f32_16x16x32_bf16 v[72:75], v[152:155], v[168:171], v[72:75]
	v_mfma_f32_16x16x32_bf16 v[64:67], v[160:163], v[168:171], v[64:67]
	s_setprio 0
	s_setprio 1
	v_mfma_f32_16x16x32_bf16 v[32:35], v[132:135], v[188:191], v[32:35]
	v_mfma_f32_16x16x32_bf16 v[28:31], v[140:143], v[188:191], v[28:31]
	v_mfma_f32_16x16x32_bf16 v[24:27], v[132:135], v[180:183], v[24:27]
	v_mfma_f32_16x16x32_bf16 v[20:23], v[140:143], v[180:183], v[20:23]
	v_mfma_f32_16x16x32_bf16 v[16:19], v[132:135], v[172:175], v[16:19]
	v_mfma_f32_16x16x32_bf16 v[12:15], v[140:143], v[172:175], v[12:15]
	v_mfma_f32_16x16x32_bf16 v[8:11], v[132:135], v[164:167], v[8:11]
	v_mfma_f32_16x16x32_bf16 v[4:7], v[140:143], v[164:167], v[4:7]
	v_mfma_f32_16x16x32_bf16 v[32:35], v[136:139], v[192:195], v[32:35]
	v_mfma_f32_16x16x32_bf16 v[28:31], v[144:147], v[192:195], v[28:31]
	v_mfma_f32_16x16x32_bf16 v[24:27], v[136:139], v[184:187], v[24:27]
	v_mfma_f32_16x16x32_bf16 v[20:23], v[144:147], v[184:187], v[20:23]
	v_mfma_f32_16x16x32_bf16 v[16:19], v[136:139], v[176:179], v[16:19]
	v_mfma_f32_16x16x32_bf16 v[12:15], v[144:147], v[176:179], v[12:15]
	v_mfma_f32_16x16x32_bf16 v[8:11], v[136:139], v[168:171], v[8:11]
	v_mfma_f32_16x16x32_bf16 v[4:7], v[144:147], v[168:171], v[4:7]
	s_setprio 0
; #define PG8_STAGE(bufoff, gbase, voff) do { _Pragma("unroll") for (int _i = 0; _i < 2; ++_i) \
;         __builtin_amdgcn_global_load_lds((const unsigned*)((const char*)(gbase) + (voff)[_i]), (PG8_LAS unsigned*)(lds + (bufoff) + ldsw + _i * 8192), 16, 0, 0); } while (0)
; #define PG8_LDA(dst, b, h) do { _Pragma("unroll") for (int m = 0; m < 4; ++m) _Pragma("unroll") for (int k = 0; k < 2; ++k) dst[m][k] = *(const PG8_LAS bf16x8*)(lds + PG8_SA(b, h) + aoff + m * 2048 + k * 1024); } while (0)
; #define PG8_WAIT_V(n) asm volatile("s_waitcnt vmcnt(" #n ")" ::: "memory")
; #define PG8_WAIT_L(n) asm volatile("s_waitcnt lgkmcnt(" #n ")" ::: "memory")
; template <class Epi, class Sched, bool ALIGN_EPI = false, bool SP2 = false>
; __device__ __forceinline__ void gemm_phase(PG8_LAS unsigned char* lds, const Gemm g, const Sched& S, const Epi& E, int wave0) {
;     ...
;         for (int t = 0; t < nt; t += 2) {
;             const bool last = (t == nt - 2);
;             const char* a1 = cA + (size_t)(t + 1) * kstep;
;             const char* a2 = last ? nA : cA + (size_t)(t + 2) * kstep; const char* b2 = last ? nB : cB + (size_t)(t + 2) * kstep;
;             const char* a3 = a2 + kstep; const char* b3 = b2 + kstep;
;             if (last && has_next) S.a_ready(nxt);
;             if constexpr (SP2) {
;             PG8_LDB(B0, 0, 0); PG8_LDB(B1, 0, 1); PG8_SCHED; PG8_LDA(At, 0, 0); PG8_STAGE(PG8_SA(1, 1), a1 + hstep, voffA);
;             PG8_WAIT_V(8); PG8_WAIT_L(0); PG8_BAR; PG8_MMA(0, 0, At, B0); PG8_MMA(0, 1, At, B1); PG8_BAR; PG8_SCHED;
;             PG8_LDA(At, 0, 1); PG8_STAGE(PG8_SB(0, 0), b2, voffB); PG8_STAGE(PG8_SB(0, 1), b2 + hstep, voffB); PG8_STAGE(PG8_SA(0, 0), a2, voffA);
;             PG8_WAIT_V(8); PG8_WAIT_L(0); PG8_BAR; if (!cur.half) { PG8_MMA(1, 0, At, B0); PG8_MMA(1, 1, At, B1); } PG8_BAR; PG8_SCHED;
;             PG8_LDB(B0, 1, 0); PG8_LDB(B1, 1, 1); PG8_SCHED; PG8_LDA(At, 1, 0); PG8_STAGE(PG8_SA(0, 1), a2 + hstep, voffA);
;             PG8_WAIT_V(8); PG8_WAIT_L(0); PG8_BAR; PG8_MMA(0, 0, At, B0); PG8_MMA(0, 1, At, B1); PG8_BAR; PG8_SCHED;
;             PG8_LDA(At, 1, 1); PG8_STAGE(PG8_SB(1, 0), b3, voffB); PG8_STAGE(PG8_SB(1, 1), b3 + hstep, voffB); PG8_STAGE(PG8_SA(1, 0), a3, voffA);
;             PG8_WAIT_V(8); PG8_WAIT_L(0); PG8_BAR; if (!cur.half) { PG8_MMA(1, 0, At, B0); PG8_MMA(1, 1, At, B1); } PG8_BAR; PG8_SCHED;
.LBB0_1003:
	s_barrier
	s_add_i32 vcc_lo, 0, 0x18000
	v_add_u32_e32 v1, vcc_lo, v220
	s_add_i32 vcc_hi, 0, 0x1c000
	ds_read_b128 v[148:151], v1
	ds_read_b128 v[152:155], v1 offset:1024
	ds_read_b128 v[156:159], v1 offset:2048
	ds_read_b128 v[160:163], v1 offset:3072
	v_add_u32_e32 v1, vcc_hi, v220
	ds_read_b128 v[132:135], v1
	ds_read_b128 v[136:139], v1 offset:1024
	ds_read_b128 v[140:143], v1 offset:2048
	ds_read_b128 v[144:147], v1 offset:3072
	s_add_u32 s86, s86, 0x40000
	s_addc_u32 s87, s87, 0
	s_mov_b32 m0, s37
	v_lshl_add_u64 v[228:229], s[86:87], 0, v[196:197]
	s_waitcnt lgkmcnt(0)
	ds_read_b128 v[164:167], v223 offset:32768
	ds_read_b128 v[168:171], v223 offset:33792
	ds_read_b128 v[172:175], v223 offset:34816
	ds_read_b128 v[176:179], v223 offset:35840
	ds_read_b128 v[180:183], v223 offset:36864
	ds_read_b128 v[184:187], v223 offset:37888
	ds_read_b128 v[188:191], v223 offset:38912
	ds_read_b128 v[192:195], v223 offset:39936
	global_load_lds_dwordx4 v[228:229], off
	v_lshl_add_u64 v[228:229], s[86:87], 0, v[200:201]
	s_mov_b32 m0, s39
	s_nop 0
	global_load_lds_dwordx4 v[228:229], off
	s_waitcnt lgkmcnt(0)
	s_setprio 1
	s_waitcnt lgkmcnt(0)
	v_mfma_f32_16x16x32_bf16 v[128:131], v[148:151], v[164:167], v[128:131]
	v_mfma_f32_16x16x32_bf16 v[124:127], v[156:159], v[164:167], v[124:127]
	v_mfma_f32_16x16x32_bf16 v[120:123], v[148:151], v[172:175], v[120:123]
	v_mfma_f32_16x16x32_bf16 v[116:119], v[156:159], v[172:175], v[116:119]
	v_mfma_f32_16x16x32_bf16 v[112:115], v[148:151], v[180:183], v[112:115]
	v_mfma_f32_16x16x32_bf16 v[108:111], v[156:159], v[180:183], v[108:111]
	v_mfma_f32_16x16x32_bf16 v[104:107], v[148:151], v[188:191], v[104:107]
	v_mfma_f32_16x16x32_bf16 v[100:103], v[156:159], v[188:191], v[100:103]
	s_waitcnt vmcnt(8)
	s_barrier
	v_mfma_f32_16x16x32_bf16 v[128:131], v[152:155], v[168:171], v[128:131]
	v_mfma_f32_16x16x32_bf16 v[124:127], v[160:163], v[168:171], v[124:127]
	v_mfma_f32_16x16x32_bf16 v[120:123], v[152:155], v[176:179], v[120:123]
	v_mfma_f32_16x16x32_bf16 v[116:119], v[160:163], v[176:179], v[116:119]
	v_mfma_f32_16x16x32_bf16 v[112:115], v[152:155], v[184:187], v[112:115]
	v_mfma_f32_16x16x32_bf16 v[108:111], v[160:163], v[184:187], v[108:111]
	v_mfma_f32_16x16x32_bf16 v[104:107], v[152:155], v[192:195], v[104:107]
	v_mfma_f32_16x16x32_bf16 v[100:103], v[160:163], v[192:195], v[100:103]
	s_setprio 0
	s_setprio 1
	v_mfma_f32_16x16x32_bf16 v[68:71], v[132:135], v[164:167], v[68:71]
	v_mfma_f32_16x16x32_bf16 v[60:63], v[140:143], v[164:167], v[60:63]
	v_mfma_f32_16x16x32_bf16 v[56:59], v[132:135], v[172:175], v[56:59]
	v_mfma_f32_16x16x32_bf16 v[52:55], v[140:143], v[172:175], v[52:55]
	v_mfma_f32_16x16x32_bf16 v[48:51], v[132:135], v[180:183], v[48:51]
	v_mfma_f32_16x16x32_bf16 v[44:47], v[140:143], v[180:183], v[44:47]
	v_mfma_f32_16x16x32_bf16 v[40:43], v[132:135], v[188:191], v[40:43]
	v_mfma_f32_16x16x32_bf16 v[36:39], v[140:143], v[188:191], v[36:39]
	v_mfma_f32_16x16x32_bf16 v[68:71], v[136:139], v[168:171], v[68:71]
	v_mfma_f32_16x16x32_bf16 v[60:63], v[144:147], v[168:171], v[60:63]
	v_mfma_f32_16x16x32_bf16 v[56:59], v[136:139], v[176:179], v[56:59]
	v_mfma_f32_16x16x32_bf16 v[52:55], v[144:147], v[176:179], v[52:55]
	v_mfma_f32_16x16x32_bf16 v[48:51], v[136:139], v[184:187], v[48:51]
	v_mfma_f32_16x16x32_bf16 v[44:47], v[144:147], v[184:187], v[44:47]
	v_mfma_f32_16x16x32_bf16 v[40:43], v[136:139], v[192:195], v[40:43]
	v_mfma_f32_16x16x32_bf16 v[36:39], v[144:147], v[192:195], v[36:39]
	s_setprio 0
	s_barrier
	s_add_i32 s86, vcc_lo, s31
	v_lshl_add_u64 v[2:3], v[2:3], 0, s[20:21]
	s_mov_b32 m0, s86
	ds_read_b128 v[188:191], v223 offset:49152
	ds_read_b128 v[192:195], v223 offset:50176
	ds_read_b128 v[180:183], v223 offset:51200
	ds_read_b128 v[184:187], v223 offset:52224
	ds_read_b128 v[172:175], v223 offset:53248
	ds_read_b128 v[176:179], v223 offset:54272
	ds_read_b128 v[164:167], v223 offset:55296
	ds_read_b128 v[168:171], v223 offset:56320
	global_load_lds_dwordx4 v[2:3], off
	s_add_i32 m0, s86, 0x2000
	s_add_u32 s10, s10, 0x40080
	v_lshl_add_u64 v[2:3], v[210:211], 0, s[20:21]
	s_addc_u32 s11, s11, 0
	s_add_i32 s86, vcc_hi, s31
	global_load_lds_dwordx4 v[2:3], off
	v_lshl_add_u64 v[2:3], s[10:11], 0, v[198:199]
	s_mov_b32 m0, s86
	s_and_b64 vcc, exec, s[0:1]
	global_load_lds_dwordx4 v[2:3], off
	v_lshl_add_u64 v[2:3], s[10:11], 0, v[202:203]
	s_add_i32 m0, s86, 0x2000
	s_nop 0
	global_load_lds_dwordx4 v[2:3], off
	v_lshl_add_u64 v[2:3], v[212:213], 0, s[20:21]
	s_mov_b32 m0, s71
	s_nop 0
	global_load_lds_dwordx4 v[2:3], off
	v_lshl_add_u64 v[2:3], v[214:215], 0, s[20:21]
	s_mov_b32 m0, s14
	s_nop 0
	global_load_lds_dwordx4 v[2:3], off
	s_waitcnt vmcnt(8)
	s_waitcnt lgkmcnt(0)
	s_barrier
	s_cbranch_vccnz .LBB0_1000
	s_setprio 1
	s_waitcnt lgkmcnt(0)
	v_mfma_f32_16x16x32_bf16 v[96:99], v[148:151], v[188:191], v[96:99]
	v_mfma_f32_16x16x32_bf16 v[92:95], v[156:159], v[188:191], v[92:95]
	v_mfma_f32_16x16x32_bf16 v[88:91], v[148:151], v[180:183], v[88:91]
	v_mfma_f32_16x16x32_bf16 v[84:87], v[156:159], v[180:183], v[84:87]
	v_mfma_f32_16x16x32_bf16 v[80:83], v[148:151], v[172:175], v[80:83]
	v_mfma_f32_16x16x32_bf16 v[76:79], v[156:159], v[172:175], v[76:79]
	v_mfma_f32_16x16x32_bf16 v[72:75], v[148:151], v[164:167], v[72:75]
	v_mfma_f32_16x16x32_bf16 v[64:67], v[156:159], v[164:167], v[64:67]
	v_mfma_f32_16x16x32_bf16 v[96:99], v[152:155], v[192:195], v[96:99]
	v_mfma_f32_16x16x32_bf16 v[92:95], v[160:163], v[192:195], v[92:95]
	v_mfma_f32_16x16x32_bf16 v[88:91], v[152:155], v[184:187], v[88:91]
	v_mfma_f32_16x16x32_bf16 v[84:87], v[160:163], v[184:187], v[84:87]
	v_mfma_f32_16x16x32_bf16 v[80:83], v[152:155], v[176:179], v[80:83]
	v_mfma_f32_16x16x32_bf16 v[76:79], v[160:163], v[176:179], v[76:79]
	v_mfma_f32_16x16x32_bf16 v[72:75], v[152:155], v[168:171], v[72:75]
	v_mfma_f32_16x16x32_bf16 v[64:67], v[160:163], v[168:171], v[64:67]
	s_setprio 0
	s_setprio 1
	v_mfma_f32_16x16x32_bf16 v[32:35], v[132:135], v[188:191], v[32:35]
	v_mfma_f32_16x16x32_bf16 v[28:31], v[140:143], v[188:191], v[28:31]
	v_mfma_f32_16x16x32_bf16 v[24:27], v[132:135], v[180:183], v[24:27]
	v_mfma_f32_16x16x32_bf16 v[20:23], v[140:143], v[180:183], v[20:23]
	v_mfma_f32_16x16x32_bf16 v[16:19], v[132:135], v[172:175], v[16:19]
	v_mfma_f32_16x16x32_bf16 v[12:15], v[140:143], v[172:175], v[12:15]
	v_mfma_f32_16x16x32_bf16 v[8:11], v[132:135], v[164:167], v[8:11]
	v_mfma_f32_16x16x32_bf16 v[2:5], v[140:143], v[164:167], v[4:7]
	v_mfma_f32_16x16x32_bf16 v[32:35], v[136:139], v[192:195], v[32:35]
	v_mfma_f32_16x16x32_bf16 v[28:31], v[144:147], v[192:195], v[28:31]
	v_mfma_f32_16x16x32_bf16 v[24:27], v[136:139], v[184:187], v[24:27]
	v_mfma_f32_16x16x32_bf16 v[20:23], v[144:147], v[184:187], v[20:23]
	v_mfma_f32_16x16x32_bf16 v[16:19], v[136:139], v[176:179], v[16:19]
	v_mfma_f32_16x16x32_bf16 v[12:15], v[144:147], v[176:179], v[12:15]
	v_mfma_f32_16x16x32_bf16 v[8:11], v[136:139], v[168:171], v[8:11]
	v_mfma_f32_16x16x32_bf16 v[4:7], v[144:147], v[168:171], v[2:5]
	s_setprio 0
	s_branch .LBB0_1000

; #define PG8_STAGE(bufoff, gbase, voff) do { _Pragma("unroll") for (int _i = 0; _i < 2; ++_i) \
;         __builtin_amdgcn_global_load_lds((const unsigned*)((const char*)(gbase) + (voff)[_i]), (PG8_LAS unsigned*)(lds + (bufoff) + ldsw + _i * 8192), 16, 0, 0); } while (0)
; #define PG8_LDA(dst, b, h) do { _Pragma("unroll") for (int m = 0; m < 4; ++m) _Pragma("unroll") for (int k = 0; k < 2; ++k) dst[m][k] = *(const PG8_LAS bf16x8*)(lds + PG8_SA(b, h) + aoff + m * 2048 + k * 1024); } while (0)
; #define PG8_WAIT_V(n) asm volatile("s_waitcnt vmcnt(" #n ")" ::: "memory")
; #define PG8_WAIT_L(n) asm volatile("s_waitcnt lgkmcnt(" #n ")" ::: "memory")
; template <class Epi, class Sched, bool ALIGN_EPI = false, bool SP2 = false>
; __device__ __forceinline__ void gemm_phase(PG8_LAS unsigned char* lds, const Gemm g, const Sched& S, const Epi& E, int wave0) {
;     ...
;         for (int t = 0; t < nt; t += 2) {
;             const bool last = (t == nt - 2);
;             const char* a1 = cA + (size_t)(t + 1) * kstep;
;             const char* a2 = last ? nA : cA + (size_t)(t + 2) * kstep; const char* b2 = last ? nB : cB + (size_t)(t + 2) * kstep;
;             const char* a3 = a2 + kstep; const char* b3 = b2 + kstep;
;             if (last && has_next) S.a_ready(nxt);
;             if constexpr (SP2) {
;             PG8_LDB(B0, 0, 0); PG8_LDB(B1, 0, 1); PG8_SCHED; PG8_LDA(At, 0, 0); PG8_STAGE(PG8_SA(1, 1), a1 + hstep, voffA);
;             PG8_WAIT_V(8); PG8_WAIT_L(0); PG8_BAR; PG8_MMA(0, 0, At, B0); PG8_MMA(0, 1, At, B1); PG8_BAR; PG8_SCHED;
;             PG8_LDA(At, 0, 1); PG8_STAGE(PG8_SB(0, 0), b2, voffB); PG8_STAGE(PG8_SB(0, 1), b2 + hstep, voffB); PG8_STAGE(PG8_SA(0, 0), a2, voffA);
;             PG8_WAIT_V(8); PG8_WAIT_L(0); PG8_BAR; if (!cur.half) { PG8_MMA(1, 0, At, B0); PG8_MMA(1, 1, At, B1); } PG8_BAR; PG8_SCHED;
;             PG8_LDB(B0, 1, 0); PG8_LDB(B1, 1, 1); PG8_SCHED; PG8_LDA(At, 1, 0); PG8_STAGE(PG8_SA(0, 1), a2 + hstep, voffA);
;             PG8_WAIT_V(8); PG8_WAIT_L(0); PG8_BAR; PG8_MMA(0, 0, At, B0); PG8_MMA(0, 1, At, B1); PG8_BAR; PG8_SCHED;
;             PG8_LDA(At, 1, 1); PG8_STAGE(PG8_SB(1, 0), b3, voffB); PG8_STAGE(PG8_SB(1, 1), b3 + hstep, voffB); PG8_STAGE(PG8_SA(1, 0), a3, voffA);
;             PG8_WAIT_V(8); PG8_WAIT_L(0); PG8_BAR; if (!cur.half) { PG8_MMA(1, 0, At, B0); PG8_MMA(1, 1, At, B1); } PG8_BAR; PG8_SCHED;
.LBB0_1101:
	ds_read_b128 v[128:131], v165
	ds_read_b128 v[132:135], v165 offset:1024
	ds_read_b128 v[152:155], v165 offset:2048
	ds_read_b128 v[156:159], v165 offset:3072
	ds_read_b128 v[170:173], v166
	ds_read_b128 v[174:177], v166 offset:1024
	ds_read_b128 v[178:181], v166 offset:2048
	ds_read_b128 v[182:185], v166 offset:3072
	s_add_u32 s0, s2, 0x100
	s_addc_u32 s1, s3, 0
	s_cmp_eq_u32 s50, 40
	s_cselect_b32 s35, s21, s1
	s_cselect_b32 s34, s20, s0
	s_cselect_b32 s31, s29, s49
	s_cselect_b32 s30, s28, s48
	v_lshl_add_u64 v[160:161], s[2:3], 0, v[144:145]
	s_add_i32 m0, s5, 0xc000
	ds_read_b128 v[186:189], v167
	ds_read_b128 v[190:193], v167 offset:1024
	ds_read_b128 v[194:197], v167 offset:2048
	ds_read_b128 v[198:201], v167 offset:3072
	ds_read_b128 v[202:205], v167 offset:4096
	ds_read_b128 v[206:209], v167 offset:5120
	ds_read_b128 v[210:213], v167 offset:6144
	ds_read_b128 v[218:221], v167 offset:7168
	global_load_lds_dwordx4 v[160:161], off
	v_lshl_add_u64 v[160:161], s[2:3], 0, v[146:147]
	s_add_i32 m0, s5, 0xe000
	s_nop 0
	global_load_lds_dwordx4 v[160:161], off
	s_waitcnt lgkmcnt(0)
	s_setprio 1
	s_waitcnt lgkmcnt(0)
	v_mfma_f32_16x16x32_bf16 v[124:127], v[128:131], v[186:189], v[124:127]
	v_mfma_f32_16x16x32_bf16 v[120:123], v[152:155], v[186:189], v[120:123]
	v_mfma_f32_16x16x32_bf16 v[108:111], v[128:131], v[194:197], v[108:111]
	v_mfma_f32_16x16x32_bf16 v[104:107], v[152:155], v[194:197], v[104:107]
	v_mfma_f32_16x16x32_bf16 v[92:95], v[128:131], v[202:205], v[92:95]
	v_mfma_f32_16x16x32_bf16 v[88:91], v[152:155], v[202:205], v[88:91]
	v_mfma_f32_16x16x32_bf16 v[76:79], v[128:131], v[210:213], v[76:79]
	v_mfma_f32_16x16x32_bf16 v[72:75], v[152:155], v[210:213], v[72:75]
	s_waitcnt vmcnt(8)
	s_barrier
	v_mfma_f32_16x16x32_bf16 v[124:127], v[132:135], v[190:193], v[124:127]
	v_mfma_f32_16x16x32_bf16 v[120:123], v[156:159], v[190:193], v[120:123]
	v_mfma_f32_16x16x32_bf16 v[108:111], v[132:135], v[198:201], v[108:111]
	v_mfma_f32_16x16x32_bf16 v[104:107], v[156:159], v[198:201], v[104:107]
	v_mfma_f32_16x16x32_bf16 v[92:95], v[132:135], v[206:209], v[92:95]
	v_mfma_f32_16x16x32_bf16 v[88:91], v[156:159], v[206:209], v[88:91]
	v_mfma_f32_16x16x32_bf16 v[76:79], v[132:135], v[218:221], v[76:79]
	v_mfma_f32_16x16x32_bf16 v[72:75], v[156:159], v[218:221], v[72:75]
	s_setprio 0
	s_setprio 1
	v_mfma_f32_16x16x32_bf16 v[116:119], v[170:173], v[186:189], v[116:119]
	v_mfma_f32_16x16x32_bf16 v[112:115], v[178:181], v[186:189], v[112:115]
	v_mfma_f32_16x16x32_bf16 v[100:103], v[170:173], v[194:197], v[100:103]
	v_mfma_f32_16x16x32_bf16 v[96:99], v[178:181], v[194:197], v[96:99]
	v_mfma_f32_16x16x32_bf16 v[84:87], v[170:173], v[202:205], v[84:87]
	v_mfma_f32_16x16x32_bf16 v[80:83], v[178:181], v[202:205], v[80:83]
	v_mfma_f32_16x16x32_bf16 v[68:71], v[170:173], v[210:213], v[68:71]
	v_mfma_f32_16x16x32_bf16 v[64:67], v[178:181], v[210:213], v[64:67]
	v_mfma_f32_16x16x32_bf16 v[116:119], v[174:177], v[190:193], v[116:119]
	v_mfma_f32_16x16x32_bf16 v[112:115], v[182:185], v[190:193], v[112:115]
	v_mfma_f32_16x16x32_bf16 v[100:103], v[174:177], v[198:201], v[100:103]
	v_mfma_f32_16x16x32_bf16 v[96:99], v[182:185], v[198:201], v[96:99]
	v_mfma_f32_16x16x32_bf16 v[84:87], v[174:177], v[206:209], v[84:87]
	v_mfma_f32_16x16x32_bf16 v[80:83], v[182:185], v[206:209], v[80:83]
	v_mfma_f32_16x16x32_bf16 v[68:71], v[174:177], v[218:221], v[68:71]
	v_mfma_f32_16x16x32_bf16 v[64:67], v[182:185], v[218:221], v[64:67]
	s_setprio 0
	s_barrier
	s_add_i32 s2, s41, s4
	v_lshl_add_u64 v[160:161], s[30:31], 0, v[138:139]
	s_mov_b32 m0, s2
	ds_read_b128 v[186:189], v167 offset:16384
	ds_read_b128 v[190:193], v167 offset:17408
	ds_read_b128 v[194:197], v167 offset:18432
	ds_read_b128 v[198:201], v167 offset:19456
	ds_read_b128 v[202:205], v167 offset:20480
	ds_read_b128 v[206:209], v167 offset:21504
	ds_read_b128 v[210:213], v167 offset:22528
	ds_read_b128 v[218:221], v167 offset:23552
	global_load_lds_dwordx4 v[160:161], off
	s_add_i32 m0, s2, 0x2000
	s_add_u32 s2, s30, 0xb0000
	v_lshl_add_u64 v[214:215], s[30:31], 0, v[142:143]
	s_addc_u32 s3, s31, 0
	s_add_i32 s51, s42, s4
	global_load_lds_dwordx4 v[214:215], off
	v_lshl_add_u64 v[222:223], s[2:3], 0, v[138:139]
	s_mov_b32 m0, s51
	v_lshl_add_u64 v[224:225], s[34:35], 0, v[140:141]
	global_load_lds_dwordx4 v[222:223], off
	v_lshl_add_u64 v[222:223], s[2:3], 0, v[142:143]
	s_add_i32 m0, s51, 0x2000
	s_nop 0
	global_load_lds_dwordx4 v[222:223], off
	v_lshl_add_u64 v[222:223], s[34:35], 0, v[136:137]
	s_mov_b32 m0, s5
	s_nop 0
	global_load_lds_dwordx4 v[222:223], off
	s_mov_b32 m0, s6
	s_nop 0
	global_load_lds_dwordx4 v[224:225], off
	s_waitcnt lgkmcnt(0)
	s_setprio 1
	s_waitcnt lgkmcnt(0)
	v_mfma_f32_16x16x32_bf16 v[60:63], v[128:131], v[186:189], v[60:63]
	v_mfma_f32_16x16x32_bf16 v[56:59], v[152:155], v[186:189], v[56:59]
	v_mfma_f32_16x16x32_bf16 v[44:47], v[128:131], v[194:197], v[44:47]
	v_mfma_f32_16x16x32_bf16 v[40:43], v[152:155], v[194:197], v[40:43]
	v_mfma_f32_16x16x32_bf16 v[28:31], v[128:131], v[202:205], v[28:31]
	v_mfma_f32_16x16x32_bf16 v[24:27], v[152:155], v[202:205], v[24:27]
	v_mfma_f32_16x16x32_bf16 v[12:15], v[128:131], v[210:213], v[12:15]
	v_mfma_f32_16x16x32_bf16 v[8:11], v[152:155], v[210:213], v[8:11]
	s_waitcnt vmcnt(8)
	s_barrier
; #define PG8_STAGE(bufoff, gbase, voff) do { _Pragma("unroll") for (int _i = 0; _i < 2; ++_i) \
;         __builtin_amdgcn_global_load_lds((const unsigned*)((const char*)(gbase) + (voff)[_i]), (PG8_LAS unsigned*)(lds + (bufoff) + ldsw + _i * 8192), 16, 0, 0); } while (0)
; #define PG8_LDA(dst, b, h) do { _Pragma("unroll") for (int m = 0; m < 4; ++m) _Pragma("unroll") for (int k = 0; k < 2; ++k) dst[m][k] = *(const PG8_LAS bf16x8*)(lds + PG8_SA(b, h) + aoff + m * 2048 + k * 1024); } while (0)
; #define PG8_LDB(dst, b, h) do { _Pragma("unroll") for (int n = 0; n < 2; ++n) _Pragma("unroll") for (int k = 0; k < 2; ++k) dst[n][k] = *(const PG8_LAS bf16x8*)(lds + PG8_SB(b, h) + boff + n * 2048 + k * 1024); } while (0)
; #define PG8_MMA(ai, bj, At, Bt) do { __builtin_amdgcn_s_setprio(1); _Pragma("unroll") for (int m = 0; m < 4; ++m) _Pragma("unroll") for (int n = 0; n < 2; ++n) _Pragma("unroll") for (int k = 0; k < 2; ++k) \
;         acc[ai][bj][m][n] = __builtin_amdgcn_mfma_f32_16x16x32_bf16(Bt[n][k], At[m][k], acc[ai][bj][m][n], 0, 0, 0); __builtin_amdgcn_s_setprio(0); } while (0)
; #define PG8_WAIT_V(n) asm volatile("s_waitcnt vmcnt(" #n ")" ::: "memory")
; #define PG8_WAIT_L(n) asm volatile("s_waitcnt lgkmcnt(" #n ")" ::: "memory")
; #define PG8_BAR __builtin_amdgcn_s_barrier()
; #define PG8_SCHED __builtin_amdgcn_sched_barrier(0)
; template <class Epi, class Sched, bool ALIGN_EPI = false, bool SP2 = false>
; __device__ __forceinline__ void gemm_phase(PG8_LAS unsigned char* lds, const Gemm g, const Sched& S, const Epi& E, int wave0) {
;     ...
;             PG8_LDB(B0, 1, 0); PG8_LDB(B1, 1, 1); PG8_SCHED; PG8_LDA(At, 1, 0); PG8_STAGE(PG8_SA(0, 1), a2 + hstep, voffA);
;             PG8_WAIT_V(8); PG8_WAIT_L(0); PG8_BAR; PG8_MMA(0, 0, At, B0); PG8_MMA(0, 1, At, B1); PG8_BAR; PG8_SCHED;
;             PG8_LDA(At, 1, 1); PG8_STAGE(PG8_SB(1, 0), b3, voffB); PG8_STAGE(PG8_SB(1, 1), b3 + hstep, voffB); PG8_STAGE(PG8_SA(1, 0), a3, voffA);
	v_mfma_f32_16x16x32_bf16 v[60:63], v[132:135], v[190:193], v[60:63]
	v_mfma_f32_16x16x32_bf16 v[56:59], v[156:159], v[190:193], v[56:59]
	v_mfma_f32_16x16x32_bf16 v[44:47], v[132:135], v[198:201], v[44:47]
	v_mfma_f32_16x16x32_bf16 v[40:43], v[156:159], v[198:201], v[40:43]
	v_mfma_f32_16x16x32_bf16 v[28:31], v[132:135], v[206:209], v[28:31]
	v_mfma_f32_16x16x32_bf16 v[24:27], v[156:159], v[206:209], v[24:27]
	v_mfma_f32_16x16x32_bf16 v[12:15], v[132:135], v[218:221], v[12:15]
	v_mfma_f32_16x16x32_bf16 v[8:11], v[156:159], v[218:221], v[8:11]
	s_setprio 0
	s_setprio 1
	v_mfma_f32_16x16x32_bf16 v[52:55], v[170:173], v[186:189], v[52:55]
	v_mfma_f32_16x16x32_bf16 v[48:51], v[178:181], v[186:189], v[48:51]
	v_mfma_f32_16x16x32_bf16 v[36:39], v[170:173], v[194:197], v[36:39]
	v_mfma_f32_16x16x32_bf16 v[32:35], v[178:181], v[194:197], v[32:35]
	v_mfma_f32_16x16x32_bf16 v[20:23], v[170:173], v[202:205], v[20:23]
	v_mfma_f32_16x16x32_bf16 v[16:19], v[178:181], v[202:205], v[16:19]
	v_mfma_f32_16x16x32_bf16 v[4:7], v[170:173], v[210:213], v[4:7]
	v_mfma_f32_16x16x32_bf16 v[0:3], v[178:181], v[210:213], v[0:3]
	v_mfma_f32_16x16x32_bf16 v[52:55], v[174:177], v[190:193], v[52:55]
	v_mfma_f32_16x16x32_bf16 v[48:51], v[182:185], v[190:193], v[48:51]
	v_mfma_f32_16x16x32_bf16 v[36:39], v[174:177], v[198:201], v[36:39]
	v_mfma_f32_16x16x32_bf16 v[32:35], v[182:185], v[198:201], v[32:35]
	v_mfma_f32_16x16x32_bf16 v[20:23], v[174:177], v[206:209], v[20:23]
	v_mfma_f32_16x16x32_bf16 v[16:19], v[182:185], v[206:209], v[16:19]
	v_mfma_f32_16x16x32_bf16 v[4:7], v[174:177], v[218:221], v[4:7]
	v_mfma_f32_16x16x32_bf16 v[0:3], v[182:185], v[218:221], v[0:3]
	s_setprio 0
	s_barrier
	s_add_i32 s51, 0, 0x18000
	s_add_i32 s52, 0, 0x1c000
	v_add_u32_e32 v156, s51, v164
	v_add_u32_e32 v169, s52, v164
	ds_read_b128 v[128:131], v156
	ds_read_b128 v[132:135], v156 offset:1024
	ds_read_b128 v[152:155], v156 offset:2048
	ds_read_b128 v[156:159], v156 offset:3072
	ds_read_b128 v[170:173], v169
	ds_read_b128 v[174:177], v169 offset:1024
	ds_read_b128 v[178:181], v169 offset:2048
	ds_read_b128 v[182:185], v169 offset:3072
	s_add_u32 s2, s34, 0xb0000
	s_addc_u32 s3, s35, 0
	s_mov_b32 m0, s7
	v_lshl_add_u64 v[226:227], s[2:3], 0, v[136:137]
	ds_read_b128 v[186:189], v167 offset:32768
	ds_read_b128 v[190:193], v167 offset:33792
	ds_read_b128 v[194:197], v167 offset:34816
	ds_read_b128 v[198:201], v167 offset:35840
	ds_read_b128 v[202:205], v167 offset:36864
	ds_read_b128 v[206:209], v167 offset:37888
	ds_read_b128 v[210:213], v167 offset:38912
	ds_read_b128 v[218:221], v167 offset:39936
	global_load_lds_dwordx4 v[226:227], off
	v_lshl_add_u64 v[226:227], s[2:3], 0, v[140:141]
	s_mov_b32 m0, s33
	s_nop 0
	global_load_lds_dwordx4 v[226:227], off
	s_waitcnt lgkmcnt(0)
	s_setprio 1
	s_waitcnt lgkmcnt(0)
	v_mfma_f32_16x16x32_bf16 v[124:127], v[128:131], v[186:189], v[124:127]
	v_mfma_f32_16x16x32_bf16 v[120:123], v[152:155], v[186:189], v[120:123]
	v_mfma_f32_16x16x32_bf16 v[108:111], v[128:131], v[194:197], v[108:111]
	v_mfma_f32_16x16x32_bf16 v[104:107], v[152:155], v[194:197], v[104:107]
	v_mfma_f32_16x16x32_bf16 v[92:95], v[128:131], v[202:205], v[92:95]
	v_mfma_f32_16x16x32_bf16 v[88:91], v[152:155], v[202:205], v[88:91]
	v_mfma_f32_16x16x32_bf16 v[76:79], v[128:131], v[210:213], v[76:79]
	v_mfma_f32_16x16x32_bf16 v[72:75], v[152:155], v[210:213], v[72:75]
	s_waitcnt vmcnt(8)
	s_barrier
	v_mfma_f32_16x16x32_bf16 v[124:127], v[132:135], v[190:193], v[124:127]
	v_mfma_f32_16x16x32_bf16 v[120:123], v[156:159], v[190:193], v[120:123]
	v_mfma_f32_16x16x32_bf16 v[108:111], v[132:135], v[198:201], v[108:111]
	v_mfma_f32_16x16x32_bf16 v[104:107], v[156:159], v[198:201], v[104:107]
	v_mfma_f32_16x16x32_bf16 v[92:95], v[132:135], v[206:209], v[92:95]
	v_mfma_f32_16x16x32_bf16 v[88:91], v[156:159], v[206:209], v[88:91]
	v_mfma_f32_16x16x32_bf16 v[76:79], v[132:135], v[218:221], v[76:79]
	v_mfma_f32_16x16x32_bf16 v[72:75], v[156:159], v[218:221], v[72:75]
	s_setprio 0
	s_setprio 1
	v_mfma_f32_16x16x32_bf16 v[116:119], v[170:173], v[186:189], v[116:119]
	v_mfma_f32_16x16x32_bf16 v[112:115], v[178:181], v[186:189], v[112:115]
	v_mfma_f32_16x16x32_bf16 v[100:103], v[170:173], v[194:197], v[100:103]
	v_mfma_f32_16x16x32_bf16 v[96:99], v[178:181], v[194:197], v[96:99]
	v_mfma_f32_16x16x32_bf16 v[84:87], v[170:173], v[202:205], v[84:87]
	v_mfma_f32_16x16x32_bf16 v[80:83], v[178:181], v[202:205], v[80:83]
	v_mfma_f32_16x16x32_bf16 v[68:71], v[170:173], v[210:213], v[68:71]
	v_mfma_f32_16x16x32_bf16 v[64:67], v[178:181], v[210:213], v[64:67]
	v_mfma_f32_16x16x32_bf16 v[116:119], v[174:177], v[190:193], v[116:119]
	v_mfma_f32_16x16x32_bf16 v[112:115], v[182:185], v[190:193], v[112:115]
	v_mfma_f32_16x16x32_bf16 v[100:103], v[174:177], v[198:201], v[100:103]
	v_mfma_f32_16x16x32_bf16 v[96:99], v[182:185], v[198:201], v[96:99]
	v_mfma_f32_16x16x32_bf16 v[84:87], v[174:177], v[206:209], v[84:87]
	v_mfma_f32_16x16x32_bf16 v[80:83], v[182:185], v[206:209], v[80:83]
	v_mfma_f32_16x16x32_bf16 v[68:71], v[174:177], v[218:221], v[68:71]
	v_mfma_f32_16x16x32_bf16 v[64:67], v[182:185], v[218:221], v[64:67]
	s_setprio 0
	s_barrier
; #define PG8_STAGE(bufoff, gbase, voff) do { _Pragma("unroll") for (int _i = 0; _i < 2; ++_i) \
;         __builtin_amdgcn_global_load_lds((const unsigned*)((const char*)(gbase) + (voff)[_i]), (PG8_LAS unsigned*)(lds + (bufoff) + ldsw + _i * 8192), 16, 0, 0); } while (0)
; #define PG8_LDA(dst, b, h) do { _Pragma("unroll") for (int m = 0; m < 4; ++m) _Pragma("unroll") for (int k = 0; k < 2; ++k) dst[m][k] = *(const PG8_LAS bf16x8*)(lds + PG8_SA(b, h) + aoff + m * 2048 + k * 1024); } while (0)
; #define PG8_MMA(ai, bj, At, Bt) do { __builtin_amdgcn_s_setprio(1); _Pragma("unroll") for (int m = 0; m < 4; ++m) _Pragma("unroll") for (int n = 0; n < 2; ++n) _Pragma("unroll") for (int k = 0; k < 2; ++k) \
;         acc[ai][bj][m][n] = __builtin_amdgcn_mfma_f32_16x16x32_bf16(Bt[n][k], At[m][k], acc[ai][bj][m][n], 0, 0, 0); __builtin_amdgcn_s_setprio(0); } while (0)
; #define PG8_WAIT_V(n) asm volatile("s_waitcnt vmcnt(" #n ")" ::: "memory")
; #define PG8_WAIT_L(n) asm volatile("s_waitcnt lgkmcnt(" #n ")" ::: "memory")
; #define PG8_BAR __builtin_amdgcn_s_barrier()
; #define PG8_SCHED __builtin_amdgcn_sched_barrier(0)
; template <class Epi, class Sched, bool ALIGN_EPI = false, bool SP2 = false>
; __device__ __forceinline__ void gemm_phase(PG8_LAS unsigned char* lds, const Gemm g, const Sched& S, const Epi& E, int wave0) {
;     ...
;             PG8_LDA(At, 1, 1); PG8_STAGE(PG8_SB(1, 0), b3, voffB); PG8_STAGE(PG8_SB(1, 1), b3 + hstep, voffB); PG8_STAGE(PG8_SA(1, 0), a3, voffA);
;             PG8_WAIT_V(8); PG8_WAIT_L(0); PG8_BAR; if (!cur.half) { PG8_MMA(1, 0, At, B0); PG8_MMA(1, 1, At, B1); } PG8_BAR; PG8_SCHED;
;     ...
;         if constexpr (ALIGN_EPI) { if (wr == 0) PG8_BAR; }
	s_add_i32 s2, s51, s4
	v_lshl_add_u64 v[160:161], v[160:161], 0, s[16:17]
	s_mov_b32 m0, s2
	ds_read_b128 v[186:189], v167 offset:49152
	ds_read_b128 v[190:193], v167 offset:50176
	ds_read_b128 v[194:197], v167 offset:51200
	ds_read_b128 v[198:201], v167 offset:52224
	ds_read_b128 v[202:205], v167 offset:53248
	ds_read_b128 v[206:209], v167 offset:54272
	ds_read_b128 v[210:213], v167 offset:55296
	ds_read_b128 v[218:221], v167 offset:56320
	global_load_lds_dwordx4 v[160:161], off
	s_add_i32 m0, s2, 0x2000
	s_add_u32 s2, s30, 0xb0080
	v_lshl_add_u64 v[160:161], v[214:215], 0, s[16:17]
	s_addc_u32 s3, s31, 0
	s_add_i32 s30, s52, s4
	global_load_lds_dwordx4 v[160:161], off
	v_lshl_add_u64 v[160:161], s[2:3], 0, v[138:139]
	s_mov_b32 m0, s30
	s_nop 0
	global_load_lds_dwordx4 v[160:161], off
	v_lshl_add_u64 v[160:161], s[2:3], 0, v[142:143]
	s_add_i32 m0, s30, 0x2000
	s_nop 0
	global_load_lds_dwordx4 v[160:161], off
	v_lshl_add_u64 v[160:161], v[222:223], 0, s[16:17]
	s_mov_b32 m0, s39
	s_nop 0
	global_load_lds_dwordx4 v[160:161], off
	v_lshl_add_u64 v[160:161], v[224:225], 0, s[16:17]
	s_mov_b32 m0, s40
	s_nop 0
	global_load_lds_dwordx4 v[160:161], off
	s_waitcnt lgkmcnt(0)
	s_setprio 1
	s_waitcnt lgkmcnt(0)
	v_mfma_f32_16x16x32_bf16 v[60:63], v[128:131], v[186:189], v[60:63]
	v_mfma_f32_16x16x32_bf16 v[56:59], v[152:155], v[186:189], v[56:59]
	v_mfma_f32_16x16x32_bf16 v[44:47], v[128:131], v[194:197], v[44:47]
	v_mfma_f32_16x16x32_bf16 v[40:43], v[152:155], v[194:197], v[40:43]
	v_mfma_f32_16x16x32_bf16 v[28:31], v[128:131], v[202:205], v[28:31]
	v_mfma_f32_16x16x32_bf16 v[24:27], v[152:155], v[202:205], v[24:27]
	v_mfma_f32_16x16x32_bf16 v[12:15], v[128:131], v[210:213], v[12:15]
	v_mfma_f32_16x16x32_bf16 v[8:11], v[152:155], v[210:213], v[8:11]
	s_waitcnt vmcnt(8)
	s_barrier
	v_mfma_f32_16x16x32_bf16 v[60:63], v[132:135], v[190:193], v[60:63]
	v_mfma_f32_16x16x32_bf16 v[56:59], v[156:159], v[190:193], v[56:59]
	v_mfma_f32_16x16x32_bf16 v[44:47], v[132:135], v[198:201], v[44:47]
	v_mfma_f32_16x16x32_bf16 v[40:43], v[156:159], v[198:201], v[40:43]
	v_mfma_f32_16x16x32_bf16 v[28:31], v[132:135], v[206:209], v[28:31]
	v_mfma_f32_16x16x32_bf16 v[24:27], v[156:159], v[206:209], v[24:27]
	v_mfma_f32_16x16x32_bf16 v[12:15], v[132:135], v[218:221], v[12:15]
	v_mfma_f32_16x16x32_bf16 v[8:11], v[156:159], v[218:221], v[8:11]
	s_setprio 0
	s_setprio 1
	v_mfma_f32_16x16x32_bf16 v[52:55], v[170:173], v[186:189], v[52:55]
	v_mfma_f32_16x16x32_bf16 v[48:51], v[178:181], v[186:189], v[48:51]
	v_mfma_f32_16x16x32_bf16 v[36:39], v[170:173], v[194:197], v[36:39]
	v_mfma_f32_16x16x32_bf16 v[32:35], v[178:181], v[194:197], v[32:35]
	v_mfma_f32_16x16x32_bf16 v[20:23], v[170:173], v[202:205], v[20:23]
	v_mfma_f32_16x16x32_bf16 v[16:19], v[178:181], v[202:205], v[16:19]
	v_mfma_f32_16x16x32_bf16 v[4:7], v[170:173], v[210:213], v[4:7]
	v_mfma_f32_16x16x32_bf16 v[0:3], v[178:181], v[210:213], v[0:3]
	v_mfma_f32_16x16x32_bf16 v[52:55], v[174:177], v[190:193], v[52:55]
	v_mfma_f32_16x16x32_bf16 v[48:51], v[182:185], v[190:193], v[48:51]
	v_mfma_f32_16x16x32_bf16 v[36:39], v[174:177], v[198:201], v[36:39]
	v_mfma_f32_16x16x32_bf16 v[32:35], v[182:185], v[198:201], v[32:35]
	v_mfma_f32_16x16x32_bf16 v[20:23], v[174:177], v[206:209], v[20:23]
	v_mfma_f32_16x16x32_bf16 v[16:19], v[182:185], v[206:209], v[16:19]
	v_mfma_f32_16x16x32_bf16 v[4:7], v[174:177], v[218:221], v[4:7]
	v_mfma_f32_16x16x32_bf16 v[0:3], v[182:185], v[218:221], v[0:3]
	s_setprio 0
	s_barrier
	s_add_i32 s50, s50, 2
	s_add_u32 s48, s48, 0x100
	s_addc_u32 s49, s49, 0
	s_cmp_gt_u32 s50, 41
	s_mov_b64 s[2:3], s[0:1]
	s_cbranch_scc0 .LBB0_1101
	s_and_b64 vcc, exec, s[18:19]
	s_cbranch_vccz .LBB0_1104
	s_barrier

; #define PG8_STAGE(bufoff, gbase, voff) do { _Pragma("unroll") for (int _i = 0; _i < 2; ++_i) \
;         __builtin_amdgcn_global_load_lds((const unsigned*)((const char*)(gbase) + (voff)[_i]), (PG8_LAS unsigned*)(lds + (bufoff) + ldsw + _i * 8192), 16, 0, 0); } while (0)
; #define PG8_LDA(dst, b, h) do { _Pragma("unroll") for (int m = 0; m < 4; ++m) _Pragma("unroll") for (int k = 0; k < 2; ++k) dst[m][k] = *(const PG8_LAS bf16x8*)(lds + PG8_SA(b, h) + aoff + m * 2048 + k * 1024); } while (0)
; #define PG8_WAIT_V(n) asm volatile("s_waitcnt vmcnt(" #n ")" ::: "memory")
; #define PG8_WAIT_L(n) asm volatile("s_waitcnt lgkmcnt(" #n ")" ::: "memory")
; template <class Epi, class Sched, bool ALIGN_EPI = false, bool SP2 = false>
; __device__ __forceinline__ void gemm_phase(PG8_LAS unsigned char* lds, const Gemm g, const Sched& S, const Epi& E, int wave0) {
;     ...
;         for (int t = 0; t < nt; t += 2) {
;             const bool last = (t == nt - 2);
;             const char* a1 = cA + (size_t)(t + 1) * kstep;
;             const char* a2 = last ? nA : cA + (size_t)(t + 2) * kstep; const char* b2 = last ? nB : cB + (size_t)(t + 2) * kstep;
;             const char* a3 = a2 + kstep; const char* b3 = b2 + kstep;
;             if (last && has_next) S.a_ready(nxt);
;             if constexpr (SP2) {
;             PG8_LDB(B0, 0, 0); PG8_LDB(B1, 0, 1); PG8_SCHED; PG8_LDA(At, 0, 0); PG8_STAGE(PG8_SA(1, 1), a1 + hstep, voffA);
;             PG8_WAIT_V(8); PG8_WAIT_L(0); PG8_BAR; PG8_MMA(0, 0, At, B0); PG8_MMA(0, 1, At, B1); PG8_BAR; PG8_SCHED;
;             PG8_LDA(At, 0, 1); PG8_STAGE(PG8_SB(0, 0), b2, voffB); PG8_STAGE(PG8_SB(0, 1), b2 + hstep, voffB); PG8_STAGE(PG8_SA(0, 0), a2, voffA);
;             PG8_WAIT_V(8); PG8_WAIT_L(0); PG8_BAR; if (!cur.half) { PG8_MMA(1, 0, At, B0); PG8_MMA(1, 1, At, B1); } PG8_BAR; PG8_SCHED;
;             PG8_LDB(B0, 1, 0); PG8_LDB(B1, 1, 1); PG8_SCHED; PG8_LDA(At, 1, 0); PG8_STAGE(PG8_SA(0, 1), a2 + hstep, voffA);
;             PG8_WAIT_V(8); PG8_WAIT_L(0); PG8_BAR; PG8_MMA(0, 0, At, B0); PG8_MMA(0, 1, At, B1); PG8_BAR; PG8_SCHED;
;             PG8_LDA(At, 1, 1); PG8_STAGE(PG8_SB(1, 0), b3, voffB); PG8_STAGE(PG8_SB(1, 1), b3 + hstep, voffB); PG8_STAGE(PG8_SA(1, 0), a3, voffA);
;             PG8_WAIT_V(8); PG8_WAIT_L(0); PG8_BAR; if (!cur.half) { PG8_MMA(1, 0, At, B0); PG8_MMA(1, 1, At, B1); } PG8_BAR; PG8_SCHED;
.LBB0_1208:
	ds_read_b128 v[128:131], v163
	ds_read_b128 v[132:135], v163 offset:1024
	ds_read_b128 v[136:139], v163 offset:2048
	ds_read_b128 v[170:173], v163 offset:3072
	ds_read_b128 v[174:177], v165
	ds_read_b128 v[178:181], v165 offset:1024
	ds_read_b128 v[182:185], v165 offset:2048
	ds_read_b128 v[186:189], v165 offset:3072
	s_add_u32 s2, s46, 0xfffc0080
	s_addc_u32 s3, s47, -1
	s_cmp_eq_u32 s68, 12
	s_cselect_b32 s51, s39, s3
	s_cselect_b32 s50, vcc_lo, s2
	s_cselect_b32 s49, s37, s62
	s_cselect_b32 s48, vcc_hi, s57
	v_lshl_add_u64 v[214:215], s[46:47], 0, v[148:149]
	s_add_i32 m0, s6, 0xc000
	ds_read_b128 v[190:193], v167
	ds_read_b128 v[194:197], v167 offset:1024
	ds_read_b128 v[198:201], v167 offset:2048
	ds_read_b128 v[202:205], v167 offset:3072
	ds_read_b128 v[206:209], v167 offset:4096
	ds_read_b128 v[210:213], v167 offset:5120
	ds_read_b128 v[218:221], v167 offset:6144
	ds_read_b128 v[222:225], v167 offset:7168
	global_load_lds_dwordx4 v[214:215], off
	v_lshl_add_u64 v[214:215], s[46:47], 0, v[150:151]
	s_add_i32 m0, s6, 0xe000
	s_nop 0
	global_load_lds_dwordx4 v[214:215], off
	s_waitcnt lgkmcnt(0)
	s_setprio 1
	s_waitcnt lgkmcnt(0)
	v_mfma_f32_16x16x32_bf16 v[124:127], v[128:131], v[190:193], v[124:127]
	v_mfma_f32_16x16x32_bf16 v[120:123], v[136:139], v[190:193], v[120:123]
	v_mfma_f32_16x16x32_bf16 v[108:111], v[128:131], v[198:201], v[108:111]
	v_mfma_f32_16x16x32_bf16 v[104:107], v[136:139], v[198:201], v[104:107]
	v_mfma_f32_16x16x32_bf16 v[96:99], v[128:131], v[206:209], v[96:99]
	v_mfma_f32_16x16x32_bf16 v[88:91], v[136:139], v[206:209], v[88:91]
	v_mfma_f32_16x16x32_bf16 v[80:83], v[128:131], v[218:221], v[80:83]
	v_mfma_f32_16x16x32_bf16 v[72:75], v[136:139], v[218:221], v[72:75]
	s_waitcnt vmcnt(8)
	s_barrier
	v_mfma_f32_16x16x32_bf16 v[124:127], v[132:135], v[194:197], v[124:127]
	v_mfma_f32_16x16x32_bf16 v[120:123], v[170:173], v[194:197], v[120:123]
	v_mfma_f32_16x16x32_bf16 v[108:111], v[132:135], v[202:205], v[108:111]
	v_mfma_f32_16x16x32_bf16 v[104:107], v[170:173], v[202:205], v[104:107]
	v_mfma_f32_16x16x32_bf16 v[96:99], v[132:135], v[210:213], v[96:99]
	v_mfma_f32_16x16x32_bf16 v[88:91], v[170:173], v[210:213], v[88:91]
	v_mfma_f32_16x16x32_bf16 v[80:83], v[132:135], v[222:225], v[80:83]
	v_mfma_f32_16x16x32_bf16 v[72:75], v[170:173], v[222:225], v[72:75]
	s_setprio 0
	s_setprio 1
	v_mfma_f32_16x16x32_bf16 v[116:119], v[174:177], v[190:193], v[116:119]
	v_mfma_f32_16x16x32_bf16 v[112:115], v[182:185], v[190:193], v[112:115]
	v_mfma_f32_16x16x32_bf16 v[100:103], v[174:177], v[198:201], v[100:103]
	v_mfma_f32_16x16x32_bf16 v[92:95], v[182:185], v[198:201], v[92:95]
	v_mfma_f32_16x16x32_bf16 v[84:87], v[174:177], v[206:209], v[84:87]
	v_mfma_f32_16x16x32_bf16 v[76:79], v[182:185], v[206:209], v[76:79]
	v_mfma_f32_16x16x32_bf16 v[68:71], v[174:177], v[218:221], v[68:71]
	v_mfma_f32_16x16x32_bf16 v[64:67], v[182:185], v[218:221], v[64:67]
	v_mfma_f32_16x16x32_bf16 v[116:119], v[178:181], v[194:197], v[116:119]
	v_mfma_f32_16x16x32_bf16 v[112:115], v[186:189], v[194:197], v[112:115]
	v_mfma_f32_16x16x32_bf16 v[100:103], v[178:181], v[202:205], v[100:103]
	v_mfma_f32_16x16x32_bf16 v[92:95], v[186:189], v[202:205], v[92:95]
	v_mfma_f32_16x16x32_bf16 v[84:87], v[178:181], v[210:213], v[84:87]
	v_mfma_f32_16x16x32_bf16 v[76:79], v[186:189], v[210:213], v[76:79]
	v_mfma_f32_16x16x32_bf16 v[68:71], v[178:181], v[222:225], v[68:71]
	v_mfma_f32_16x16x32_bf16 v[64:67], v[186:189], v[222:225], v[64:67]
	s_setprio 0
	s_barrier
	s_add_i32 s2, s84, s4
	v_lshl_add_u64 v[214:215], s[48:49], 0, v[144:145]
	s_mov_b32 m0, s2
	ds_read_b128 v[190:193], v167 offset:16384
	ds_read_b128 v[194:197], v167 offset:17408
	ds_read_b128 v[198:201], v167 offset:18432
	ds_read_b128 v[202:205], v167 offset:19456
	ds_read_b128 v[206:209], v167 offset:20480
	ds_read_b128 v[210:213], v167 offset:21504
	ds_read_b128 v[218:221], v167 offset:22528
	ds_read_b128 v[222:225], v167 offset:23552
	global_load_lds_dwordx4 v[214:215], off
	s_add_i32 m0, s2, 0x2000
	s_add_u32 s2, s48, 0x40000
	v_lshl_add_u64 v[226:227], s[48:49], 0, v[140:141]
	s_addc_u32 s3, s49, 0
	s_add_i32 s69, s85, s4
	global_load_lds_dwordx4 v[226:227], off
	v_lshl_add_u64 v[228:229], s[2:3], 0, v[144:145]
	s_mov_b32 m0, s69
	v_lshl_add_u64 v[230:231], s[50:51], 0, v[142:143]
	global_load_lds_dwordx4 v[228:229], off
	v_lshl_add_u64 v[228:229], s[2:3], 0, v[140:141]
	s_add_i32 m0, s69, 0x2000
	s_nop 0
	global_load_lds_dwordx4 v[228:229], off
	v_lshl_add_u64 v[228:229], s[50:51], 0, v[146:147]
	s_mov_b32 m0, s6
	s_nop 0
	global_load_lds_dwordx4 v[228:229], off
	s_mov_b32 m0, s7
	s_nop 0
	global_load_lds_dwordx4 v[230:231], off
	s_waitcnt lgkmcnt(0)
	s_setprio 1
	s_waitcnt lgkmcnt(0)
	v_mfma_f32_16x16x32_bf16 v[60:63], v[128:131], v[190:193], v[60:63]
	v_mfma_f32_16x16x32_bf16 v[56:59], v[136:139], v[190:193], v[56:59]
	v_mfma_f32_16x16x32_bf16 v[48:51], v[128:131], v[198:201], v[48:51]
	v_mfma_f32_16x16x32_bf16 v[40:43], v[136:139], v[198:201], v[40:43]
	v_mfma_f32_16x16x32_bf16 v[32:35], v[128:131], v[206:209], v[32:35]
	v_mfma_f32_16x16x32_bf16 v[24:27], v[136:139], v[206:209], v[24:27]
	v_mfma_f32_16x16x32_bf16 v[16:19], v[128:131], v[218:221], v[16:19]
	v_mfma_f32_16x16x32_bf16 v[8:11], v[136:139], v[218:221], v[8:11]
	s_waitcnt vmcnt(8)
	s_barrier
; #define PG8_STAGE(bufoff, gbase, voff) do { _Pragma("unroll") for (int _i = 0; _i < 2; ++_i) \
;         __builtin_amdgcn_global_load_lds((const unsigned*)((const char*)(gbase) + (voff)[_i]), (PG8_LAS unsigned*)(lds + (bufoff) + ldsw + _i * 8192), 16, 0, 0); } while (0)
; #define PG8_LDA(dst, b, h) do { _Pragma("unroll") for (int m = 0; m < 4; ++m) _Pragma("unroll") for (int k = 0; k < 2; ++k) dst[m][k] = *(const PG8_LAS bf16x8*)(lds + PG8_SA(b, h) + aoff + m * 2048 + k * 1024); } while (0)
; #define PG8_LDB(dst, b, h) do { _Pragma("unroll") for (int n = 0; n < 2; ++n) _Pragma("unroll") for (int k = 0; k < 2; ++k) dst[n][k] = *(const PG8_LAS bf16x8*)(lds + PG8_SB(b, h) + boff + n * 2048 + k * 1024); } while (0)
; #define PG8_MMA(ai, bj, At, Bt) do { __builtin_amdgcn_s_setprio(1); _Pragma("unroll") for (int m = 0; m < 4; ++m) _Pragma("unroll") for (int n = 0; n < 2; ++n) _Pragma("unroll") for (int k = 0; k < 2; ++k) \
;         acc[ai][bj][m][n] = __builtin_amdgcn_mfma_f32_16x16x32_bf16(Bt[n][k], At[m][k], acc[ai][bj][m][n], 0, 0, 0); __builtin_amdgcn_s_setprio(0); } while (0)
; #define PG8_WAIT_V(n) asm volatile("s_waitcnt vmcnt(" #n ")" ::: "memory")
; #define PG8_WAIT_L(n) asm volatile("s_waitcnt lgkmcnt(" #n ")" ::: "memory")
; #define PG8_BAR __builtin_amdgcn_s_barrier()
; #define PG8_SCHED __builtin_amdgcn_sched_barrier(0)
; template <class Epi, class Sched, bool ALIGN_EPI = false, bool SP2 = false>
; __device__ __forceinline__ void gemm_phase(PG8_LAS unsigned char* lds, const Gemm g, const Sched& S, const Epi& E, int wave0) {
;     ...
;             PG8_LDB(B0, 1, 0); PG8_LDB(B1, 1, 1); PG8_SCHED; PG8_LDA(At, 1, 0); PG8_STAGE(PG8_SA(0, 1), a2 + hstep, voffA);
;             PG8_WAIT_V(8); PG8_WAIT_L(0); PG8_BAR; PG8_MMA(0, 0, At, B0); PG8_MMA(0, 1, At, B1); PG8_BAR; PG8_SCHED;
;             PG8_LDA(At, 1, 1); PG8_STAGE(PG8_SB(1, 0), b3, voffB); PG8_STAGE(PG8_SB(1, 1), b3 + hstep, voffB); PG8_STAGE(PG8_SA(1, 0), a3, voffA);
	v_mfma_f32_16x16x32_bf16 v[60:63], v[132:135], v[194:197], v[60:63]
	v_mfma_f32_16x16x32_bf16 v[56:59], v[170:173], v[194:197], v[56:59]
	v_mfma_f32_16x16x32_bf16 v[48:51], v[132:135], v[202:205], v[48:51]
	v_mfma_f32_16x16x32_bf16 v[40:43], v[170:173], v[202:205], v[40:43]
	v_mfma_f32_16x16x32_bf16 v[32:35], v[132:135], v[210:213], v[32:35]
	v_mfma_f32_16x16x32_bf16 v[24:27], v[170:173], v[210:213], v[24:27]
	v_mfma_f32_16x16x32_bf16 v[16:19], v[132:135], v[222:225], v[16:19]
	v_mfma_f32_16x16x32_bf16 v[8:11], v[170:173], v[222:225], v[8:11]
	s_setprio 0
	s_setprio 1
	v_mfma_f32_16x16x32_bf16 v[52:55], v[174:177], v[190:193], v[52:55]
	v_mfma_f32_16x16x32_bf16 v[44:47], v[182:185], v[190:193], v[44:47]
	v_mfma_f32_16x16x32_bf16 v[36:39], v[174:177], v[198:201], v[36:39]
	v_mfma_f32_16x16x32_bf16 v[28:31], v[182:185], v[198:201], v[28:31]
	v_mfma_f32_16x16x32_bf16 v[20:23], v[174:177], v[206:209], v[20:23]
	v_mfma_f32_16x16x32_bf16 v[12:15], v[182:185], v[206:209], v[12:15]
	v_mfma_f32_16x16x32_bf16 v[4:7], v[174:177], v[218:221], v[4:7]
	v_mfma_f32_16x16x32_bf16 v[0:3], v[182:185], v[218:221], v[0:3]
	v_mfma_f32_16x16x32_bf16 v[52:55], v[178:181], v[194:197], v[52:55]
	v_mfma_f32_16x16x32_bf16 v[44:47], v[186:189], v[194:197], v[44:47]
	v_mfma_f32_16x16x32_bf16 v[36:39], v[178:181], v[202:205], v[36:39]
	v_mfma_f32_16x16x32_bf16 v[28:31], v[186:189], v[202:205], v[28:31]
	v_mfma_f32_16x16x32_bf16 v[20:23], v[178:181], v[210:213], v[20:23]
	v_mfma_f32_16x16x32_bf16 v[12:15], v[186:189], v[210:213], v[12:15]
	v_mfma_f32_16x16x32_bf16 v[4:7], v[178:181], v[222:225], v[4:7]
	v_mfma_f32_16x16x32_bf16 v[0:3], v[186:189], v[222:225], v[0:3]
	s_setprio 0
	s_barrier
	s_add_i32 s69, 0, 0x18000
	v_add_u32_e32 v156, s69, v161
	s_add_i32 s16, 0, 0x1c000
	ds_read_b128 v[128:131], v156
	ds_read_b128 v[132:135], v156 offset:1024
	ds_read_b128 v[136:139], v156 offset:2048
	ds_read_b128 v[170:173], v156 offset:3072
	v_add_u32_e32 v156, s16, v161
	ds_read_b128 v[174:177], v156
	ds_read_b128 v[178:181], v156 offset:1024
	ds_read_b128 v[182:185], v156 offset:2048
	ds_read_b128 v[186:189], v156 offset:3072
	s_add_u32 s2, s50, 0x40000
	s_addc_u32 s3, s51, 0
	s_mov_b32 m0, s33
	v_lshl_add_u64 v[232:233], s[2:3], 0, v[146:147]
	ds_read_b128 v[190:193], v167 offset:32768
	ds_read_b128 v[194:197], v167 offset:33792
	ds_read_b128 v[198:201], v167 offset:34816
	ds_read_b128 v[202:205], v167 offset:35840
	ds_read_b128 v[206:209], v167 offset:36864
	ds_read_b128 v[210:213], v167 offset:37888
	ds_read_b128 v[218:221], v167 offset:38912
	ds_read_b128 v[222:225], v167 offset:39936
	global_load_lds_dwordx4 v[232:233], off
	v_lshl_add_u64 v[232:233], s[2:3], 0, v[142:143]
	s_mov_b32 m0, s52
	s_nop 0
	global_load_lds_dwordx4 v[232:233], off
	s_waitcnt lgkmcnt(0)
	s_setprio 1
	s_waitcnt lgkmcnt(0)
	v_mfma_f32_16x16x32_bf16 v[124:127], v[128:131], v[190:193], v[124:127]
	v_mfma_f32_16x16x32_bf16 v[120:123], v[136:139], v[190:193], v[120:123]
	v_mfma_f32_16x16x32_bf16 v[108:111], v[128:131], v[198:201], v[108:111]
	v_mfma_f32_16x16x32_bf16 v[104:107], v[136:139], v[198:201], v[104:107]
	v_mfma_f32_16x16x32_bf16 v[96:99], v[128:131], v[206:209], v[96:99]
	v_mfma_f32_16x16x32_bf16 v[88:91], v[136:139], v[206:209], v[88:91]
	v_mfma_f32_16x16x32_bf16 v[80:83], v[128:131], v[218:221], v[80:83]
	v_mfma_f32_16x16x32_bf16 v[72:75], v[136:139], v[218:221], v[72:75]
	s_waitcnt vmcnt(8)
	s_barrier
	v_mfma_f32_16x16x32_bf16 v[124:127], v[132:135], v[194:197], v[124:127]
	v_mfma_f32_16x16x32_bf16 v[120:123], v[170:173], v[194:197], v[120:123]
	v_mfma_f32_16x16x32_bf16 v[108:111], v[132:135], v[202:205], v[108:111]
	v_mfma_f32_16x16x32_bf16 v[104:107], v[170:173], v[202:205], v[104:107]
	v_mfma_f32_16x16x32_bf16 v[96:99], v[132:135], v[210:213], v[96:99]
	v_mfma_f32_16x16x32_bf16 v[88:91], v[170:173], v[210:213], v[88:91]
	v_mfma_f32_16x16x32_bf16 v[80:83], v[132:135], v[222:225], v[80:83]
	v_mfma_f32_16x16x32_bf16 v[72:75], v[170:173], v[222:225], v[72:75]
	s_setprio 0
	s_setprio 1
	v_mfma_f32_16x16x32_bf16 v[116:119], v[174:177], v[190:193], v[116:119]
	v_mfma_f32_16x16x32_bf16 v[112:115], v[182:185], v[190:193], v[112:115]
	v_mfma_f32_16x16x32_bf16 v[100:103], v[174:177], v[198:201], v[100:103]
	v_mfma_f32_16x16x32_bf16 v[92:95], v[182:185], v[198:201], v[92:95]
	v_mfma_f32_16x16x32_bf16 v[84:87], v[174:177], v[206:209], v[84:87]
	v_mfma_f32_16x16x32_bf16 v[76:79], v[182:185], v[206:209], v[76:79]
	v_mfma_f32_16x16x32_bf16 v[68:71], v[174:177], v[218:221], v[68:71]
	v_mfma_f32_16x16x32_bf16 v[64:67], v[182:185], v[218:221], v[64:67]
	v_mfma_f32_16x16x32_bf16 v[116:119], v[178:181], v[194:197], v[116:119]
	v_mfma_f32_16x16x32_bf16 v[112:115], v[186:189], v[194:197], v[112:115]
	v_mfma_f32_16x16x32_bf16 v[100:103], v[178:181], v[202:205], v[100:103]
	v_mfma_f32_16x16x32_bf16 v[92:95], v[186:189], v[202:205], v[92:95]
	v_mfma_f32_16x16x32_bf16 v[84:87], v[178:181], v[210:213], v[84:87]
	v_mfma_f32_16x16x32_bf16 v[76:79], v[186:189], v[210:213], v[76:79]
	v_mfma_f32_16x16x32_bf16 v[68:71], v[178:181], v[222:225], v[68:71]
	v_mfma_f32_16x16x32_bf16 v[64:67], v[186:189], v[222:225], v[64:67]
	s_setprio 0
	s_barrier
; #define PG8_STAGE(bufoff, gbase, voff) do { _Pragma("unroll") for (int _i = 0; _i < 2; ++_i) \
;         __builtin_amdgcn_global_load_lds((const unsigned*)((const char*)(gbase) + (voff)[_i]), (PG8_LAS unsigned*)(lds + (bufoff) + ldsw + _i * 8192), 16, 0, 0); } while (0)
; #define PG8_LDA(dst, b, h) do { _Pragma("unroll") for (int m = 0; m < 4; ++m) _Pragma("unroll") for (int k = 0; k < 2; ++k) dst[m][k] = *(const PG8_LAS bf16x8*)(lds + PG8_SA(b, h) + aoff + m * 2048 + k * 1024); } while (0)
; #define PG8_MMA(ai, bj, At, Bt) do { __builtin_amdgcn_s_setprio(1); _Pragma("unroll") for (int m = 0; m < 4; ++m) _Pragma("unroll") for (int n = 0; n < 2; ++n) _Pragma("unroll") for (int k = 0; k < 2; ++k) \
;         acc[ai][bj][m][n] = __builtin_amdgcn_mfma_f32_16x16x32_bf16(Bt[n][k], At[m][k], acc[ai][bj][m][n], 0, 0, 0); __builtin_amdgcn_s_setprio(0); } while (0)
; #define PG8_WAIT_V(n) asm volatile("s_waitcnt vmcnt(" #n ")" ::: "memory")
; #define PG8_WAIT_L(n) asm volatile("s_waitcnt lgkmcnt(" #n ")" ::: "memory")
; #define PG8_BAR __builtin_amdgcn_s_barrier()
; #define PG8_SCHED __builtin_amdgcn_sched_barrier(0)
; template <class Epi, class Sched, bool ALIGN_EPI = false, bool SP2 = false>
; __device__ __forceinline__ void gemm_phase(PG8_LAS unsigned char* lds, const Gemm g, const Sched& S, const Epi& E, int wave0) {
;     ...
;             PG8_LDA(At, 1, 1); PG8_STAGE(PG8_SB(1, 0), b3, voffB); PG8_STAGE(PG8_SB(1, 1), b3 + hstep, voffB); PG8_STAGE(PG8_SA(1, 0), a3, voffA);
;             PG8_WAIT_V(8); PG8_WAIT_L(0); PG8_BAR; if (!cur.half) { PG8_MMA(1, 0, At, B0); PG8_MMA(1, 1, At, B1); } PG8_BAR; PG8_SCHED;
;     ...
;         if constexpr (ALIGN_EPI) { if (wr == 0) PG8_BAR; }
	s_add_i32 s2, s69, s4
	v_lshl_add_u64 v[214:215], v[214:215], 0, s[12:13]
	s_mov_b32 m0, s2
	ds_read_b128 v[190:193], v167 offset:49152
	ds_read_b128 v[194:197], v167 offset:50176
	ds_read_b128 v[198:201], v167 offset:51200
	ds_read_b128 v[202:205], v167 offset:52224
	ds_read_b128 v[206:209], v167 offset:53248
	ds_read_b128 v[210:213], v167 offset:54272
	ds_read_b128 v[218:221], v167 offset:55296
	ds_read_b128 v[222:225], v167 offset:56320
	global_load_lds_dwordx4 v[214:215], off
	s_add_i32 m0, s2, 0x2000
	s_add_u32 s2, s48, 0x40080
	v_lshl_add_u64 v[214:215], v[226:227], 0, s[12:13]
	s_addc_u32 s3, s49, 0
	s_add_i32 s16, s16, s4
	global_load_lds_dwordx4 v[214:215], off
	v_lshl_add_u64 v[214:215], s[2:3], 0, v[144:145]
	s_mov_b32 m0, s16
	s_nop 0
	global_load_lds_dwordx4 v[214:215], off
	v_lshl_add_u64 v[214:215], s[2:3], 0, v[140:141]
	s_add_i32 m0, s16, 0x2000
	s_nop 0
	global_load_lds_dwordx4 v[214:215], off
	v_lshl_add_u64 v[214:215], v[228:229], 0, s[12:13]
	s_mov_b32 m0, s63
	s_nop 0
	global_load_lds_dwordx4 v[214:215], off
	v_lshl_add_u64 v[214:215], v[230:231], 0, s[12:13]
	s_mov_b32 m0, s70
	s_nop 0
	global_load_lds_dwordx4 v[214:215], off
	s_waitcnt lgkmcnt(0)
	s_setprio 1
	s_waitcnt lgkmcnt(0)
	v_mfma_f32_16x16x32_bf16 v[60:63], v[128:131], v[190:193], v[60:63]
	v_mfma_f32_16x16x32_bf16 v[56:59], v[136:139], v[190:193], v[56:59]
	v_mfma_f32_16x16x32_bf16 v[48:51], v[128:131], v[198:201], v[48:51]
	v_mfma_f32_16x16x32_bf16 v[40:43], v[136:139], v[198:201], v[40:43]
	v_mfma_f32_16x16x32_bf16 v[32:35], v[128:131], v[206:209], v[32:35]
	v_mfma_f32_16x16x32_bf16 v[24:27], v[136:139], v[206:209], v[24:27]
	v_mfma_f32_16x16x32_bf16 v[16:19], v[128:131], v[218:221], v[16:19]
	v_mfma_f32_16x16x32_bf16 v[8:11], v[136:139], v[218:221], v[8:11]
	s_waitcnt vmcnt(8)
	s_barrier
	v_mfma_f32_16x16x32_bf16 v[60:63], v[132:135], v[194:197], v[60:63]
	v_mfma_f32_16x16x32_bf16 v[56:59], v[170:173], v[194:197], v[56:59]
	v_mfma_f32_16x16x32_bf16 v[48:51], v[132:135], v[202:205], v[48:51]
	v_mfma_f32_16x16x32_bf16 v[40:43], v[170:173], v[202:205], v[40:43]
	v_mfma_f32_16x16x32_bf16 v[32:35], v[132:135], v[210:213], v[32:35]
	v_mfma_f32_16x16x32_bf16 v[24:27], v[170:173], v[210:213], v[24:27]
	v_mfma_f32_16x16x32_bf16 v[16:19], v[132:135], v[222:225], v[16:19]
	v_mfma_f32_16x16x32_bf16 v[8:11], v[170:173], v[222:225], v[8:11]
	s_setprio 0
	s_setprio 1
	v_mfma_f32_16x16x32_bf16 v[52:55], v[174:177], v[190:193], v[52:55]
	v_mfma_f32_16x16x32_bf16 v[44:47], v[182:185], v[190:193], v[44:47]
	v_mfma_f32_16x16x32_bf16 v[36:39], v[174:177], v[198:201], v[36:39]
	v_mfma_f32_16x16x32_bf16 v[28:31], v[182:185], v[198:201], v[28:31]
	v_mfma_f32_16x16x32_bf16 v[20:23], v[174:177], v[206:209], v[20:23]
	v_mfma_f32_16x16x32_bf16 v[12:15], v[182:185], v[206:209], v[12:15]
	v_mfma_f32_16x16x32_bf16 v[4:7], v[174:177], v[218:221], v[4:7]
	v_mfma_f32_16x16x32_bf16 v[0:3], v[182:185], v[218:221], v[0:3]
	v_mfma_f32_16x16x32_bf16 v[52:55], v[178:181], v[194:197], v[52:55]
	v_mfma_f32_16x16x32_bf16 v[44:47], v[186:189], v[194:197], v[44:47]
	v_mfma_f32_16x16x32_bf16 v[36:39], v[178:181], v[202:205], v[36:39]
	v_mfma_f32_16x16x32_bf16 v[28:31], v[186:189], v[202:205], v[28:31]
	v_mfma_f32_16x16x32_bf16 v[20:23], v[178:181], v[210:213], v[20:23]
	v_mfma_f32_16x16x32_bf16 v[12:15], v[186:189], v[210:213], v[12:15]
	v_mfma_f32_16x16x32_bf16 v[4:7], v[178:181], v[222:225], v[4:7]
	v_mfma_f32_16x16x32_bf16 v[0:3], v[186:189], v[222:225], v[0:3]
	s_setprio 0
	s_barrier
	s_add_i32 s68, s68, 2
	s_add_u32 s46, s46, 0x100
	s_addc_u32 s47, s47, 0
	s_add_u32 s57, s57, 0x100
	s_addc_u32 s62, s62, 0
	s_cmp_gt_u32 s68, 13
	s_cbranch_scc0 .LBB0_1208
	s_and_b64 vcc, exec, s[14:15]
	s_cbranch_vccz .LBB0_1211
	s_barrier

; #define PG8_STAGE(bufoff, gbase, voff) do { _Pragma("unroll") for (int _i = 0; _i < 2; ++_i) \
;         __builtin_amdgcn_global_load_lds((const unsigned*)((const char*)(gbase) + (voff)[_i]), (PG8_LAS unsigned*)(lds + (bufoff) + ldsw + _i * 8192), 16, 0, 0); } while (0)
; #define PG8_LDA(dst, b, h) do { _Pragma("unroll") for (int m = 0; m < 4; ++m) _Pragma("unroll") for (int k = 0; k < 2; ++k) dst[m][k] = *(const PG8_LAS bf16x8*)(lds + PG8_SA(b, h) + aoff + m * 2048 + k * 1024); } while (0)
; #define PG8_WAIT_V(n) asm volatile("s_waitcnt vmcnt(" #n ")" ::: "memory")
; #define PG8_WAIT_L(n) asm volatile("s_waitcnt lgkmcnt(" #n ")" ::: "memory")
; template <class Epi, class Sched, bool ALIGN_EPI = false, bool SP2 = false>
; __device__ __forceinline__ void gemm_phase(PG8_LAS unsigned char* lds, const Gemm g, const Sched& S, const Epi& E, int wave0) {
;     ...
;         for (int t = 0; t < nt; t += 2) {
;             const bool last = (t == nt - 2);
;             const char* a1 = cA + (size_t)(t + 1) * kstep;
;             const char* a2 = last ? nA : cA + (size_t)(t + 2) * kstep; const char* b2 = last ? nB : cB + (size_t)(t + 2) * kstep;
;             const char* a3 = a2 + kstep; const char* b3 = b2 + kstep;
;             if (last && has_next) S.a_ready(nxt);
;             if constexpr (SP2) {
;             PG8_LDB(B0, 0, 0); PG8_LDB(B1, 0, 1); PG8_SCHED; PG8_LDA(At, 0, 0); PG8_STAGE(PG8_SA(1, 1), a1 + hstep, voffA);
;             PG8_WAIT_V(8); PG8_WAIT_L(0); PG8_BAR; PG8_MMA(0, 0, At, B0); PG8_MMA(0, 1, At, B1); PG8_BAR; PG8_SCHED;
;             PG8_LDA(At, 0, 1); PG8_STAGE(PG8_SB(0, 0), b2, voffB); PG8_STAGE(PG8_SB(0, 1), b2 + hstep, voffB); PG8_STAGE(PG8_SA(0, 0), a2, voffA);
;             PG8_WAIT_V(8); PG8_WAIT_L(0); PG8_BAR; if (!cur.half) { PG8_MMA(1, 0, At, B0); PG8_MMA(1, 1, At, B1); } PG8_BAR; PG8_SCHED;
;             PG8_LDB(B0, 1, 0); PG8_LDB(B1, 1, 1); PG8_SCHED; PG8_LDA(At, 1, 0); PG8_STAGE(PG8_SA(0, 1), a2 + hstep, voffA);
;             PG8_WAIT_V(8); PG8_WAIT_L(0); PG8_BAR; PG8_MMA(0, 0, At, B0); PG8_MMA(0, 1, At, B1); PG8_BAR; PG8_SCHED;
;             PG8_LDA(At, 1, 1); PG8_STAGE(PG8_SB(1, 0), b3, voffB); PG8_STAGE(PG8_SB(1, 1), b3 + hstep, voffB); PG8_STAGE(PG8_SA(1, 0), a3, voffA);
;             PG8_WAIT_V(8); PG8_WAIT_L(0); PG8_BAR; if (!cur.half) { PG8_MMA(1, 0, At, B0); PG8_MMA(1, 1, At, B1); } PG8_BAR; PG8_SCHED;
.LBB0_2493:
	ds_read_b128 v[128:131], v165
	ds_read_b128 v[132:135], v165 offset:1024
	ds_read_b128 v[152:155], v165 offset:2048
	ds_read_b128 v[156:159], v165 offset:3072
	ds_read_b128 v[170:173], v166
	ds_read_b128 v[174:177], v166 offset:1024
	ds_read_b128 v[178:181], v166 offset:2048
	ds_read_b128 v[182:185], v166 offset:3072
	s_add_u32 s26, s24, 0xfffc0080
	s_addc_u32 s27, s25, -1
	s_cmp_eq_u32 s44, 12
	s_cselect_b32 s29, s1, s27
	s_cselect_b32 s28, s19, s26
	s_cselect_b32 s27, s17, s43
	s_cselect_b32 s26, s41, s42
	v_lshl_add_u64 v[160:161], s[24:25], 0, v[144:145]
	s_add_i32 m0, s5, 0xc000
	ds_read_b128 v[186:189], v167
	ds_read_b128 v[190:193], v167 offset:1024
	ds_read_b128 v[194:197], v167 offset:2048
	ds_read_b128 v[198:201], v167 offset:3072
	ds_read_b128 v[202:205], v167 offset:4096
	ds_read_b128 v[206:209], v167 offset:5120
	ds_read_b128 v[210:213], v167 offset:6144
	ds_read_b128 v[218:221], v167 offset:7168
	global_load_lds_dwordx4 v[160:161], off
	v_lshl_add_u64 v[160:161], s[24:25], 0, v[146:147]
	s_add_i32 m0, s5, 0xe000
	s_nop 0
	global_load_lds_dwordx4 v[160:161], off
	s_waitcnt lgkmcnt(0)
	s_setprio 1
	s_waitcnt lgkmcnt(0)
	v_mfma_f32_16x16x32_bf16 v[124:127], v[128:131], v[186:189], v[124:127]
	v_mfma_f32_16x16x32_bf16 v[120:123], v[152:155], v[186:189], v[120:123]
	v_mfma_f32_16x16x32_bf16 v[108:111], v[128:131], v[194:197], v[108:111]
	v_mfma_f32_16x16x32_bf16 v[104:107], v[152:155], v[194:197], v[104:107]
	v_mfma_f32_16x16x32_bf16 v[92:95], v[128:131], v[202:205], v[92:95]
	v_mfma_f32_16x16x32_bf16 v[88:91], v[152:155], v[202:205], v[88:91]
	v_mfma_f32_16x16x32_bf16 v[76:79], v[128:131], v[210:213], v[76:79]
	v_mfma_f32_16x16x32_bf16 v[72:75], v[152:155], v[210:213], v[72:75]
	s_waitcnt vmcnt(8)
	s_barrier
	v_mfma_f32_16x16x32_bf16 v[124:127], v[132:135], v[190:193], v[124:127]
	v_mfma_f32_16x16x32_bf16 v[120:123], v[156:159], v[190:193], v[120:123]
	v_mfma_f32_16x16x32_bf16 v[108:111], v[132:135], v[198:201], v[108:111]
	v_mfma_f32_16x16x32_bf16 v[104:107], v[156:159], v[198:201], v[104:107]
	v_mfma_f32_16x16x32_bf16 v[92:95], v[132:135], v[206:209], v[92:95]
	v_mfma_f32_16x16x32_bf16 v[88:91], v[156:159], v[206:209], v[88:91]
	v_mfma_f32_16x16x32_bf16 v[76:79], v[132:135], v[218:221], v[76:79]
	v_mfma_f32_16x16x32_bf16 v[72:75], v[156:159], v[218:221], v[72:75]
	s_setprio 0
	s_setprio 1
	v_mfma_f32_16x16x32_bf16 v[116:119], v[170:173], v[186:189], v[116:119]
	v_mfma_f32_16x16x32_bf16 v[112:115], v[178:181], v[186:189], v[112:115]
	v_mfma_f32_16x16x32_bf16 v[100:103], v[170:173], v[194:197], v[100:103]
	v_mfma_f32_16x16x32_bf16 v[96:99], v[178:181], v[194:197], v[96:99]
	v_mfma_f32_16x16x32_bf16 v[84:87], v[170:173], v[202:205], v[84:87]
	v_mfma_f32_16x16x32_bf16 v[80:83], v[178:181], v[202:205], v[80:83]
	v_mfma_f32_16x16x32_bf16 v[68:71], v[170:173], v[210:213], v[68:71]
	v_mfma_f32_16x16x32_bf16 v[64:67], v[178:181], v[210:213], v[64:67]
	v_mfma_f32_16x16x32_bf16 v[116:119], v[174:177], v[190:193], v[116:119]
	v_mfma_f32_16x16x32_bf16 v[112:115], v[182:185], v[190:193], v[112:115]
	v_mfma_f32_16x16x32_bf16 v[100:103], v[174:177], v[198:201], v[100:103]
	v_mfma_f32_16x16x32_bf16 v[96:99], v[182:185], v[198:201], v[96:99]
	v_mfma_f32_16x16x32_bf16 v[84:87], v[174:177], v[206:209], v[84:87]
	v_mfma_f32_16x16x32_bf16 v[80:83], v[182:185], v[206:209], v[80:83]
	v_mfma_f32_16x16x32_bf16 v[68:71], v[174:177], v[218:221], v[68:71]
	v_mfma_f32_16x16x32_bf16 v[64:67], v[182:185], v[218:221], v[64:67]
	s_setprio 0
	s_barrier
	s_add_i32 s45, s37, s4
	v_lshl_add_u64 v[160:161], s[26:27], 0, v[138:139]
	s_mov_b32 m0, s45
	ds_read_b128 v[186:189], v167 offset:16384
	ds_read_b128 v[190:193], v167 offset:17408
	ds_read_b128 v[194:197], v167 offset:18432
	ds_read_b128 v[198:201], v167 offset:19456
	ds_read_b128 v[202:205], v167 offset:20480
	ds_read_b128 v[206:209], v167 offset:21504
	ds_read_b128 v[210:213], v167 offset:22528
	ds_read_b128 v[218:221], v167 offset:23552
	global_load_lds_dwordx4 v[160:161], off
	s_add_i32 m0, s45, 0x2000
	s_add_u32 s46, s26, 0x40000
	v_lshl_add_u64 v[214:215], s[26:27], 0, v[142:143]
	s_addc_u32 s47, s27, 0
	s_add_i32 s45, s38, s4
	global_load_lds_dwordx4 v[214:215], off
	v_lshl_add_u64 v[222:223], s[46:47], 0, v[138:139]
	s_mov_b32 m0, s45
	v_lshl_add_u64 v[224:225], s[28:29], 0, v[140:141]
	global_load_lds_dwordx4 v[222:223], off
	v_lshl_add_u64 v[222:223], s[46:47], 0, v[142:143]
	s_add_i32 m0, s45, 0x2000
	s_nop 0
	global_load_lds_dwordx4 v[222:223], off
	v_lshl_add_u64 v[222:223], s[28:29], 0, v[136:137]
	s_mov_b32 m0, s5
	s_nop 0
	global_load_lds_dwordx4 v[222:223], off
	s_mov_b32 m0, s6
	s_nop 0
	global_load_lds_dwordx4 v[224:225], off
	s_waitcnt lgkmcnt(0)
	s_setprio 1
	s_waitcnt lgkmcnt(0)
	v_mfma_f32_16x16x32_bf16 v[60:63], v[128:131], v[186:189], v[60:63]
	v_mfma_f32_16x16x32_bf16 v[56:59], v[152:155], v[186:189], v[56:59]
	v_mfma_f32_16x16x32_bf16 v[44:47], v[128:131], v[194:197], v[44:47]
	v_mfma_f32_16x16x32_bf16 v[40:43], v[152:155], v[194:197], v[40:43]
	v_mfma_f32_16x16x32_bf16 v[28:31], v[128:131], v[202:205], v[28:31]
	v_mfma_f32_16x16x32_bf16 v[24:27], v[152:155], v[202:205], v[24:27]
	v_mfma_f32_16x16x32_bf16 v[12:15], v[128:131], v[210:213], v[12:15]
	v_mfma_f32_16x16x32_bf16 v[8:11], v[152:155], v[210:213], v[8:11]
	s_waitcnt vmcnt(8)
	s_barrier
; #define PG8_STAGE(bufoff, gbase, voff) do { _Pragma("unroll") for (int _i = 0; _i < 2; ++_i) \
;         __builtin_amdgcn_global_load_lds((const unsigned*)((const char*)(gbase) + (voff)[_i]), (PG8_LAS unsigned*)(lds + (bufoff) + ldsw + _i * 8192), 16, 0, 0); } while (0)
; #define PG8_LDA(dst, b, h) do { _Pragma("unroll") for (int m = 0; m < 4; ++m) _Pragma("unroll") for (int k = 0; k < 2; ++k) dst[m][k] = *(const PG8_LAS bf16x8*)(lds + PG8_SA(b, h) + aoff + m * 2048 + k * 1024); } while (0)
; #define PG8_LDB(dst, b, h) do { _Pragma("unroll") for (int n = 0; n < 2; ++n) _Pragma("unroll") for (int k = 0; k < 2; ++k) dst[n][k] = *(const PG8_LAS bf16x8*)(lds + PG8_SB(b, h) + boff + n * 2048 + k * 1024); } while (0)
; #define PG8_MMA(ai, bj, At, Bt) do { __builtin_amdgcn_s_setprio(1); _Pragma("unroll") for (int m = 0; m < 4; ++m) _Pragma("unroll") for (int n = 0; n < 2; ++n) _Pragma("unroll") for (int k = 0; k < 2; ++k) \
;         acc[ai][bj][m][n] = __builtin_amdgcn_mfma_f32_16x16x32_bf16(Bt[n][k], At[m][k], acc[ai][bj][m][n], 0, 0, 0); __builtin_amdgcn_s_setprio(0); } while (0)
; #define PG8_WAIT_V(n) asm volatile("s_waitcnt vmcnt(" #n ")" ::: "memory")
; #define PG8_WAIT_L(n) asm volatile("s_waitcnt lgkmcnt(" #n ")" ::: "memory")
; #define PG8_BAR __builtin_amdgcn_s_barrier()
; #define PG8_SCHED __builtin_amdgcn_sched_barrier(0)
; template <class Epi, class Sched, bool ALIGN_EPI = false, bool SP2 = false>
; __device__ __forceinline__ void gemm_phase(PG8_LAS unsigned char* lds, const Gemm g, const Sched& S, const Epi& E, int wave0) {
;     ...
;             PG8_LDB(B0, 1, 0); PG8_LDB(B1, 1, 1); PG8_SCHED; PG8_LDA(At, 1, 0); PG8_STAGE(PG8_SA(0, 1), a2 + hstep, voffA);
;             PG8_WAIT_V(8); PG8_WAIT_L(0); PG8_BAR; PG8_MMA(0, 0, At, B0); PG8_MMA(0, 1, At, B1); PG8_BAR; PG8_SCHED;
;             PG8_LDA(At, 1, 1); PG8_STAGE(PG8_SB(1, 0), b3, voffB); PG8_STAGE(PG8_SB(1, 1), b3 + hstep, voffB); PG8_STAGE(PG8_SA(1, 0), a3, voffA);
	v_mfma_f32_16x16x32_bf16 v[60:63], v[132:135], v[190:193], v[60:63]
	v_mfma_f32_16x16x32_bf16 v[56:59], v[156:159], v[190:193], v[56:59]
	v_mfma_f32_16x16x32_bf16 v[44:47], v[132:135], v[198:201], v[44:47]
	v_mfma_f32_16x16x32_bf16 v[40:43], v[156:159], v[198:201], v[40:43]
	v_mfma_f32_16x16x32_bf16 v[28:31], v[132:135], v[206:209], v[28:31]
	v_mfma_f32_16x16x32_bf16 v[24:27], v[156:159], v[206:209], v[24:27]
	v_mfma_f32_16x16x32_bf16 v[12:15], v[132:135], v[218:221], v[12:15]
	v_mfma_f32_16x16x32_bf16 v[8:11], v[156:159], v[218:221], v[8:11]
	s_setprio 0
	s_setprio 1
	v_mfma_f32_16x16x32_bf16 v[52:55], v[170:173], v[186:189], v[52:55]
	v_mfma_f32_16x16x32_bf16 v[48:51], v[178:181], v[186:189], v[48:51]
	v_mfma_f32_16x16x32_bf16 v[36:39], v[170:173], v[194:197], v[36:39]
	v_mfma_f32_16x16x32_bf16 v[32:35], v[178:181], v[194:197], v[32:35]
	v_mfma_f32_16x16x32_bf16 v[20:23], v[170:173], v[202:205], v[20:23]
	v_mfma_f32_16x16x32_bf16 v[16:19], v[178:181], v[202:205], v[16:19]
	v_mfma_f32_16x16x32_bf16 v[4:7], v[170:173], v[210:213], v[4:7]
	v_mfma_f32_16x16x32_bf16 v[0:3], v[178:181], v[210:213], v[0:3]
	v_mfma_f32_16x16x32_bf16 v[52:55], v[174:177], v[190:193], v[52:55]
	v_mfma_f32_16x16x32_bf16 v[48:51], v[182:185], v[190:193], v[48:51]
	v_mfma_f32_16x16x32_bf16 v[36:39], v[174:177], v[198:201], v[36:39]
	v_mfma_f32_16x16x32_bf16 v[32:35], v[182:185], v[198:201], v[32:35]
	v_mfma_f32_16x16x32_bf16 v[20:23], v[174:177], v[206:209], v[20:23]
	v_mfma_f32_16x16x32_bf16 v[16:19], v[182:185], v[206:209], v[16:19]
	v_mfma_f32_16x16x32_bf16 v[4:7], v[174:177], v[218:221], v[4:7]
	v_mfma_f32_16x16x32_bf16 v[0:3], v[182:185], v[218:221], v[0:3]
	s_setprio 0
	s_barrier
	s_add_i32 s45, 0, 0x18000
	s_add_i32 s46, 0, 0x1c000
	v_add_u32_e32 v156, s45, v164
	v_add_u32_e32 v169, s46, v164
	ds_read_b128 v[128:131], v156
	ds_read_b128 v[132:135], v156 offset:1024
	ds_read_b128 v[152:155], v156 offset:2048
	ds_read_b128 v[156:159], v156 offset:3072
	ds_read_b128 v[170:173], v169
	ds_read_b128 v[174:177], v169 offset:1024
	ds_read_b128 v[178:181], v169 offset:2048
	ds_read_b128 v[182:185], v169 offset:3072
	s_add_u32 s28, s28, 0x40000
	s_addc_u32 s29, s29, 0
	s_mov_b32 m0, s7
	v_lshl_add_u64 v[226:227], s[28:29], 0, v[136:137]
	ds_read_b128 v[186:189], v167 offset:32768
	ds_read_b128 v[190:193], v167 offset:33792
	ds_read_b128 v[194:197], v167 offset:34816
	ds_read_b128 v[198:201], v167 offset:35840
	ds_read_b128 v[202:205], v167 offset:36864
	ds_read_b128 v[206:209], v167 offset:37888
	ds_read_b128 v[210:213], v167 offset:38912
	ds_read_b128 v[218:221], v167 offset:39936
	global_load_lds_dwordx4 v[226:227], off
	v_lshl_add_u64 v[226:227], s[28:29], 0, v[140:141]
	s_mov_b32 m0, s30
	s_nop 0
	global_load_lds_dwordx4 v[226:227], off
	s_waitcnt lgkmcnt(0)
	s_setprio 1
	s_waitcnt lgkmcnt(0)
	v_mfma_f32_16x16x32_bf16 v[124:127], v[128:131], v[186:189], v[124:127]
	v_mfma_f32_16x16x32_bf16 v[120:123], v[152:155], v[186:189], v[120:123]
	v_mfma_f32_16x16x32_bf16 v[108:111], v[128:131], v[194:197], v[108:111]
	v_mfma_f32_16x16x32_bf16 v[104:107], v[152:155], v[194:197], v[104:107]
	v_mfma_f32_16x16x32_bf16 v[92:95], v[128:131], v[202:205], v[92:95]
	v_mfma_f32_16x16x32_bf16 v[88:91], v[152:155], v[202:205], v[88:91]
	v_mfma_f32_16x16x32_bf16 v[76:79], v[128:131], v[210:213], v[76:79]
	v_mfma_f32_16x16x32_bf16 v[72:75], v[152:155], v[210:213], v[72:75]
	s_waitcnt vmcnt(8)
	s_barrier
	v_mfma_f32_16x16x32_bf16 v[124:127], v[132:135], v[190:193], v[124:127]
	v_mfma_f32_16x16x32_bf16 v[120:123], v[156:159], v[190:193], v[120:123]
	v_mfma_f32_16x16x32_bf16 v[108:111], v[132:135], v[198:201], v[108:111]
	v_mfma_f32_16x16x32_bf16 v[104:107], v[156:159], v[198:201], v[104:107]
	v_mfma_f32_16x16x32_bf16 v[92:95], v[132:135], v[206:209], v[92:95]
	v_mfma_f32_16x16x32_bf16 v[88:91], v[156:159], v[206:209], v[88:91]
	v_mfma_f32_16x16x32_bf16 v[76:79], v[132:135], v[218:221], v[76:79]
	v_mfma_f32_16x16x32_bf16 v[72:75], v[156:159], v[218:221], v[72:75]
	s_setprio 0
	s_setprio 1
	v_mfma_f32_16x16x32_bf16 v[116:119], v[170:173], v[186:189], v[116:119]
	v_mfma_f32_16x16x32_bf16 v[112:115], v[178:181], v[186:189], v[112:115]
	v_mfma_f32_16x16x32_bf16 v[100:103], v[170:173], v[194:197], v[100:103]
	v_mfma_f32_16x16x32_bf16 v[96:99], v[178:181], v[194:197], v[96:99]
	v_mfma_f32_16x16x32_bf16 v[84:87], v[170:173], v[202:205], v[84:87]
	v_mfma_f32_16x16x32_bf16 v[80:83], v[178:181], v[202:205], v[80:83]
	v_mfma_f32_16x16x32_bf16 v[68:71], v[170:173], v[210:213], v[68:71]
	v_mfma_f32_16x16x32_bf16 v[64:67], v[178:181], v[210:213], v[64:67]
	v_mfma_f32_16x16x32_bf16 v[116:119], v[174:177], v[190:193], v[116:119]
	v_mfma_f32_16x16x32_bf16 v[112:115], v[182:185], v[190:193], v[112:115]
	v_mfma_f32_16x16x32_bf16 v[100:103], v[174:177], v[198:201], v[100:103]
	v_mfma_f32_16x16x32_bf16 v[96:99], v[182:185], v[198:201], v[96:99]
	v_mfma_f32_16x16x32_bf16 v[84:87], v[174:177], v[206:209], v[84:87]
	v_mfma_f32_16x16x32_bf16 v[80:83], v[182:185], v[206:209], v[80:83]
	v_mfma_f32_16x16x32_bf16 v[68:71], v[174:177], v[218:221], v[68:71]
	v_mfma_f32_16x16x32_bf16 v[64:67], v[182:185], v[218:221], v[64:67]
	s_setprio 0
	s_barrier
; #define PG8_STAGE(bufoff, gbase, voff) do { _Pragma("unroll") for (int _i = 0; _i < 2; ++_i) \
;         __builtin_amdgcn_global_load_lds((const unsigned*)((const char*)(gbase) + (voff)[_i]), (PG8_LAS unsigned*)(lds + (bufoff) + ldsw + _i * 8192), 16, 0, 0); } while (0)
; #define PG8_LDA(dst, b, h) do { _Pragma("unroll") for (int m = 0; m < 4; ++m) _Pragma("unroll") for (int k = 0; k < 2; ++k) dst[m][k] = *(const PG8_LAS bf16x8*)(lds + PG8_SA(b, h) + aoff + m * 2048 + k * 1024); } while (0)
; #define PG8_MMA(ai, bj, At, Bt) do { __builtin_amdgcn_s_setprio(1); _Pragma("unroll") for (int m = 0; m < 4; ++m) _Pragma("unroll") for (int n = 0; n < 2; ++n) _Pragma("unroll") for (int k = 0; k < 2; ++k) \
;         acc[ai][bj][m][n] = __builtin_amdgcn_mfma_f32_16x16x32_bf16(Bt[n][k], At[m][k], acc[ai][bj][m][n], 0, 0, 0); __builtin_amdgcn_s_setprio(0); } while (0)
; #define PG8_WAIT_V(n) asm volatile("s_waitcnt vmcnt(" #n ")" ::: "memory")
; #define PG8_WAIT_L(n) asm volatile("s_waitcnt lgkmcnt(" #n ")" ::: "memory")
; #define PG8_BAR __builtin_amdgcn_s_barrier()
; #define PG8_SCHED __builtin_amdgcn_sched_barrier(0)
; template <class Epi, class Sched, bool ALIGN_EPI = false, bool SP2 = false>
; __device__ __forceinline__ void gemm_phase(PG8_LAS unsigned char* lds, const Gemm g, const Sched& S, const Epi& E, int wave0) {
;     ...
;             PG8_LDA(At, 1, 1); PG8_STAGE(PG8_SB(1, 0), b3, voffB); PG8_STAGE(PG8_SB(1, 1), b3 + hstep, voffB); PG8_STAGE(PG8_SA(1, 0), a3, voffA);
;             PG8_WAIT_V(8); PG8_WAIT_L(0); PG8_BAR; if (!cur.half) { PG8_MMA(1, 0, At, B0); PG8_MMA(1, 1, At, B1); } PG8_BAR; PG8_SCHED;
;     ...
;         if constexpr (ALIGN_EPI) { if (wr == 0) PG8_BAR; }
	s_add_i32 s28, s45, s4
	v_lshl_add_u64 v[160:161], v[160:161], 0, s[10:11]
	s_mov_b32 m0, s28
	ds_read_b128 v[186:189], v167 offset:49152
	ds_read_b128 v[190:193], v167 offset:50176
	ds_read_b128 v[194:197], v167 offset:51200
	ds_read_b128 v[198:201], v167 offset:52224
	ds_read_b128 v[202:205], v167 offset:53248
	ds_read_b128 v[206:209], v167 offset:54272
	ds_read_b128 v[210:213], v167 offset:55296
	ds_read_b128 v[218:221], v167 offset:56320
	global_load_lds_dwordx4 v[160:161], off
	s_add_i32 m0, s28, 0x2000
	s_add_u32 s26, s26, 0x40080
	v_lshl_add_u64 v[160:161], v[214:215], 0, s[10:11]
	s_addc_u32 s27, s27, 0
	s_add_i32 s28, s46, s4
	global_load_lds_dwordx4 v[160:161], off
	v_lshl_add_u64 v[160:161], s[26:27], 0, v[138:139]
	s_mov_b32 m0, s28
	s_nop 0
	global_load_lds_dwordx4 v[160:161], off
	v_lshl_add_u64 v[160:161], s[26:27], 0, v[142:143]
	s_add_i32 m0, s28, 0x2000
	s_nop 0
	global_load_lds_dwordx4 v[160:161], off
	v_lshl_add_u64 v[160:161], v[222:223], 0, s[10:11]
	s_mov_b32 m0, s35
	s_nop 0
	global_load_lds_dwordx4 v[160:161], off
	v_lshl_add_u64 v[160:161], v[224:225], 0, s[10:11]
	s_mov_b32 m0, s36
	s_nop 0
	global_load_lds_dwordx4 v[160:161], off
	s_waitcnt lgkmcnt(0)
	s_setprio 1
	s_waitcnt lgkmcnt(0)
	v_mfma_f32_16x16x32_bf16 v[60:63], v[128:131], v[186:189], v[60:63]
	v_mfma_f32_16x16x32_bf16 v[56:59], v[152:155], v[186:189], v[56:59]
	v_mfma_f32_16x16x32_bf16 v[44:47], v[128:131], v[194:197], v[44:47]
	v_mfma_f32_16x16x32_bf16 v[40:43], v[152:155], v[194:197], v[40:43]
	v_mfma_f32_16x16x32_bf16 v[28:31], v[128:131], v[202:205], v[28:31]
	v_mfma_f32_16x16x32_bf16 v[24:27], v[152:155], v[202:205], v[24:27]
	v_mfma_f32_16x16x32_bf16 v[12:15], v[128:131], v[210:213], v[12:15]
	v_mfma_f32_16x16x32_bf16 v[8:11], v[152:155], v[210:213], v[8:11]
	s_waitcnt vmcnt(8)
	s_barrier
	v_mfma_f32_16x16x32_bf16 v[60:63], v[132:135], v[190:193], v[60:63]
	v_mfma_f32_16x16x32_bf16 v[56:59], v[156:159], v[190:193], v[56:59]
	v_mfma_f32_16x16x32_bf16 v[44:47], v[132:135], v[198:201], v[44:47]
	v_mfma_f32_16x16x32_bf16 v[40:43], v[156:159], v[198:201], v[40:43]
	v_mfma_f32_16x16x32_bf16 v[28:31], v[132:135], v[206:209], v[28:31]
	v_mfma_f32_16x16x32_bf16 v[24:27], v[156:159], v[206:209], v[24:27]
	v_mfma_f32_16x16x32_bf16 v[12:15], v[132:135], v[218:221], v[12:15]
	v_mfma_f32_16x16x32_bf16 v[8:11], v[156:159], v[218:221], v[8:11]
	s_setprio 0
	s_setprio 1
	v_mfma_f32_16x16x32_bf16 v[52:55], v[170:173], v[186:189], v[52:55]
	v_mfma_f32_16x16x32_bf16 v[48:51], v[178:181], v[186:189], v[48:51]
	v_mfma_f32_16x16x32_bf16 v[36:39], v[170:173], v[194:197], v[36:39]
	v_mfma_f32_16x16x32_bf16 v[32:35], v[178:181], v[194:197], v[32:35]
	v_mfma_f32_16x16x32_bf16 v[20:23], v[170:173], v[202:205], v[20:23]
	v_mfma_f32_16x16x32_bf16 v[16:19], v[178:181], v[202:205], v[16:19]
	v_mfma_f32_16x16x32_bf16 v[4:7], v[170:173], v[210:213], v[4:7]
	v_mfma_f32_16x16x32_bf16 v[0:3], v[178:181], v[210:213], v[0:3]
	v_mfma_f32_16x16x32_bf16 v[52:55], v[174:177], v[190:193], v[52:55]
	v_mfma_f32_16x16x32_bf16 v[48:51], v[182:185], v[190:193], v[48:51]
	v_mfma_f32_16x16x32_bf16 v[36:39], v[174:177], v[198:201], v[36:39]
	v_mfma_f32_16x16x32_bf16 v[32:35], v[182:185], v[198:201], v[32:35]
	v_mfma_f32_16x16x32_bf16 v[20:23], v[174:177], v[206:209], v[20:23]
	v_mfma_f32_16x16x32_bf16 v[16:19], v[182:185], v[206:209], v[16:19]
	v_mfma_f32_16x16x32_bf16 v[4:7], v[174:177], v[218:221], v[4:7]
	v_mfma_f32_16x16x32_bf16 v[0:3], v[182:185], v[218:221], v[0:3]
	s_setprio 0
	s_barrier
	s_add_i32 s44, s44, 2
	s_add_u32 s24, s24, 0x100
	s_addc_u32 s25, s25, 0
	s_add_u32 s42, s42, 0x100
	s_addc_u32 s43, s43, 0
	s_cmp_gt_u32 s44, 13
	s_cbranch_scc0 .LBB0_2493
	s_and_b64 vcc, exec, s[14:15]
	s_cbranch_vccz .LBB0_2496
	s_barrier

; #define PG8_STAGE(bufoff, gbase, voff) do { _Pragma("unroll") for (int _i = 0; _i < 2; ++_i) \
;         __builtin_amdgcn_global_load_lds((const unsigned*)((const char*)(gbase) + (voff)[_i]), (PG8_LAS unsigned*)(lds + (bufoff) + ldsw + _i * 8192), 16, 0, 0); } while (0)
; #define PG8_LDA(dst, b, h) do { _Pragma("unroll") for (int m = 0; m < 4; ++m) _Pragma("unroll") for (int k = 0; k < 2; ++k) dst[m][k] = *(const PG8_LAS bf16x8*)(lds + PG8_SA(b, h) + aoff + m * 2048 + k * 1024); } while (0)
; #define PG8_WAIT_V(n) asm volatile("s_waitcnt vmcnt(" #n ")" ::: "memory")
; #define PG8_WAIT_L(n) asm volatile("s_waitcnt lgkmcnt(" #n ")" ::: "memory")
; template <class Epi, class Sched, bool ALIGN_EPI = false, bool SP2 = false>
; __device__ __forceinline__ void gemm_phase(PG8_LAS unsigned char* lds, const Gemm g, const Sched& S, const Epi& E, int wave0) {
;     ...
;         for (int t = 0; t < nt; t += 2) {
;             const bool last = (t == nt - 2);
;             const char* a1 = cA + (size_t)(t + 1) * kstep;
;             const char* a2 = last ? nA : cA + (size_t)(t + 2) * kstep; const char* b2 = last ? nB : cB + (size_t)(t + 2) * kstep;
;             const char* a3 = a2 + kstep; const char* b3 = b2 + kstep;
;             if (last && has_next) S.a_ready(nxt);
;             if constexpr (SP2) {
;             PG8_LDB(B0, 0, 0); PG8_LDB(B1, 0, 1); PG8_SCHED; PG8_LDA(At, 0, 0); PG8_STAGE(PG8_SA(1, 1), a1 + hstep, voffA);
;             PG8_WAIT_V(8); PG8_WAIT_L(0); PG8_BAR; PG8_MMA(0, 0, At, B0); PG8_MMA(0, 1, At, B1); PG8_BAR; PG8_SCHED;
;             PG8_LDA(At, 0, 1); PG8_STAGE(PG8_SB(0, 0), b2, voffB); PG8_STAGE(PG8_SB(0, 1), b2 + hstep, voffB); PG8_STAGE(PG8_SA(0, 0), a2, voffA);
;             PG8_WAIT_V(8); PG8_WAIT_L(0); PG8_BAR; if (!cur.half) { PG8_MMA(1, 0, At, B0); PG8_MMA(1, 1, At, B1); } PG8_BAR; PG8_SCHED;
;             PG8_LDB(B0, 1, 0); PG8_LDB(B1, 1, 1); PG8_SCHED; PG8_LDA(At, 1, 0); PG8_STAGE(PG8_SA(0, 1), a2 + hstep, voffA);
;             PG8_WAIT_V(8); PG8_WAIT_L(0); PG8_BAR; PG8_MMA(0, 0, At, B0); PG8_MMA(0, 1, At, B1); PG8_BAR; PG8_SCHED;
;             PG8_LDA(At, 1, 1); PG8_STAGE(PG8_SB(1, 0), b3, voffB); PG8_STAGE(PG8_SB(1, 1), b3 + hstep, voffB); PG8_STAGE(PG8_SA(1, 0), a3, voffA);
;             PG8_WAIT_V(8); PG8_WAIT_L(0); PG8_BAR; if (!cur.half) { PG8_MMA(1, 0, At, B0); PG8_MMA(1, 1, At, B1); } PG8_BAR; PG8_SCHED;
.LBB0_2610:
	ds_read_b128 v[144:147], v169
	ds_read_b128 v[148:151], v169 offset:1024
	ds_read_b128 v[152:155], v169 offset:2048
	ds_read_b128 v[156:159], v169 offset:3072
	ds_read_b128 v[160:163], v170
	ds_read_b128 v[174:177], v170 offset:1024
	ds_read_b128 v[178:181], v170 offset:2048
	ds_read_b128 v[182:185], v170 offset:3072
	s_add_u32 s48, s46, 0xfffc0080
	s_addc_u32 s49, s47, -1
	s_cmp_eq_u32 s62, 12
	s_cselect_b32 s51, s3, s49
	s_cselect_b32 s50, s11, s48
	s_cselect_b32 s49, s39, s57
	s_cselect_b32 s48, s41, s56
	v_lshl_add_u64 v[164:165], s[46:47], 0, v[136:137]
	s_add_i32 m0, s5, 0xc000
	ds_read_b128 v[186:189], v171
	ds_read_b128 v[190:193], v171 offset:1024
	ds_read_b128 v[194:197], v171 offset:2048
	ds_read_b128 v[198:201], v171 offset:3072
	ds_read_b128 v[202:205], v171 offset:4096
	ds_read_b128 v[206:209], v171 offset:5120
	ds_read_b128 v[210:213], v171 offset:6144
	ds_read_b128 v[218:221], v171 offset:7168
	global_load_lds_dwordx4 v[164:165], off
	v_lshl_add_u64 v[164:165], s[46:47], 0, v[138:139]
	s_add_i32 m0, s5, 0xe000
	s_nop 0
	global_load_lds_dwordx4 v[164:165], off
	s_waitcnt lgkmcnt(0)
	s_setprio 1
	s_waitcnt lgkmcnt(0)
	v_mfma_f32_16x16x32_bf16 v[124:127], v[144:147], v[186:189], v[124:127]
	v_mfma_f32_16x16x32_bf16 v[120:123], v[152:155], v[186:189], v[120:123]
	v_mfma_f32_16x16x32_bf16 v[108:111], v[144:147], v[194:197], v[108:111]
	v_mfma_f32_16x16x32_bf16 v[104:107], v[152:155], v[194:197], v[104:107]
	v_mfma_f32_16x16x32_bf16 v[92:95], v[144:147], v[202:205], v[92:95]
	v_mfma_f32_16x16x32_bf16 v[88:91], v[152:155], v[202:205], v[88:91]
	v_mfma_f32_16x16x32_bf16 v[76:79], v[144:147], v[210:213], v[76:79]
	v_mfma_f32_16x16x32_bf16 v[72:75], v[152:155], v[210:213], v[72:75]
	s_waitcnt vmcnt(8)
	s_barrier
	v_mfma_f32_16x16x32_bf16 v[124:127], v[148:151], v[190:193], v[124:127]
	v_mfma_f32_16x16x32_bf16 v[120:123], v[156:159], v[190:193], v[120:123]
	v_mfma_f32_16x16x32_bf16 v[108:111], v[148:151], v[198:201], v[108:111]
	v_mfma_f32_16x16x32_bf16 v[104:107], v[156:159], v[198:201], v[104:107]
	v_mfma_f32_16x16x32_bf16 v[92:95], v[148:151], v[206:209], v[92:95]
	v_mfma_f32_16x16x32_bf16 v[88:91], v[156:159], v[206:209], v[88:91]
	v_mfma_f32_16x16x32_bf16 v[76:79], v[148:151], v[218:221], v[76:79]
	v_mfma_f32_16x16x32_bf16 v[72:75], v[156:159], v[218:221], v[72:75]
	s_setprio 0
	s_setprio 1
	v_mfma_f32_16x16x32_bf16 v[116:119], v[160:163], v[186:189], v[116:119]
	v_mfma_f32_16x16x32_bf16 v[112:115], v[178:181], v[186:189], v[112:115]
	v_mfma_f32_16x16x32_bf16 v[100:103], v[160:163], v[194:197], v[100:103]
	v_mfma_f32_16x16x32_bf16 v[96:99], v[178:181], v[194:197], v[96:99]
	v_mfma_f32_16x16x32_bf16 v[84:87], v[160:163], v[202:205], v[84:87]
	v_mfma_f32_16x16x32_bf16 v[80:83], v[178:181], v[202:205], v[80:83]
	v_mfma_f32_16x16x32_bf16 v[68:71], v[160:163], v[210:213], v[68:71]
	v_mfma_f32_16x16x32_bf16 v[64:67], v[178:181], v[210:213], v[64:67]
	v_mfma_f32_16x16x32_bf16 v[116:119], v[174:177], v[190:193], v[116:119]
	v_mfma_f32_16x16x32_bf16 v[112:115], v[182:185], v[190:193], v[112:115]
	v_mfma_f32_16x16x32_bf16 v[100:103], v[174:177], v[198:201], v[100:103]
	v_mfma_f32_16x16x32_bf16 v[96:99], v[182:185], v[198:201], v[96:99]
	v_mfma_f32_16x16x32_bf16 v[84:87], v[174:177], v[206:209], v[84:87]
	v_mfma_f32_16x16x32_bf16 v[80:83], v[182:185], v[206:209], v[80:83]
	v_mfma_f32_16x16x32_bf16 v[68:71], v[174:177], v[218:221], v[68:71]
	v_mfma_f32_16x16x32_bf16 v[64:67], v[182:185], v[218:221], v[64:67]
	s_setprio 0
	s_barrier
	s_add_i32 s63, s35, s4
	v_lshl_add_u64 v[164:165], s[48:49], 0, v[130:131]
	s_mov_b32 m0, s63
	ds_read_b128 v[186:189], v171 offset:16384
	ds_read_b128 v[190:193], v171 offset:17408
	ds_read_b128 v[194:197], v171 offset:18432
	ds_read_b128 v[198:201], v171 offset:19456
	ds_read_b128 v[202:205], v171 offset:20480
	ds_read_b128 v[206:209], v171 offset:21504
	ds_read_b128 v[210:213], v171 offset:22528
	ds_read_b128 v[218:221], v171 offset:23552
	global_load_lds_dwordx4 v[164:165], off
	s_add_i32 m0, s63, 0x2000
	s_add_u32 s68, s48, 0x40000
	v_lshl_add_u64 v[214:215], s[48:49], 0, v[134:135]
	s_addc_u32 s69, s49, 0
	s_add_i32 s63, s37, s4
	global_load_lds_dwordx4 v[214:215], off
	v_lshl_add_u64 v[222:223], s[68:69], 0, v[130:131]
	s_mov_b32 m0, s63
	v_lshl_add_u64 v[224:225], s[50:51], 0, v[132:133]
	global_load_lds_dwordx4 v[222:223], off
	v_lshl_add_u64 v[222:223], s[68:69], 0, v[134:135]
	s_add_i32 m0, s63, 0x2000
	s_nop 0
	global_load_lds_dwordx4 v[222:223], off
	v_lshl_add_u64 v[222:223], s[50:51], 0, v[128:129]
	s_mov_b32 m0, s5
	s_nop 0
	global_load_lds_dwordx4 v[222:223], off
	s_mov_b32 m0, s19
	s_nop 0
	global_load_lds_dwordx4 v[224:225], off
	s_waitcnt lgkmcnt(0)
	s_setprio 1
	s_waitcnt lgkmcnt(0)
	v_mfma_f32_16x16x32_bf16 v[60:63], v[144:147], v[186:189], v[60:63]
	v_mfma_f32_16x16x32_bf16 v[56:59], v[152:155], v[186:189], v[56:59]
	v_mfma_f32_16x16x32_bf16 v[44:47], v[144:147], v[194:197], v[44:47]
	v_mfma_f32_16x16x32_bf16 v[40:43], v[152:155], v[194:197], v[40:43]
	v_mfma_f32_16x16x32_bf16 v[28:31], v[144:147], v[202:205], v[28:31]
	v_mfma_f32_16x16x32_bf16 v[24:27], v[152:155], v[202:205], v[24:27]
	v_mfma_f32_16x16x32_bf16 v[12:15], v[144:147], v[210:213], v[12:15]
	v_mfma_f32_16x16x32_bf16 v[8:11], v[152:155], v[210:213], v[8:11]
	s_waitcnt vmcnt(8)
	s_barrier
; #define PG8_STAGE(bufoff, gbase, voff) do { _Pragma("unroll") for (int _i = 0; _i < 2; ++_i) \
;         __builtin_amdgcn_global_load_lds((const unsigned*)((const char*)(gbase) + (voff)[_i]), (PG8_LAS unsigned*)(lds + (bufoff) + ldsw + _i * 8192), 16, 0, 0); } while (0)
; #define PG8_LDA(dst, b, h) do { _Pragma("unroll") for (int m = 0; m < 4; ++m) _Pragma("unroll") for (int k = 0; k < 2; ++k) dst[m][k] = *(const PG8_LAS bf16x8*)(lds + PG8_SA(b, h) + aoff + m * 2048 + k * 1024); } while (0)
; #define PG8_LDB(dst, b, h) do { _Pragma("unroll") for (int n = 0; n < 2; ++n) _Pragma("unroll") for (int k = 0; k < 2; ++k) dst[n][k] = *(const PG8_LAS bf16x8*)(lds + PG8_SB(b, h) + boff + n * 2048 + k * 1024); } while (0)
; #define PG8_MMA(ai, bj, At, Bt) do { __builtin_amdgcn_s_setprio(1); _Pragma("unroll") for (int m = 0; m < 4; ++m) _Pragma("unroll") for (int n = 0; n < 2; ++n) _Pragma("unroll") for (int k = 0; k < 2; ++k) \
;         acc[ai][bj][m][n] = __builtin_amdgcn_mfma_f32_16x16x32_bf16(Bt[n][k], At[m][k], acc[ai][bj][m][n], 0, 0, 0); __builtin_amdgcn_s_setprio(0); } while (0)
; #define PG8_WAIT_V(n) asm volatile("s_waitcnt vmcnt(" #n ")" ::: "memory")
; #define PG8_WAIT_L(n) asm volatile("s_waitcnt lgkmcnt(" #n ")" ::: "memory")
; #define PG8_BAR __builtin_amdgcn_s_barrier()
; #define PG8_SCHED __builtin_amdgcn_sched_barrier(0)
; template <class Epi, class Sched, bool ALIGN_EPI = false, bool SP2 = false>
; __device__ __forceinline__ void gemm_phase(PG8_LAS unsigned char* lds, const Gemm g, const Sched& S, const Epi& E, int wave0) {
;     ...
;             PG8_LDB(B0, 1, 0); PG8_LDB(B1, 1, 1); PG8_SCHED; PG8_LDA(At, 1, 0); PG8_STAGE(PG8_SA(0, 1), a2 + hstep, voffA);
;             PG8_WAIT_V(8); PG8_WAIT_L(0); PG8_BAR; PG8_MMA(0, 0, At, B0); PG8_MMA(0, 1, At, B1); PG8_BAR; PG8_SCHED;
;             PG8_LDA(At, 1, 1); PG8_STAGE(PG8_SB(1, 0), b3, voffB); PG8_STAGE(PG8_SB(1, 1), b3 + hstep, voffB); PG8_STAGE(PG8_SA(1, 0), a3, voffA);
	v_mfma_f32_16x16x32_bf16 v[60:63], v[148:151], v[190:193], v[60:63]
	v_mfma_f32_16x16x32_bf16 v[56:59], v[156:159], v[190:193], v[56:59]
	v_mfma_f32_16x16x32_bf16 v[44:47], v[148:151], v[198:201], v[44:47]
	v_mfma_f32_16x16x32_bf16 v[40:43], v[156:159], v[198:201], v[40:43]
	v_mfma_f32_16x16x32_bf16 v[28:31], v[148:151], v[206:209], v[28:31]
	v_mfma_f32_16x16x32_bf16 v[24:27], v[156:159], v[206:209], v[24:27]
	v_mfma_f32_16x16x32_bf16 v[12:15], v[148:151], v[218:221], v[12:15]
	v_mfma_f32_16x16x32_bf16 v[8:11], v[156:159], v[218:221], v[8:11]
	s_setprio 0
	s_setprio 1
	v_mfma_f32_16x16x32_bf16 v[52:55], v[160:163], v[186:189], v[52:55]
	v_mfma_f32_16x16x32_bf16 v[48:51], v[178:181], v[186:189], v[48:51]
	v_mfma_f32_16x16x32_bf16 v[36:39], v[160:163], v[194:197], v[36:39]
	v_mfma_f32_16x16x32_bf16 v[32:35], v[178:181], v[194:197], v[32:35]
	v_mfma_f32_16x16x32_bf16 v[20:23], v[160:163], v[202:205], v[20:23]
	v_mfma_f32_16x16x32_bf16 v[16:19], v[178:181], v[202:205], v[16:19]
	v_mfma_f32_16x16x32_bf16 v[4:7], v[160:163], v[210:213], v[4:7]
	v_mfma_f32_16x16x32_bf16 v[0:3], v[178:181], v[210:213], v[0:3]
	v_mfma_f32_16x16x32_bf16 v[52:55], v[174:177], v[190:193], v[52:55]
	v_mfma_f32_16x16x32_bf16 v[48:51], v[182:185], v[190:193], v[48:51]
	v_mfma_f32_16x16x32_bf16 v[36:39], v[174:177], v[198:201], v[36:39]
	v_mfma_f32_16x16x32_bf16 v[32:35], v[182:185], v[198:201], v[32:35]
	v_mfma_f32_16x16x32_bf16 v[20:23], v[174:177], v[206:209], v[20:23]
	v_mfma_f32_16x16x32_bf16 v[16:19], v[182:185], v[206:209], v[16:19]
	v_mfma_f32_16x16x32_bf16 v[4:7], v[174:177], v[218:221], v[4:7]
	v_mfma_f32_16x16x32_bf16 v[0:3], v[182:185], v[218:221], v[0:3]
	s_setprio 0
	s_barrier
	s_add_i32 s63, 0, 0x18000
	s_add_i32 s68, 0, 0x1c000
	v_add_u32_e32 v156, s63, v168
	v_add_u32_e32 v182, s68, v168
	ds_read_b128 v[144:147], v156
	ds_read_b128 v[148:151], v156 offset:1024
	ds_read_b128 v[152:155], v156 offset:2048
	ds_read_b128 v[156:159], v156 offset:3072
	ds_read_b128 v[160:163], v182
	ds_read_b128 v[174:177], v182 offset:1024
	ds_read_b128 v[178:181], v182 offset:2048
	ds_read_b128 v[182:185], v182 offset:3072
	s_add_u32 s50, s50, 0x40000
	s_addc_u32 s51, s51, 0
	s_mov_b32 m0, s21
	v_lshl_add_u64 v[226:227], s[50:51], 0, v[128:129]
	ds_read_b128 v[186:189], v171 offset:32768
	ds_read_b128 v[190:193], v171 offset:33792
	ds_read_b128 v[194:197], v171 offset:34816
	ds_read_b128 v[198:201], v171 offset:35840
	ds_read_b128 v[202:205], v171 offset:36864
	ds_read_b128 v[206:209], v171 offset:37888
	ds_read_b128 v[210:213], v171 offset:38912
	ds_read_b128 v[218:221], v171 offset:39936
	global_load_lds_dwordx4 v[226:227], off
	v_lshl_add_u64 v[226:227], s[50:51], 0, v[132:133]
	s_mov_b32 m0, s23
	s_nop 0
	global_load_lds_dwordx4 v[226:227], off
	s_waitcnt lgkmcnt(0)
	s_setprio 1
	s_waitcnt lgkmcnt(0)
	v_mfma_f32_16x16x32_bf16 v[124:127], v[144:147], v[186:189], v[124:127]
	v_mfma_f32_16x16x32_bf16 v[120:123], v[152:155], v[186:189], v[120:123]
	v_mfma_f32_16x16x32_bf16 v[108:111], v[144:147], v[194:197], v[108:111]
	v_mfma_f32_16x16x32_bf16 v[104:107], v[152:155], v[194:197], v[104:107]
	v_mfma_f32_16x16x32_bf16 v[92:95], v[144:147], v[202:205], v[92:95]
	v_mfma_f32_16x16x32_bf16 v[88:91], v[152:155], v[202:205], v[88:91]
	v_mfma_f32_16x16x32_bf16 v[76:79], v[144:147], v[210:213], v[76:79]
	v_mfma_f32_16x16x32_bf16 v[72:75], v[152:155], v[210:213], v[72:75]
	s_waitcnt vmcnt(8)
	s_barrier
	v_mfma_f32_16x16x32_bf16 v[124:127], v[148:151], v[190:193], v[124:127]
	v_mfma_f32_16x16x32_bf16 v[120:123], v[156:159], v[190:193], v[120:123]
	v_mfma_f32_16x16x32_bf16 v[108:111], v[148:151], v[198:201], v[108:111]
	v_mfma_f32_16x16x32_bf16 v[104:107], v[156:159], v[198:201], v[104:107]
	v_mfma_f32_16x16x32_bf16 v[92:95], v[148:151], v[206:209], v[92:95]
	v_mfma_f32_16x16x32_bf16 v[88:91], v[156:159], v[206:209], v[88:91]
	v_mfma_f32_16x16x32_bf16 v[76:79], v[148:151], v[218:221], v[76:79]
	v_mfma_f32_16x16x32_bf16 v[72:75], v[156:159], v[218:221], v[72:75]
	s_setprio 0
	s_setprio 1
	v_mfma_f32_16x16x32_bf16 v[116:119], v[160:163], v[186:189], v[116:119]
	v_mfma_f32_16x16x32_bf16 v[112:115], v[178:181], v[186:189], v[112:115]
	v_mfma_f32_16x16x32_bf16 v[100:103], v[160:163], v[194:197], v[100:103]
	v_mfma_f32_16x16x32_bf16 v[96:99], v[178:181], v[194:197], v[96:99]
	v_mfma_f32_16x16x32_bf16 v[84:87], v[160:163], v[202:205], v[84:87]
	v_mfma_f32_16x16x32_bf16 v[80:83], v[178:181], v[202:205], v[80:83]
	v_mfma_f32_16x16x32_bf16 v[68:71], v[160:163], v[210:213], v[68:71]
	v_mfma_f32_16x16x32_bf16 v[64:67], v[178:181], v[210:213], v[64:67]
	v_mfma_f32_16x16x32_bf16 v[116:119], v[174:177], v[190:193], v[116:119]
	v_mfma_f32_16x16x32_bf16 v[112:115], v[182:185], v[190:193], v[112:115]
	v_mfma_f32_16x16x32_bf16 v[100:103], v[174:177], v[198:201], v[100:103]
	v_mfma_f32_16x16x32_bf16 v[96:99], v[182:185], v[198:201], v[96:99]
	v_mfma_f32_16x16x32_bf16 v[84:87], v[174:177], v[206:209], v[84:87]
	v_mfma_f32_16x16x32_bf16 v[80:83], v[182:185], v[206:209], v[80:83]
	v_mfma_f32_16x16x32_bf16 v[68:71], v[174:177], v[218:221], v[68:71]
	v_mfma_f32_16x16x32_bf16 v[64:67], v[182:185], v[218:221], v[64:67]
	s_setprio 0
	s_barrier
; #define PG8_STAGE(bufoff, gbase, voff) do { _Pragma("unroll") for (int _i = 0; _i < 2; ++_i) \
;         __builtin_amdgcn_global_load_lds((const unsigned*)((const char*)(gbase) + (voff)[_i]), (PG8_LAS unsigned*)(lds + (bufoff) + ldsw + _i * 8192), 16, 0, 0); } while (0)
; #define PG8_LDA(dst, b, h) do { _Pragma("unroll") for (int m = 0; m < 4; ++m) _Pragma("unroll") for (int k = 0; k < 2; ++k) dst[m][k] = *(const PG8_LAS bf16x8*)(lds + PG8_SA(b, h) + aoff + m * 2048 + k * 1024); } while (0)
; #define PG8_MMA(ai, bj, At, Bt) do { __builtin_amdgcn_s_setprio(1); _Pragma("unroll") for (int m = 0; m < 4; ++m) _Pragma("unroll") for (int n = 0; n < 2; ++n) _Pragma("unroll") for (int k = 0; k < 2; ++k) \
;         acc[ai][bj][m][n] = __builtin_amdgcn_mfma_f32_16x16x32_bf16(Bt[n][k], At[m][k], acc[ai][bj][m][n], 0, 0, 0); __builtin_amdgcn_s_setprio(0); } while (0)
; #define PG8_WAIT_V(n) asm volatile("s_waitcnt vmcnt(" #n ")" ::: "memory")
; #define PG8_WAIT_L(n) asm volatile("s_waitcnt lgkmcnt(" #n ")" ::: "memory")
; #define PG8_BAR __builtin_amdgcn_s_barrier()
; #define PG8_SCHED __builtin_amdgcn_sched_barrier(0)
; template <class Epi, class Sched, bool ALIGN_EPI = false, bool SP2 = false>
; __device__ __forceinline__ void gemm_phase(PG8_LAS unsigned char* lds, const Gemm g, const Sched& S, const Epi& E, int wave0) {
;     ...
;             PG8_LDA(At, 1, 1); PG8_STAGE(PG8_SB(1, 0), b3, voffB); PG8_STAGE(PG8_SB(1, 1), b3 + hstep, voffB); PG8_STAGE(PG8_SA(1, 0), a3, voffA);
;             PG8_WAIT_V(8); PG8_WAIT_L(0); PG8_BAR; if (!cur.half) { PG8_MMA(1, 0, At, B0); PG8_MMA(1, 1, At, B1); } PG8_BAR; PG8_SCHED;
;     ...
;         if constexpr (ALIGN_EPI) { if (wr == 0) PG8_BAR; }
	s_add_i32 s50, s63, s4
	v_lshl_add_u64 v[164:165], v[164:165], 0, s[14:15]
	s_mov_b32 m0, s50
	ds_read_b128 v[186:189], v171 offset:49152
	ds_read_b128 v[190:193], v171 offset:50176
	ds_read_b128 v[194:197], v171 offset:51200
	ds_read_b128 v[198:201], v171 offset:52224
	ds_read_b128 v[202:205], v171 offset:53248
	ds_read_b128 v[206:209], v171 offset:54272
	ds_read_b128 v[210:213], v171 offset:55296
	ds_read_b128 v[218:221], v171 offset:56320
	global_load_lds_dwordx4 v[164:165], off
	s_add_i32 m0, s50, 0x2000
	s_add_u32 s48, s48, 0x40080
	v_lshl_add_u64 v[164:165], v[214:215], 0, s[14:15]
	s_addc_u32 s49, s49, 0
	s_add_i32 s50, s68, s4
	global_load_lds_dwordx4 v[164:165], off
	v_lshl_add_u64 v[164:165], s[48:49], 0, v[130:131]
	s_mov_b32 m0, s50
	s_nop 0
	global_load_lds_dwordx4 v[164:165], off
	v_lshl_add_u64 v[164:165], s[48:49], 0, v[134:135]
	s_add_i32 m0, s50, 0x2000
	s_nop 0
	global_load_lds_dwordx4 v[164:165], off
	v_lshl_add_u64 v[164:165], v[222:223], 0, s[14:15]
	s_mov_b32 m0, s31
	s_nop 0
	global_load_lds_dwordx4 v[164:165], off
	v_lshl_add_u64 v[164:165], v[224:225], 0, s[14:15]
	s_mov_b32 m0, s33
	s_nop 0
	global_load_lds_dwordx4 v[164:165], off
	s_waitcnt lgkmcnt(0)
	s_setprio 1
	s_waitcnt lgkmcnt(0)
	v_mfma_f32_16x16x32_bf16 v[60:63], v[144:147], v[186:189], v[60:63]
	v_mfma_f32_16x16x32_bf16 v[56:59], v[152:155], v[186:189], v[56:59]
	v_mfma_f32_16x16x32_bf16 v[44:47], v[144:147], v[194:197], v[44:47]
	v_mfma_f32_16x16x32_bf16 v[40:43], v[152:155], v[194:197], v[40:43]
	v_mfma_f32_16x16x32_bf16 v[28:31], v[144:147], v[202:205], v[28:31]
	v_mfma_f32_16x16x32_bf16 v[24:27], v[152:155], v[202:205], v[24:27]
	v_mfma_f32_16x16x32_bf16 v[12:15], v[144:147], v[210:213], v[12:15]
	v_mfma_f32_16x16x32_bf16 v[8:11], v[152:155], v[210:213], v[8:11]
	s_waitcnt vmcnt(8)
	s_barrier
	v_mfma_f32_16x16x32_bf16 v[60:63], v[148:151], v[190:193], v[60:63]
	v_mfma_f32_16x16x32_bf16 v[56:59], v[156:159], v[190:193], v[56:59]
	v_mfma_f32_16x16x32_bf16 v[44:47], v[148:151], v[198:201], v[44:47]
	v_mfma_f32_16x16x32_bf16 v[40:43], v[156:159], v[198:201], v[40:43]
	v_mfma_f32_16x16x32_bf16 v[28:31], v[148:151], v[206:209], v[28:31]
	v_mfma_f32_16x16x32_bf16 v[24:27], v[156:159], v[206:209], v[24:27]
	v_mfma_f32_16x16x32_bf16 v[12:15], v[148:151], v[218:221], v[12:15]
	v_mfma_f32_16x16x32_bf16 v[8:11], v[156:159], v[218:221], v[8:11]
	s_setprio 0
	s_setprio 1
	v_mfma_f32_16x16x32_bf16 v[52:55], v[160:163], v[186:189], v[52:55]
	v_mfma_f32_16x16x32_bf16 v[48:51], v[178:181], v[186:189], v[48:51]
	v_mfma_f32_16x16x32_bf16 v[36:39], v[160:163], v[194:197], v[36:39]
	v_mfma_f32_16x16x32_bf16 v[32:35], v[178:181], v[194:197], v[32:35]
	v_mfma_f32_16x16x32_bf16 v[20:23], v[160:163], v[202:205], v[20:23]
	v_mfma_f32_16x16x32_bf16 v[16:19], v[178:181], v[202:205], v[16:19]
	v_mfma_f32_16x16x32_bf16 v[4:7], v[160:163], v[210:213], v[4:7]
	v_mfma_f32_16x16x32_bf16 v[0:3], v[178:181], v[210:213], v[0:3]
	v_mfma_f32_16x16x32_bf16 v[52:55], v[174:177], v[190:193], v[52:55]
	v_mfma_f32_16x16x32_bf16 v[48:51], v[182:185], v[190:193], v[48:51]
	v_mfma_f32_16x16x32_bf16 v[36:39], v[174:177], v[198:201], v[36:39]
	v_mfma_f32_16x16x32_bf16 v[32:35], v[182:185], v[198:201], v[32:35]
	v_mfma_f32_16x16x32_bf16 v[20:23], v[174:177], v[206:209], v[20:23]
	v_mfma_f32_16x16x32_bf16 v[16:19], v[182:185], v[206:209], v[16:19]
	v_mfma_f32_16x16x32_bf16 v[4:7], v[174:177], v[218:221], v[4:7]
	v_mfma_f32_16x16x32_bf16 v[0:3], v[182:185], v[218:221], v[0:3]
	s_setprio 0
	s_barrier
	s_add_i32 s62, s62, 2
	s_add_u32 s46, s46, 0x100
	s_addc_u32 s47, s47, 0
	s_add_u32 s56, s56, 0x100
	s_addc_u32 s57, s57, 0
	s_cmp_gt_u32 s62, 13
	s_cbranch_scc0 .LBB0_2610
	s_and_b64 vcc, exec, s[16:17]
	s_cbranch_vccz .LBB0_2613
	s_barrier

; #define PG8_STAGE(bufoff, gbase, voff) do { _Pragma("unroll") for (int _i = 0; _i < 2; ++_i) \
;         __builtin_amdgcn_global_load_lds((const unsigned*)((const char*)(gbase) + (voff)[_i]), (PG8_LAS unsigned*)(lds + (bufoff) + ldsw + _i * 8192), 16, 0, 0); } while (0)
; #define PG8_LDA(dst, b, h) do { _Pragma("unroll") for (int m = 0; m < 4; ++m) _Pragma("unroll") for (int k = 0; k < 2; ++k) dst[m][k] = *(const PG8_LAS bf16x8*)(lds + PG8_SA(b, h) + aoff + m * 2048 + k * 1024); } while (0)
; #define PG8_WAIT_V(n) asm volatile("s_waitcnt vmcnt(" #n ")" ::: "memory")
; #define PG8_WAIT_L(n) asm volatile("s_waitcnt lgkmcnt(" #n ")" ::: "memory")
; template <class Epi, class Sched, bool ALIGN_EPI = false, bool SP2 = false>
; __device__ __forceinline__ void gemm_phase(PG8_LAS unsigned char* lds, const Gemm g, const Sched& S, const Epi& E, int wave0) {
;     ...
;         for (int t = 0; t < nt; t += 2) {
;             const bool last = (t == nt - 2);
;             const char* a1 = cA + (size_t)(t + 1) * kstep;
;             const char* a2 = last ? nA : cA + (size_t)(t + 2) * kstep; const char* b2 = last ? nB : cB + (size_t)(t + 2) * kstep;
;             const char* a3 = a2 + kstep; const char* b3 = b2 + kstep;
;             if (last && has_next) S.a_ready(nxt);
;             if constexpr (SP2) {
;             PG8_LDB(B0, 0, 0); PG8_LDB(B1, 0, 1); PG8_SCHED; PG8_LDA(At, 0, 0); PG8_STAGE(PG8_SA(1, 1), a1 + hstep, voffA);
;             PG8_WAIT_V(8); PG8_WAIT_L(0); PG8_BAR; PG8_MMA(0, 0, At, B0); PG8_MMA(0, 1, At, B1); PG8_BAR; PG8_SCHED;
;             PG8_LDA(At, 0, 1); PG8_STAGE(PG8_SB(0, 0), b2, voffB); PG8_STAGE(PG8_SB(0, 1), b2 + hstep, voffB); PG8_STAGE(PG8_SA(0, 0), a2, voffA);
;             PG8_WAIT_V(8); PG8_WAIT_L(0); PG8_BAR; if (!cur.half) { PG8_MMA(1, 0, At, B0); PG8_MMA(1, 1, At, B1); } PG8_BAR; PG8_SCHED;
;             PG8_LDB(B0, 1, 0); PG8_LDB(B1, 1, 1); PG8_SCHED; PG8_LDA(At, 1, 0); PG8_STAGE(PG8_SA(0, 1), a2 + hstep, voffA);
;             PG8_WAIT_V(8); PG8_WAIT_L(0); PG8_BAR; PG8_MMA(0, 0, At, B0); PG8_MMA(0, 1, At, B1); PG8_BAR; PG8_SCHED;
;             PG8_LDA(At, 1, 1); PG8_STAGE(PG8_SB(1, 0), b3, voffB); PG8_STAGE(PG8_SB(1, 1), b3 + hstep, voffB); PG8_STAGE(PG8_SA(1, 0), a3, voffA);
;             PG8_WAIT_V(8); PG8_WAIT_L(0); PG8_BAR; if (!cur.half) { PG8_MMA(1, 0, At, B0); PG8_MMA(1, 1, At, B1); } PG8_BAR; PG8_SCHED;
.LBB0_2836:
	ds_read_b128 v[128:131], v165
	ds_read_b128 v[132:135], v165 offset:1024
	ds_read_b128 v[152:155], v165 offset:2048
	ds_read_b128 v[156:159], v165 offset:3072
	ds_read_b128 v[170:173], v166
	ds_read_b128 v[174:177], v166 offset:1024
	ds_read_b128 v[178:181], v166 offset:2048
	ds_read_b128 v[182:185], v166 offset:3072
	s_add_u32 s26, s24, 0xfffe0080
	s_addc_u32 s27, s25, -1
	s_cmp_eq_u32 s46, 4
	s_cselect_b32 s29, s7, s27
	s_cselect_b32 s28, s19, s26
	s_cselect_b32 s27, s17, s45
	s_cselect_b32 s26, s43, s44
	v_lshl_add_u64 v[160:161], s[24:25], 0, v[144:145]
	s_add_i32 m0, s5, 0xc000
	ds_read_b128 v[186:189], v167
	ds_read_b128 v[190:193], v167 offset:1024
	ds_read_b128 v[194:197], v167 offset:2048
	ds_read_b128 v[198:201], v167 offset:3072
	ds_read_b128 v[202:205], v167 offset:4096
	ds_read_b128 v[206:209], v167 offset:5120
	ds_read_b128 v[210:213], v167 offset:6144
	ds_read_b128 v[218:221], v167 offset:7168
	global_load_lds_dwordx4 v[160:161], off
	v_lshl_add_u64 v[160:161], s[24:25], 0, v[146:147]
	s_add_i32 m0, s5, 0xe000
	s_nop 0
	global_load_lds_dwordx4 v[160:161], off
	s_waitcnt lgkmcnt(0)
	s_setprio 1
	s_waitcnt lgkmcnt(0)
	v_mfma_f32_16x16x32_bf16 v[124:127], v[128:131], v[186:189], v[124:127]
	v_mfma_f32_16x16x32_bf16 v[120:123], v[152:155], v[186:189], v[120:123]
	v_mfma_f32_16x16x32_bf16 v[108:111], v[128:131], v[194:197], v[108:111]
	v_mfma_f32_16x16x32_bf16 v[104:107], v[152:155], v[194:197], v[104:107]
	v_mfma_f32_16x16x32_bf16 v[92:95], v[128:131], v[202:205], v[92:95]
	v_mfma_f32_16x16x32_bf16 v[88:91], v[152:155], v[202:205], v[88:91]
	v_mfma_f32_16x16x32_bf16 v[76:79], v[128:131], v[210:213], v[76:79]
	v_mfma_f32_16x16x32_bf16 v[72:75], v[152:155], v[210:213], v[72:75]
	s_waitcnt vmcnt(8)
	s_barrier
	v_mfma_f32_16x16x32_bf16 v[124:127], v[132:135], v[190:193], v[124:127]
	v_mfma_f32_16x16x32_bf16 v[120:123], v[156:159], v[190:193], v[120:123]
	v_mfma_f32_16x16x32_bf16 v[108:111], v[132:135], v[198:201], v[108:111]
	v_mfma_f32_16x16x32_bf16 v[104:107], v[156:159], v[198:201], v[104:107]
	v_mfma_f32_16x16x32_bf16 v[92:95], v[132:135], v[206:209], v[92:95]
	v_mfma_f32_16x16x32_bf16 v[88:91], v[156:159], v[206:209], v[88:91]
	v_mfma_f32_16x16x32_bf16 v[76:79], v[132:135], v[218:221], v[76:79]
	v_mfma_f32_16x16x32_bf16 v[72:75], v[156:159], v[218:221], v[72:75]
	s_setprio 0
	s_setprio 1
	v_mfma_f32_16x16x32_bf16 v[116:119], v[170:173], v[186:189], v[116:119]
	v_mfma_f32_16x16x32_bf16 v[112:115], v[178:181], v[186:189], v[112:115]
	v_mfma_f32_16x16x32_bf16 v[100:103], v[170:173], v[194:197], v[100:103]
	v_mfma_f32_16x16x32_bf16 v[96:99], v[178:181], v[194:197], v[96:99]
	v_mfma_f32_16x16x32_bf16 v[84:87], v[170:173], v[202:205], v[84:87]
	v_mfma_f32_16x16x32_bf16 v[80:83], v[178:181], v[202:205], v[80:83]
	v_mfma_f32_16x16x32_bf16 v[68:71], v[170:173], v[210:213], v[68:71]
	v_mfma_f32_16x16x32_bf16 v[64:67], v[178:181], v[210:213], v[64:67]
	v_mfma_f32_16x16x32_bf16 v[116:119], v[174:177], v[190:193], v[116:119]
	v_mfma_f32_16x16x32_bf16 v[112:115], v[182:185], v[190:193], v[112:115]
	v_mfma_f32_16x16x32_bf16 v[100:103], v[174:177], v[198:201], v[100:103]
	v_mfma_f32_16x16x32_bf16 v[96:99], v[182:185], v[198:201], v[96:99]
	v_mfma_f32_16x16x32_bf16 v[84:87], v[174:177], v[206:209], v[84:87]
	v_mfma_f32_16x16x32_bf16 v[80:83], v[182:185], v[206:209], v[80:83]
	v_mfma_f32_16x16x32_bf16 v[68:71], v[174:177], v[218:221], v[68:71]
	v_mfma_f32_16x16x32_bf16 v[64:67], v[182:185], v[218:221], v[64:67]
	s_setprio 0
	s_barrier
	s_add_i32 s47, s39, s4
	v_lshl_add_u64 v[160:161], s[26:27], 0, v[138:139]
	s_mov_b32 m0, s47
	ds_read_b128 v[186:189], v167 offset:16384
	ds_read_b128 v[190:193], v167 offset:17408
	ds_read_b128 v[194:197], v167 offset:18432
	ds_read_b128 v[198:201], v167 offset:19456
	ds_read_b128 v[202:205], v167 offset:20480
	ds_read_b128 v[206:209], v167 offset:21504
	ds_read_b128 v[210:213], v167 offset:22528
	ds_read_b128 v[218:221], v167 offset:23552
	global_load_lds_dwordx4 v[160:161], off
	s_add_i32 m0, s47, 0x2000
	s_add_u32 s48, s26, 0x20000
	v_lshl_add_u64 v[214:215], s[26:27], 0, v[142:143]
	s_addc_u32 s49, s27, 0
	s_add_i32 s47, s40, s4
	global_load_lds_dwordx4 v[214:215], off
	v_lshl_add_u64 v[222:223], s[48:49], 0, v[138:139]
	s_mov_b32 m0, s47
	v_lshl_add_u64 v[224:225], s[28:29], 0, v[140:141]
	global_load_lds_dwordx4 v[222:223], off
	v_lshl_add_u64 v[222:223], s[48:49], 0, v[142:143]
	s_add_i32 m0, s47, 0x2000
	s_nop 0
	global_load_lds_dwordx4 v[222:223], off
	v_lshl_add_u64 v[222:223], s[28:29], 0, v[136:137]
	s_mov_b32 m0, s5
	s_nop 0
	global_load_lds_dwordx4 v[222:223], off
	s_mov_b32 m0, s30
	s_nop 0
	global_load_lds_dwordx4 v[224:225], off
	s_waitcnt lgkmcnt(0)
	s_setprio 1
	s_waitcnt lgkmcnt(0)
	v_mfma_f32_16x16x32_bf16 v[60:63], v[128:131], v[186:189], v[60:63]
	v_mfma_f32_16x16x32_bf16 v[56:59], v[152:155], v[186:189], v[56:59]
	v_mfma_f32_16x16x32_bf16 v[44:47], v[128:131], v[194:197], v[44:47]
	v_mfma_f32_16x16x32_bf16 v[40:43], v[152:155], v[194:197], v[40:43]
	v_mfma_f32_16x16x32_bf16 v[28:31], v[128:131], v[202:205], v[28:31]
	v_mfma_f32_16x16x32_bf16 v[24:27], v[152:155], v[202:205], v[24:27]
	v_mfma_f32_16x16x32_bf16 v[12:15], v[128:131], v[210:213], v[12:15]
	v_mfma_f32_16x16x32_bf16 v[8:11], v[152:155], v[210:213], v[8:11]
	s_waitcnt vmcnt(8)
	s_barrier
; #define PG8_STAGE(bufoff, gbase, voff) do { _Pragma("unroll") for (int _i = 0; _i < 2; ++_i) \
;         __builtin_amdgcn_global_load_lds((const unsigned*)((const char*)(gbase) + (voff)[_i]), (PG8_LAS unsigned*)(lds + (bufoff) + ldsw + _i * 8192), 16, 0, 0); } while (0)
; #define PG8_LDA(dst, b, h) do { _Pragma("unroll") for (int m = 0; m < 4; ++m) _Pragma("unroll") for (int k = 0; k < 2; ++k) dst[m][k] = *(const PG8_LAS bf16x8*)(lds + PG8_SA(b, h) + aoff + m * 2048 + k * 1024); } while (0)
; #define PG8_LDB(dst, b, h) do { _Pragma("unroll") for (int n = 0; n < 2; ++n) _Pragma("unroll") for (int k = 0; k < 2; ++k) dst[n][k] = *(const PG8_LAS bf16x8*)(lds + PG8_SB(b, h) + boff + n * 2048 + k * 1024); } while (0)
; #define PG8_MMA(ai, bj, At, Bt) do { __builtin_amdgcn_s_setprio(1); _Pragma("unroll") for (int m = 0; m < 4; ++m) _Pragma("unroll") for (int n = 0; n < 2; ++n) _Pragma("unroll") for (int k = 0; k < 2; ++k) \
;         acc[ai][bj][m][n] = __builtin_amdgcn_mfma_f32_16x16x32_bf16(Bt[n][k], At[m][k], acc[ai][bj][m][n], 0, 0, 0); __builtin_amdgcn_s_setprio(0); } while (0)
; #define PG8_WAIT_V(n) asm volatile("s_waitcnt vmcnt(" #n ")" ::: "memory")
; #define PG8_WAIT_L(n) asm volatile("s_waitcnt lgkmcnt(" #n ")" ::: "memory")
; #define PG8_BAR __builtin_amdgcn_s_barrier()
; #define PG8_SCHED __builtin_amdgcn_sched_barrier(0)
; template <class Epi, class Sched, bool ALIGN_EPI = false, bool SP2 = false>
; __device__ __forceinline__ void gemm_phase(PG8_LAS unsigned char* lds, const Gemm g, const Sched& S, const Epi& E, int wave0) {
;     ...
;             PG8_LDB(B0, 1, 0); PG8_LDB(B1, 1, 1); PG8_SCHED; PG8_LDA(At, 1, 0); PG8_STAGE(PG8_SA(0, 1), a2 + hstep, voffA);
;             PG8_WAIT_V(8); PG8_WAIT_L(0); PG8_BAR; PG8_MMA(0, 0, At, B0); PG8_MMA(0, 1, At, B1); PG8_BAR; PG8_SCHED;
;             PG8_LDA(At, 1, 1); PG8_STAGE(PG8_SB(1, 0), b3, voffB); PG8_STAGE(PG8_SB(1, 1), b3 + hstep, voffB); PG8_STAGE(PG8_SA(1, 0), a3, voffA);
	v_mfma_f32_16x16x32_bf16 v[60:63], v[132:135], v[190:193], v[60:63]
	v_mfma_f32_16x16x32_bf16 v[56:59], v[156:159], v[190:193], v[56:59]
	v_mfma_f32_16x16x32_bf16 v[44:47], v[132:135], v[198:201], v[44:47]
	v_mfma_f32_16x16x32_bf16 v[40:43], v[156:159], v[198:201], v[40:43]
	v_mfma_f32_16x16x32_bf16 v[28:31], v[132:135], v[206:209], v[28:31]
	v_mfma_f32_16x16x32_bf16 v[24:27], v[156:159], v[206:209], v[24:27]
	v_mfma_f32_16x16x32_bf16 v[12:15], v[132:135], v[218:221], v[12:15]
	v_mfma_f32_16x16x32_bf16 v[8:11], v[156:159], v[218:221], v[8:11]
	s_setprio 0
	s_setprio 1
	v_mfma_f32_16x16x32_bf16 v[52:55], v[170:173], v[186:189], v[52:55]
	v_mfma_f32_16x16x32_bf16 v[48:51], v[178:181], v[186:189], v[48:51]
	v_mfma_f32_16x16x32_bf16 v[36:39], v[170:173], v[194:197], v[36:39]
	v_mfma_f32_16x16x32_bf16 v[32:35], v[178:181], v[194:197], v[32:35]
	v_mfma_f32_16x16x32_bf16 v[20:23], v[170:173], v[202:205], v[20:23]
	v_mfma_f32_16x16x32_bf16 v[16:19], v[178:181], v[202:205], v[16:19]
	v_mfma_f32_16x16x32_bf16 v[4:7], v[170:173], v[210:213], v[4:7]
	v_mfma_f32_16x16x32_bf16 v[0:3], v[178:181], v[210:213], v[0:3]
	v_mfma_f32_16x16x32_bf16 v[52:55], v[174:177], v[190:193], v[52:55]
	v_mfma_f32_16x16x32_bf16 v[48:51], v[182:185], v[190:193], v[48:51]
	v_mfma_f32_16x16x32_bf16 v[36:39], v[174:177], v[198:201], v[36:39]
	v_mfma_f32_16x16x32_bf16 v[32:35], v[182:185], v[198:201], v[32:35]
	v_mfma_f32_16x16x32_bf16 v[20:23], v[174:177], v[206:209], v[20:23]
	v_mfma_f32_16x16x32_bf16 v[16:19], v[182:185], v[206:209], v[16:19]
	v_mfma_f32_16x16x32_bf16 v[4:7], v[174:177], v[218:221], v[4:7]
	v_mfma_f32_16x16x32_bf16 v[0:3], v[182:185], v[218:221], v[0:3]
	s_setprio 0
	s_barrier
	s_add_i32 s47, 0, 0x18000
	s_add_i32 s48, 0, 0x1c000
	v_add_u32_e32 v156, s47, v164
	v_add_u32_e32 v169, s48, v164
	ds_read_b128 v[128:131], v156
	ds_read_b128 v[132:135], v156 offset:1024
	ds_read_b128 v[152:155], v156 offset:2048
	ds_read_b128 v[156:159], v156 offset:3072
	ds_read_b128 v[170:173], v169
	ds_read_b128 v[174:177], v169 offset:1024
	ds_read_b128 v[178:181], v169 offset:2048
	ds_read_b128 v[182:185], v169 offset:3072
	s_add_u32 s28, s28, 0x20000
	s_addc_u32 s29, s29, 0
	s_mov_b32 m0, s31
	v_lshl_add_u64 v[226:227], s[28:29], 0, v[136:137]
	ds_read_b128 v[186:189], v167 offset:32768
	ds_read_b128 v[190:193], v167 offset:33792
	ds_read_b128 v[194:197], v167 offset:34816
	ds_read_b128 v[198:201], v167 offset:35840
	ds_read_b128 v[202:205], v167 offset:36864
	ds_read_b128 v[206:209], v167 offset:37888
	ds_read_b128 v[210:213], v167 offset:38912
	ds_read_b128 v[218:221], v167 offset:39936
	global_load_lds_dwordx4 v[226:227], off
	v_lshl_add_u64 v[226:227], s[28:29], 0, v[140:141]
	s_mov_b32 m0, s33
	s_nop 0
	global_load_lds_dwordx4 v[226:227], off
	s_waitcnt lgkmcnt(0)
	s_setprio 1
	s_waitcnt lgkmcnt(0)
	v_mfma_f32_16x16x32_bf16 v[124:127], v[128:131], v[186:189], v[124:127]
	v_mfma_f32_16x16x32_bf16 v[120:123], v[152:155], v[186:189], v[120:123]
	v_mfma_f32_16x16x32_bf16 v[108:111], v[128:131], v[194:197], v[108:111]
	v_mfma_f32_16x16x32_bf16 v[104:107], v[152:155], v[194:197], v[104:107]
	v_mfma_f32_16x16x32_bf16 v[92:95], v[128:131], v[202:205], v[92:95]
	v_mfma_f32_16x16x32_bf16 v[88:91], v[152:155], v[202:205], v[88:91]
	v_mfma_f32_16x16x32_bf16 v[76:79], v[128:131], v[210:213], v[76:79]
	v_mfma_f32_16x16x32_bf16 v[72:75], v[152:155], v[210:213], v[72:75]
	s_waitcnt vmcnt(8)
	s_barrier
	v_mfma_f32_16x16x32_bf16 v[124:127], v[132:135], v[190:193], v[124:127]
	v_mfma_f32_16x16x32_bf16 v[120:123], v[156:159], v[190:193], v[120:123]
	v_mfma_f32_16x16x32_bf16 v[108:111], v[132:135], v[198:201], v[108:111]
	v_mfma_f32_16x16x32_bf16 v[104:107], v[156:159], v[198:201], v[104:107]
	v_mfma_f32_16x16x32_bf16 v[92:95], v[132:135], v[206:209], v[92:95]
	v_mfma_f32_16x16x32_bf16 v[88:91], v[156:159], v[206:209], v[88:91]
	v_mfma_f32_16x16x32_bf16 v[76:79], v[132:135], v[218:221], v[76:79]
	v_mfma_f32_16x16x32_bf16 v[72:75], v[156:159], v[218:221], v[72:75]
	s_setprio 0
	s_setprio 1
	v_mfma_f32_16x16x32_bf16 v[116:119], v[170:173], v[186:189], v[116:119]
	v_mfma_f32_16x16x32_bf16 v[112:115], v[178:181], v[186:189], v[112:115]
	v_mfma_f32_16x16x32_bf16 v[100:103], v[170:173], v[194:197], v[100:103]
	v_mfma_f32_16x16x32_bf16 v[96:99], v[178:181], v[194:197], v[96:99]
	v_mfma_f32_16x16x32_bf16 v[84:87], v[170:173], v[202:205], v[84:87]
	v_mfma_f32_16x16x32_bf16 v[80:83], v[178:181], v[202:205], v[80:83]
	v_mfma_f32_16x16x32_bf16 v[68:71], v[170:173], v[210:213], v[68:71]
	v_mfma_f32_16x16x32_bf16 v[64:67], v[178:181], v[210:213], v[64:67]
	v_mfma_f32_16x16x32_bf16 v[116:119], v[174:177], v[190:193], v[116:119]
	v_mfma_f32_16x16x32_bf16 v[112:115], v[182:185], v[190:193], v[112:115]
	v_mfma_f32_16x16x32_bf16 v[100:103], v[174:177], v[198:201], v[100:103]
	v_mfma_f32_16x16x32_bf16 v[96:99], v[182:185], v[198:201], v[96:99]
	v_mfma_f32_16x16x32_bf16 v[84:87], v[174:177], v[206:209], v[84:87]
	v_mfma_f32_16x16x32_bf16 v[80:83], v[182:185], v[206:209], v[80:83]
	v_mfma_f32_16x16x32_bf16 v[68:71], v[174:177], v[218:221], v[68:71]
	v_mfma_f32_16x16x32_bf16 v[64:67], v[182:185], v[218:221], v[64:67]
	s_setprio 0
	s_barrier
; #define PG8_STAGE(bufoff, gbase, voff) do { _Pragma("unroll") for (int _i = 0; _i < 2; ++_i) \
;         __builtin_amdgcn_global_load_lds((const unsigned*)((const char*)(gbase) + (voff)[_i]), (PG8_LAS unsigned*)(lds + (bufoff) + ldsw + _i * 8192), 16, 0, 0); } while (0)
; #define PG8_LDA(dst, b, h) do { _Pragma("unroll") for (int m = 0; m < 4; ++m) _Pragma("unroll") for (int k = 0; k < 2; ++k) dst[m][k] = *(const PG8_LAS bf16x8*)(lds + PG8_SA(b, h) + aoff + m * 2048 + k * 1024); } while (0)
; #define PG8_MMA(ai, bj, At, Bt) do { __builtin_amdgcn_s_setprio(1); _Pragma("unroll") for (int m = 0; m < 4; ++m) _Pragma("unroll") for (int n = 0; n < 2; ++n) _Pragma("unroll") for (int k = 0; k < 2; ++k) \
;         acc[ai][bj][m][n] = __builtin_amdgcn_mfma_f32_16x16x32_bf16(Bt[n][k], At[m][k], acc[ai][bj][m][n], 0, 0, 0); __builtin_amdgcn_s_setprio(0); } while (0)
; #define PG8_WAIT_V(n) asm volatile("s_waitcnt vmcnt(" #n ")" ::: "memory")
; #define PG8_WAIT_L(n) asm volatile("s_waitcnt lgkmcnt(" #n ")" ::: "memory")
; #define PG8_BAR __builtin_amdgcn_s_barrier()
; #define PG8_SCHED __builtin_amdgcn_sched_barrier(0)
; template <class Epi, class Sched, bool ALIGN_EPI = false, bool SP2 = false>
; __device__ __forceinline__ void gemm_phase(PG8_LAS unsigned char* lds, const Gemm g, const Sched& S, const Epi& E, int wave0) {
;     ...
;             PG8_LDA(At, 1, 1); PG8_STAGE(PG8_SB(1, 0), b3, voffB); PG8_STAGE(PG8_SB(1, 1), b3 + hstep, voffB); PG8_STAGE(PG8_SA(1, 0), a3, voffA);
;             PG8_WAIT_V(8); PG8_WAIT_L(0); PG8_BAR; if (!cur.half) { PG8_MMA(1, 0, At, B0); PG8_MMA(1, 1, At, B1); } PG8_BAR; PG8_SCHED;
;     ...
;         if constexpr (ALIGN_EPI) { if (wr == 0) PG8_BAR; }
	s_add_i32 s28, s47, s4
	v_lshl_add_u64 v[160:161], v[160:161], 0, s[12:13]
	s_mov_b32 m0, s28
	ds_read_b128 v[186:189], v167 offset:49152
	ds_read_b128 v[190:193], v167 offset:50176
	ds_read_b128 v[194:197], v167 offset:51200
	ds_read_b128 v[198:201], v167 offset:52224
	ds_read_b128 v[202:205], v167 offset:53248
	ds_read_b128 v[206:209], v167 offset:54272
	ds_read_b128 v[210:213], v167 offset:55296
	ds_read_b128 v[218:221], v167 offset:56320
	global_load_lds_dwordx4 v[160:161], off
	s_add_i32 m0, s28, 0x2000
	s_add_u32 s26, s26, 0x20080
	v_lshl_add_u64 v[160:161], v[214:215], 0, s[12:13]
	s_addc_u32 s27, s27, 0
	s_add_i32 s28, s48, s4
	global_load_lds_dwordx4 v[160:161], off
	v_lshl_add_u64 v[160:161], s[26:27], 0, v[138:139]
	s_mov_b32 m0, s28
	s_nop 0
	global_load_lds_dwordx4 v[160:161], off
	v_lshl_add_u64 v[160:161], s[26:27], 0, v[142:143]
	s_add_i32 m0, s28, 0x2000
	s_nop 0
	global_load_lds_dwordx4 v[160:161], off
	v_lshl_add_u64 v[160:161], v[222:223], 0, s[12:13]
	s_mov_b32 m0, s37
	s_nop 0
	global_load_lds_dwordx4 v[160:161], off
	v_lshl_add_u64 v[160:161], v[224:225], 0, s[12:13]
	s_mov_b32 m0, s38
	s_nop 0
	global_load_lds_dwordx4 v[160:161], off
	s_waitcnt lgkmcnt(0)
	s_setprio 1
	s_waitcnt lgkmcnt(0)
	v_mfma_f32_16x16x32_bf16 v[60:63], v[128:131], v[186:189], v[60:63]
	v_mfma_f32_16x16x32_bf16 v[56:59], v[152:155], v[186:189], v[56:59]
	v_mfma_f32_16x16x32_bf16 v[44:47], v[128:131], v[194:197], v[44:47]
	v_mfma_f32_16x16x32_bf16 v[40:43], v[152:155], v[194:197], v[40:43]
	v_mfma_f32_16x16x32_bf16 v[28:31], v[128:131], v[202:205], v[28:31]
	v_mfma_f32_16x16x32_bf16 v[24:27], v[152:155], v[202:205], v[24:27]
	v_mfma_f32_16x16x32_bf16 v[12:15], v[128:131], v[210:213], v[12:15]
	v_mfma_f32_16x16x32_bf16 v[8:11], v[152:155], v[210:213], v[8:11]
	s_waitcnt vmcnt(8)
	s_barrier
	v_mfma_f32_16x16x32_bf16 v[60:63], v[132:135], v[190:193], v[60:63]
	v_mfma_f32_16x16x32_bf16 v[56:59], v[156:159], v[190:193], v[56:59]
	v_mfma_f32_16x16x32_bf16 v[44:47], v[132:135], v[198:201], v[44:47]
	v_mfma_f32_16x16x32_bf16 v[40:43], v[156:159], v[198:201], v[40:43]
	v_mfma_f32_16x16x32_bf16 v[28:31], v[132:135], v[206:209], v[28:31]
	v_mfma_f32_16x16x32_bf16 v[24:27], v[156:159], v[206:209], v[24:27]
	v_mfma_f32_16x16x32_bf16 v[12:15], v[132:135], v[218:221], v[12:15]
	v_mfma_f32_16x16x32_bf16 v[8:11], v[156:159], v[218:221], v[8:11]
	s_setprio 0
	s_setprio 1
	v_mfma_f32_16x16x32_bf16 v[52:55], v[170:173], v[186:189], v[52:55]
	v_mfma_f32_16x16x32_bf16 v[48:51], v[178:181], v[186:189], v[48:51]
	v_mfma_f32_16x16x32_bf16 v[36:39], v[170:173], v[194:197], v[36:39]
	v_mfma_f32_16x16x32_bf16 v[32:35], v[178:181], v[194:197], v[32:35]
	v_mfma_f32_16x16x32_bf16 v[20:23], v[170:173], v[202:205], v[20:23]
	v_mfma_f32_16x16x32_bf16 v[16:19], v[178:181], v[202:205], v[16:19]
	v_mfma_f32_16x16x32_bf16 v[4:7], v[170:173], v[210:213], v[4:7]
	v_mfma_f32_16x16x32_bf16 v[0:3], v[178:181], v[210:213], v[0:3]
	v_mfma_f32_16x16x32_bf16 v[52:55], v[174:177], v[190:193], v[52:55]
	v_mfma_f32_16x16x32_bf16 v[48:51], v[182:185], v[190:193], v[48:51]
	v_mfma_f32_16x16x32_bf16 v[36:39], v[174:177], v[198:201], v[36:39]
	v_mfma_f32_16x16x32_bf16 v[32:35], v[182:185], v[198:201], v[32:35]
	v_mfma_f32_16x16x32_bf16 v[20:23], v[174:177], v[206:209], v[20:23]
	v_mfma_f32_16x16x32_bf16 v[16:19], v[182:185], v[206:209], v[16:19]
	v_mfma_f32_16x16x32_bf16 v[4:7], v[174:177], v[218:221], v[4:7]
	v_mfma_f32_16x16x32_bf16 v[0:3], v[182:185], v[218:221], v[0:3]
	s_setprio 0
	s_barrier
	s_add_i32 s46, s46, 2
	s_add_u32 s24, s24, 0x100
	s_addc_u32 s25, s25, 0
	s_add_u32 s44, s44, 0x100
	s_addc_u32 s45, s45, 0
	s_cmp_gt_u32 s46, 5
	s_cbranch_scc0 .LBB0_2836
	s_and_b64 vcc, exec, s[14:15]
	s_cbranch_vccz .LBB0_2839
	s_barrier

; #define PG8_STAGE(bufoff, gbase, voff) do { _Pragma("unroll") for (int _i = 0; _i < 2; ++_i) \
;         __builtin_amdgcn_global_load_lds((const unsigned*)((const char*)(gbase) + (voff)[_i]), (PG8_LAS unsigned*)(lds + (bufoff) + ldsw + _i * 8192), 16, 0, 0); } while (0)
; #define PG8_LDA(dst, b, h) do { _Pragma("unroll") for (int m = 0; m < 4; ++m) _Pragma("unroll") for (int k = 0; k < 2; ++k) dst[m][k] = *(const PG8_LAS bf16x8*)(lds + PG8_SA(b, h) + aoff + m * 2048 + k * 1024); } while (0)
; #define PG8_LDB(dst, b, h) do { _Pragma("unroll") for (int n = 0; n < 2; ++n) _Pragma("unroll") for (int k = 0; k < 2; ++k) dst[n][k] = *(const PG8_LAS bf16x8*)(lds + PG8_SB(b, h) + boff + n * 2048 + k * 1024); } while (0)
; #define PG8_MMA(ai, bj, At, Bt) do { __builtin_amdgcn_s_setprio(1); _Pragma("unroll") for (int m = 0; m < 4; ++m) _Pragma("unroll") for (int n = 0; n < 2; ++n) _Pragma("unroll") for (int k = 0; k < 2; ++k) \
;         acc[ai][bj][m][n] = __builtin_amdgcn_mfma_f32_16x16x32_bf16(Bt[n][k], At[m][k], acc[ai][bj][m][n], 0, 0, 0); __builtin_amdgcn_s_setprio(0); } while (0)
; #define PG8_WAIT_V(n) asm volatile("s_waitcnt vmcnt(" #n ")" ::: "memory")
; template <class Epi, class Sched, bool ALIGN_EPI = false, bool SP2 = false>
; __device__ __forceinline__ void gemm_phase(PG8_LAS unsigned char* lds, const Gemm g, const Sched& S, const Epi& E, int wave0) {
;     ...
;         for (int t = 0; t < nt; t += 2) {
;             const bool last = (t == nt - 2);
;             const char* a1 = cA + (size_t)(t + 1) * kstep;
;             const char* a2 = last ? nA : cA + (size_t)(t + 2) * kstep; const char* b2 = last ? nB : cB + (size_t)(t + 2) * kstep;
;             const char* a3 = a2 + kstep; const char* b3 = b2 + kstep;
;             if (last && has_next) S.a_ready(nxt);
;             if constexpr (SP2) {
;             PG8_LDB(B0, 0, 0); PG8_LDB(B1, 0, 1); PG8_SCHED; PG8_LDA(At, 0, 0); PG8_STAGE(PG8_SA(1, 1), a1 + hstep, voffA);
;             PG8_WAIT_V(8); PG8_WAIT_L(0); PG8_BAR; PG8_MMA(0, 0, At, B0); PG8_MMA(0, 1, At, B1); PG8_BAR; PG8_SCHED;
;             PG8_LDA(At, 0, 1); PG8_STAGE(PG8_SB(0, 0), b2, voffB); PG8_STAGE(PG8_SB(0, 1), b2 + hstep, voffB); PG8_STAGE(PG8_SA(0, 0), a2, voffA);
;             PG8_WAIT_V(8); PG8_WAIT_L(0); PG8_BAR; if (!cur.half) { PG8_MMA(1, 0, At, B0); PG8_MMA(1, 1, At, B1); } PG8_BAR; PG8_SCHED;
.LBB0_2953:
	ds_read_b128 v[148:151], v220
	ds_read_b128 v[152:155], v220 offset:1024
	ds_read_b128 v[156:159], v220 offset:2048
	ds_read_b128 v[160:163], v220 offset:3072
	ds_read_b128 v[132:135], v221
	ds_read_b128 v[136:139], v221 offset:1024
	ds_read_b128 v[140:143], v221 offset:2048
	ds_read_b128 v[144:147], v221 offset:3072
	s_add_u32 s6, s28, 0xfffc0080
	s_addc_u32 s7, s29, -1
	s_cmp_eq_u32 s58, 12
	s_cselect_b32 s35, s1, s7
	s_cselect_b32 s34, s19, s6
	s_cselect_b32 s31, s17, s57
	s_cselect_b32 s30, s55, s56
	v_lshl_add_u64 v[2:3], s[28:29], 0, v[204:205]
	s_add_i32 m0, s38, 0xc000
	s_waitcnt lgkmcnt(0)
	ds_read_b128 v[164:167], v222
	ds_read_b128 v[168:171], v222 offset:1024
	ds_read_b128 v[172:175], v222 offset:2048
	ds_read_b128 v[176:179], v222 offset:3072
	ds_read_b128 v[180:183], v222 offset:4096
	ds_read_b128 v[184:187], v222 offset:5120
	ds_read_b128 v[188:191], v222 offset:6144
	ds_read_b128 v[192:195], v222 offset:7168
	global_load_lds_dwordx4 v[2:3], off
	v_lshl_add_u64 v[2:3], s[28:29], 0, v[206:207]
	s_add_i32 m0, s38, 0xe000
	s_nop 0
	global_load_lds_dwordx4 v[2:3], off
	s_waitcnt lgkmcnt(0)
	s_setprio 1
	s_waitcnt lgkmcnt(0)
	v_mfma_f32_16x16x32_bf16 v[128:131], v[148:151], v[164:167], v[128:131]
	v_mfma_f32_16x16x32_bf16 v[124:127], v[156:159], v[164:167], v[124:127]
	v_mfma_f32_16x16x32_bf16 v[112:115], v[148:151], v[172:175], v[112:115]
	v_mfma_f32_16x16x32_bf16 v[108:111], v[156:159], v[172:175], v[108:111]
	v_mfma_f32_16x16x32_bf16 v[96:99], v[148:151], v[180:183], v[96:99]
	v_mfma_f32_16x16x32_bf16 v[92:95], v[156:159], v[180:183], v[92:95]
	v_mfma_f32_16x16x32_bf16 v[80:83], v[148:151], v[188:191], v[80:83]
	v_mfma_f32_16x16x32_bf16 v[76:79], v[156:159], v[188:191], v[76:79]
	s_waitcnt vmcnt(8)
	s_barrier
	v_mfma_f32_16x16x32_bf16 v[128:131], v[152:155], v[168:171], v[128:131]
	v_mfma_f32_16x16x32_bf16 v[124:127], v[160:163], v[168:171], v[124:127]
	v_mfma_f32_16x16x32_bf16 v[112:115], v[152:155], v[176:179], v[112:115]
	v_mfma_f32_16x16x32_bf16 v[108:111], v[160:163], v[176:179], v[108:111]
	v_mfma_f32_16x16x32_bf16 v[96:99], v[152:155], v[184:187], v[96:99]
	v_mfma_f32_16x16x32_bf16 v[92:95], v[160:163], v[184:187], v[92:95]
	v_mfma_f32_16x16x32_bf16 v[80:83], v[152:155], v[192:195], v[80:83]
	v_mfma_f32_16x16x32_bf16 v[76:79], v[160:163], v[192:195], v[76:79]
	s_setprio 0
	s_setprio 1
	v_mfma_f32_16x16x32_bf16 v[120:123], v[132:135], v[164:167], v[120:123]
	v_mfma_f32_16x16x32_bf16 v[116:119], v[140:143], v[164:167], v[116:119]
	v_mfma_f32_16x16x32_bf16 v[104:107], v[132:135], v[172:175], v[104:107]
	v_mfma_f32_16x16x32_bf16 v[100:103], v[140:143], v[172:175], v[100:103]
	v_mfma_f32_16x16x32_bf16 v[88:91], v[132:135], v[180:183], v[88:91]
	v_mfma_f32_16x16x32_bf16 v[84:87], v[140:143], v[180:183], v[84:87]
	v_mfma_f32_16x16x32_bf16 v[72:75], v[132:135], v[188:191], v[72:75]
	v_mfma_f32_16x16x32_bf16 v[68:71], v[140:143], v[188:191], v[68:71]
	v_mfma_f32_16x16x32_bf16 v[120:123], v[136:139], v[168:171], v[120:123]
	v_mfma_f32_16x16x32_bf16 v[116:119], v[144:147], v[168:171], v[116:119]
	v_mfma_f32_16x16x32_bf16 v[104:107], v[136:139], v[176:179], v[104:107]
	v_mfma_f32_16x16x32_bf16 v[100:103], v[144:147], v[176:179], v[100:103]
	v_mfma_f32_16x16x32_bf16 v[88:91], v[136:139], v[184:187], v[88:91]
	v_mfma_f32_16x16x32_bf16 v[84:87], v[144:147], v[184:187], v[84:87]
	v_mfma_f32_16x16x32_bf16 v[72:75], v[136:139], v[192:195], v[72:75]
	v_mfma_f32_16x16x32_bf16 v[68:71], v[144:147], v[192:195], v[68:71]
	s_setprio 0
	s_barrier
	s_add_i32 s6, s47, s37
	v_lshl_add_u64 v[2:3], s[30:31], 0, v[198:199]
	s_mov_b32 m0, s6
	ds_read_b128 v[188:191], v222 offset:16384
	ds_read_b128 v[192:195], v222 offset:17408
	ds_read_b128 v[180:183], v222 offset:18432
	ds_read_b128 v[184:187], v222 offset:19456
	ds_read_b128 v[172:175], v222 offset:20480
	ds_read_b128 v[176:179], v222 offset:21504
	ds_read_b128 v[164:167], v222 offset:22528
	ds_read_b128 v[168:171], v222 offset:23552
	global_load_lds_dwordx4 v[2:3], off
	s_add_i32 m0, s6, 0x2000
	s_add_u32 s6, s30, 0x40000
	v_lshl_add_u64 v[210:211], s[30:31], 0, v[202:203]
	s_addc_u32 s7, s31, 0
	s_add_i32 s59, s48, s37
	global_load_lds_dwordx4 v[210:211], off
	v_lshl_add_u64 v[212:213], s[6:7], 0, v[198:199]
	s_mov_b32 m0, s59
	v_lshl_add_u64 v[214:215], s[34:35], 0, v[200:201]
	global_load_lds_dwordx4 v[212:213], off
	v_lshl_add_u64 v[212:213], s[6:7], 0, v[202:203]
	s_add_i32 m0, s59, 0x2000
	v_cmp_ne_u32_e64 s[6:7], 1, v224
	global_load_lds_dwordx4 v[212:213], off
	v_lshl_add_u64 v[212:213], s[34:35], 0, v[196:197]
	s_mov_b32 m0, s38
	s_andn2_b64 vcc, exec, s[26:27]
	global_load_lds_dwordx4 v[212:213], off
	s_mov_b32 m0, s39
	s_nop 0
	global_load_lds_dwordx4 v[214:215], off
	s_waitcnt vmcnt(8)
	s_waitcnt lgkmcnt(0)
	s_barrier
	s_cbranch_vccnz .LBB0_2955
; #define PG8_MMA(ai, bj, At, Bt) do { __builtin_amdgcn_s_setprio(1); _Pragma("unroll") for (int m = 0; m < 4; ++m) _Pragma("unroll") for (int n = 0; n < 2; ++n) _Pragma("unroll") for (int k = 0; k < 2; ++k) \
;         acc[ai][bj][m][n] = __builtin_amdgcn_mfma_f32_16x16x32_bf16(Bt[n][k], At[m][k], acc[ai][bj][m][n], 0, 0, 0); __builtin_amdgcn_s_setprio(0); } while (0)
; #define PG8_WAIT_V(n) asm volatile("s_waitcnt vmcnt(" #n ")" ::: "memory")
; #define PG8_WAIT_L(n) asm volatile("s_waitcnt lgkmcnt(" #n ")" ::: "memory")
; #define PG8_BAR __builtin_amdgcn_s_barrier()
; #define PG8_SCHED __builtin_amdgcn_sched_barrier(0)
; template <class Epi, class Sched, bool ALIGN_EPI = false, bool SP2 = false>
; __device__ __forceinline__ void gemm_phase(PG8_LAS unsigned char* lds, const Gemm g, const Sched& S, const Epi& E, int wave0) {
;     ...
;             PG8_WAIT_V(8); PG8_WAIT_L(0); PG8_BAR; if (!cur.half) { PG8_MMA(1, 0, At, B0); PG8_MMA(1, 1, At, B1); } PG8_BAR; PG8_SCHED;
	s_setprio 1
	s_waitcnt lgkmcnt(0)
	v_mfma_f32_16x16x32_bf16 v[64:67], v[148:151], v[188:191], v[64:67]
	v_mfma_f32_16x16x32_bf16 v[60:63], v[156:159], v[188:191], v[60:63]
	v_mfma_f32_16x16x32_bf16 v[48:51], v[148:151], v[180:183], v[48:51]
	v_mfma_f32_16x16x32_bf16 v[44:47], v[156:159], v[180:183], v[44:47]
	v_mfma_f32_16x16x32_bf16 v[32:35], v[148:151], v[172:175], v[32:35]
	v_mfma_f32_16x16x32_bf16 v[28:31], v[156:159], v[172:175], v[28:31]
	v_mfma_f32_16x16x32_bf16 v[16:19], v[148:151], v[164:167], v[16:19]
	v_mfma_f32_16x16x32_bf16 v[12:15], v[156:159], v[164:167], v[12:15]
	v_mfma_f32_16x16x32_bf16 v[64:67], v[152:155], v[192:195], v[64:67]
	v_mfma_f32_16x16x32_bf16 v[60:63], v[160:163], v[192:195], v[60:63]
	v_mfma_f32_16x16x32_bf16 v[48:51], v[152:155], v[184:187], v[48:51]
	v_mfma_f32_16x16x32_bf16 v[44:47], v[160:163], v[184:187], v[44:47]
	v_mfma_f32_16x16x32_bf16 v[32:35], v[152:155], v[176:179], v[32:35]
	v_mfma_f32_16x16x32_bf16 v[28:31], v[160:163], v[176:179], v[28:31]
	v_mfma_f32_16x16x32_bf16 v[16:19], v[152:155], v[168:171], v[16:19]
	v_mfma_f32_16x16x32_bf16 v[12:15], v[160:163], v[168:171], v[12:15]
	s_setprio 0
	s_setprio 1
	v_mfma_f32_16x16x32_bf16 v[56:59], v[132:135], v[188:191], v[56:59]
	v_mfma_f32_16x16x32_bf16 v[52:55], v[140:143], v[188:191], v[52:55]
	v_mfma_f32_16x16x32_bf16 v[40:43], v[132:135], v[180:183], v[40:43]
	v_mfma_f32_16x16x32_bf16 v[36:39], v[140:143], v[180:183], v[36:39]
	v_mfma_f32_16x16x32_bf16 v[24:27], v[132:135], v[172:175], v[24:27]
	v_mfma_f32_16x16x32_bf16 v[20:23], v[140:143], v[172:175], v[20:23]
	v_mfma_f32_16x16x32_bf16 v[8:11], v[132:135], v[164:167], v[8:11]
	v_mfma_f32_16x16x32_bf16 v[4:7], v[140:143], v[164:167], v[4:7]
	v_mfma_f32_16x16x32_bf16 v[56:59], v[136:139], v[192:195], v[56:59]
	v_mfma_f32_16x16x32_bf16 v[52:55], v[144:147], v[192:195], v[52:55]
	v_mfma_f32_16x16x32_bf16 v[40:43], v[136:139], v[184:187], v[40:43]
	v_mfma_f32_16x16x32_bf16 v[36:39], v[144:147], v[184:187], v[36:39]
	v_mfma_f32_16x16x32_bf16 v[24:27], v[136:139], v[176:179], v[24:27]
	v_mfma_f32_16x16x32_bf16 v[20:23], v[144:147], v[176:179], v[20:23]
	v_mfma_f32_16x16x32_bf16 v[8:11], v[136:139], v[168:171], v[8:11]
	v_mfma_f32_16x16x32_bf16 v[4:7], v[144:147], v[168:171], v[4:7]
	s_setprio 0
; #define PG8_STAGE(bufoff, gbase, voff) do { _Pragma("unroll") for (int _i = 0; _i < 2; ++_i) \
;         __builtin_amdgcn_global_load_lds((const unsigned*)((const char*)(gbase) + (voff)[_i]), (PG8_LAS unsigned*)(lds + (bufoff) + ldsw + _i * 8192), 16, 0, 0); } while (0)
; #define PG8_LDA(dst, b, h) do { _Pragma("unroll") for (int m = 0; m < 4; ++m) _Pragma("unroll") for (int k = 0; k < 2; ++k) dst[m][k] = *(const PG8_LAS bf16x8*)(lds + PG8_SA(b, h) + aoff + m * 2048 + k * 1024); } while (0)
; #define PG8_WAIT_V(n) asm volatile("s_waitcnt vmcnt(" #n ")" ::: "memory")
; #define PG8_WAIT_L(n) asm volatile("s_waitcnt lgkmcnt(" #n ")" ::: "memory")
; template <class Epi, class Sched, bool ALIGN_EPI = false, bool SP2 = false>
; __device__ __forceinline__ void gemm_phase(PG8_LAS unsigned char* lds, const Gemm g, const Sched& S, const Epi& E, int wave0) {
;     ...
;         for (int t = 0; t < nt; t += 2) {
;             const bool last = (t == nt - 2);
;             const char* a1 = cA + (size_t)(t + 1) * kstep;
;             const char* a2 = last ? nA : cA + (size_t)(t + 2) * kstep; const char* b2 = last ? nB : cB + (size_t)(t + 2) * kstep;
;             const char* a3 = a2 + kstep; const char* b3 = b2 + kstep;
;             if (last && has_next) S.a_ready(nxt);
;             if constexpr (SP2) {
;             PG8_LDB(B0, 0, 0); PG8_LDB(B1, 0, 1); PG8_SCHED; PG8_LDA(At, 0, 0); PG8_STAGE(PG8_SA(1, 1), a1 + hstep, voffA);
;             PG8_WAIT_V(8); PG8_WAIT_L(0); PG8_BAR; PG8_MMA(0, 0, At, B0); PG8_MMA(0, 1, At, B1); PG8_BAR; PG8_SCHED;
;             PG8_LDA(At, 0, 1); PG8_STAGE(PG8_SB(0, 0), b2, voffB); PG8_STAGE(PG8_SB(0, 1), b2 + hstep, voffB); PG8_STAGE(PG8_SA(0, 0), a2, voffA);
;             PG8_WAIT_V(8); PG8_WAIT_L(0); PG8_BAR; if (!cur.half) { PG8_MMA(1, 0, At, B0); PG8_MMA(1, 1, At, B1); } PG8_BAR; PG8_SCHED;
;             PG8_LDB(B0, 1, 0); PG8_LDB(B1, 1, 1); PG8_SCHED; PG8_LDA(At, 1, 0); PG8_STAGE(PG8_SA(0, 1), a2 + hstep, voffA);
;             PG8_WAIT_V(8); PG8_WAIT_L(0); PG8_BAR; PG8_MMA(0, 0, At, B0); PG8_MMA(0, 1, At, B1); PG8_BAR; PG8_SCHED;
;             PG8_LDA(At, 1, 1); PG8_STAGE(PG8_SB(1, 0), b3, voffB); PG8_STAGE(PG8_SB(1, 1), b3 + hstep, voffB); PG8_STAGE(PG8_SA(1, 0), a3, voffA);
;             PG8_WAIT_V(8); PG8_WAIT_L(0); PG8_BAR; if (!cur.half) { PG8_MMA(1, 0, At, B0); PG8_MMA(1, 1, At, B1); } PG8_BAR; PG8_SCHED;
.LBB0_2955:
	s_barrier
	s_add_i32 s59, 0, 0x18000
	v_add_u32_e32 v1, s59, v219
	s_add_i32 s60, 0, 0x1c000
	ds_read_b128 v[148:151], v1
	ds_read_b128 v[152:155], v1 offset:1024
	ds_read_b128 v[156:159], v1 offset:2048
	ds_read_b128 v[160:163], v1 offset:3072
	v_add_u32_e32 v1, s60, v219
	ds_read_b128 v[132:135], v1
	ds_read_b128 v[136:139], v1 offset:1024
	ds_read_b128 v[140:143], v1 offset:2048
	ds_read_b128 v[144:147], v1 offset:3072
	s_add_u32 s34, s34, 0x40000
	s_addc_u32 s35, s35, 0
	s_mov_b32 m0, s40
	v_lshl_add_u64 v[226:227], s[34:35], 0, v[196:197]
	s_waitcnt lgkmcnt(0)
	ds_read_b128 v[164:167], v222 offset:32768
	ds_read_b128 v[168:171], v222 offset:33792
	ds_read_b128 v[172:175], v222 offset:34816
	ds_read_b128 v[176:179], v222 offset:35840
	ds_read_b128 v[180:183], v222 offset:36864
	ds_read_b128 v[184:187], v222 offset:37888
	ds_read_b128 v[188:191], v222 offset:38912
	ds_read_b128 v[192:195], v222 offset:39936
	global_load_lds_dwordx4 v[226:227], off
	v_lshl_add_u64 v[226:227], s[34:35], 0, v[200:201]
	s_mov_b32 m0, s41
	s_nop 0
	global_load_lds_dwordx4 v[226:227], off
	s_waitcnt lgkmcnt(0)
	s_setprio 1
	s_waitcnt lgkmcnt(0)
	v_mfma_f32_16x16x32_bf16 v[128:131], v[148:151], v[164:167], v[128:131]
	v_mfma_f32_16x16x32_bf16 v[124:127], v[156:159], v[164:167], v[124:127]
	v_mfma_f32_16x16x32_bf16 v[112:115], v[148:151], v[172:175], v[112:115]
	v_mfma_f32_16x16x32_bf16 v[108:111], v[156:159], v[172:175], v[108:111]
	v_mfma_f32_16x16x32_bf16 v[96:99], v[148:151], v[180:183], v[96:99]
	v_mfma_f32_16x16x32_bf16 v[92:95], v[156:159], v[180:183], v[92:95]
	v_mfma_f32_16x16x32_bf16 v[80:83], v[148:151], v[188:191], v[80:83]
	v_mfma_f32_16x16x32_bf16 v[76:79], v[156:159], v[188:191], v[76:79]
	s_waitcnt vmcnt(8)
	s_barrier
	v_mfma_f32_16x16x32_bf16 v[128:131], v[152:155], v[168:171], v[128:131]
	v_mfma_f32_16x16x32_bf16 v[124:127], v[160:163], v[168:171], v[124:127]
	v_mfma_f32_16x16x32_bf16 v[112:115], v[152:155], v[176:179], v[112:115]
	v_mfma_f32_16x16x32_bf16 v[108:111], v[160:163], v[176:179], v[108:111]
	v_mfma_f32_16x16x32_bf16 v[96:99], v[152:155], v[184:187], v[96:99]
	v_mfma_f32_16x16x32_bf16 v[92:95], v[160:163], v[184:187], v[92:95]
	v_mfma_f32_16x16x32_bf16 v[80:83], v[152:155], v[192:195], v[80:83]
	v_mfma_f32_16x16x32_bf16 v[76:79], v[160:163], v[192:195], v[76:79]
	s_setprio 0
	s_setprio 1
	v_mfma_f32_16x16x32_bf16 v[120:123], v[132:135], v[164:167], v[120:123]
	v_mfma_f32_16x16x32_bf16 v[116:119], v[140:143], v[164:167], v[116:119]
	v_mfma_f32_16x16x32_bf16 v[104:107], v[132:135], v[172:175], v[104:107]
	v_mfma_f32_16x16x32_bf16 v[100:103], v[140:143], v[172:175], v[100:103]
	v_mfma_f32_16x16x32_bf16 v[88:91], v[132:135], v[180:183], v[88:91]
	v_mfma_f32_16x16x32_bf16 v[84:87], v[140:143], v[180:183], v[84:87]
	v_mfma_f32_16x16x32_bf16 v[72:75], v[132:135], v[188:191], v[72:75]
	v_mfma_f32_16x16x32_bf16 v[68:71], v[140:143], v[188:191], v[68:71]
	v_mfma_f32_16x16x32_bf16 v[120:123], v[136:139], v[168:171], v[120:123]
	v_mfma_f32_16x16x32_bf16 v[116:119], v[144:147], v[168:171], v[116:119]
	v_mfma_f32_16x16x32_bf16 v[104:107], v[136:139], v[176:179], v[104:107]
	v_mfma_f32_16x16x32_bf16 v[100:103], v[144:147], v[176:179], v[100:103]
	v_mfma_f32_16x16x32_bf16 v[88:91], v[136:139], v[184:187], v[88:91]
	v_mfma_f32_16x16x32_bf16 v[84:87], v[144:147], v[184:187], v[84:87]
	v_mfma_f32_16x16x32_bf16 v[72:75], v[136:139], v[192:195], v[72:75]
	v_mfma_f32_16x16x32_bf16 v[68:71], v[144:147], v[192:195], v[68:71]
	s_setprio 0
	s_barrier
	s_add_i32 s34, s59, s37
	v_lshl_add_u64 v[2:3], v[2:3], 0, s[12:13]
	s_mov_b32 m0, s34
	ds_read_b128 v[188:191], v222 offset:49152
	ds_read_b128 v[192:195], v222 offset:50176
	ds_read_b128 v[180:183], v222 offset:51200
	ds_read_b128 v[184:187], v222 offset:52224
	ds_read_b128 v[172:175], v222 offset:53248
	ds_read_b128 v[176:179], v222 offset:54272
	ds_read_b128 v[164:167], v222 offset:55296
	ds_read_b128 v[168:171], v222 offset:56320
	global_load_lds_dwordx4 v[2:3], off
	s_add_i32 m0, s34, 0x2000
	s_add_u32 s30, s30, 0x40080
	v_lshl_add_u64 v[2:3], v[210:211], 0, s[12:13]
	s_addc_u32 s31, s31, 0
	s_add_i32 s34, s60, s37
	global_load_lds_dwordx4 v[2:3], off
	v_lshl_add_u64 v[2:3], s[30:31], 0, v[198:199]
	s_mov_b32 m0, s34
	s_and_b64 vcc, exec, s[6:7]
	global_load_lds_dwordx4 v[2:3], off
	v_lshl_add_u64 v[2:3], s[30:31], 0, v[202:203]
	s_add_i32 m0, s34, 0x2000
	s_nop 0
	global_load_lds_dwordx4 v[2:3], off
	v_lshl_add_u64 v[2:3], v[212:213], 0, s[12:13]
	s_mov_b32 m0, s45
	s_nop 0
	global_load_lds_dwordx4 v[2:3], off
	v_lshl_add_u64 v[2:3], v[214:215], 0, s[12:13]
	s_mov_b32 m0, s46
	s_nop 0
	global_load_lds_dwordx4 v[2:3], off
	s_waitcnt vmcnt(8)
	s_waitcnt lgkmcnt(0)
	s_barrier
	s_cbranch_vccnz .LBB0_2952
	s_setprio 1
	s_waitcnt lgkmcnt(0)
	v_mfma_f32_16x16x32_bf16 v[64:67], v[148:151], v[188:191], v[64:67]
	v_mfma_f32_16x16x32_bf16 v[60:63], v[156:159], v[188:191], v[60:63]
	v_mfma_f32_16x16x32_bf16 v[48:51], v[148:151], v[180:183], v[48:51]
	v_mfma_f32_16x16x32_bf16 v[44:47], v[156:159], v[180:183], v[44:47]
	v_mfma_f32_16x16x32_bf16 v[32:35], v[148:151], v[172:175], v[32:35]
	v_mfma_f32_16x16x32_bf16 v[28:31], v[156:159], v[172:175], v[28:31]
	v_mfma_f32_16x16x32_bf16 v[16:19], v[148:151], v[164:167], v[16:19]
	v_mfma_f32_16x16x32_bf16 v[12:15], v[156:159], v[164:167], v[12:15]
	v_mfma_f32_16x16x32_bf16 v[64:67], v[152:155], v[192:195], v[64:67]
	v_mfma_f32_16x16x32_bf16 v[60:63], v[160:163], v[192:195], v[60:63]
	v_mfma_f32_16x16x32_bf16 v[48:51], v[152:155], v[184:187], v[48:51]
	v_mfma_f32_16x16x32_bf16 v[44:47], v[160:163], v[184:187], v[44:47]
	v_mfma_f32_16x16x32_bf16 v[32:35], v[152:155], v[176:179], v[32:35]
	v_mfma_f32_16x16x32_bf16 v[28:31], v[160:163], v[176:179], v[28:31]
	v_mfma_f32_16x16x32_bf16 v[16:19], v[152:155], v[168:171], v[16:19]
	v_mfma_f32_16x16x32_bf16 v[12:15], v[160:163], v[168:171], v[12:15]
	s_setprio 0
	s_setprio 1
	v_mfma_f32_16x16x32_bf16 v[56:59], v[132:135], v[188:191], v[56:59]
	v_mfma_f32_16x16x32_bf16 v[52:55], v[140:143], v[188:191], v[52:55]
	v_mfma_f32_16x16x32_bf16 v[40:43], v[132:135], v[180:183], v[40:43]
	v_mfma_f32_16x16x32_bf16 v[36:39], v[140:143], v[180:183], v[36:39]
	v_mfma_f32_16x16x32_bf16 v[24:27], v[132:135], v[172:175], v[24:27]
	v_mfma_f32_16x16x32_bf16 v[20:23], v[140:143], v[172:175], v[20:23]
	v_mfma_f32_16x16x32_bf16 v[8:11], v[132:135], v[164:167], v[8:11]
	v_mfma_f32_16x16x32_bf16 v[2:5], v[140:143], v[164:167], v[4:7]
	v_mfma_f32_16x16x32_bf16 v[56:59], v[136:139], v[192:195], v[56:59]
	v_mfma_f32_16x16x32_bf16 v[52:55], v[144:147], v[192:195], v[52:55]
	v_mfma_f32_16x16x32_bf16 v[40:43], v[136:139], v[184:187], v[40:43]
	v_mfma_f32_16x16x32_bf16 v[36:39], v[144:147], v[184:187], v[36:39]
	v_mfma_f32_16x16x32_bf16 v[24:27], v[136:139], v[176:179], v[24:27]
	v_mfma_f32_16x16x32_bf16 v[20:23], v[144:147], v[176:179], v[20:23]
	v_mfma_f32_16x16x32_bf16 v[8:11], v[136:139], v[168:171], v[8:11]
	v_mfma_f32_16x16x32_bf16 v[4:7], v[144:147], v[168:171], v[2:5]
	s_setprio 0
	s_branch .LBB0_2952

; #define PG8_STAGE(bufoff, gbase, voff) do { _Pragma("unroll") for (int _i = 0; _i < 2; ++_i) \
;         __builtin_amdgcn_global_load_lds((const unsigned*)((const char*)(gbase) + (voff)[_i]), (PG8_LAS unsigned*)(lds + (bufoff) + ldsw + _i * 8192), 16, 0, 0); } while (0)
; #define PG8_LDA(dst, b, h) do { _Pragma("unroll") for (int m = 0; m < 4; ++m) _Pragma("unroll") for (int k = 0; k < 2; ++k) dst[m][k] = *(const PG8_LAS bf16x8*)(lds + PG8_SA(b, h) + aoff + m * 2048 + k * 1024); } while (0)
; #define PG8_LDB(dst, b, h) do { _Pragma("unroll") for (int n = 0; n < 2; ++n) _Pragma("unroll") for (int k = 0; k < 2; ++k) dst[n][k] = *(const PG8_LAS bf16x8*)(lds + PG8_SB(b, h) + boff + n * 2048 + k * 1024); } while (0)
; #define PG8_MMA(ai, bj, At, Bt) do { __builtin_amdgcn_s_setprio(1); _Pragma("unroll") for (int m = 0; m < 4; ++m) _Pragma("unroll") for (int n = 0; n < 2; ++n) _Pragma("unroll") for (int k = 0; k < 2; ++k) \
;         acc[ai][bj][m][n] = __builtin_amdgcn_mfma_f32_16x16x32_bf16(Bt[n][k], At[m][k], acc[ai][bj][m][n], 0, 0, 0); __builtin_amdgcn_s_setprio(0); } while (0)
; #define PG8_WAIT_V(n) asm volatile("s_waitcnt vmcnt(" #n ")" ::: "memory")
; template <class Epi, class Sched, bool ALIGN_EPI = false, bool SP2 = false>
; __device__ __forceinline__ void gemm_phase(PG8_LAS unsigned char* lds, const Gemm g, const Sched& S, const Epi& E, int wave0) {
;     ...
;         for (int t = 0; t < nt; t += 2) {
;             const bool last = (t == nt - 2);
;             const char* a1 = cA + (size_t)(t + 1) * kstep;
;             const char* a2 = last ? nA : cA + (size_t)(t + 2) * kstep; const char* b2 = last ? nB : cB + (size_t)(t + 2) * kstep;
;             const char* a3 = a2 + kstep; const char* b3 = b2 + kstep;
;             if (last && has_next) S.a_ready(nxt);
;             if constexpr (SP2) {
;             PG8_LDB(B0, 0, 0); PG8_LDB(B1, 0, 1); PG8_SCHED; PG8_LDA(At, 0, 0); PG8_STAGE(PG8_SA(1, 1), a1 + hstep, voffA);
;             PG8_WAIT_V(8); PG8_WAIT_L(0); PG8_BAR; PG8_MMA(0, 0, At, B0); PG8_MMA(0, 1, At, B1); PG8_BAR; PG8_SCHED;
;             PG8_LDA(At, 0, 1); PG8_STAGE(PG8_SB(0, 0), b2, voffB); PG8_STAGE(PG8_SB(0, 1), b2 + hstep, voffB); PG8_STAGE(PG8_SA(0, 0), a2, voffA);
;             PG8_WAIT_V(8); PG8_WAIT_L(0); PG8_BAR; if (!cur.half) { PG8_MMA(1, 0, At, B0); PG8_MMA(1, 1, At, B1); } PG8_BAR; PG8_SCHED;
.LBB0_3132:
	ds_read_b128 v[148:151], v220
	ds_read_b128 v[152:155], v220 offset:1024
	ds_read_b128 v[156:159], v220 offset:2048
	ds_read_b128 v[160:163], v220 offset:3072
	ds_read_b128 v[132:135], v221
	ds_read_b128 v[136:139], v221 offset:1024
	ds_read_b128 v[140:143], v221 offset:2048
	ds_read_b128 v[144:147], v221 offset:3072
	s_add_u32 s0, s6, 0xfffc0080
	s_addc_u32 s1, s7, -1
	s_cmp_eq_u32 s76, 12
	s_cselect_b32 s57, s49, s1
	s_cselect_b32 s56, s68, s0
	s_cselect_b32 s9, s47, s75
	s_cselect_b32 s8, s69, s74
	v_lshl_add_u64 v[2:3], s[6:7], 0, v[204:205]
	s_add_i32 m0, s33, 0xc000
	s_waitcnt lgkmcnt(0)
	ds_read_b128 v[164:167], v222
	ds_read_b128 v[168:171], v222 offset:1024
	ds_read_b128 v[172:175], v222 offset:2048
	ds_read_b128 v[176:179], v222 offset:3072
	ds_read_b128 v[180:183], v222 offset:4096
	ds_read_b128 v[184:187], v222 offset:5120
	ds_read_b128 v[188:191], v222 offset:6144
	ds_read_b128 v[192:195], v222 offset:7168
	global_load_lds_dwordx4 v[2:3], off
	v_lshl_add_u64 v[2:3], s[6:7], 0, v[206:207]
	s_add_i32 m0, s33, 0xe000
	s_nop 0
	global_load_lds_dwordx4 v[2:3], off
	s_waitcnt lgkmcnt(0)
	s_setprio 1
	s_waitcnt lgkmcnt(0)
	v_mfma_f32_16x16x32_bf16 v[128:131], v[148:151], v[164:167], v[128:131]
	v_mfma_f32_16x16x32_bf16 v[124:127], v[156:159], v[164:167], v[124:127]
	v_mfma_f32_16x16x32_bf16 v[120:123], v[148:151], v[172:175], v[120:123]
	v_mfma_f32_16x16x32_bf16 v[116:119], v[156:159], v[172:175], v[116:119]
	v_mfma_f32_16x16x32_bf16 v[112:115], v[148:151], v[180:183], v[112:115]
	v_mfma_f32_16x16x32_bf16 v[108:111], v[156:159], v[180:183], v[108:111]
	v_mfma_f32_16x16x32_bf16 v[104:107], v[148:151], v[188:191], v[104:107]
	v_mfma_f32_16x16x32_bf16 v[100:103], v[156:159], v[188:191], v[100:103]
	s_waitcnt vmcnt(8)
	s_barrier
	v_mfma_f32_16x16x32_bf16 v[128:131], v[152:155], v[168:171], v[128:131]
	v_mfma_f32_16x16x32_bf16 v[124:127], v[160:163], v[168:171], v[124:127]
	v_mfma_f32_16x16x32_bf16 v[120:123], v[152:155], v[176:179], v[120:123]
	v_mfma_f32_16x16x32_bf16 v[116:119], v[160:163], v[176:179], v[116:119]
	v_mfma_f32_16x16x32_bf16 v[112:115], v[152:155], v[184:187], v[112:115]
	v_mfma_f32_16x16x32_bf16 v[108:111], v[160:163], v[184:187], v[108:111]
	v_mfma_f32_16x16x32_bf16 v[104:107], v[152:155], v[192:195], v[104:107]
	v_mfma_f32_16x16x32_bf16 v[100:103], v[160:163], v[192:195], v[100:103]
	s_setprio 0
	s_setprio 1
	v_mfma_f32_16x16x32_bf16 v[68:71], v[132:135], v[164:167], v[68:71]
	v_mfma_f32_16x16x32_bf16 v[60:63], v[140:143], v[164:167], v[60:63]
	v_mfma_f32_16x16x32_bf16 v[56:59], v[132:135], v[172:175], v[56:59]
	v_mfma_f32_16x16x32_bf16 v[52:55], v[140:143], v[172:175], v[52:55]
	v_mfma_f32_16x16x32_bf16 v[48:51], v[132:135], v[180:183], v[48:51]
	v_mfma_f32_16x16x32_bf16 v[44:47], v[140:143], v[180:183], v[44:47]
	v_mfma_f32_16x16x32_bf16 v[40:43], v[132:135], v[188:191], v[40:43]
	v_mfma_f32_16x16x32_bf16 v[36:39], v[140:143], v[188:191], v[36:39]
	v_mfma_f32_16x16x32_bf16 v[68:71], v[136:139], v[168:171], v[68:71]
	v_mfma_f32_16x16x32_bf16 v[60:63], v[144:147], v[168:171], v[60:63]
	v_mfma_f32_16x16x32_bf16 v[56:59], v[136:139], v[176:179], v[56:59]
	v_mfma_f32_16x16x32_bf16 v[52:55], v[144:147], v[176:179], v[52:55]
	v_mfma_f32_16x16x32_bf16 v[48:51], v[136:139], v[184:187], v[48:51]
	v_mfma_f32_16x16x32_bf16 v[44:47], v[144:147], v[184:187], v[44:47]
	v_mfma_f32_16x16x32_bf16 v[40:43], v[136:139], v[192:195], v[40:43]
	v_mfma_f32_16x16x32_bf16 v[36:39], v[144:147], v[192:195], v[36:39]
	s_setprio 0
	s_barrier
	s_add_i32 s0, s62, s31
	v_lshl_add_u64 v[2:3], s[8:9], 0, v[198:199]
	s_mov_b32 m0, s0
	ds_read_b128 v[188:191], v222 offset:16384
	ds_read_b128 v[192:195], v222 offset:17408
	ds_read_b128 v[180:183], v222 offset:18432
	ds_read_b128 v[184:187], v222 offset:19456
	ds_read_b128 v[172:175], v222 offset:20480
	ds_read_b128 v[176:179], v222 offset:21504
	ds_read_b128 v[164:167], v222 offset:22528
	ds_read_b128 v[168:171], v222 offset:23552
	global_load_lds_dwordx4 v[2:3], off
	s_add_i32 m0, s0, 0x2000
	s_add_u32 s0, s8, 0x40000
	v_lshl_add_u64 v[210:211], s[8:9], 0, v[202:203]
	s_addc_u32 s1, s9, 0
	s_add_i32 s77, s63, s31
	global_load_lds_dwordx4 v[210:211], off
	v_lshl_add_u64 v[212:213], s[0:1], 0, v[198:199]
	s_mov_b32 m0, s77
	v_lshl_add_u64 v[214:215], s[56:57], 0, v[200:201]
	global_load_lds_dwordx4 v[212:213], off
	v_lshl_add_u64 v[212:213], s[0:1], 0, v[202:203]
	s_add_i32 m0, s77, 0x2000
	v_cmp_ne_u32_e64 s[0:1], 1, v225
	global_load_lds_dwordx4 v[212:213], off
	v_lshl_add_u64 v[212:213], s[56:57], 0, v[196:197]
	s_mov_b32 m0, s33
	s_andn2_b64 vcc, exec, s[2:3]
	global_load_lds_dwordx4 v[212:213], off
	s_mov_b32 m0, s35
	s_nop 0
	global_load_lds_dwordx4 v[214:215], off
	s_waitcnt vmcnt(8)
	s_waitcnt lgkmcnt(0)
	s_barrier
	s_cbranch_vccnz .LBB0_3134
; #define PG8_MMA(ai, bj, At, Bt) do { __builtin_amdgcn_s_setprio(1); _Pragma("unroll") for (int m = 0; m < 4; ++m) _Pragma("unroll") for (int n = 0; n < 2; ++n) _Pragma("unroll") for (int k = 0; k < 2; ++k) \
;         acc[ai][bj][m][n] = __builtin_amdgcn_mfma_f32_16x16x32_bf16(Bt[n][k], At[m][k], acc[ai][bj][m][n], 0, 0, 0); __builtin_amdgcn_s_setprio(0); } while (0)
; #define PG8_WAIT_V(n) asm volatile("s_waitcnt vmcnt(" #n ")" ::: "memory")
; #define PG8_WAIT_L(n) asm volatile("s_waitcnt lgkmcnt(" #n ")" ::: "memory")
; #define PG8_BAR __builtin_amdgcn_s_barrier()
; #define PG8_SCHED __builtin_amdgcn_sched_barrier(0)
; template <class Epi, class Sched, bool ALIGN_EPI = false, bool SP2 = false>
; __device__ __forceinline__ void gemm_phase(PG8_LAS unsigned char* lds, const Gemm g, const Sched& S, const Epi& E, int wave0) {
;     ...
;             PG8_WAIT_V(8); PG8_WAIT_L(0); PG8_BAR; if (!cur.half) { PG8_MMA(1, 0, At, B0); PG8_MMA(1, 1, At, B1); } PG8_BAR; PG8_SCHED;
	s_setprio 1
	s_waitcnt lgkmcnt(0)
	v_mfma_f32_16x16x32_bf16 v[96:99], v[148:151], v[188:191], v[96:99]
	v_mfma_f32_16x16x32_bf16 v[92:95], v[156:159], v[188:191], v[92:95]
	v_mfma_f32_16x16x32_bf16 v[88:91], v[148:151], v[180:183], v[88:91]
	v_mfma_f32_16x16x32_bf16 v[84:87], v[156:159], v[180:183], v[84:87]
	v_mfma_f32_16x16x32_bf16 v[80:83], v[148:151], v[172:175], v[80:83]
	v_mfma_f32_16x16x32_bf16 v[76:79], v[156:159], v[172:175], v[76:79]
	v_mfma_f32_16x16x32_bf16 v[72:75], v[148:151], v[164:167], v[72:75]
	v_mfma_f32_16x16x32_bf16 v[64:67], v[156:159], v[164:167], v[64:67]
	v_mfma_f32_16x16x32_bf16 v[96:99], v[152:155], v[192:195], v[96:99]
	v_mfma_f32_16x16x32_bf16 v[92:95], v[160:163], v[192:195], v[92:95]
	v_mfma_f32_16x16x32_bf16 v[88:91], v[152:155], v[184:187], v[88:91]
	v_mfma_f32_16x16x32_bf16 v[84:87], v[160:163], v[184:187], v[84:87]
	v_mfma_f32_16x16x32_bf16 v[80:83], v[152:155], v[176:179], v[80:83]
	v_mfma_f32_16x16x32_bf16 v[76:79], v[160:163], v[176:179], v[76:79]
	v_mfma_f32_16x16x32_bf16 v[72:75], v[152:155], v[168:171], v[72:75]
	v_mfma_f32_16x16x32_bf16 v[64:67], v[160:163], v[168:171], v[64:67]
	s_setprio 0
	s_setprio 1
	v_mfma_f32_16x16x32_bf16 v[32:35], v[132:135], v[188:191], v[32:35]
	v_mfma_f32_16x16x32_bf16 v[28:31], v[140:143], v[188:191], v[28:31]
	v_mfma_f32_16x16x32_bf16 v[24:27], v[132:135], v[180:183], v[24:27]
	v_mfma_f32_16x16x32_bf16 v[20:23], v[140:143], v[180:183], v[20:23]
	v_mfma_f32_16x16x32_bf16 v[16:19], v[132:135], v[172:175], v[16:19]
	v_mfma_f32_16x16x32_bf16 v[12:15], v[140:143], v[172:175], v[12:15]
	v_mfma_f32_16x16x32_bf16 v[8:11], v[132:135], v[164:167], v[8:11]
	v_mfma_f32_16x16x32_bf16 v[4:7], v[140:143], v[164:167], v[4:7]
	v_mfma_f32_16x16x32_bf16 v[32:35], v[136:139], v[192:195], v[32:35]
	v_mfma_f32_16x16x32_bf16 v[28:31], v[144:147], v[192:195], v[28:31]
	v_mfma_f32_16x16x32_bf16 v[24:27], v[136:139], v[184:187], v[24:27]
	v_mfma_f32_16x16x32_bf16 v[20:23], v[144:147], v[184:187], v[20:23]
	v_mfma_f32_16x16x32_bf16 v[16:19], v[136:139], v[176:179], v[16:19]
	v_mfma_f32_16x16x32_bf16 v[12:15], v[144:147], v[176:179], v[12:15]
	v_mfma_f32_16x16x32_bf16 v[8:11], v[136:139], v[168:171], v[8:11]
	v_mfma_f32_16x16x32_bf16 v[4:7], v[144:147], v[168:171], v[4:7]
	s_setprio 0
; #define PG8_STAGE(bufoff, gbase, voff) do { _Pragma("unroll") for (int _i = 0; _i < 2; ++_i) \
;         __builtin_amdgcn_global_load_lds((const unsigned*)((const char*)(gbase) + (voff)[_i]), (PG8_LAS unsigned*)(lds + (bufoff) + ldsw + _i * 8192), 16, 0, 0); } while (0)
; #define PG8_LDA(dst, b, h) do { _Pragma("unroll") for (int m = 0; m < 4; ++m) _Pragma("unroll") for (int k = 0; k < 2; ++k) dst[m][k] = *(const PG8_LAS bf16x8*)(lds + PG8_SA(b, h) + aoff + m * 2048 + k * 1024); } while (0)
; #define PG8_WAIT_V(n) asm volatile("s_waitcnt vmcnt(" #n ")" ::: "memory")
; #define PG8_WAIT_L(n) asm volatile("s_waitcnt lgkmcnt(" #n ")" ::: "memory")
; template <class Epi, class Sched, bool ALIGN_EPI = false, bool SP2 = false>
; __device__ __forceinline__ void gemm_phase(PG8_LAS unsigned char* lds, const Gemm g, const Sched& S, const Epi& E, int wave0) {
;     ...
;         for (int t = 0; t < nt; t += 2) {
;             const bool last = (t == nt - 2);
;             const char* a1 = cA + (size_t)(t + 1) * kstep;
;             const char* a2 = last ? nA : cA + (size_t)(t + 2) * kstep; const char* b2 = last ? nB : cB + (size_t)(t + 2) * kstep;
;             const char* a3 = a2 + kstep; const char* b3 = b2 + kstep;
;             if (last && has_next) S.a_ready(nxt);
;             if constexpr (SP2) {
;             PG8_LDB(B0, 0, 0); PG8_LDB(B1, 0, 1); PG8_SCHED; PG8_LDA(At, 0, 0); PG8_STAGE(PG8_SA(1, 1), a1 + hstep, voffA);
;             PG8_WAIT_V(8); PG8_WAIT_L(0); PG8_BAR; PG8_MMA(0, 0, At, B0); PG8_MMA(0, 1, At, B1); PG8_BAR; PG8_SCHED;
;             PG8_LDA(At, 0, 1); PG8_STAGE(PG8_SB(0, 0), b2, voffB); PG8_STAGE(PG8_SB(0, 1), b2 + hstep, voffB); PG8_STAGE(PG8_SA(0, 0), a2, voffA);
;             PG8_WAIT_V(8); PG8_WAIT_L(0); PG8_BAR; if (!cur.half) { PG8_MMA(1, 0, At, B0); PG8_MMA(1, 1, At, B1); } PG8_BAR; PG8_SCHED;
;             PG8_LDB(B0, 1, 0); PG8_LDB(B1, 1, 1); PG8_SCHED; PG8_LDA(At, 1, 0); PG8_STAGE(PG8_SA(0, 1), a2 + hstep, voffA);
;             PG8_WAIT_V(8); PG8_WAIT_L(0); PG8_BAR; PG8_MMA(0, 0, At, B0); PG8_MMA(0, 1, At, B1); PG8_BAR; PG8_SCHED;
;             PG8_LDA(At, 1, 1); PG8_STAGE(PG8_SB(1, 0), b3, voffB); PG8_STAGE(PG8_SB(1, 1), b3 + hstep, voffB); PG8_STAGE(PG8_SA(1, 0), a3, voffA);
;             PG8_WAIT_V(8); PG8_WAIT_L(0); PG8_BAR; if (!cur.half) { PG8_MMA(1, 0, At, B0); PG8_MMA(1, 1, At, B1); } PG8_BAR; PG8_SCHED;
.LBB0_3134:
	s_barrier
	s_add_i32 s77, 0, 0x18000
	v_add_u32_e32 v1, s77, v219
	s_add_i32 s78, 0, 0x1c000
	ds_read_b128 v[148:151], v1
	ds_read_b128 v[152:155], v1 offset:1024
	ds_read_b128 v[156:159], v1 offset:2048
	ds_read_b128 v[160:163], v1 offset:3072
	v_add_u32_e32 v1, s78, v219
	ds_read_b128 v[132:135], v1
	ds_read_b128 v[136:139], v1 offset:1024
	ds_read_b128 v[140:143], v1 offset:2048
	ds_read_b128 v[144:147], v1 offset:3072
	s_add_u32 s56, s56, 0x40000
	s_addc_u32 s57, s57, 0
	s_mov_b32 m0, s37
	v_lshl_add_u64 v[226:227], s[56:57], 0, v[196:197]
	s_waitcnt lgkmcnt(0)
	ds_read_b128 v[164:167], v222 offset:32768
	ds_read_b128 v[168:171], v222 offset:33792
	ds_read_b128 v[172:175], v222 offset:34816
	ds_read_b128 v[176:179], v222 offset:35840
	ds_read_b128 v[180:183], v222 offset:36864
	ds_read_b128 v[184:187], v222 offset:37888
	ds_read_b128 v[188:191], v222 offset:38912
	ds_read_b128 v[192:195], v222 offset:39936
	global_load_lds_dwordx4 v[226:227], off
	v_lshl_add_u64 v[226:227], s[56:57], 0, v[200:201]
	s_mov_b32 m0, s39
	s_nop 0
	global_load_lds_dwordx4 v[226:227], off
	s_waitcnt lgkmcnt(0)
	s_setprio 1
	s_waitcnt lgkmcnt(0)
	v_mfma_f32_16x16x32_bf16 v[128:131], v[148:151], v[164:167], v[128:131]
	v_mfma_f32_16x16x32_bf16 v[124:127], v[156:159], v[164:167], v[124:127]
	v_mfma_f32_16x16x32_bf16 v[120:123], v[148:151], v[172:175], v[120:123]
	v_mfma_f32_16x16x32_bf16 v[116:119], v[156:159], v[172:175], v[116:119]
	v_mfma_f32_16x16x32_bf16 v[112:115], v[148:151], v[180:183], v[112:115]
	v_mfma_f32_16x16x32_bf16 v[108:111], v[156:159], v[180:183], v[108:111]
	v_mfma_f32_16x16x32_bf16 v[104:107], v[148:151], v[188:191], v[104:107]
	v_mfma_f32_16x16x32_bf16 v[100:103], v[156:159], v[188:191], v[100:103]
	s_waitcnt vmcnt(8)
	s_barrier
	v_mfma_f32_16x16x32_bf16 v[128:131], v[152:155], v[168:171], v[128:131]
	v_mfma_f32_16x16x32_bf16 v[124:127], v[160:163], v[168:171], v[124:127]
	v_mfma_f32_16x16x32_bf16 v[120:123], v[152:155], v[176:179], v[120:123]
	v_mfma_f32_16x16x32_bf16 v[116:119], v[160:163], v[176:179], v[116:119]
	v_mfma_f32_16x16x32_bf16 v[112:115], v[152:155], v[184:187], v[112:115]
	v_mfma_f32_16x16x32_bf16 v[108:111], v[160:163], v[184:187], v[108:111]
	v_mfma_f32_16x16x32_bf16 v[104:107], v[152:155], v[192:195], v[104:107]
	v_mfma_f32_16x16x32_bf16 v[100:103], v[160:163], v[192:195], v[100:103]
	s_setprio 0
	s_setprio 1
	v_mfma_f32_16x16x32_bf16 v[68:71], v[132:135], v[164:167], v[68:71]
	v_mfma_f32_16x16x32_bf16 v[60:63], v[140:143], v[164:167], v[60:63]
	v_mfma_f32_16x16x32_bf16 v[56:59], v[132:135], v[172:175], v[56:59]
	v_mfma_f32_16x16x32_bf16 v[52:55], v[140:143], v[172:175], v[52:55]
	v_mfma_f32_16x16x32_bf16 v[48:51], v[132:135], v[180:183], v[48:51]
	v_mfma_f32_16x16x32_bf16 v[44:47], v[140:143], v[180:183], v[44:47]
	v_mfma_f32_16x16x32_bf16 v[40:43], v[132:135], v[188:191], v[40:43]
	v_mfma_f32_16x16x32_bf16 v[36:39], v[140:143], v[188:191], v[36:39]
	v_mfma_f32_16x16x32_bf16 v[68:71], v[136:139], v[168:171], v[68:71]
	v_mfma_f32_16x16x32_bf16 v[60:63], v[144:147], v[168:171], v[60:63]
	v_mfma_f32_16x16x32_bf16 v[56:59], v[136:139], v[176:179], v[56:59]
	v_mfma_f32_16x16x32_bf16 v[52:55], v[144:147], v[176:179], v[52:55]
	v_mfma_f32_16x16x32_bf16 v[48:51], v[136:139], v[184:187], v[48:51]
	v_mfma_f32_16x16x32_bf16 v[44:47], v[144:147], v[184:187], v[44:47]
	v_mfma_f32_16x16x32_bf16 v[40:43], v[136:139], v[192:195], v[40:43]
	v_mfma_f32_16x16x32_bf16 v[36:39], v[144:147], v[192:195], v[36:39]
	s_setprio 0
	s_barrier
	s_add_i32 s56, s77, s31
	v_lshl_add_u64 v[2:3], v[2:3], 0, s[22:23]
	s_mov_b32 m0, s56
	ds_read_b128 v[188:191], v222 offset:49152
	ds_read_b128 v[192:195], v222 offset:50176
	ds_read_b128 v[180:183], v222 offset:51200
	ds_read_b128 v[184:187], v222 offset:52224
	ds_read_b128 v[172:175], v222 offset:53248
	ds_read_b128 v[176:179], v222 offset:54272
	ds_read_b128 v[164:167], v222 offset:55296
	ds_read_b128 v[168:171], v222 offset:56320
	global_load_lds_dwordx4 v[2:3], off
	s_add_i32 m0, s56, 0x2000
	s_add_u32 s8, s8, 0x40080
	v_lshl_add_u64 v[2:3], v[210:211], 0, s[22:23]
	s_addc_u32 s9, s9, 0
	s_add_i32 s56, s78, s31
	global_load_lds_dwordx4 v[2:3], off
	v_lshl_add_u64 v[2:3], s[8:9], 0, v[198:199]
	s_mov_b32 m0, s56
	s_and_b64 vcc, exec, s[0:1]
	global_load_lds_dwordx4 v[2:3], off
	v_lshl_add_u64 v[2:3], s[8:9], 0, v[202:203]
	s_add_i32 m0, s56, 0x2000
	s_nop 0
	global_load_lds_dwordx4 v[2:3], off
	v_lshl_add_u64 v[2:3], v[212:213], 0, s[22:23]
	s_mov_b32 m0, s60
	s_nop 0
	global_load_lds_dwordx4 v[2:3], off
	v_lshl_add_u64 v[2:3], v[214:215], 0, s[22:23]
	s_mov_b32 m0, s61
	s_nop 0
	global_load_lds_dwordx4 v[2:3], off
	s_waitcnt vmcnt(8)
	s_waitcnt lgkmcnt(0)
	s_barrier
	s_cbranch_vccnz .LBB0_3131
	s_setprio 1
	s_waitcnt lgkmcnt(0)
	v_mfma_f32_16x16x32_bf16 v[96:99], v[148:151], v[188:191], v[96:99]
	v_mfma_f32_16x16x32_bf16 v[92:95], v[156:159], v[188:191], v[92:95]
	v_mfma_f32_16x16x32_bf16 v[88:91], v[148:151], v[180:183], v[88:91]
	v_mfma_f32_16x16x32_bf16 v[84:87], v[156:159], v[180:183], v[84:87]
	v_mfma_f32_16x16x32_bf16 v[80:83], v[148:151], v[172:175], v[80:83]
	v_mfma_f32_16x16x32_bf16 v[76:79], v[156:159], v[172:175], v[76:79]
	v_mfma_f32_16x16x32_bf16 v[72:75], v[148:151], v[164:167], v[72:75]
	v_mfma_f32_16x16x32_bf16 v[64:67], v[156:159], v[164:167], v[64:67]
	v_mfma_f32_16x16x32_bf16 v[96:99], v[152:155], v[192:195], v[96:99]
	v_mfma_f32_16x16x32_bf16 v[92:95], v[160:163], v[192:195], v[92:95]
	v_mfma_f32_16x16x32_bf16 v[88:91], v[152:155], v[184:187], v[88:91]
	v_mfma_f32_16x16x32_bf16 v[84:87], v[160:163], v[184:187], v[84:87]
	v_mfma_f32_16x16x32_bf16 v[80:83], v[152:155], v[176:179], v[80:83]
	v_mfma_f32_16x16x32_bf16 v[76:79], v[160:163], v[176:179], v[76:79]
	v_mfma_f32_16x16x32_bf16 v[72:75], v[152:155], v[168:171], v[72:75]
	v_mfma_f32_16x16x32_bf16 v[64:67], v[160:163], v[168:171], v[64:67]
	s_setprio 0
	s_setprio 1
	v_mfma_f32_16x16x32_bf16 v[32:35], v[132:135], v[188:191], v[32:35]
	v_mfma_f32_16x16x32_bf16 v[28:31], v[140:143], v[188:191], v[28:31]
	v_mfma_f32_16x16x32_bf16 v[24:27], v[132:135], v[180:183], v[24:27]
	v_mfma_f32_16x16x32_bf16 v[20:23], v[140:143], v[180:183], v[20:23]
	v_mfma_f32_16x16x32_bf16 v[16:19], v[132:135], v[172:175], v[16:19]
	v_mfma_f32_16x16x32_bf16 v[12:15], v[140:143], v[172:175], v[12:15]
	v_mfma_f32_16x16x32_bf16 v[8:11], v[132:135], v[164:167], v[8:11]
	v_mfma_f32_16x16x32_bf16 v[2:5], v[140:143], v[164:167], v[4:7]
	v_mfma_f32_16x16x32_bf16 v[32:35], v[136:139], v[192:195], v[32:35]
	v_mfma_f32_16x16x32_bf16 v[28:31], v[144:147], v[192:195], v[28:31]
	v_mfma_f32_16x16x32_bf16 v[24:27], v[136:139], v[184:187], v[24:27]
	v_mfma_f32_16x16x32_bf16 v[20:23], v[144:147], v[184:187], v[20:23]
	v_mfma_f32_16x16x32_bf16 v[16:19], v[136:139], v[176:179], v[16:19]
	v_mfma_f32_16x16x32_bf16 v[12:15], v[144:147], v[176:179], v[12:15]
	v_mfma_f32_16x16x32_bf16 v[8:11], v[136:139], v[168:171], v[8:11]
	v_mfma_f32_16x16x32_bf16 v[4:7], v[144:147], v[168:171], v[2:5]
	s_setprio 0
	s_branch .LBB0_3131

; #define PG8_STAGE(bufoff, gbase, voff) do { _Pragma("unroll") for (int _i = 0; _i < 2; ++_i) \
;         __builtin_amdgcn_global_load_lds((const unsigned*)((const char*)(gbase) + (voff)[_i]), (PG8_LAS unsigned*)(lds + (bufoff) + ldsw + _i * 8192), 16, 0, 0); } while (0)
; #define PG8_LDA(dst, b, h) do { _Pragma("unroll") for (int m = 0; m < 4; ++m) _Pragma("unroll") for (int k = 0; k < 2; ++k) dst[m][k] = *(const PG8_LAS bf16x8*)(lds + PG8_SA(b, h) + aoff + m * 2048 + k * 1024); } while (0)
; #define PG8_WAIT_V(n) asm volatile("s_waitcnt vmcnt(" #n ")" ::: "memory")
; #define PG8_WAIT_L(n) asm volatile("s_waitcnt lgkmcnt(" #n ")" ::: "memory")
; template <class Epi, class Sched, bool ALIGN_EPI = false, bool SP2 = false>
; __device__ __forceinline__ void gemm_phase(PG8_LAS unsigned char* lds, const Gemm g, const Sched& S, const Epi& E, int wave0) {
;     ...
;         for (int t = 0; t < nt; t += 2) {
;             const bool last = (t == nt - 2);
;             const char* a1 = cA + (size_t)(t + 1) * kstep;
;             const char* a2 = last ? nA : cA + (size_t)(t + 2) * kstep; const char* b2 = last ? nB : cB + (size_t)(t + 2) * kstep;
;             const char* a3 = a2 + kstep; const char* b3 = b2 + kstep;
;             if (last && has_next) S.a_ready(nxt);
;             if constexpr (SP2) {
;             PG8_LDB(B0, 0, 0); PG8_LDB(B1, 0, 1); PG8_SCHED; PG8_LDA(At, 0, 0); PG8_STAGE(PG8_SA(1, 1), a1 + hstep, voffA);
;             PG8_WAIT_V(8); PG8_WAIT_L(0); PG8_BAR; PG8_MMA(0, 0, At, B0); PG8_MMA(0, 1, At, B1); PG8_BAR; PG8_SCHED;
;             PG8_LDA(At, 0, 1); PG8_STAGE(PG8_SB(0, 0), b2, voffB); PG8_STAGE(PG8_SB(0, 1), b2 + hstep, voffB); PG8_STAGE(PG8_SA(0, 0), a2, voffA);
;             PG8_WAIT_V(8); PG8_WAIT_L(0); PG8_BAR; if (!cur.half) { PG8_MMA(1, 0, At, B0); PG8_MMA(1, 1, At, B1); } PG8_BAR; PG8_SCHED;
;             PG8_LDB(B0, 1, 0); PG8_LDB(B1, 1, 1); PG8_SCHED; PG8_LDA(At, 1, 0); PG8_STAGE(PG8_SA(0, 1), a2 + hstep, voffA);
;             PG8_WAIT_V(8); PG8_WAIT_L(0); PG8_BAR; PG8_MMA(0, 0, At, B0); PG8_MMA(0, 1, At, B1); PG8_BAR; PG8_SCHED;
;             PG8_LDA(At, 1, 1); PG8_STAGE(PG8_SB(1, 0), b3, voffB); PG8_STAGE(PG8_SB(1, 1), b3 + hstep, voffB); PG8_STAGE(PG8_SA(1, 0), a3, voffA);
;             PG8_WAIT_V(8); PG8_WAIT_L(0); PG8_BAR; if (!cur.half) { PG8_MMA(1, 0, At, B0); PG8_MMA(1, 1, At, B1); } PG8_BAR; PG8_SCHED;
.LBB0_3229:
	ds_read_b128 v[144:147], v153
	ds_read_b128 v[156:159], v153 offset:1024
	ds_read_b128 v[160:163], v153 offset:2048
	ds_read_b128 v[164:167], v153 offset:3072
	ds_read_b128 v[168:171], v154
	ds_read_b128 v[172:175], v154 offset:1024
	ds_read_b128 v[176:179], v154 offset:2048
	ds_read_b128 v[180:183], v154 offset:3072
	s_add_u32 s18, s16, 0x100
	s_addc_u32 s19, s17, 0
	s_cmp_eq_u32 s44, 40
	s_cselect_b32 s23, s7, s19
	s_cselect_b32 s22, s6, s18
	s_cselect_b32 s21, s15, s43
	s_cselect_b32 s20, s14, s42
	v_lshl_add_u64 v[148:149], s[16:17], 0, v[136:137]
	s_add_i32 m0, s25, 0xc000
	ds_read_b128 v[184:187], v155
	ds_read_b128 v[188:191], v155 offset:1024
	ds_read_b128 v[192:195], v155 offset:2048
	ds_read_b128 v[196:199], v155 offset:3072
	ds_read_b128 v[200:203], v155 offset:4096
	ds_read_b128 v[204:207], v155 offset:5120
	ds_read_b128 v[208:211], v155 offset:6144
	ds_read_b128 v[212:215], v155 offset:7168
	global_load_lds_dwordx4 v[148:149], off
	v_lshl_add_u64 v[148:149], s[16:17], 0, v[138:139]
	s_add_i32 m0, s25, 0xe000
	s_nop 0
	global_load_lds_dwordx4 v[148:149], off
	s_waitcnt lgkmcnt(0)
	s_setprio 1
	s_waitcnt lgkmcnt(0)
	v_mfma_f32_16x16x32_bf16 v[124:127], v[144:147], v[184:187], v[124:127]
	v_mfma_f32_16x16x32_bf16 v[120:123], v[160:163], v[184:187], v[120:123]
	v_mfma_f32_16x16x32_bf16 v[116:119], v[144:147], v[192:195], v[116:119]
	v_mfma_f32_16x16x32_bf16 v[108:111], v[160:163], v[192:195], v[108:111]
	v_mfma_f32_16x16x32_bf16 v[92:95], v[144:147], v[200:203], v[92:95]
	v_mfma_f32_16x16x32_bf16 v[88:91], v[160:163], v[200:203], v[88:91]
	v_mfma_f32_16x16x32_bf16 v[84:87], v[144:147], v[208:211], v[84:87]
	v_mfma_f32_16x16x32_bf16 v[80:83], v[160:163], v[208:211], v[80:83]
	s_waitcnt vmcnt(8)
	s_barrier
	v_mfma_f32_16x16x32_bf16 v[124:127], v[156:159], v[188:191], v[124:127]
	v_mfma_f32_16x16x32_bf16 v[120:123], v[164:167], v[188:191], v[120:123]
	v_mfma_f32_16x16x32_bf16 v[116:119], v[156:159], v[196:199], v[116:119]
	v_mfma_f32_16x16x32_bf16 v[108:111], v[164:167], v[196:199], v[108:111]
	v_mfma_f32_16x16x32_bf16 v[92:95], v[156:159], v[204:207], v[92:95]
	v_mfma_f32_16x16x32_bf16 v[88:91], v[164:167], v[204:207], v[88:91]
	v_mfma_f32_16x16x32_bf16 v[84:87], v[156:159], v[212:215], v[84:87]
	v_mfma_f32_16x16x32_bf16 v[80:83], v[164:167], v[212:215], v[80:83]
	s_setprio 0
	s_setprio 1
	v_mfma_f32_16x16x32_bf16 v[112:115], v[168:171], v[184:187], v[112:115]
	v_mfma_f32_16x16x32_bf16 v[104:107], v[176:179], v[184:187], v[104:107]
	v_mfma_f32_16x16x32_bf16 v[100:103], v[168:171], v[192:195], v[100:103]
	v_mfma_f32_16x16x32_bf16 v[96:99], v[176:179], v[192:195], v[96:99]
	v_mfma_f32_16x16x32_bf16 v[76:79], v[168:171], v[200:203], v[76:79]
	v_mfma_f32_16x16x32_bf16 v[72:75], v[176:179], v[200:203], v[72:75]
	v_mfma_f32_16x16x32_bf16 v[68:71], v[168:171], v[208:211], v[68:71]
	v_mfma_f32_16x16x32_bf16 v[64:67], v[176:179], v[208:211], v[64:67]
	v_mfma_f32_16x16x32_bf16 v[112:115], v[172:175], v[188:191], v[112:115]
	v_mfma_f32_16x16x32_bf16 v[104:107], v[180:183], v[188:191], v[104:107]
	v_mfma_f32_16x16x32_bf16 v[100:103], v[172:175], v[196:199], v[100:103]
	v_mfma_f32_16x16x32_bf16 v[96:99], v[180:183], v[196:199], v[96:99]
	v_mfma_f32_16x16x32_bf16 v[76:79], v[172:175], v[204:207], v[76:79]
	v_mfma_f32_16x16x32_bf16 v[72:75], v[180:183], v[204:207], v[72:75]
	v_mfma_f32_16x16x32_bf16 v[68:71], v[172:175], v[212:215], v[68:71]
	v_mfma_f32_16x16x32_bf16 v[64:67], v[180:183], v[212:215], v[64:67]
	s_setprio 0
	s_barrier
	s_add_i32 s16, s35, s24
	v_lshl_add_u64 v[148:149], s[20:21], 0, v[130:131]
	s_mov_b32 m0, s16
	ds_read_b128 v[184:187], v155 offset:16384
	ds_read_b128 v[188:191], v155 offset:17408
	ds_read_b128 v[192:195], v155 offset:18432
	ds_read_b128 v[196:199], v155 offset:19456
	ds_read_b128 v[200:203], v155 offset:20480
	ds_read_b128 v[204:207], v155 offset:21504
	ds_read_b128 v[208:211], v155 offset:22528
	ds_read_b128 v[212:215], v155 offset:23552
	global_load_lds_dwordx4 v[148:149], off
	s_add_i32 m0, s16, 0x2000
	s_add_u32 s16, s20, 0xb0000
	v_lshl_add_u64 v[218:219], s[20:21], 0, v[134:135]
	s_addc_u32 s17, s21, 0
	s_add_i32 s45, s36, s24
	global_load_lds_dwordx4 v[218:219], off
	v_lshl_add_u64 v[220:221], s[16:17], 0, v[130:131]
	s_mov_b32 m0, s45
	v_lshl_add_u64 v[222:223], s[22:23], 0, v[132:133]
	global_load_lds_dwordx4 v[220:221], off
	v_lshl_add_u64 v[220:221], s[16:17], 0, v[134:135]
	s_add_i32 m0, s45, 0x2000
	s_nop 0
	global_load_lds_dwordx4 v[220:221], off
	v_lshl_add_u64 v[220:221], s[22:23], 0, v[128:129]
	s_mov_b32 m0, s25
	s_nop 0
	global_load_lds_dwordx4 v[220:221], off
	s_mov_b32 m0, s26
	s_nop 0
	global_load_lds_dwordx4 v[222:223], off
	s_waitcnt lgkmcnt(0)
	s_setprio 1
	s_waitcnt lgkmcnt(0)
	v_mfma_f32_16x16x32_bf16 v[60:63], v[144:147], v[184:187], v[60:63]
	v_mfma_f32_16x16x32_bf16 v[56:59], v[160:163], v[184:187], v[56:59]
	v_mfma_f32_16x16x32_bf16 v[52:55], v[144:147], v[192:195], v[52:55]
	v_mfma_f32_16x16x32_bf16 v[48:51], v[160:163], v[192:195], v[48:51]
	v_mfma_f32_16x16x32_bf16 v[28:31], v[144:147], v[200:203], v[28:31]
	v_mfma_f32_16x16x32_bf16 v[24:27], v[160:163], v[200:203], v[24:27]
	v_mfma_f32_16x16x32_bf16 v[20:23], v[144:147], v[208:211], v[20:23]
	v_mfma_f32_16x16x32_bf16 v[16:19], v[160:163], v[208:211], v[16:19]
	s_waitcnt vmcnt(8)
	s_barrier
; #define PG8_STAGE(bufoff, gbase, voff) do { _Pragma("unroll") for (int _i = 0; _i < 2; ++_i) \
;         __builtin_amdgcn_global_load_lds((const unsigned*)((const char*)(gbase) + (voff)[_i]), (PG8_LAS unsigned*)(lds + (bufoff) + ldsw + _i * 8192), 16, 0, 0); } while (0)
; #define PG8_LDA(dst, b, h) do { _Pragma("unroll") for (int m = 0; m < 4; ++m) _Pragma("unroll") for (int k = 0; k < 2; ++k) dst[m][k] = *(const PG8_LAS bf16x8*)(lds + PG8_SA(b, h) + aoff + m * 2048 + k * 1024); } while (0)
; #define PG8_LDB(dst, b, h) do { _Pragma("unroll") for (int n = 0; n < 2; ++n) _Pragma("unroll") for (int k = 0; k < 2; ++k) dst[n][k] = *(const PG8_LAS bf16x8*)(lds + PG8_SB(b, h) + boff + n * 2048 + k * 1024); } while (0)
; #define PG8_MMA(ai, bj, At, Bt) do { __builtin_amdgcn_s_setprio(1); _Pragma("unroll") for (int m = 0; m < 4; ++m) _Pragma("unroll") for (int n = 0; n < 2; ++n) _Pragma("unroll") for (int k = 0; k < 2; ++k) \
;         acc[ai][bj][m][n] = __builtin_amdgcn_mfma_f32_16x16x32_bf16(Bt[n][k], At[m][k], acc[ai][bj][m][n], 0, 0, 0); __builtin_amdgcn_s_setprio(0); } while (0)
; #define PG8_WAIT_V(n) asm volatile("s_waitcnt vmcnt(" #n ")" ::: "memory")
; #define PG8_WAIT_L(n) asm volatile("s_waitcnt lgkmcnt(" #n ")" ::: "memory")
; #define PG8_BAR __builtin_amdgcn_s_barrier()
; #define PG8_SCHED __builtin_amdgcn_sched_barrier(0)
; template <class Epi, class Sched, bool ALIGN_EPI = false, bool SP2 = false>
; __device__ __forceinline__ void gemm_phase(PG8_LAS unsigned char* lds, const Gemm g, const Sched& S, const Epi& E, int wave0) {
;     ...
;             PG8_WAIT_V(8); PG8_WAIT_L(0); PG8_BAR; if (!cur.half) { PG8_MMA(1, 0, At, B0); PG8_MMA(1, 1, At, B1); } PG8_BAR; PG8_SCHED;
;             PG8_LDB(B0, 1, 0); PG8_LDB(B1, 1, 1); PG8_SCHED; PG8_LDA(At, 1, 0); PG8_STAGE(PG8_SA(0, 1), a2 + hstep, voffA);
;             PG8_WAIT_V(8); PG8_WAIT_L(0); PG8_BAR; PG8_MMA(0, 0, At, B0); PG8_MMA(0, 1, At, B1); PG8_BAR; PG8_SCHED;
;             PG8_LDA(At, 1, 1); PG8_STAGE(PG8_SB(1, 0), b3, voffB); PG8_STAGE(PG8_SB(1, 1), b3 + hstep, voffB); PG8_STAGE(PG8_SA(1, 0), a3, voffA);
	v_mfma_f32_16x16x32_bf16 v[60:63], v[156:159], v[188:191], v[60:63]
	v_mfma_f32_16x16x32_bf16 v[56:59], v[164:167], v[188:191], v[56:59]
	v_mfma_f32_16x16x32_bf16 v[52:55], v[156:159], v[196:199], v[52:55]
	v_mfma_f32_16x16x32_bf16 v[48:51], v[164:167], v[196:199], v[48:51]
	v_mfma_f32_16x16x32_bf16 v[28:31], v[156:159], v[204:207], v[28:31]
	v_mfma_f32_16x16x32_bf16 v[24:27], v[164:167], v[204:207], v[24:27]
	v_mfma_f32_16x16x32_bf16 v[20:23], v[156:159], v[212:215], v[20:23]
	v_mfma_f32_16x16x32_bf16 v[16:19], v[164:167], v[212:215], v[16:19]
	s_setprio 0
	s_setprio 1
	v_mfma_f32_16x16x32_bf16 v[44:47], v[168:171], v[184:187], v[44:47]
	v_mfma_f32_16x16x32_bf16 v[40:43], v[176:179], v[184:187], v[40:43]
	v_mfma_f32_16x16x32_bf16 v[36:39], v[168:171], v[192:195], v[36:39]
	v_mfma_f32_16x16x32_bf16 v[32:35], v[176:179], v[192:195], v[32:35]
	v_mfma_f32_16x16x32_bf16 v[12:15], v[168:171], v[200:203], v[12:15]
	v_mfma_f32_16x16x32_bf16 v[8:11], v[176:179], v[200:203], v[8:11]
	v_mfma_f32_16x16x32_bf16 v[4:7], v[168:171], v[208:211], v[4:7]
	v_mfma_f32_16x16x32_bf16 v[0:3], v[176:179], v[208:211], v[0:3]
	v_mfma_f32_16x16x32_bf16 v[44:47], v[172:175], v[188:191], v[44:47]
	v_mfma_f32_16x16x32_bf16 v[40:43], v[180:183], v[188:191], v[40:43]
	v_mfma_f32_16x16x32_bf16 v[36:39], v[172:175], v[196:199], v[36:39]
	v_mfma_f32_16x16x32_bf16 v[32:35], v[180:183], v[196:199], v[32:35]
	v_mfma_f32_16x16x32_bf16 v[12:15], v[172:175], v[204:207], v[12:15]
	v_mfma_f32_16x16x32_bf16 v[8:11], v[180:183], v[204:207], v[8:11]
	v_mfma_f32_16x16x32_bf16 v[4:7], v[172:175], v[212:215], v[4:7]
	v_mfma_f32_16x16x32_bf16 v[0:3], v[180:183], v[212:215], v[0:3]
	s_setprio 0
	s_barrier
	s_add_i32 s45, 0, 0x18000
	s_add_i32 s46, 0, 0x1c000
	v_add_u32_e32 v164, s45, v152
	v_add_u32_e32 v180, s46, v152
	ds_read_b128 v[144:147], v164
	ds_read_b128 v[156:159], v164 offset:1024
	ds_read_b128 v[160:163], v164 offset:2048
	ds_read_b128 v[164:167], v164 offset:3072
	ds_read_b128 v[168:171], v180
	ds_read_b128 v[172:175], v180 offset:1024
	ds_read_b128 v[176:179], v180 offset:2048
	ds_read_b128 v[180:183], v180 offset:3072
	s_add_u32 s16, s22, 0xb0000
	s_addc_u32 s17, s23, 0
	s_mov_b32 m0, s27
	v_lshl_add_u64 v[224:225], s[16:17], 0, v[128:129]
	ds_read_b128 v[184:187], v155 offset:32768
	ds_read_b128 v[188:191], v155 offset:33792
	ds_read_b128 v[192:195], v155 offset:34816
	ds_read_b128 v[196:199], v155 offset:35840
	ds_read_b128 v[200:203], v155 offset:36864
	ds_read_b128 v[204:207], v155 offset:37888
	ds_read_b128 v[208:211], v155 offset:38912
	ds_read_b128 v[212:215], v155 offset:39936
	global_load_lds_dwordx4 v[224:225], off
	v_lshl_add_u64 v[224:225], s[16:17], 0, v[132:133]
	s_mov_b32 m0, s28
	s_nop 0
	global_load_lds_dwordx4 v[224:225], off
	s_waitcnt lgkmcnt(0)
	s_setprio 1
	s_waitcnt lgkmcnt(0)
	v_mfma_f32_16x16x32_bf16 v[124:127], v[144:147], v[184:187], v[124:127]
	v_mfma_f32_16x16x32_bf16 v[120:123], v[160:163], v[184:187], v[120:123]
	v_mfma_f32_16x16x32_bf16 v[116:119], v[144:147], v[192:195], v[116:119]
	v_mfma_f32_16x16x32_bf16 v[108:111], v[160:163], v[192:195], v[108:111]
	v_mfma_f32_16x16x32_bf16 v[92:95], v[144:147], v[200:203], v[92:95]
	v_mfma_f32_16x16x32_bf16 v[88:91], v[160:163], v[200:203], v[88:91]
	v_mfma_f32_16x16x32_bf16 v[84:87], v[144:147], v[208:211], v[84:87]
	v_mfma_f32_16x16x32_bf16 v[80:83], v[160:163], v[208:211], v[80:83]
	s_waitcnt vmcnt(8)
	s_barrier
	v_mfma_f32_16x16x32_bf16 v[124:127], v[156:159], v[188:191], v[124:127]
	v_mfma_f32_16x16x32_bf16 v[120:123], v[164:167], v[188:191], v[120:123]
	v_mfma_f32_16x16x32_bf16 v[116:119], v[156:159], v[196:199], v[116:119]
	v_mfma_f32_16x16x32_bf16 v[108:111], v[164:167], v[196:199], v[108:111]
	v_mfma_f32_16x16x32_bf16 v[92:95], v[156:159], v[204:207], v[92:95]
	v_mfma_f32_16x16x32_bf16 v[88:91], v[164:167], v[204:207], v[88:91]
	v_mfma_f32_16x16x32_bf16 v[84:87], v[156:159], v[212:215], v[84:87]
	v_mfma_f32_16x16x32_bf16 v[80:83], v[164:167], v[212:215], v[80:83]
	s_setprio 0
	s_setprio 1
	v_mfma_f32_16x16x32_bf16 v[112:115], v[168:171], v[184:187], v[112:115]
	v_mfma_f32_16x16x32_bf16 v[104:107], v[176:179], v[184:187], v[104:107]
	v_mfma_f32_16x16x32_bf16 v[100:103], v[168:171], v[192:195], v[100:103]
	v_mfma_f32_16x16x32_bf16 v[96:99], v[176:179], v[192:195], v[96:99]
	v_mfma_f32_16x16x32_bf16 v[76:79], v[168:171], v[200:203], v[76:79]
	v_mfma_f32_16x16x32_bf16 v[72:75], v[176:179], v[200:203], v[72:75]
	v_mfma_f32_16x16x32_bf16 v[68:71], v[168:171], v[208:211], v[68:71]
	v_mfma_f32_16x16x32_bf16 v[64:67], v[176:179], v[208:211], v[64:67]
	v_mfma_f32_16x16x32_bf16 v[112:115], v[172:175], v[188:191], v[112:115]
	v_mfma_f32_16x16x32_bf16 v[104:107], v[180:183], v[188:191], v[104:107]
	v_mfma_f32_16x16x32_bf16 v[100:103], v[172:175], v[196:199], v[100:103]
	v_mfma_f32_16x16x32_bf16 v[96:99], v[180:183], v[196:199], v[96:99]
	v_mfma_f32_16x16x32_bf16 v[76:79], v[172:175], v[204:207], v[76:79]
	v_mfma_f32_16x16x32_bf16 v[72:75], v[180:183], v[204:207], v[72:75]
	v_mfma_f32_16x16x32_bf16 v[68:71], v[172:175], v[212:215], v[68:71]
	v_mfma_f32_16x16x32_bf16 v[64:67], v[180:183], v[212:215], v[64:67]
	s_setprio 0
	s_barrier
; #define PG8_STAGE(bufoff, gbase, voff) do { _Pragma("unroll") for (int _i = 0; _i < 2; ++_i) \
;         __builtin_amdgcn_global_load_lds((const unsigned*)((const char*)(gbase) + (voff)[_i]), (PG8_LAS unsigned*)(lds + (bufoff) + ldsw + _i * 8192), 16, 0, 0); } while (0)
; #define PG8_LDA(dst, b, h) do { _Pragma("unroll") for (int m = 0; m < 4; ++m) _Pragma("unroll") for (int k = 0; k < 2; ++k) dst[m][k] = *(const PG8_LAS bf16x8*)(lds + PG8_SA(b, h) + aoff + m * 2048 + k * 1024); } while (0)
; #define PG8_MMA(ai, bj, At, Bt) do { __builtin_amdgcn_s_setprio(1); _Pragma("unroll") for (int m = 0; m < 4; ++m) _Pragma("unroll") for (int n = 0; n < 2; ++n) _Pragma("unroll") for (int k = 0; k < 2; ++k) \
;         acc[ai][bj][m][n] = __builtin_amdgcn_mfma_f32_16x16x32_bf16(Bt[n][k], At[m][k], acc[ai][bj][m][n], 0, 0, 0); __builtin_amdgcn_s_setprio(0); } while (0)
; #define PG8_WAIT_V(n) asm volatile("s_waitcnt vmcnt(" #n ")" ::: "memory")
; #define PG8_WAIT_L(n) asm volatile("s_waitcnt lgkmcnt(" #n ")" ::: "memory")
; #define PG8_BAR __builtin_amdgcn_s_barrier()
; #define PG8_SCHED __builtin_amdgcn_sched_barrier(0)
; template <class Epi, class Sched, bool ALIGN_EPI = false, bool SP2 = false>
; __device__ __forceinline__ void gemm_phase(PG8_LAS unsigned char* lds, const Gemm g, const Sched& S, const Epi& E, int wave0) {
;     ...
;             PG8_LDA(At, 1, 1); PG8_STAGE(PG8_SB(1, 0), b3, voffB); PG8_STAGE(PG8_SB(1, 1), b3 + hstep, voffB); PG8_STAGE(PG8_SA(1, 0), a3, voffA);
;             PG8_WAIT_V(8); PG8_WAIT_L(0); PG8_BAR; if (!cur.half) { PG8_MMA(1, 0, At, B0); PG8_MMA(1, 1, At, B1); } PG8_BAR; PG8_SCHED;
;     ...
;         if constexpr (ALIGN_EPI) { if (wr == 0) PG8_BAR; }
	s_add_i32 s16, s45, s24
	v_lshl_add_u64 v[148:149], v[148:149], 0, s[8:9]
	s_mov_b32 m0, s16
	ds_read_b128 v[184:187], v155 offset:49152
	ds_read_b128 v[188:191], v155 offset:50176
	ds_read_b128 v[192:195], v155 offset:51200
	ds_read_b128 v[196:199], v155 offset:52224
	ds_read_b128 v[200:203], v155 offset:53248
	ds_read_b128 v[204:207], v155 offset:54272
	ds_read_b128 v[208:211], v155 offset:55296
	ds_read_b128 v[212:215], v155 offset:56320
	global_load_lds_dwordx4 v[148:149], off
	s_add_i32 m0, s16, 0x2000
	s_add_u32 s16, s20, 0xb0080
	v_lshl_add_u64 v[148:149], v[218:219], 0, s[8:9]
	s_addc_u32 s17, s21, 0
	s_add_i32 s20, s46, s24
	global_load_lds_dwordx4 v[148:149], off
	v_lshl_add_u64 v[148:149], s[16:17], 0, v[130:131]
	s_mov_b32 m0, s20
	s_nop 0
	global_load_lds_dwordx4 v[148:149], off
	v_lshl_add_u64 v[148:149], s[16:17], 0, v[134:135]
	s_add_i32 m0, s20, 0x2000
	s_nop 0
	global_load_lds_dwordx4 v[148:149], off
	v_lshl_add_u64 v[148:149], v[220:221], 0, s[8:9]
	s_mov_b32 m0, s33
	s_nop 0
	global_load_lds_dwordx4 v[148:149], off
	v_lshl_add_u64 v[148:149], v[222:223], 0, s[8:9]
	s_mov_b32 m0, s34
	s_nop 0
	global_load_lds_dwordx4 v[148:149], off
	s_waitcnt lgkmcnt(0)
	s_setprio 1
	s_waitcnt lgkmcnt(0)
	v_mfma_f32_16x16x32_bf16 v[60:63], v[144:147], v[184:187], v[60:63]
	v_mfma_f32_16x16x32_bf16 v[56:59], v[160:163], v[184:187], v[56:59]
	v_mfma_f32_16x16x32_bf16 v[52:55], v[144:147], v[192:195], v[52:55]
	v_mfma_f32_16x16x32_bf16 v[48:51], v[160:163], v[192:195], v[48:51]
	v_mfma_f32_16x16x32_bf16 v[28:31], v[144:147], v[200:203], v[28:31]
	v_mfma_f32_16x16x32_bf16 v[24:27], v[160:163], v[200:203], v[24:27]
	v_mfma_f32_16x16x32_bf16 v[20:23], v[144:147], v[208:211], v[20:23]
	v_mfma_f32_16x16x32_bf16 v[16:19], v[160:163], v[208:211], v[16:19]
	s_waitcnt vmcnt(8)
	s_barrier
	v_mfma_f32_16x16x32_bf16 v[60:63], v[156:159], v[188:191], v[60:63]
	v_mfma_f32_16x16x32_bf16 v[56:59], v[164:167], v[188:191], v[56:59]
	v_mfma_f32_16x16x32_bf16 v[52:55], v[156:159], v[196:199], v[52:55]
	v_mfma_f32_16x16x32_bf16 v[48:51], v[164:167], v[196:199], v[48:51]
	v_mfma_f32_16x16x32_bf16 v[28:31], v[156:159], v[204:207], v[28:31]
	v_mfma_f32_16x16x32_bf16 v[24:27], v[164:167], v[204:207], v[24:27]
	v_mfma_f32_16x16x32_bf16 v[20:23], v[156:159], v[212:215], v[20:23]
	v_mfma_f32_16x16x32_bf16 v[16:19], v[164:167], v[212:215], v[16:19]
	s_setprio 0
	s_setprio 1
	v_mfma_f32_16x16x32_bf16 v[44:47], v[168:171], v[184:187], v[44:47]
	v_mfma_f32_16x16x32_bf16 v[40:43], v[176:179], v[184:187], v[40:43]
	v_mfma_f32_16x16x32_bf16 v[36:39], v[168:171], v[192:195], v[36:39]
	v_mfma_f32_16x16x32_bf16 v[32:35], v[176:179], v[192:195], v[32:35]
	v_mfma_f32_16x16x32_bf16 v[12:15], v[168:171], v[200:203], v[12:15]
	v_mfma_f32_16x16x32_bf16 v[8:11], v[176:179], v[200:203], v[8:11]
	v_mfma_f32_16x16x32_bf16 v[4:7], v[168:171], v[208:211], v[4:7]
	v_mfma_f32_16x16x32_bf16 v[0:3], v[176:179], v[208:211], v[0:3]
	v_mfma_f32_16x16x32_bf16 v[44:47], v[172:175], v[188:191], v[44:47]
	v_mfma_f32_16x16x32_bf16 v[40:43], v[180:183], v[188:191], v[40:43]
	v_mfma_f32_16x16x32_bf16 v[36:39], v[172:175], v[196:199], v[36:39]
	v_mfma_f32_16x16x32_bf16 v[32:35], v[180:183], v[196:199], v[32:35]
	v_mfma_f32_16x16x32_bf16 v[12:15], v[172:175], v[204:207], v[12:15]
	v_mfma_f32_16x16x32_bf16 v[8:11], v[180:183], v[204:207], v[8:11]
	v_mfma_f32_16x16x32_bf16 v[4:7], v[172:175], v[212:215], v[4:7]
	v_mfma_f32_16x16x32_bf16 v[0:3], v[180:183], v[212:215], v[0:3]
	s_setprio 0
	s_barrier
	s_add_i32 s44, s44, 2
	s_add_u32 s42, s42, 0x100
	s_addc_u32 s43, s43, 0
	s_cmp_gt_u32 s44, 41
	s_mov_b64 s[16:17], s[18:19]
	s_cbranch_scc0 .LBB0_3229
	s_and_b64 vcc, exec, s[10:11]
	s_cbranch_vccz .LBB0_3232
	s_barrier
